# GEMM K-loops: loop-counter SALU and next-phase address/m0 setup moved from the MFMA-segment tail (before s_barrier) into the MFMA shadow
# speedup vs baseline: 1.0126x; 1.0015x over previous
; #define PG8_STAGE(bufoff, gbase, voff) do { _Pragma("unroll") for (int _i = 0; _i < 2; ++_i) \
;         __builtin_amdgcn_global_load_lds((const unsigned*)((const char*)(gbase) + (voff)[_i]), (LAS unsigned*)(lds + (bufoff) + ldsw + _i * 8192), 16, 0, 0); } while (0)
; #define PG8_LDA(dst, b, h) do { _Pragma("unroll") for (int m = 0; m < 4; ++m) _Pragma("unroll") for (int k = 0; k < 2; ++k) dst[m][k] = *(const LAS bf16x8*)(lds + PG8_SA(b, h) + aoff + m * 2048 + k * 1024); } while (0)
; #define PG8_LDB(dst, b, h) do { _Pragma("unroll") for (int n = 0; n < 2; ++n) _Pragma("unroll") for (int k = 0; k < 2; ++k) dst[n][k] = *(const LAS bf16x8*)(lds + PG8_SB(b, h) + boff + n * 2048 + k * 1024); } while (0)
; #define PG8_MMA(ai, bj, At, Bt) do { __builtin_amdgcn_s_setprio(1); _Pragma("unroll") for (int m = 0; m < 4; ++m) _Pragma("unroll") for (int n = 0; n < 2; ++n) _Pragma("unroll") for (int k = 0; k < 2; ++k) \
;         acc[ai][bj][m][n] = __builtin_amdgcn_mfma_f32_16x16x32_bf16(Bt[n][k], At[m][k], acc[ai][bj][m][n], 0, 0, 0); __builtin_amdgcn_s_setprio(0); } while (0)
; #define PG8_WAIT_V(n) asm volatile("s_waitcnt vmcnt(" #n ")" ::: "memory")
; #define PG8_WAIT_L(n) asm volatile("s_waitcnt lgkmcnt(" #n ")" ::: "memory")
; #define PG8_BAR __builtin_amdgcn_s_barrier()
; #define PG8_SCHED __builtin_amdgcn_sched_barrier(0)
; template <class Map, class Epi>
; DI void gemm_phase(LAS unsigned char* lds, const Map& MP, const Epi& E, const int nM, const int nN, const int K, const int lda, const int ldb) {
;     ...
;             PG8_LDB(B0, 0, 0); PG8_SCHED; PG8_LDA(At, 0, 0); PG8_STAGE(PG8_SA(1, 1), a1 + hstepA, voffA);
;             PG8_WAIT_L(8); PG8_BAR; PG8_WAIT_L(0); PG8_MMA(0, 0, At, B0); PG8_BAR; PG8_SCHED;
;             PG8_LDB(B1, 0, 1); PG8_STAGE(PG8_SB(0, 0), b2, voffB);
;             PG8_BAR; PG8_WAIT_L(0); PG8_MMA(0, 1, At, B1); PG8_BAR;
;             PG8_LDA(At, 0, 1); PG8_STAGE(PG8_SA(0, 0), a2, voffA);
;             PG8_BAR; PG8_WAIT_L(0); PG8_MMA(1, 0, At, B0); PG8_BAR; PG8_SCHED;
;             PG8_STAGE(PG8_SB(0, 1), b2 + hstepB, voffB);
;             PG8_WAIT_V(6); PG8_BAR; PG8_MMA(1, 1, At, B1); PG8_BAR;
.LBB1_229:
	s_add_u32 s26, s24, 0xfff80080
	s_addc_u32 s27, s25, -1
	s_cmp_eq_u32 s57, 4
	s_cselect_b32 s29, s17, s27
	s_cselect_b32 s28, s43, s26
	s_cselect_b32 s27, s53, s56
	s_cselect_b32 s26, s54, s55
	s_add_i32 m0, s2, 0xc000
	ds_read_b128 v[160:163], v168
	ds_read_b128 v[170:173], v168 offset:1024
	ds_read_b128 v[174:177], v168 offset:2048
	ds_read_b128 v[178:181], v168 offset:3072
	ds_read_b128 v[182:185], v168 offset:4096
	ds_read_b128 v[186:189], v168 offset:5120
	ds_read_b128 v[190:193], v168 offset:6144
	ds_read_b128 v[198:201], v168 offset:7168
	global_load_lds_dwordx4 v154, s[24:25]
	s_add_i32 m0, s2, 0xe000
	s_nop 0
	global_load_lds_dwordx4 v152, s[24:25]
	s_waitcnt lgkmcnt(8)
	s_barrier
	s_setprio 1
	s_waitcnt lgkmcnt(7)
	v_mfma_f32_16x16x32_bf16 v[140:143], v[72:75], v[160:163], v[140:143]
	v_mfma_f32_16x16x32_bf16 v[136:139], v[80:83], v[160:163], v[136:139]
	s_waitcnt lgkmcnt(5)
	v_mfma_f32_16x16x32_bf16 v[124:127], v[72:75], v[174:177], v[124:127]
	v_mfma_f32_16x16x32_bf16 v[120:123], v[80:83], v[174:177], v[120:123]
	s_waitcnt lgkmcnt(3)
	v_mfma_f32_16x16x32_bf16 v[108:111], v[72:75], v[182:185], v[108:111]
	v_mfma_f32_16x16x32_bf16 v[104:107], v[80:83], v[182:185], v[104:107]
	s_waitcnt lgkmcnt(1)
	v_mfma_f32_16x16x32_bf16 v[92:95], v[72:75], v[190:193], v[92:95]
	v_mfma_f32_16x16x32_bf16 v[88:91], v[80:83], v[190:193], v[88:91]
	v_mfma_f32_16x16x32_bf16 v[140:143], v[76:79], v[170:173], v[140:143]
	v_mfma_f32_16x16x32_bf16 v[136:139], v[84:87], v[170:173], v[136:139]
	v_mfma_f32_16x16x32_bf16 v[124:127], v[76:79], v[178:181], v[124:127]
	v_mfma_f32_16x16x32_bf16 v[120:123], v[84:87], v[178:181], v[120:123]
	v_mfma_f32_16x16x32_bf16 v[108:111], v[76:79], v[186:189], v[108:111]
	v_mfma_f32_16x16x32_bf16 v[104:107], v[84:87], v[186:189], v[104:107]
	s_waitcnt lgkmcnt(0)
	v_mfma_f32_16x16x32_bf16 v[92:95], v[76:79], v[198:201], v[92:95]
	v_mfma_f32_16x16x32_bf16 v[88:91], v[84:87], v[198:201], v[88:91]
	s_setprio 0
	s_barrier
	s_add_i32 s58, s48, s34
	v_lshl_add_u64 v[194:195], s[26:27], 0, v[148:149]
	s_mov_b32 m0, s58
	ds_read_b128 v[202:205], v169
	ds_read_b128 v[206:209], v169 offset:1024
	ds_read_b128 v[210:213], v169 offset:2048
	ds_read_b128 v[214:217], v169 offset:3072
	global_load_lds_dwordx4 v[194:195], off
	v_lshl_add_u64 v[218:219], s[26:27], 0, v[144:145]
	s_add_i32 m0, s58, 0x2000
	s_nop 0
	global_load_lds_dwordx4 v[218:219], off
	s_barrier
	s_setprio 1
	s_waitcnt lgkmcnt(3)
	v_mfma_f32_16x16x32_bf16 v[132:135], v[202:205], v[160:163], v[132:135]
	s_waitcnt lgkmcnt(1)
	v_mfma_f32_16x16x32_bf16 v[128:131], v[210:213], v[160:163], v[128:131]
	v_mfma_f32_16x16x32_bf16 v[116:119], v[202:205], v[174:177], v[116:119]
	v_mfma_f32_16x16x32_bf16 v[112:115], v[210:213], v[174:177], v[112:115]
	v_mfma_f32_16x16x32_bf16 v[100:103], v[202:205], v[182:185], v[100:103]
	v_mfma_f32_16x16x32_bf16 v[96:99], v[210:213], v[182:185], v[96:99]
	v_mfma_f32_16x16x32_bf16 v[68:71], v[202:205], v[190:193], v[68:71]
	v_mfma_f32_16x16x32_bf16 v[64:67], v[210:213], v[190:193], v[64:67]
	v_mfma_f32_16x16x32_bf16 v[132:135], v[206:209], v[170:173], v[132:135]
	s_mov_b32 m0, s2
	s_waitcnt lgkmcnt(0)
	v_mfma_f32_16x16x32_bf16 v[128:131], v[214:217], v[170:173], v[128:131]
	v_lshl_add_u64 v[220:221], s[28:29], 0, v[150:151]
	v_mfma_f32_16x16x32_bf16 v[116:119], v[206:209], v[178:181], v[116:119]
	v_mfma_f32_16x16x32_bf16 v[112:115], v[214:217], v[178:181], v[112:115]
	v_mfma_f32_16x16x32_bf16 v[100:103], v[206:209], v[186:189], v[100:103]
	v_mfma_f32_16x16x32_bf16 v[96:99], v[214:217], v[186:189], v[96:99]
	v_mfma_f32_16x16x32_bf16 v[68:71], v[206:209], v[198:201], v[68:71]
	v_mfma_f32_16x16x32_bf16 v[64:67], v[214:217], v[198:201], v[64:67]
	s_setprio 0
	s_barrier
	ds_read_b128 v[160:163], v168 offset:16384
	ds_read_b128 v[170:173], v168 offset:17408
	ds_read_b128 v[174:177], v168 offset:18432
	ds_read_b128 v[178:181], v168 offset:19456
	ds_read_b128 v[182:185], v168 offset:20480
	ds_read_b128 v[186:189], v168 offset:21504
	ds_read_b128 v[190:193], v168 offset:22528
	ds_read_b128 v[198:201], v168 offset:23552
	global_load_lds_dwordx4 v[220:221], off
	v_lshl_add_u64 v[222:223], s[28:29], 0, v[146:147]
	s_mov_b32 m0, s4
	s_nop 0
	global_load_lds_dwordx4 v[222:223], off
	s_waitcnt vmcnt(10)
	s_barrier
	s_setprio 1
	s_waitcnt lgkmcnt(7)
	v_mfma_f32_16x16x32_bf16 v[60:63], v[72:75], v[160:163], v[60:63]
	v_mfma_f32_16x16x32_bf16 v[56:59], v[80:83], v[160:163], v[56:59]
	s_waitcnt lgkmcnt(5)
	v_mfma_f32_16x16x32_bf16 v[44:47], v[72:75], v[174:177], v[44:47]
	v_mfma_f32_16x16x32_bf16 v[40:43], v[80:83], v[174:177], v[40:43]
	s_waitcnt lgkmcnt(3)
	v_mfma_f32_16x16x32_bf16 v[28:31], v[72:75], v[182:185], v[28:31]
	v_mfma_f32_16x16x32_bf16 v[24:27], v[80:83], v[182:185], v[24:27]
	s_waitcnt lgkmcnt(1)
	v_mfma_f32_16x16x32_bf16 v[12:15], v[72:75], v[190:193], v[12:15]
	v_mfma_f32_16x16x32_bf16 v[8:11], v[80:83], v[190:193], v[8:11]
	v_mfma_f32_16x16x32_bf16 v[60:63], v[76:79], v[170:173], v[60:63]
	v_mfma_f32_16x16x32_bf16 v[56:59], v[84:87], v[170:173], v[56:59]
	v_mfma_f32_16x16x32_bf16 v[44:47], v[76:79], v[178:181], v[44:47]
	v_mfma_f32_16x16x32_bf16 v[40:43], v[84:87], v[178:181], v[40:43]
	v_mfma_f32_16x16x32_bf16 v[28:31], v[76:79], v[186:189], v[28:31]
	v_mfma_f32_16x16x32_bf16 v[24:27], v[84:87], v[186:189], v[24:27]
	s_waitcnt lgkmcnt(0)
	v_mfma_f32_16x16x32_bf16 v[12:15], v[76:79], v[198:201], v[12:15]
	v_mfma_f32_16x16x32_bf16 v[8:11], v[84:87], v[198:201], v[8:11]
	s_setprio 0
	s_barrier
	s_add_u32 s58, s26, 0x20000
	s_addc_u32 s59, s27, 0
	s_add_i32 s60, s49, s34
	s_mov_b32 m0, s60
	s_nop 0
	global_load_lds_dwordx4 v148, s[58:59]
	s_add_i32 m0, s60, 0x2000
	s_nop 0
	global_load_lds_dwordx4 v144, s[58:59]
	s_waitcnt vmcnt(6)
	s_barrier
; #define PG8_STAGE(bufoff, gbase, voff) do { _Pragma("unroll") for (int _i = 0; _i < 2; ++_i) \
;         __builtin_amdgcn_global_load_lds((const unsigned*)((const char*)(gbase) + (voff)[_i]), (LAS unsigned*)(lds + (bufoff) + ldsw + _i * 8192), 16, 0, 0); } while (0)
; #define PG8_LDA(dst, b, h) do { _Pragma("unroll") for (int m = 0; m < 4; ++m) _Pragma("unroll") for (int k = 0; k < 2; ++k) dst[m][k] = *(const LAS bf16x8*)(lds + PG8_SA(b, h) + aoff + m * 2048 + k * 1024); } while (0)
; #define PG8_LDB(dst, b, h) do { _Pragma("unroll") for (int n = 0; n < 2; ++n) _Pragma("unroll") for (int k = 0; k < 2; ++k) dst[n][k] = *(const LAS bf16x8*)(lds + PG8_SB(b, h) + boff + n * 2048 + k * 1024); } while (0)
; #define PG8_MMA(ai, bj, At, Bt) do { __builtin_amdgcn_s_setprio(1); _Pragma("unroll") for (int m = 0; m < 4; ++m) _Pragma("unroll") for (int n = 0; n < 2; ++n) _Pragma("unroll") for (int k = 0; k < 2; ++k) \
;         acc[ai][bj][m][n] = __builtin_amdgcn_mfma_f32_16x16x32_bf16(Bt[n][k], At[m][k], acc[ai][bj][m][n], 0, 0, 0); __builtin_amdgcn_s_setprio(0); } while (0)
; #define PG8_WAIT_V(n) asm volatile("s_waitcnt vmcnt(" #n ")" ::: "memory")
; #define PG8_WAIT_L(n) asm volatile("s_waitcnt lgkmcnt(" #n ")" ::: "memory")
; #define PG8_BAR __builtin_amdgcn_s_barrier()
; #define PG8_SCHED __builtin_amdgcn_sched_barrier(0)
; template <class Map, class Epi>
; DI void gemm_phase(LAS unsigned char* lds, const Map& MP, const Epi& E, const int nM, const int nN, const int K, const int lda, const int ldb) {
;     ...
;             PG8_BAR; PG8_WAIT_L(0); PG8_MMA(1, 0, At, B0); PG8_BAR; PG8_SCHED;
;             PG8_STAGE(PG8_SB(0, 1), b2 + hstepB, voffB);
;             PG8_WAIT_V(6); PG8_BAR; PG8_MMA(1, 1, At, B1); PG8_BAR;
;             PG8_LDB(B0, 1, 0); PG8_SCHED; PG8_LDA(At, 1, 0); PG8_STAGE(PG8_SA(0, 1), a2 + hstepA, voffA);
;             PG8_WAIT_L(8); PG8_BAR; PG8_WAIT_L(0); PG8_MMA(0, 0, At, B0); PG8_BAR; PG8_SCHED;
;             PG8_LDB(B1, 1, 1); PG8_STAGE(PG8_SB(1, 0), b3, voffB);
;             PG8_BAR; PG8_WAIT_L(0); PG8_MMA(0, 1, At, B1); PG8_BAR;
;             PG8_LDA(At, 1, 1); PG8_STAGE(PG8_SA(1, 0), a3, voffA);
;             PG8_BAR; PG8_WAIT_L(0); PG8_MMA(1, 0, At, B0); PG8_BAR; PG8_SCHED;
	s_setprio 1
	v_mfma_f32_16x16x32_bf16 v[52:55], v[202:205], v[160:163], v[52:55]
	v_mfma_f32_16x16x32_bf16 v[48:51], v[210:213], v[160:163], v[48:51]
	s_add_i32 s58, 0, 0x18000
	v_add_u32_e32 v84, s58, v166
	ds_read_b128 v[72:75], v84
	v_mfma_f32_16x16x32_bf16 v[36:39], v[202:205], v[174:177], v[36:39]
	v_mfma_f32_16x16x32_bf16 v[32:35], v[210:213], v[174:177], v[32:35]
	ds_read_b128 v[76:79], v84 offset:1024
	v_mfma_f32_16x16x32_bf16 v[20:23], v[202:205], v[182:185], v[20:23]
	v_mfma_f32_16x16x32_bf16 v[16:19], v[210:213], v[182:185], v[16:19]
	ds_read_b128 v[80:83], v84 offset:2048
	v_mfma_f32_16x16x32_bf16 v[4:7], v[202:205], v[190:193], v[4:7]
	v_mfma_f32_16x16x32_bf16 v[0:3], v[210:213], v[190:193], v[0:3]
	ds_read_b128 v[84:87], v84 offset:3072
	v_mfma_f32_16x16x32_bf16 v[52:55], v[206:209], v[170:173], v[52:55]
	v_mfma_f32_16x16x32_bf16 v[48:51], v[214:217], v[170:173], v[48:51]
	v_mfma_f32_16x16x32_bf16 v[36:39], v[206:209], v[178:181], v[36:39]
	v_mfma_f32_16x16x32_bf16 v[32:35], v[214:217], v[178:181], v[32:35]
	v_mfma_f32_16x16x32_bf16 v[20:23], v[206:209], v[186:189], v[20:23]
	v_mfma_f32_16x16x32_bf16 v[16:19], v[214:217], v[186:189], v[16:19]
	v_mfma_f32_16x16x32_bf16 v[4:7], v[206:209], v[198:201], v[4:7]
	v_mfma_f32_16x16x32_bf16 v[0:3], v[214:217], v[198:201], v[0:3]
	s_setprio 0
	s_barrier
	s_add_u32 s28, s28, 0x80000
	s_addc_u32 s29, s29, 0
	s_mov_b32 m0, s5
	ds_read_b128 v[160:163], v168 offset:32768
	ds_read_b128 v[170:173], v168 offset:33792
	ds_read_b128 v[174:177], v168 offset:34816
	ds_read_b128 v[178:181], v168 offset:35840
	ds_read_b128 v[182:185], v168 offset:36864
	ds_read_b128 v[186:189], v168 offset:37888
	ds_read_b128 v[190:193], v168 offset:38912
	ds_read_b128 v[198:201], v168 offset:39936
	global_load_lds_dwordx4 v150, s[28:29]
	s_mov_b32 m0, s23
	s_nop 0
	global_load_lds_dwordx4 v146, s[28:29]
	s_waitcnt lgkmcnt(8)
	s_barrier
	s_setprio 1
	s_waitcnt lgkmcnt(7)
	v_mfma_f32_16x16x32_bf16 v[140:143], v[72:75], v[160:163], v[140:143]
	v_mfma_f32_16x16x32_bf16 v[136:139], v[80:83], v[160:163], v[136:139]
	s_waitcnt lgkmcnt(5)
	v_mfma_f32_16x16x32_bf16 v[124:127], v[72:75], v[174:177], v[124:127]
	v_mfma_f32_16x16x32_bf16 v[120:123], v[80:83], v[174:177], v[120:123]
	s_waitcnt lgkmcnt(3)
	v_mfma_f32_16x16x32_bf16 v[108:111], v[72:75], v[182:185], v[108:111]
	v_mfma_f32_16x16x32_bf16 v[104:107], v[80:83], v[182:185], v[104:107]
	s_waitcnt lgkmcnt(1)
	v_mfma_f32_16x16x32_bf16 v[92:95], v[72:75], v[190:193], v[92:95]
	v_mfma_f32_16x16x32_bf16 v[88:91], v[80:83], v[190:193], v[88:91]
	v_mfma_f32_16x16x32_bf16 v[140:143], v[76:79], v[170:173], v[140:143]
	v_mfma_f32_16x16x32_bf16 v[136:139], v[84:87], v[170:173], v[136:139]
	v_mfma_f32_16x16x32_bf16 v[124:127], v[76:79], v[178:181], v[124:127]
	v_mfma_f32_16x16x32_bf16 v[120:123], v[84:87], v[178:181], v[120:123]
	v_mfma_f32_16x16x32_bf16 v[108:111], v[76:79], v[186:189], v[108:111]
	v_mfma_f32_16x16x32_bf16 v[104:107], v[84:87], v[186:189], v[104:107]
	s_waitcnt lgkmcnt(0)
	v_mfma_f32_16x16x32_bf16 v[92:95], v[76:79], v[198:201], v[92:95]
	v_mfma_f32_16x16x32_bf16 v[88:91], v[84:87], v[198:201], v[88:91]
	s_setprio 0
	s_barrier
	s_add_i32 s28, 0, 0x1c000
	s_add_i32 s29, s58, s34
	v_add_u32_e32 v196, s28, v166
	v_lshl_add_u64 v[194:195], v[194:195], 0, s[12:13]
	s_mov_b32 m0, s29
	ds_read_b128 v[202:205], v196
	ds_read_b128 v[206:209], v196 offset:1024
	ds_read_b128 v[210:213], v196 offset:2048
	ds_read_b128 v[214:217], v196 offset:3072
	global_load_lds_dwordx4 v[194:195], off
	v_lshl_add_u64 v[194:195], v[218:219], 0, s[12:13]
	s_add_i32 m0, s29, 0x2000
	s_nop 0
	global_load_lds_dwordx4 v[194:195], off
	s_barrier
	s_setprio 1
	s_waitcnt lgkmcnt(3)
	v_mfma_f32_16x16x32_bf16 v[132:135], v[202:205], v[160:163], v[132:135]
	s_waitcnt lgkmcnt(1)
	v_mfma_f32_16x16x32_bf16 v[128:131], v[210:213], v[160:163], v[128:131]
	v_mfma_f32_16x16x32_bf16 v[116:119], v[202:205], v[174:177], v[116:119]
	v_mfma_f32_16x16x32_bf16 v[112:115], v[210:213], v[174:177], v[112:115]
	v_mfma_f32_16x16x32_bf16 v[100:103], v[202:205], v[182:185], v[100:103]
	v_mfma_f32_16x16x32_bf16 v[96:99], v[210:213], v[182:185], v[96:99]
	v_mfma_f32_16x16x32_bf16 v[68:71], v[202:205], v[190:193], v[68:71]
	v_mfma_f32_16x16x32_bf16 v[64:67], v[210:213], v[190:193], v[64:67]
	v_mfma_f32_16x16x32_bf16 v[132:135], v[206:209], v[170:173], v[132:135]
	s_mov_b32 m0, s39
	s_waitcnt lgkmcnt(0)
	v_mfma_f32_16x16x32_bf16 v[128:131], v[214:217], v[170:173], v[128:131]
	v_lshl_add_u64 v[194:195], v[220:221], 0, s[12:13]
	v_mfma_f32_16x16x32_bf16 v[116:119], v[206:209], v[178:181], v[116:119]
	v_mfma_f32_16x16x32_bf16 v[112:115], v[214:217], v[178:181], v[112:115]
	v_mfma_f32_16x16x32_bf16 v[100:103], v[206:209], v[186:189], v[100:103]
	v_mfma_f32_16x16x32_bf16 v[96:99], v[214:217], v[186:189], v[96:99]
	v_mfma_f32_16x16x32_bf16 v[68:71], v[206:209], v[198:201], v[68:71]
	v_mfma_f32_16x16x32_bf16 v[64:67], v[214:217], v[198:201], v[64:67]
	s_setprio 0
	s_barrier
; #define PG8_STAGE(bufoff, gbase, voff) do { _Pragma("unroll") for (int _i = 0; _i < 2; ++_i) \
;         __builtin_amdgcn_global_load_lds((const unsigned*)((const char*)(gbase) + (voff)[_i]), (LAS unsigned*)(lds + (bufoff) + ldsw + _i * 8192), 16, 0, 0); } while (0)
; #define PG8_LDA(dst, b, h) do { _Pragma("unroll") for (int m = 0; m < 4; ++m) _Pragma("unroll") for (int k = 0; k < 2; ++k) dst[m][k] = *(const LAS bf16x8*)(lds + PG8_SA(b, h) + aoff + m * 2048 + k * 1024); } while (0)
; #define PG8_MMA(ai, bj, At, Bt) do { __builtin_amdgcn_s_setprio(1); _Pragma("unroll") for (int m = 0; m < 4; ++m) _Pragma("unroll") for (int n = 0; n < 2; ++n) _Pragma("unroll") for (int k = 0; k < 2; ++k) \
;         acc[ai][bj][m][n] = __builtin_amdgcn_mfma_f32_16x16x32_bf16(Bt[n][k], At[m][k], acc[ai][bj][m][n], 0, 0, 0); __builtin_amdgcn_s_setprio(0); } while (0)
; #define PG8_WAIT_V(n) asm volatile("s_waitcnt vmcnt(" #n ")" ::: "memory")
; #define PG8_WAIT_L(n) asm volatile("s_waitcnt lgkmcnt(" #n ")" ::: "memory")
; #define PG8_BAR __builtin_amdgcn_s_barrier()
; #define PG8_SCHED __builtin_amdgcn_sched_barrier(0)
;     DI void operator()(const f32x4 (&acc)[2][2][4][2], const Unit& u, int wr, int wc, int fr, int fq) const {
;         const int row0 = u.pm * BM + wr * 64 + fr, col0 = u.pn * BM + wc * 32 + 8 * fq;
;         f32x4 sc[2][2];
; #pragma unroll
;         for (int bj = 0; bj < 2; ++bj)
; #pragma unroll
;             for (int n = 0; n < 2; ++n) sc[bj][n] = scale ? *(const f32x4*)(scale + col0 + bj * HALF + 4 * n) : (f32x4){1.f, 1.f, 1.f, 1.f};
; #pragma unroll
; template <class Map, class Epi>
; DI void gemm_phase(LAS unsigned char* lds, const Map& MP, const Epi& E, const int nM, const int nN, const int K, const int lda, const int ldb) {
;     ...
;             PG8_BAR; PG8_WAIT_L(0); PG8_MMA(0, 1, At, B1); PG8_BAR;
;             PG8_LDA(At, 1, 1); PG8_STAGE(PG8_SA(1, 0), a3, voffA);
;             PG8_BAR; PG8_WAIT_L(0); PG8_MMA(1, 0, At, B0); PG8_BAR; PG8_SCHED;
;             PG8_STAGE(PG8_SB(1, 1), b3 + hstepB, voffB);
;             PG8_WAIT_V(6); PG8_BAR; PG8_MMA(1, 1, At, B1); PG8_BAR;
;         }
;         { int frr = fr, fqq = fq; asm volatile("" : "+v"(frr), "+v"(fqq)); E(acc, cur, wr, wc, frr, fqq); }
	ds_read_b128 v[160:163], v168 offset:49152
	ds_read_b128 v[170:173], v168 offset:50176
	ds_read_b128 v[174:177], v168 offset:51200
	ds_read_b128 v[178:181], v168 offset:52224
	ds_read_b128 v[182:185], v168 offset:53248
	ds_read_b128 v[186:189], v168 offset:54272
	ds_read_b128 v[190:193], v168 offset:55296
	ds_read_b128 v[198:201], v168 offset:56320
	global_load_lds_dwordx4 v[194:195], off
	v_lshl_add_u64 v[194:195], v[222:223], 0, s[12:13]
	s_mov_b32 m0, s46
	s_nop 0
	global_load_lds_dwordx4 v[194:195], off
	s_waitcnt vmcnt(10)
	s_barrier
	s_setprio 1
	s_waitcnt lgkmcnt(7)
	v_mfma_f32_16x16x32_bf16 v[60:63], v[72:75], v[160:163], v[60:63]
	v_mfma_f32_16x16x32_bf16 v[56:59], v[80:83], v[160:163], v[56:59]
	s_waitcnt lgkmcnt(5)
	v_mfma_f32_16x16x32_bf16 v[44:47], v[72:75], v[174:177], v[44:47]
	v_mfma_f32_16x16x32_bf16 v[40:43], v[80:83], v[174:177], v[40:43]
	s_waitcnt lgkmcnt(3)
	v_mfma_f32_16x16x32_bf16 v[28:31], v[72:75], v[182:185], v[28:31]
	v_mfma_f32_16x16x32_bf16 v[24:27], v[80:83], v[182:185], v[24:27]
	s_waitcnt lgkmcnt(1)
	v_mfma_f32_16x16x32_bf16 v[12:15], v[72:75], v[190:193], v[12:15]
	v_mfma_f32_16x16x32_bf16 v[8:11], v[80:83], v[190:193], v[8:11]
	v_mfma_f32_16x16x32_bf16 v[60:63], v[76:79], v[170:173], v[60:63]
	v_mfma_f32_16x16x32_bf16 v[56:59], v[84:87], v[170:173], v[56:59]
	v_mfma_f32_16x16x32_bf16 v[44:47], v[76:79], v[178:181], v[44:47]
	v_mfma_f32_16x16x32_bf16 v[40:43], v[84:87], v[178:181], v[40:43]
	v_mfma_f32_16x16x32_bf16 v[28:31], v[76:79], v[186:189], v[28:31]
	v_mfma_f32_16x16x32_bf16 v[24:27], v[84:87], v[186:189], v[24:27]
	s_waitcnt lgkmcnt(0)
	v_mfma_f32_16x16x32_bf16 v[12:15], v[76:79], v[198:201], v[12:15]
	v_mfma_f32_16x16x32_bf16 v[8:11], v[84:87], v[198:201], v[8:11]
	s_setprio 0
	s_barrier
	s_add_u32 s26, s26, 0x20080
	s_addc_u32 s27, s27, 0
	s_add_i32 s28, s28, s34
	s_mov_b32 m0, s28
	s_nop 0
	global_load_lds_dwordx4 v148, s[26:27]
	s_add_i32 m0, s28, 0x2000
	s_nop 0
	global_load_lds_dwordx4 v144, s[26:27]
	s_waitcnt vmcnt(6)
	s_barrier
	s_setprio 1
	v_mfma_f32_16x16x32_bf16 v[52:55], v[202:205], v[160:163], v[52:55]
	v_mfma_f32_16x16x32_bf16 v[48:51], v[210:213], v[160:163], v[48:51]
	ds_read_b128 v[72:75], v167
	v_mfma_f32_16x16x32_bf16 v[36:39], v[202:205], v[174:177], v[36:39]
	v_mfma_f32_16x16x32_bf16 v[32:35], v[210:213], v[174:177], v[32:35]
	ds_read_b128 v[76:79], v167 offset:1024
	v_mfma_f32_16x16x32_bf16 v[20:23], v[202:205], v[182:185], v[20:23]
	v_mfma_f32_16x16x32_bf16 v[16:19], v[210:213], v[182:185], v[16:19]
	ds_read_b128 v[80:83], v167 offset:2048
	v_mfma_f32_16x16x32_bf16 v[4:7], v[202:205], v[190:193], v[4:7]
	v_mfma_f32_16x16x32_bf16 v[0:3], v[210:213], v[190:193], v[0:3]
	ds_read_b128 v[84:87], v167 offset:3072
	v_mfma_f32_16x16x32_bf16 v[52:55], v[206:209], v[170:173], v[52:55]
	s_add_i32 s57, s57, 2
	v_mfma_f32_16x16x32_bf16 v[48:51], v[214:217], v[170:173], v[48:51]
	s_add_u32 s55, s55, 0x100
	s_addc_u32 s56, s56, 0
	v_mfma_f32_16x16x32_bf16 v[36:39], v[206:209], v[178:181], v[36:39]
	s_add_u32 s24, s24, 0x100
	s_addc_u32 s25, s25, 0
	v_mfma_f32_16x16x32_bf16 v[32:35], v[214:217], v[178:181], v[32:35]
	s_cmp_gt_u32 s57, 5
	v_mfma_f32_16x16x32_bf16 v[20:23], v[206:209], v[186:189], v[20:23]
	v_mfma_f32_16x16x32_bf16 v[16:19], v[214:217], v[186:189], v[16:19]
	v_mfma_f32_16x16x32_bf16 v[4:7], v[206:209], v[198:201], v[4:7]
	v_mfma_f32_16x16x32_bf16 v[0:3], v[214:217], v[198:201], v[0:3]
	s_setprio 0
	s_barrier
	s_cbranch_scc0 .LBB1_229
	s_waitcnt lgkmcnt(0)
	s_lshl_b32 s17, s42, 8
	v_mov_b32_e32 v170, v164
	v_mov_b32_e32 v72, v165
	s_or_b32 s17, s17, s38
	v_mov_b32_e32 v80, 1.0
	v_lshl_add_u32 v160, v72, 3, s17
	v_ashrrev_i32_e32 v161, 31, v160
	v_cndmask_b32_e64 v72, 0, 1, s[14:15]
	v_lshl_add_u64 v[162:163], v[160:161], 2, s[8:9]
	v_cmp_ne_u32_e64 s[42:43], 1, v72
	s_andn2_b64 vcc, exec, s[14:15]
	v_mov_b32_e32 v84, 1.0
	v_mov_b32_e32 v85, 1.0
	v_mov_b32_e32 v86, 1.0
	v_mov_b32_e32 v87, 1.0
	s_cbranch_vccnz .LBB1_232
	global_load_dwordx4 v[84:87], v[162:163], off

; #define PG8_STAGE(bufoff, gbase, voff) do { _Pragma("unroll") for (int _i = 0; _i < 2; ++_i) \
;         __builtin_amdgcn_global_load_lds((const unsigned*)((const char*)(gbase) + (voff)[_i]), (LAS unsigned*)(lds + (bufoff) + ldsw + _i * 8192), 16, 0, 0); } while (0)
; #define PG8_LDA(dst, b, h) do { _Pragma("unroll") for (int m = 0; m < 4; ++m) _Pragma("unroll") for (int k = 0; k < 2; ++k) dst[m][k] = *(const LAS bf16x8*)(lds + PG8_SA(b, h) + aoff + m * 2048 + k * 1024); } while (0)
; #define PG8_LDB(dst, b, h) do { _Pragma("unroll") for (int n = 0; n < 2; ++n) _Pragma("unroll") for (int k = 0; k < 2; ++k) dst[n][k] = *(const LAS bf16x8*)(lds + PG8_SB(b, h) + boff + n * 2048 + k * 1024); } while (0)
; #define PG8_MMA(ai, bj, At, Bt) do { __builtin_amdgcn_s_setprio(1); _Pragma("unroll") for (int m = 0; m < 4; ++m) _Pragma("unroll") for (int n = 0; n < 2; ++n) _Pragma("unroll") for (int k = 0; k < 2; ++k) \
;         acc[ai][bj][m][n] = __builtin_amdgcn_mfma_f32_16x16x32_bf16(Bt[n][k], At[m][k], acc[ai][bj][m][n], 0, 0, 0); __builtin_amdgcn_s_setprio(0); } while (0)
; #define PG8_WAIT_L(n) asm volatile("s_waitcnt lgkmcnt(" #n ")" ::: "memory")
; #define PG8_BAR __builtin_amdgcn_s_barrier()
; #define PG8_SCHED __builtin_amdgcn_sched_barrier(0)
; template <class Map, class Epi>
; DI void gemm_phase(LAS unsigned char* lds, const Map& MP, const Epi& E, const int nM, const int nN, const int K, const int lda, const int ldb) {
;     ...
;             PG8_LDB(B0, 0, 0); PG8_SCHED; PG8_LDA(At, 0, 0); PG8_STAGE(PG8_SA(1, 1), a1 + hstepA, voffA);
;             PG8_WAIT_L(8); PG8_BAR; PG8_WAIT_L(0); PG8_MMA(0, 0, At, B0); PG8_BAR; PG8_SCHED;
;             PG8_LDB(B1, 0, 1); PG8_STAGE(PG8_SB(0, 0), b2, voffB);
;             PG8_BAR; PG8_WAIT_L(0); PG8_MMA(0, 1, At, B1); PG8_BAR;
;             PG8_LDA(At, 0, 1); PG8_STAGE(PG8_SA(0, 0), a2, voffA);
;             PG8_BAR; PG8_WAIT_L(0); PG8_MMA(1, 0, At, B0); PG8_BAR; PG8_SCHED;
.LBB1_380:
	s_add_u32 s28, s44, 0xfff80080
	s_addc_u32 s29, s45, -1
	s_cmp_eq_u32 vcc_hi, 28
	s_cselect_b32 s47, s23, s29
	s_cselect_b32 s46, s61, s28
	s_cselect_b32 s29, s21, vcc_lo
	s_cselect_b32 s28, s58, s59
	s_add_i32 m0, s38, 0xc000
	ds_read_b128 v[96:99], v190
	ds_read_b128 v[100:103], v190 offset:1024
	ds_read_b128 v[108:111], v190 offset:2048
	ds_read_b128 v[112:115], v190 offset:3072
	ds_read_b128 v[160:163], v190 offset:4096
	ds_read_b128 v[164:167], v190 offset:5120
	ds_read_b128 v[198:201], v190 offset:6144
	ds_read_b128 v[202:205], v190 offset:7168
	global_load_lds_dwordx4 v178, s[44:45]
	s_add_i32 m0, s38, 0xe000
	s_nop 0
	global_load_lds_dwordx4 v176, s[44:45]
	s_waitcnt lgkmcnt(8)
	s_barrier
	s_setprio 1
	s_waitcnt lgkmcnt(7)
	v_mfma_f32_16x16x32_bf16 v[148:151], v[80:83], v[96:99], v[148:151]
	v_mfma_f32_16x16x32_bf16 v[144:147], v[88:91], v[96:99], v[144:147]
	s_waitcnt lgkmcnt(5)
	v_mfma_f32_16x16x32_bf16 v[136:139], v[80:83], v[108:111], v[136:139]
	v_mfma_f32_16x16x32_bf16 v[128:131], v[88:91], v[108:111], v[128:131]
	s_waitcnt lgkmcnt(3)
	v_mfma_f32_16x16x32_bf16 v[120:123], v[80:83], v[160:163], v[120:123]
	v_mfma_f32_16x16x32_bf16 v[104:107], v[88:91], v[160:163], v[104:107]
	s_waitcnt lgkmcnt(1)
	v_mfma_f32_16x16x32_bf16 v[76:79], v[80:83], v[198:201], v[76:79]
	v_mfma_f32_16x16x32_bf16 v[72:75], v[88:91], v[198:201], v[72:75]
	v_mfma_f32_16x16x32_bf16 v[148:151], v[84:87], v[100:103], v[148:151]
	v_mfma_f32_16x16x32_bf16 v[144:147], v[92:95], v[100:103], v[144:147]
	v_mfma_f32_16x16x32_bf16 v[136:139], v[84:87], v[112:115], v[136:139]
	v_mfma_f32_16x16x32_bf16 v[128:131], v[92:95], v[112:115], v[128:131]
	v_mfma_f32_16x16x32_bf16 v[120:123], v[84:87], v[164:167], v[120:123]
	v_mfma_f32_16x16x32_bf16 v[104:107], v[92:95], v[164:167], v[104:107]
	s_waitcnt lgkmcnt(0)
	v_mfma_f32_16x16x32_bf16 v[76:79], v[84:87], v[202:205], v[76:79]
	v_mfma_f32_16x16x32_bf16 v[72:75], v[92:95], v[202:205], v[72:75]
	s_setprio 0
	s_barrier
	s_add_i32 s68, s5, s37
	v_lshl_add_u64 v[184:185], s[28:29], 0, v[172:173]
	s_mov_b32 m0, s68
	ds_read_b128 v[206:209], v191
	ds_read_b128 v[210:213], v191 offset:1024
	ds_read_b128 v[214:217], v191 offset:2048
	ds_read_b128 v[218:221], v191 offset:3072
	global_load_lds_dwordx4 v[184:185], off
	v_lshl_add_u64 v[194:195], s[28:29], 0, v[168:169]
	s_add_i32 m0, s68, 0x2000
	s_nop 0
	global_load_lds_dwordx4 v[194:195], off
	s_barrier
	s_setprio 1
	s_waitcnt lgkmcnt(3)
	v_mfma_f32_16x16x32_bf16 v[156:159], v[206:209], v[96:99], v[156:159]
	s_waitcnt lgkmcnt(1)
	v_mfma_f32_16x16x32_bf16 v[96:99], v[214:217], v[96:99], v[152:155]
	v_mfma_f32_16x16x32_bf16 v[156:159], v[210:213], v[100:103], v[156:159]
	s_waitcnt lgkmcnt(0)
	v_mfma_f32_16x16x32_bf16 v[96:99], v[218:221], v[100:103], v[96:99]
	v_mfma_f32_16x16x32_bf16 v[100:103], v[206:209], v[108:111], v[140:143]
	v_mfma_f32_16x16x32_bf16 v[108:111], v[214:217], v[108:111], v[132:135]
	v_mfma_f32_16x16x32_bf16 v[116:119], v[214:217], v[160:163], v[116:119]
	v_mfma_f32_16x16x32_bf16 v[68:71], v[206:209], v[198:201], v[68:71]
	v_mfma_f32_16x16x32_bf16 v[64:67], v[214:217], v[198:201], v[64:67]
	s_mov_b32 m0, s38
	v_mfma_f32_16x16x32_bf16 v[100:103], v[210:213], v[112:115], v[100:103]
	v_lshl_add_u64 v[226:227], s[46:47], 0, v[174:175]
	v_mfma_f32_16x16x32_bf16 v[108:111], v[218:221], v[112:115], v[108:111]
	v_mfma_f32_16x16x32_bf16 v[112:115], v[206:209], v[160:163], v[124:127]
	v_mfma_f32_16x16x32_bf16 v[116:119], v[218:221], v[164:167], v[116:119]
	v_mfma_f32_16x16x32_bf16 v[68:71], v[210:213], v[202:205], v[68:71]
	v_mfma_f32_16x16x32_bf16 v[64:67], v[218:221], v[202:205], v[64:67]
	v_mfma_f32_16x16x32_bf16 v[112:115], v[210:213], v[164:167], v[112:115]
	s_setprio 0
	s_barrier
	ds_read_b128 v[124:127], v190 offset:16384
	ds_read_b128 v[132:135], v190 offset:17408
	ds_read_b128 v[140:143], v190 offset:18432
	ds_read_b128 v[152:155], v190 offset:19456
	ds_read_b128 v[160:163], v190 offset:20480
	ds_read_b128 v[164:167], v190 offset:21504
	ds_read_b128 v[198:201], v190 offset:22528
	ds_read_b128 v[202:205], v190 offset:23552
	global_load_lds_dwordx4 v[226:227], off
	v_lshl_add_u64 v[234:235], s[46:47], 0, v[170:171]
	s_mov_b32 m0, s39
	s_nop 0
	global_load_lds_dwordx4 v[234:235], off
	s_waitcnt vmcnt(10)
	s_barrier
	s_setprio 1
	s_waitcnt lgkmcnt(7)
	v_mfma_f32_16x16x32_bf16 v[60:63], v[80:83], v[124:127], v[60:63]
	v_mfma_f32_16x16x32_bf16 v[48:51], v[88:91], v[124:127], v[48:51]
	s_waitcnt lgkmcnt(5)
	v_mfma_f32_16x16x32_bf16 v[40:43], v[80:83], v[140:143], v[40:43]
	v_mfma_f32_16x16x32_bf16 v[32:35], v[88:91], v[140:143], v[32:35]
	s_waitcnt lgkmcnt(3)
	v_mfma_f32_16x16x32_bf16 v[24:27], v[80:83], v[160:163], v[24:27]
	v_mfma_f32_16x16x32_bf16 v[16:19], v[88:91], v[160:163], v[16:19]
	s_waitcnt lgkmcnt(1)
	v_mfma_f32_16x16x32_bf16 v[12:15], v[80:83], v[198:201], v[12:15]
	v_mfma_f32_16x16x32_bf16 v[8:11], v[88:91], v[198:201], v[8:11]
	v_mfma_f32_16x16x32_bf16 v[60:63], v[84:87], v[132:135], v[60:63]
	v_mfma_f32_16x16x32_bf16 v[48:51], v[92:95], v[132:135], v[48:51]
	v_mfma_f32_16x16x32_bf16 v[40:43], v[84:87], v[152:155], v[40:43]
	v_mfma_f32_16x16x32_bf16 v[32:35], v[92:95], v[152:155], v[32:35]
	v_mfma_f32_16x16x32_bf16 v[24:27], v[84:87], v[164:167], v[24:27]
	v_mfma_f32_16x16x32_bf16 v[16:19], v[92:95], v[164:167], v[16:19]
	s_waitcnt lgkmcnt(0)
	v_mfma_f32_16x16x32_bf16 v[12:15], v[84:87], v[202:205], v[12:15]
	v_mfma_f32_16x16x32_bf16 v[8:11], v[92:95], v[202:205], v[8:11]
	s_setprio 0
	s_barrier
	s_add_u32 s68, s28, 0x80000
	s_addc_u32 s69, s29, 0
	s_add_i32 s70, s2, s37
	s_mov_b32 m0, s70
	s_nop 0
	global_load_lds_dwordx4 v172, s[68:69]
	s_add_i32 m0, s70, 0x2000
	s_nop 0
	global_load_lds_dwordx4 v168, s[68:69]
	s_waitcnt vmcnt(6)
	s_barrier
; #define PG8_STAGE(bufoff, gbase, voff) do { _Pragma("unroll") for (int _i = 0; _i < 2; ++_i) \
;         __builtin_amdgcn_global_load_lds((const unsigned*)((const char*)(gbase) + (voff)[_i]), (LAS unsigned*)(lds + (bufoff) + ldsw + _i * 8192), 16, 0, 0); } while (0)
; #define PG8_LDA(dst, b, h) do { _Pragma("unroll") for (int m = 0; m < 4; ++m) _Pragma("unroll") for (int k = 0; k < 2; ++k) dst[m][k] = *(const LAS bf16x8*)(lds + PG8_SA(b, h) + aoff + m * 2048 + k * 1024); } while (0)
; #define PG8_LDB(dst, b, h) do { _Pragma("unroll") for (int n = 0; n < 2; ++n) _Pragma("unroll") for (int k = 0; k < 2; ++k) dst[n][k] = *(const LAS bf16x8*)(lds + PG8_SB(b, h) + boff + n * 2048 + k * 1024); } while (0)
; #define PG8_MMA(ai, bj, At, Bt) do { __builtin_amdgcn_s_setprio(1); _Pragma("unroll") for (int m = 0; m < 4; ++m) _Pragma("unroll") for (int n = 0; n < 2; ++n) _Pragma("unroll") for (int k = 0; k < 2; ++k) \
;         acc[ai][bj][m][n] = __builtin_amdgcn_mfma_f32_16x16x32_bf16(Bt[n][k], At[m][k], acc[ai][bj][m][n], 0, 0, 0); __builtin_amdgcn_s_setprio(0); } while (0)
; #define PG8_WAIT_V(n) asm volatile("s_waitcnt vmcnt(" #n ")" ::: "memory")
; #define PG8_WAIT_L(n) asm volatile("s_waitcnt lgkmcnt(" #n ")" ::: "memory")
; #define PG8_BAR __builtin_amdgcn_s_barrier()
; #define PG8_SCHED __builtin_amdgcn_sched_barrier(0)
; template <class Map, class Epi>
; DI void gemm_phase(LAS unsigned char* lds, const Map& MP, const Epi& E, const int nM, const int nN, const int K, const int lda, const int ldb) {
;     ...
;             PG8_BAR; PG8_WAIT_L(0); PG8_MMA(1, 0, At, B0); PG8_BAR; PG8_SCHED;
;             PG8_STAGE(PG8_SB(0, 1), b2 + hstepB, voffB);
;             PG8_WAIT_V(6); PG8_BAR; PG8_MMA(1, 1, At, B1); PG8_BAR;
;             PG8_LDB(B0, 1, 0); PG8_SCHED; PG8_LDA(At, 1, 0); PG8_STAGE(PG8_SA(0, 1), a2 + hstepA, voffA);
;             PG8_WAIT_L(8); PG8_BAR; PG8_WAIT_L(0); PG8_MMA(0, 0, At, B0); PG8_BAR; PG8_SCHED;
;             PG8_LDB(B1, 1, 1); PG8_STAGE(PG8_SB(1, 0), b3, voffB);
;             PG8_BAR; PG8_WAIT_L(0); PG8_MMA(0, 1, At, B1); PG8_BAR;
;             PG8_LDA(At, 1, 1); PG8_STAGE(PG8_SA(1, 0), a3, voffA);
;             PG8_BAR; PG8_WAIT_L(0); PG8_MMA(1, 0, At, B0); PG8_BAR; PG8_SCHED;
	s_setprio 1
	v_mfma_f32_16x16x32_bf16 v[56:59], v[206:209], v[124:127], v[56:59]
	v_mfma_f32_16x16x32_bf16 v[52:55], v[214:217], v[124:127], v[52:55]
	s_add_i32 s68, 0, 0x18000
	v_add_u32_e32 v92, s68, v188
	ds_read_b128 v[80:83], v92
	v_mfma_f32_16x16x32_bf16 v[44:47], v[206:209], v[140:143], v[44:47]
	v_mfma_f32_16x16x32_bf16 v[36:39], v[214:217], v[140:143], v[36:39]
	ds_read_b128 v[84:87], v92 offset:1024
	v_mfma_f32_16x16x32_bf16 v[28:31], v[206:209], v[160:163], v[28:31]
	v_mfma_f32_16x16x32_bf16 v[20:23], v[214:217], v[160:163], v[20:23]
	ds_read_b128 v[88:91], v92 offset:2048
	v_mfma_f32_16x16x32_bf16 v[4:7], v[206:209], v[198:201], v[4:7]
	v_mfma_f32_16x16x32_bf16 v[0:3], v[214:217], v[198:201], v[0:3]
	ds_read_b128 v[92:95], v92 offset:3072
	v_mfma_f32_16x16x32_bf16 v[56:59], v[210:213], v[132:135], v[56:59]
	v_mfma_f32_16x16x32_bf16 v[52:55], v[218:221], v[132:135], v[52:55]
	v_mfma_f32_16x16x32_bf16 v[44:47], v[210:213], v[152:155], v[44:47]
	v_mfma_f32_16x16x32_bf16 v[36:39], v[218:221], v[152:155], v[36:39]
	v_mfma_f32_16x16x32_bf16 v[28:31], v[210:213], v[164:167], v[28:31]
	v_mfma_f32_16x16x32_bf16 v[20:23], v[218:221], v[164:167], v[20:23]
	v_mfma_f32_16x16x32_bf16 v[4:7], v[210:213], v[202:205], v[4:7]
	v_mfma_f32_16x16x32_bf16 v[0:3], v[218:221], v[202:205], v[0:3]
	s_setprio 0
	s_barrier
	s_add_u32 s46, s46, 0x80000
	s_addc_u32 s47, s47, 0
	s_mov_b32 m0, s56
	ds_read_b128 v[124:127], v190 offset:32768
	ds_read_b128 v[132:135], v190 offset:33792
	ds_read_b128 v[160:163], v190 offset:34816
	ds_read_b128 v[164:167], v190 offset:35840
	ds_read_b128 v[198:201], v190 offset:36864
	ds_read_b128 v[202:205], v190 offset:37888
	ds_read_b128 v[206:209], v190 offset:38912
	ds_read_b128 v[210:213], v190 offset:39936
	global_load_lds_dwordx4 v174, s[46:47]
	s_mov_b32 m0, s57
	s_nop 0
	global_load_lds_dwordx4 v170, s[46:47]
	s_waitcnt lgkmcnt(8)
	s_barrier
	s_setprio 1
	s_waitcnt lgkmcnt(7)
	v_mfma_f32_16x16x32_bf16 v[140:143], v[80:83], v[124:127], v[148:151]
	s_waitcnt lgkmcnt(6)
	v_mfma_f32_16x16x32_bf16 v[148:151], v[84:87], v[132:135], v[140:143]
	v_mfma_f32_16x16x32_bf16 v[140:143], v[88:91], v[124:127], v[144:147]
	s_waitcnt lgkmcnt(5)
	v_mfma_f32_16x16x32_bf16 v[136:139], v[80:83], v[160:163], v[136:139]
	v_mfma_f32_16x16x32_bf16 v[128:131], v[88:91], v[160:163], v[128:131]
	s_waitcnt lgkmcnt(3)
	v_mfma_f32_16x16x32_bf16 v[120:123], v[80:83], v[198:201], v[120:123]
	v_mfma_f32_16x16x32_bf16 v[104:107], v[88:91], v[198:201], v[104:107]
	s_waitcnt lgkmcnt(1)
	v_mfma_f32_16x16x32_bf16 v[76:79], v[80:83], v[206:209], v[76:79]
	v_mfma_f32_16x16x32_bf16 v[72:75], v[88:91], v[206:209], v[72:75]
	v_mfma_f32_16x16x32_bf16 v[144:147], v[92:95], v[132:135], v[140:143]
	v_mfma_f32_16x16x32_bf16 v[136:139], v[84:87], v[164:167], v[136:139]
	v_mfma_f32_16x16x32_bf16 v[128:131], v[92:95], v[164:167], v[128:131]
	v_mfma_f32_16x16x32_bf16 v[120:123], v[84:87], v[202:205], v[120:123]
	v_mfma_f32_16x16x32_bf16 v[104:107], v[92:95], v[202:205], v[104:107]
	s_waitcnt lgkmcnt(0)
	v_mfma_f32_16x16x32_bf16 v[76:79], v[84:87], v[210:213], v[76:79]
	v_mfma_f32_16x16x32_bf16 v[72:75], v[92:95], v[210:213], v[72:75]
	s_setprio 0
	s_barrier
	s_add_i32 s46, 0, 0x1c000
	v_add_u32_e32 v140, s46, v188
	s_add_i32 s47, s68, s37
	ds_read_b128 v[214:217], v140
	ds_read_b128 v[218:221], v140 offset:1024
	ds_read_b128 v[222:225], v140 offset:2048
	ds_read_b128 v[230:233], v140 offset:3072
	v_lshl_add_u64 v[140:141], v[184:185], 0, s[14:15]
	s_mov_b32 m0, s47
	s_nop 0
	global_load_lds_dwordx4 v[140:141], off
	v_lshl_add_u64 v[140:141], v[194:195], 0, s[14:15]
	s_add_i32 m0, s47, 0x2000
	s_nop 0
	global_load_lds_dwordx4 v[140:141], off
	s_barrier
	s_setprio 1
	s_waitcnt lgkmcnt(1)
	v_mfma_f32_16x16x32_bf16 v[96:99], v[222:225], v[124:127], v[96:99]
	v_mfma_f32_16x16x32_bf16 v[140:143], v[214:217], v[124:127], v[156:159]
	s_waitcnt lgkmcnt(0)
	v_mfma_f32_16x16x32_bf16 v[152:155], v[230:233], v[132:135], v[96:99]
	v_mfma_f32_16x16x32_bf16 v[96:99], v[214:217], v[160:163], v[100:103]
	v_mfma_f32_16x16x32_bf16 v[156:159], v[218:221], v[132:135], v[140:143]
	v_mfma_f32_16x16x32_bf16 v[140:143], v[218:221], v[164:167], v[96:99]
	v_mfma_f32_16x16x32_bf16 v[96:99], v[222:225], v[160:163], v[108:111]
	v_mfma_f32_16x16x32_bf16 v[132:135], v[230:233], v[164:167], v[96:99]
	v_mfma_f32_16x16x32_bf16 v[96:99], v[214:217], v[198:201], v[112:115]
	s_mov_b32 m0, s62
	v_mfma_f32_16x16x32_bf16 v[124:127], v[218:221], v[202:205], v[96:99]
	v_lshl_add_u64 v[184:185], v[226:227], 0, s[14:15]
	v_mfma_f32_16x16x32_bf16 v[96:99], v[222:225], v[198:201], v[116:119]
	v_mfma_f32_16x16x32_bf16 v[68:71], v[214:217], v[206:209], v[68:71]
	v_mfma_f32_16x16x32_bf16 v[64:67], v[222:225], v[206:209], v[64:67]
	v_mfma_f32_16x16x32_bf16 v[116:119], v[230:233], v[202:205], v[96:99]
	v_mfma_f32_16x16x32_bf16 v[68:71], v[218:221], v[210:213], v[68:71]
	v_mfma_f32_16x16x32_bf16 v[64:67], v[230:233], v[210:213], v[64:67]
	s_setprio 0
	s_barrier
	ds_read_b128 v[96:99], v190 offset:49152
	ds_read_b128 v[100:103], v190 offset:50176
	ds_read_b128 v[108:111], v190 offset:51200
	ds_read_b128 v[112:115], v190 offset:52224
	ds_read_b128 v[160:163], v190 offset:53248
	ds_read_b128 v[164:167], v190 offset:54272
	ds_read_b128 v[198:201], v190 offset:55296
	ds_read_b128 v[202:205], v190 offset:56320
	global_load_lds_dwordx4 v[184:185], off
	v_lshl_add_u64 v[184:185], v[234:235], 0, s[14:15]
	s_mov_b32 m0, s63
	s_nop 0
	global_load_lds_dwordx4 v[184:185], off
	s_waitcnt vmcnt(10)
	s_barrier
; #define PG8_STAGE(bufoff, gbase, voff) do { _Pragma("unroll") for (int _i = 0; _i < 2; ++_i) \
;         __builtin_amdgcn_global_load_lds((const unsigned*)((const char*)(gbase) + (voff)[_i]), (LAS unsigned*)(lds + (bufoff) + ldsw + _i * 8192), 16, 0, 0); } while (0)
; #define PG8_MMA(ai, bj, At, Bt) do { __builtin_amdgcn_s_setprio(1); _Pragma("unroll") for (int m = 0; m < 4; ++m) _Pragma("unroll") for (int n = 0; n < 2; ++n) _Pragma("unroll") for (int k = 0; k < 2; ++k) \
;         acc[ai][bj][m][n] = __builtin_amdgcn_mfma_f32_16x16x32_bf16(Bt[n][k], At[m][k], acc[ai][bj][m][n], 0, 0, 0); __builtin_amdgcn_s_setprio(0); } while (0)
; #define PG8_WAIT_V(n) asm volatile("s_waitcnt vmcnt(" #n ")" ::: "memory")
; #define PG8_WAIT_L(n) asm volatile("s_waitcnt lgkmcnt(" #n ")" ::: "memory")
; #define PG8_BAR __builtin_amdgcn_s_barrier()
; #define PG8_SCHED __builtin_amdgcn_sched_barrier(0)
; template <class Map, class Epi>
; DI void gemm_phase(LAS unsigned char* lds, const Map& MP, const Epi& E, const int nM, const int nN, const int K, const int lda, const int ldb) {
;     ...
;             PG8_BAR; PG8_WAIT_L(0); PG8_MMA(1, 0, At, B0); PG8_BAR; PG8_SCHED;
;             PG8_STAGE(PG8_SB(1, 1), b3 + hstepB, voffB);
;             PG8_WAIT_V(6); PG8_BAR; PG8_MMA(1, 1, At, B1); PG8_BAR;
;         }
	s_setprio 1
	s_waitcnt lgkmcnt(7)
	v_mfma_f32_16x16x32_bf16 v[60:63], v[80:83], v[96:99], v[60:63]
	v_mfma_f32_16x16x32_bf16 v[48:51], v[88:91], v[96:99], v[48:51]
	s_waitcnt lgkmcnt(5)
	v_mfma_f32_16x16x32_bf16 v[40:43], v[80:83], v[108:111], v[40:43]
	v_mfma_f32_16x16x32_bf16 v[32:35], v[88:91], v[108:111], v[32:35]
	s_waitcnt lgkmcnt(3)
	v_mfma_f32_16x16x32_bf16 v[24:27], v[80:83], v[160:163], v[24:27]
	v_mfma_f32_16x16x32_bf16 v[16:19], v[88:91], v[160:163], v[16:19]
	s_waitcnt lgkmcnt(1)
	v_mfma_f32_16x16x32_bf16 v[12:15], v[80:83], v[198:201], v[12:15]
	v_mfma_f32_16x16x32_bf16 v[8:11], v[88:91], v[198:201], v[8:11]
	v_mfma_f32_16x16x32_bf16 v[60:63], v[84:87], v[100:103], v[60:63]
	v_mfma_f32_16x16x32_bf16 v[48:51], v[92:95], v[100:103], v[48:51]
	v_mfma_f32_16x16x32_bf16 v[40:43], v[84:87], v[112:115], v[40:43]
	v_mfma_f32_16x16x32_bf16 v[32:35], v[92:95], v[112:115], v[32:35]
	v_mfma_f32_16x16x32_bf16 v[24:27], v[84:87], v[164:167], v[24:27]
	v_mfma_f32_16x16x32_bf16 v[16:19], v[92:95], v[164:167], v[16:19]
	s_waitcnt lgkmcnt(0)
	v_mfma_f32_16x16x32_bf16 v[12:15], v[84:87], v[202:205], v[12:15]
	v_mfma_f32_16x16x32_bf16 v[8:11], v[92:95], v[202:205], v[8:11]
	s_setprio 0
	s_barrier
	s_add_u32 s28, s28, 0x80080
	s_addc_u32 s29, s29, 0
	s_add_i32 s46, s46, s37
	s_mov_b32 m0, s46
	s_nop 0
	global_load_lds_dwordx4 v172, s[28:29]
	s_add_i32 m0, s46, 0x2000
	s_nop 0
	global_load_lds_dwordx4 v168, s[28:29]
	s_waitcnt vmcnt(6)
	s_barrier
	s_setprio 1
	v_mfma_f32_16x16x32_bf16 v[56:59], v[214:217], v[96:99], v[56:59]
	v_mfma_f32_16x16x32_bf16 v[52:55], v[222:225], v[96:99], v[52:55]
	ds_read_b128 v[80:83], v189
	v_mfma_f32_16x16x32_bf16 v[44:47], v[214:217], v[108:111], v[44:47]
	v_mfma_f32_16x16x32_bf16 v[36:39], v[222:225], v[108:111], v[36:39]
	ds_read_b128 v[84:87], v189 offset:1024
	v_mfma_f32_16x16x32_bf16 v[28:31], v[214:217], v[160:163], v[28:31]
	v_mfma_f32_16x16x32_bf16 v[20:23], v[222:225], v[160:163], v[20:23]
	ds_read_b128 v[88:91], v189 offset:2048
	v_mfma_f32_16x16x32_bf16 v[4:7], v[214:217], v[198:201], v[4:7]
	v_mfma_f32_16x16x32_bf16 v[0:3], v[222:225], v[198:201], v[0:3]
	ds_read_b128 v[92:95], v189 offset:3072
	v_mfma_f32_16x16x32_bf16 v[56:59], v[218:221], v[100:103], v[56:59]
	s_add_i32 vcc_hi, vcc_hi, 2
	v_mfma_f32_16x16x32_bf16 v[52:55], v[230:233], v[100:103], v[52:55]
	s_add_u32 s59, s59, 0x100
	s_addc_u32 vcc_lo, vcc_lo, 0
	v_mfma_f32_16x16x32_bf16 v[44:47], v[218:221], v[112:115], v[44:47]
	s_add_u32 s44, s44, 0x100
	s_addc_u32 s45, s45, 0
	v_mfma_f32_16x16x32_bf16 v[36:39], v[230:233], v[112:115], v[36:39]
	s_cmp_gt_u32 vcc_hi, 29
	v_mfma_f32_16x16x32_bf16 v[28:31], v[218:221], v[164:167], v[28:31]
	v_mfma_f32_16x16x32_bf16 v[20:23], v[230:233], v[164:167], v[20:23]
	v_mfma_f32_16x16x32_bf16 v[4:7], v[218:221], v[202:205], v[4:7]
	v_mfma_f32_16x16x32_bf16 v[0:3], v[230:233], v[202:205], v[0:3]
	s_setprio 0
	s_barrier
	s_cbranch_scc0 .LBB1_380
; DI float silu_mul(float g, float v) { return g * v * __builtin_amdgcn_rcpf(1.0f + __builtin_amdgcn_exp2f(-LOG2E * g)); }
;     DI void operator()(const f32x4 (&acc)[2][2][4][2], const Unit& u, int wr, int wc, int fr, int fq) const {
;         const int row0 = u.pm * BM + wr * 64 + fr, ch0 = u.pn * 128 + wc * 32 + 8 * fq;
;         f32x4 w0[2], w1[2], w2[2], bb[2];
; #pragma unroll
;         for (int n = 0; n < 2; ++n) { w0[n] = *(const f32x4*)(cw + ch0 + 4 * n); w1[n] = *(const f32x4*)(cw + DFF + ch0 + 4 * n); w2[n] = *(const f32x4*)(cw + 2 * DFF + ch0 + 4 * n); bb[n] = *(const f32x4*)(cb + ch0 + 4 * n); }
; #pragma unroll
;         for (int ai = 0; ai < 2; ++ai)
; #pragma unroll
;             for (int m = 0; m < 4; ++m) {
;                 const bool efirst = (m == 0) && (fr == 0), elast = (m == 3) && (fr == 15);
;                 const int row = row0 + ai * HALF + m * 16;
;                 f32x4 gc[2];
; #pragma unroll
;                 for (int n = 0; n < 2; ++n) {
;                     const f32x4 g = acc[ai][0][m][n];
;                     const f32x4 gprev = acc[ai][0][m > 0 ? m - 1 : 0][n], gnext = acc[ai][0][m < 3 ? m + 1 : 3][n];
;                     f32x4 up, dn;
; #pragma unroll
;                     for (int e = 0; e < 4; ++e) {
;                         const float pu = (m > 0 && fr == 15) ? gprev[e] : g[e];
;                         const float pd = (m < 3 && fr == 0) ? gnext[e] : g[e];
;                         up[e] = dpp_ror1(pu); dn[e] = dpp_ror15(pd);
;                     }
;                     if (efirst) up = (f32x4){0.f, 0.f, 0.f, 0.f};
;                     if (elast) dn = (f32x4){0.f, 0.f, 0.f, 0.f};
;                     gc[n] = w0[n] * up + w1[n] * g + w2[n] * dn + bb[n];
;                 }
;                 if (efirst || elast) {
;                     const size_t eo = (size_t)((row >> 6) * 2 + (elast ? 1 : 0)) * DFF + ch0;
; #pragma unroll
;                     for (int n = 0; n < 2; ++n) { *(f32x4*)(EP + eo + 4 * n) = gc[n]; *(f32x4*)(ER + eo + 4 * n) = acc[ai][0][m][n]; *(f32x4*)(EV + eo + 4 * n) = acc[ai][1][m][n]; }
;                 } else {
;                     const f32x4 v0 = acc[ai][1][m][0], v1 = acc[ai][1][m][1];
;                     u32x4 o;
;                     o[0] = pack2(silu_mul(gc[0][0], v0[0]), silu_mul(gc[0][1], v0[1])); o[1] = pack2(silu_mul(gc[0][2], v0[2]), silu_mul(gc[0][3], v0[3]));
	s_waitcnt lgkmcnt(0)
	s_lshl_b32 s23, s43, 7
	v_mov_b32_e32 v194, v186
	v_mov_b32_e32 v80, v187
	s_or_b32 s23, s23, s67
	v_mov_b32_e32 v160, 0
	v_lshl_add_u32 v184, v80, 3, s23
	v_ashrrev_i32_e32 v185, 31, v184
	v_lshlrev_b64 v[80:81], 2, v[184:185]
	v_lshl_add_u64 v[84:85], s[52:53], 0, v[80:81]
	v_lshl_add_u64 v[88:89], s[16:17], 0, v[80:81]
	v_lshl_add_u64 v[92:93], s[18:19], 0, v[80:81]
	v_lshl_add_u64 v[112:113], s[54:55], 0, v[80:81]
	global_load_dwordx4 v[80:83], v[84:85], off offset:16
	global_load_dwordx4 v[96:99], v[84:85], off
	s_nop 0
	global_load_dwordx4 v[84:87], v[88:89], off offset:16
	global_load_dwordx4 v[100:103], v[88:89], off
	s_nop 0
	global_load_dwordx4 v[88:91], v[92:93], off offset:16
	global_load_dwordx4 v[108:111], v[92:93], off
	s_nop 0
	global_load_dwordx4 v[92:95], v[112:113], off offset:16
	s_nop 0
	global_load_dwordx4 v[112:115], v[112:113], off
	v_cmp_eq_u32_e32 vcc, 0, v194
	v_mov_b32_e32 v164, 0
	v_mov_b32_e32 v195, 0
	v_cndmask_b32_e32 v161, v148, v136, vcc
	v_cndmask_b32_e32 v162, v149, v137, vcc
	v_cndmask_b32_e32 v163, v150, v138, vcc
	v_mov_b32_dpp v160, v161 row_ror:15 row_mask:0xf bank_mask:0xf
	v_mov_b32_e32 v161, 0
	v_mov_b32_e32 v166, 0
	v_mov_b32_e32 v167, 0
	v_mov_b32_dpp v161, v162 row_ror:15 row_mask:0xf bank_mask:0xf
	v_mov_b32_e32 v162, 0
	v_mov_b32_dpp v164, v150 row_ror:1 row_mask:0xf bank_mask:0xf
	v_cndmask_b32_e32 v165, v151, v139, vcc
	v_mov_b32_dpp v162, v163 row_ror:15 row_mask:0xf bank_mask:0xf
	v_mov_b32_dpp v195, v151 row_ror:1 row_mask:0xf bank_mask:0xf
	v_mov_b32_e32 v163, 0
	v_mov_b32_dpp v166, v148 row_ror:1 row_mask:0xf bank_mask:0xf
	v_mov_b32_dpp v167, v149 row_ror:1 row_mask:0xf bank_mask:0xf
	v_mov_b32_dpp v163, v165 row_ror:15 row_mask:0xf bank_mask:0xf
	v_cndmask_b32_e64 v165, v195, 0, vcc
	v_cndmask_b32_e64 v164, v164, 0, vcc
	v_cndmask_b32_e64 v167, v167, 0, vcc
	v_cndmask_b32_e64 v166, v166, 0, vcc
	v_mov_b32_e32 v195, 0
	v_mov_b32_e32 v196, 0
	v_mov_b32_e32 v198, 0
	v_mov_b32_e32 v200, 0
	v_mov_b32_dpp v195, v144 row_ror:1 row_mask:0xf bank_mask:0xf
	v_mov_b32_dpp v196, v145 row_ror:1 row_mask:0xf bank_mask:0xf
	v_mov_b32_dpp v198, v146 row_ror:1 row_mask:0xf bank_mask:0xf
	v_cndmask_b32_e32 v199, v147, v131, vcc
	v_mov_b32_dpp v200, v147 row_ror:1 row_mask:0xf bank_mask:0xf
	v_cndmask_b32_e64 v198, v198, 0, vcc
	v_cndmask_b32_e64 v201, v196, 0, vcc
	s_lshl_b32 s21, s42, 8
	s_add_i32 s21, s21, s49
	v_add_u32_e32 v193, s21, v194
	v_cmp_ne_u32_e64 s[46:47], 0, v194
	s_waitcnt vmcnt(0)
	v_pk_mul_f32 v[164:165], v[98:99], v[164:165]
	v_pk_mul_f32 v[166:167], v[96:97], v[166:167]
	v_pk_fma_f32 v[164:165], v[150:151], v[102:103], v[164:165]
	v_pk_fma_f32 v[166:167], v[148:149], v[100:101], v[166:167]
	v_pk_fma_f32 v[162:163], v[110:111], v[162:163], v[164:165]
	v_cndmask_b32_e32 v165, v144, v128, vcc
	v_mov_b32_e32 v164, 0
	v_pk_fma_f32 v[160:161], v[108:109], v[160:161], v[166:167]
	v_cndmask_b32_e32 v166, v145, v129, vcc
	v_mov_b32_dpp v164, v165 row_ror:15 row_mask:0xf bank_mask:0xf
	v_mov_b32_e32 v165, 0
	v_cndmask_b32_e32 v167, v146, v130, vcc
	v_pk_add_f32 v[162:163], v[114:115], v[162:163]
	v_mov_b32_dpp v165, v166 row_ror:15 row_mask:0xf bank_mask:0xf
	v_mov_b32_e32 v166, 0
	v_pk_add_f32 v[160:161], v[112:113], v[160:161]
	s_nop 0
	v_mov_b32_dpp v166, v167 row_ror:15 row_mask:0xf bank_mask:0xf
	v_mov_b32_e32 v167, 0
	s_nop 1
	v_mov_b32_dpp v167, v199 row_ror:15 row_mask:0xf bank_mask:0xf
	v_cndmask_b32_e64 v199, v200, 0, vcc
	v_cndmask_b32_e64 v200, v195, 0, vcc
	v_pk_mul_f32 v[200:201], v[80:81], v[200:201]
	v_pk_mul_f32 v[198:199], v[82:83], v[198:199]
	v_pk_fma_f32 v[200:201], v[144:145], v[84:85], v[200:201]
	v_pk_fma_f32 v[198:199], v[146:147], v[86:87], v[198:199]
	v_pk_fma_f32 v[164:165], v[88:89], v[164:165], v[200:201]
	v_pk_fma_f32 v[166:167], v[90:91], v[166:167], v[198:199]
	v_pk_add_f32 v[164:165], v[92:93], v[164:165]
	v_pk_add_f32 v[166:167], v[94:95], v[166:167]
	s_and_saveexec_b64 s[28:29], s[46:47]
	s_xor_b64 s[28:29], exec, s[28:29]
	s_cbranch_execz .LBB1_383
	v_mul_f32_e32 v195, 0xbfb8aa3b, v160
	v_exp_f32_e32 v195, v195
	v_mul_f32_e32 v196, 0xbfb8aa3b, v161
	v_exp_f32_e32 v196, v196
	v_pk_mul_f32 v[160:161], v[156:157], v[160:161]
	v_add_f32_e32 v195, 1.0, v195
	v_rcp_f32_e32 v198, v195
	v_add_f32_e32 v196, 1.0, v196
	v_mul_f32_e32 v195, 0xbfb8aa3b, v162
	v_rcp_f32_e32 v199, v196
	v_exp_f32_e32 v195, v195
	v_mul_f32_e32 v196, 0xbfb8aa3b, v163
	v_exp_f32_e32 v196, v196
	v_pk_mul_f32 v[160:161], v[160:161], v[198:199]
	v_add_f32_e32 v195, 1.0, v195
	v_rcp_f32_e32 v200, v195
	v_add_f32_e32 v195, 1.0, v196
	v_rcp_f32_e32 v201, v195
	v_cvt_pk_bf16_f32 v160, v160, v161
	v_mul_f32_e32 v161, 0xbfb8aa3b, v164
	v_exp_f32_e32 v195, v161
	v_mul_f32_e32 v161, 0xbfb8aa3b, v165
	v_exp_f32_e32 v196, v161
	v_pk_mul_f32 v[162:163], v[158:159], v[162:163]
	v_pk_mul_f32 v[164:165], v[152:153], v[164:165]
	v_pk_mul_f32 v[162:163], v[162:163], v[200:201]
	s_nop 0
	v_cvt_pk_bf16_f32 v161, v162, v163
	v_add_f32_e32 v162, 1.0, v195
	v_mul_f32_e32 v195, 0xbfb8aa3b, v166
	v_add_f32_e32 v163, 1.0, v196
	v_exp_f32_e32 v195, v195
	v_mul_f32_e32 v196, 0xbfb8aa3b, v167
	v_exp_f32_e32 v196, v196
	v_rcp_f32_e32 v162, v162
	v_add_f32_e32 v195, 1.0, v195
	v_rcp_f32_e32 v198, v195
	v_add_f32_e32 v195, 1.0, v196
	v_rcp_f32_e32 v163, v163
	v_rcp_f32_e32 v199, v195
	v_pk_mul_f32 v[166:167], v[154:155], v[166:167]
	v_pk_mul_f32 v[162:163], v[164:165], v[162:163]
	v_pk_mul_f32 v[164:165], v[166:167], v[198:199]
	v_cvt_pk_bf16_f32 v162, v162, v163
	v_cvt_pk_bf16_f32 v163, v164, v165
	v_mov_b64_e32 v[164:165], s[6:7]
	v_mad_i64_i32 v[164:165], s[42:43], v193, s30, v[164:165]
	v_lshl_add_u64 v[164:165], v[184:185], 1, v[164:165]
	global_store_dwordx4 v[164:165], v[160:163], off

; #define PG8_STAGE(bufoff, gbase, voff) do { _Pragma("unroll") for (int _i = 0; _i < 2; ++_i) \
;         __builtin_amdgcn_global_load_lds((const unsigned*)((const char*)(gbase) + (voff)[_i]), (LAS unsigned*)(lds + (bufoff) + ldsw + _i * 8192), 16, 0, 0); } while (0)
; #define PG8_LDA(dst, b, h) do { _Pragma("unroll") for (int m = 0; m < 4; ++m) _Pragma("unroll") for (int k = 0; k < 2; ++k) dst[m][k] = *(const LAS bf16x8*)(lds + PG8_SA(b, h) + aoff + m * 2048 + k * 1024); } while (0)
; #define PG8_LDB(dst, b, h) do { _Pragma("unroll") for (int n = 0; n < 2; ++n) _Pragma("unroll") for (int k = 0; k < 2; ++k) dst[n][k] = *(const LAS bf16x8*)(lds + PG8_SB(b, h) + boff + n * 2048 + k * 1024); } while (0)
; #define PG8_MMA(ai, bj, At, Bt) do { __builtin_amdgcn_s_setprio(1); _Pragma("unroll") for (int m = 0; m < 4; ++m) _Pragma("unroll") for (int n = 0; n < 2; ++n) _Pragma("unroll") for (int k = 0; k < 2; ++k) \
;         acc[ai][bj][m][n] = __builtin_amdgcn_mfma_f32_16x16x32_bf16(Bt[n][k], At[m][k], acc[ai][bj][m][n], 0, 0, 0); __builtin_amdgcn_s_setprio(0); } while (0)
; #define PG8_WAIT_L(n) asm volatile("s_waitcnt lgkmcnt(" #n ")" ::: "memory")
; #define PG8_BAR __builtin_amdgcn_s_barrier()
; #define PG8_SCHED __builtin_amdgcn_sched_barrier(0)
; template <class Map, class Epi>
; DI void gemm_phase(LAS unsigned char* lds, const Map& MP, const Epi& E, const int nM, const int nN, const int K, const int lda, const int ldb) {
;     ...
;             PG8_LDB(B0, 0, 0); PG8_SCHED; PG8_LDA(At, 0, 0); PG8_STAGE(PG8_SA(1, 1), a1 + hstepA, voffA);
;             PG8_WAIT_L(8); PG8_BAR; PG8_WAIT_L(0); PG8_MMA(0, 0, At, B0); PG8_BAR; PG8_SCHED;
;             PG8_LDB(B1, 0, 1); PG8_STAGE(PG8_SB(0, 0), b2, voffB);
;             PG8_BAR; PG8_WAIT_L(0); PG8_MMA(0, 1, At, B1); PG8_BAR;
;             PG8_LDA(At, 0, 1); PG8_STAGE(PG8_SA(0, 0), a2, voffA);
;             PG8_BAR; PG8_WAIT_L(0); PG8_MMA(1, 0, At, B0); PG8_BAR; PG8_SCHED;
.LBB1_550:
	s_add_u32 s10, s8, 0x100
	s_addc_u32 s11, s9, 0
	s_cmpk_eq_i32 s3, 0x54
	s_cselect_b32 s15, s43, s11
	s_cselect_b32 s14, s42, s10
	s_cselect_b32 s13, s7, s38
	s_cselect_b32 s12, s6, s5
	s_add_i32 m0, s24, 0xc000
	ds_read_b128 v[168:171], v150
	ds_read_b128 v[172:175], v150 offset:1024
	ds_read_b128 v[176:179], v150 offset:2048
	ds_read_b128 v[180:183], v150 offset:3072
	ds_read_b128 v[184:187], v150 offset:4096
	ds_read_b128 v[188:191], v150 offset:5120
	ds_read_b128 v[192:195], v150 offset:6144
	ds_read_b128 v[198:201], v150 offset:7168
	global_load_lds_dwordx4 v138, s[8:9]
	s_add_i32 m0, s24, 0xe000
	s_nop 0
	global_load_lds_dwordx4 v136, s[8:9]
	s_waitcnt lgkmcnt(8)
	s_barrier
	s_setprio 1
	s_waitcnt lgkmcnt(7)
	v_mfma_f32_16x16x32_bf16 v[124:127], v[152:155], v[168:171], v[124:127]
	v_mfma_f32_16x16x32_bf16 v[120:123], v[160:163], v[168:171], v[120:123]
	s_waitcnt lgkmcnt(5)
	v_mfma_f32_16x16x32_bf16 v[108:111], v[152:155], v[176:179], v[108:111]
	v_mfma_f32_16x16x32_bf16 v[104:107], v[160:163], v[176:179], v[104:107]
	s_waitcnt lgkmcnt(3)
	v_mfma_f32_16x16x32_bf16 v[92:95], v[152:155], v[184:187], v[92:95]
	v_mfma_f32_16x16x32_bf16 v[88:91], v[160:163], v[184:187], v[88:91]
	s_waitcnt lgkmcnt(1)
	v_mfma_f32_16x16x32_bf16 v[76:79], v[152:155], v[192:195], v[76:79]
	v_mfma_f32_16x16x32_bf16 v[72:75], v[160:163], v[192:195], v[72:75]
	v_mfma_f32_16x16x32_bf16 v[124:127], v[156:159], v[172:175], v[124:127]
	v_mfma_f32_16x16x32_bf16 v[120:123], v[164:167], v[172:175], v[120:123]
	v_mfma_f32_16x16x32_bf16 v[108:111], v[156:159], v[180:183], v[108:111]
	v_mfma_f32_16x16x32_bf16 v[104:107], v[164:167], v[180:183], v[104:107]
	v_mfma_f32_16x16x32_bf16 v[92:95], v[156:159], v[188:191], v[92:95]
	v_mfma_f32_16x16x32_bf16 v[88:91], v[164:167], v[188:191], v[88:91]
	s_waitcnt lgkmcnt(0)
	v_mfma_f32_16x16x32_bf16 v[76:79], v[156:159], v[198:201], v[76:79]
	v_mfma_f32_16x16x32_bf16 v[72:75], v[164:167], v[198:201], v[72:75]
	s_setprio 0
	s_barrier
	s_add_i32 s8, s35, s22
	v_lshl_add_u64 v[144:145], s[12:13], 0, v[132:133]
	s_mov_b32 m0, s8
	ds_read_b128 v[202:205], v151
	ds_read_b128 v[206:209], v151 offset:1024
	ds_read_b128 v[210:213], v151 offset:2048
	ds_read_b128 v[214:217], v151 offset:3072
	global_load_lds_dwordx4 v[144:145], off
	v_lshl_add_u64 v[218:219], s[12:13], 0, v[128:129]
	s_add_i32 m0, s8, 0x2000
	s_nop 0
	global_load_lds_dwordx4 v[218:219], off
	s_barrier
	s_setprio 1
	s_waitcnt lgkmcnt(3)
	v_mfma_f32_16x16x32_bf16 v[116:119], v[202:205], v[168:171], v[116:119]
	s_waitcnt lgkmcnt(1)
	v_mfma_f32_16x16x32_bf16 v[112:115], v[210:213], v[168:171], v[112:115]
	v_mfma_f32_16x16x32_bf16 v[100:103], v[202:205], v[176:179], v[100:103]
	v_mfma_f32_16x16x32_bf16 v[96:99], v[210:213], v[176:179], v[96:99]
	v_mfma_f32_16x16x32_bf16 v[84:87], v[202:205], v[184:187], v[84:87]
	v_mfma_f32_16x16x32_bf16 v[80:83], v[210:213], v[184:187], v[80:83]
	v_mfma_f32_16x16x32_bf16 v[68:71], v[202:205], v[192:195], v[68:71]
	v_mfma_f32_16x16x32_bf16 v[64:67], v[210:213], v[192:195], v[64:67]
	v_mfma_f32_16x16x32_bf16 v[116:119], v[206:209], v[172:175], v[116:119]
	s_mov_b32 m0, s24
	s_waitcnt lgkmcnt(0)
	v_mfma_f32_16x16x32_bf16 v[112:115], v[214:217], v[172:175], v[112:115]
	v_lshl_add_u64 v[220:221], s[14:15], 0, v[134:135]
	v_mfma_f32_16x16x32_bf16 v[100:103], v[206:209], v[180:183], v[100:103]
	v_mfma_f32_16x16x32_bf16 v[96:99], v[214:217], v[180:183], v[96:99]
	v_mfma_f32_16x16x32_bf16 v[84:87], v[206:209], v[188:191], v[84:87]
	v_mfma_f32_16x16x32_bf16 v[80:83], v[214:217], v[188:191], v[80:83]
	v_mfma_f32_16x16x32_bf16 v[68:71], v[206:209], v[198:201], v[68:71]
	v_mfma_f32_16x16x32_bf16 v[64:67], v[214:217], v[198:201], v[64:67]
	s_setprio 0
	s_barrier
	ds_read_b128 v[168:171], v150 offset:16384
	ds_read_b128 v[172:175], v150 offset:17408
	ds_read_b128 v[176:179], v150 offset:18432
	ds_read_b128 v[180:183], v150 offset:19456
	ds_read_b128 v[184:187], v150 offset:20480
	ds_read_b128 v[188:191], v150 offset:21504
	ds_read_b128 v[192:195], v150 offset:22528
	ds_read_b128 v[198:201], v150 offset:23552
	global_load_lds_dwordx4 v[220:221], off
	v_lshl_add_u64 v[222:223], s[14:15], 0, v[130:131]
	s_mov_b32 m0, s25
	s_nop 0
	global_load_lds_dwordx4 v[222:223], off
	s_waitcnt vmcnt(10)
	s_barrier
	s_setprio 1
	s_waitcnt lgkmcnt(7)
	v_mfma_f32_16x16x32_bf16 v[60:63], v[152:155], v[168:171], v[60:63]
	v_mfma_f32_16x16x32_bf16 v[56:59], v[160:163], v[168:171], v[56:59]
	s_waitcnt lgkmcnt(5)
	v_mfma_f32_16x16x32_bf16 v[44:47], v[152:155], v[176:179], v[44:47]
	v_mfma_f32_16x16x32_bf16 v[40:43], v[160:163], v[176:179], v[40:43]
	s_waitcnt lgkmcnt(3)
	v_mfma_f32_16x16x32_bf16 v[28:31], v[152:155], v[184:187], v[28:31]
	v_mfma_f32_16x16x32_bf16 v[24:27], v[160:163], v[184:187], v[24:27]
	s_waitcnt lgkmcnt(1)
	v_mfma_f32_16x16x32_bf16 v[12:15], v[152:155], v[192:195], v[12:15]
	v_mfma_f32_16x16x32_bf16 v[8:11], v[160:163], v[192:195], v[8:11]
	v_mfma_f32_16x16x32_bf16 v[60:63], v[156:159], v[172:175], v[60:63]
	v_mfma_f32_16x16x32_bf16 v[56:59], v[164:167], v[172:175], v[56:59]
	v_mfma_f32_16x16x32_bf16 v[44:47], v[156:159], v[180:183], v[44:47]
	v_mfma_f32_16x16x32_bf16 v[40:43], v[164:167], v[180:183], v[40:43]
	v_mfma_f32_16x16x32_bf16 v[28:31], v[156:159], v[188:191], v[28:31]
	v_mfma_f32_16x16x32_bf16 v[24:27], v[164:167], v[188:191], v[24:27]
	s_waitcnt lgkmcnt(0)
	v_mfma_f32_16x16x32_bf16 v[12:15], v[156:159], v[198:201], v[12:15]
	v_mfma_f32_16x16x32_bf16 v[8:11], v[164:167], v[198:201], v[8:11]
	s_setprio 0
	s_barrier
	s_add_u32 s8, s12, 0x160000
	s_addc_u32 s9, s13, 0
	s_add_i32 s39, s36, s22
	s_mov_b32 m0, s39
	s_nop 0
	global_load_lds_dwordx4 v132, s[8:9]
	s_add_i32 m0, s39, 0x2000
	s_nop 0
	global_load_lds_dwordx4 v128, s[8:9]
	s_waitcnt vmcnt(6)
	s_barrier
; #define PG8_STAGE(bufoff, gbase, voff) do { _Pragma("unroll") for (int _i = 0; _i < 2; ++_i) \
;         __builtin_amdgcn_global_load_lds((const unsigned*)((const char*)(gbase) + (voff)[_i]), (LAS unsigned*)(lds + (bufoff) + ldsw + _i * 8192), 16, 0, 0); } while (0)
; #define PG8_LDA(dst, b, h) do { _Pragma("unroll") for (int m = 0; m < 4; ++m) _Pragma("unroll") for (int k = 0; k < 2; ++k) dst[m][k] = *(const LAS bf16x8*)(lds + PG8_SA(b, h) + aoff + m * 2048 + k * 1024); } while (0)
; #define PG8_LDB(dst, b, h) do { _Pragma("unroll") for (int n = 0; n < 2; ++n) _Pragma("unroll") for (int k = 0; k < 2; ++k) dst[n][k] = *(const LAS bf16x8*)(lds + PG8_SB(b, h) + boff + n * 2048 + k * 1024); } while (0)
; #define PG8_MMA(ai, bj, At, Bt) do { __builtin_amdgcn_s_setprio(1); _Pragma("unroll") for (int m = 0; m < 4; ++m) _Pragma("unroll") for (int n = 0; n < 2; ++n) _Pragma("unroll") for (int k = 0; k < 2; ++k) \
;         acc[ai][bj][m][n] = __builtin_amdgcn_mfma_f32_16x16x32_bf16(Bt[n][k], At[m][k], acc[ai][bj][m][n], 0, 0, 0); __builtin_amdgcn_s_setprio(0); } while (0)
; #define PG8_WAIT_V(n) asm volatile("s_waitcnt vmcnt(" #n ")" ::: "memory")
; #define PG8_WAIT_L(n) asm volatile("s_waitcnt lgkmcnt(" #n ")" ::: "memory")
; #define PG8_BAR __builtin_amdgcn_s_barrier()
; #define PG8_SCHED __builtin_amdgcn_sched_barrier(0)
; template <class Map, class Epi>
; DI void gemm_phase(LAS unsigned char* lds, const Map& MP, const Epi& E, const int nM, const int nN, const int K, const int lda, const int ldb) {
;     ...
;             PG8_BAR; PG8_WAIT_L(0); PG8_MMA(1, 0, At, B0); PG8_BAR; PG8_SCHED;
;             PG8_STAGE(PG8_SB(0, 1), b2 + hstepB, voffB);
;             PG8_WAIT_V(6); PG8_BAR; PG8_MMA(1, 1, At, B1); PG8_BAR;
;             PG8_LDB(B0, 1, 0); PG8_SCHED; PG8_LDA(At, 1, 0); PG8_STAGE(PG8_SA(0, 1), a2 + hstepA, voffA);
;             PG8_WAIT_L(8); PG8_BAR; PG8_WAIT_L(0); PG8_MMA(0, 0, At, B0); PG8_BAR; PG8_SCHED;
;             PG8_LDB(B1, 1, 1); PG8_STAGE(PG8_SB(1, 0), b3, voffB);
;             PG8_BAR; PG8_WAIT_L(0); PG8_MMA(0, 1, At, B1); PG8_BAR;
;             PG8_LDA(At, 1, 1); PG8_STAGE(PG8_SA(1, 0), a3, voffA);
;             PG8_BAR; PG8_WAIT_L(0); PG8_MMA(1, 0, At, B0); PG8_BAR; PG8_SCHED;
	s_setprio 1
	v_mfma_f32_16x16x32_bf16 v[52:55], v[202:205], v[168:171], v[52:55]
	v_mfma_f32_16x16x32_bf16 v[48:51], v[210:213], v[168:171], v[48:51]
	s_add_i32 s39, 0, 0x18000
	v_add_u32_e32 v164, s39, v148
	ds_read_b128 v[152:155], v164
	v_mfma_f32_16x16x32_bf16 v[36:39], v[202:205], v[176:179], v[36:39]
	v_mfma_f32_16x16x32_bf16 v[32:35], v[210:213], v[176:179], v[32:35]
	ds_read_b128 v[156:159], v164 offset:1024
	v_mfma_f32_16x16x32_bf16 v[20:23], v[202:205], v[184:187], v[20:23]
	v_mfma_f32_16x16x32_bf16 v[16:19], v[210:213], v[184:187], v[16:19]
	ds_read_b128 v[160:163], v164 offset:2048
	v_mfma_f32_16x16x32_bf16 v[4:7], v[202:205], v[192:195], v[4:7]
	v_mfma_f32_16x16x32_bf16 v[0:3], v[210:213], v[192:195], v[0:3]
	ds_read_b128 v[164:167], v164 offset:3072
	v_mfma_f32_16x16x32_bf16 v[52:55], v[206:209], v[172:175], v[52:55]
	v_mfma_f32_16x16x32_bf16 v[48:51], v[214:217], v[172:175], v[48:51]
	v_mfma_f32_16x16x32_bf16 v[36:39], v[206:209], v[180:183], v[36:39]
	v_mfma_f32_16x16x32_bf16 v[32:35], v[214:217], v[180:183], v[32:35]
	v_mfma_f32_16x16x32_bf16 v[20:23], v[206:209], v[188:191], v[20:23]
	v_mfma_f32_16x16x32_bf16 v[16:19], v[214:217], v[188:191], v[16:19]
	v_mfma_f32_16x16x32_bf16 v[4:7], v[206:209], v[198:201], v[4:7]
	v_mfma_f32_16x16x32_bf16 v[0:3], v[214:217], v[198:201], v[0:3]
	s_setprio 0
	s_barrier
	s_add_u32 s8, s14, 0x160000
	s_addc_u32 s9, s15, 0
	s_mov_b32 m0, s26
	ds_read_b128 v[168:171], v150 offset:32768
	ds_read_b128 v[172:175], v150 offset:33792
	ds_read_b128 v[176:179], v150 offset:34816
	ds_read_b128 v[180:183], v150 offset:35840
	ds_read_b128 v[184:187], v150 offset:36864
	ds_read_b128 v[188:191], v150 offset:37888
	ds_read_b128 v[192:195], v150 offset:38912
	ds_read_b128 v[198:201], v150 offset:39936
	global_load_lds_dwordx4 v134, s[8:9]
	s_mov_b32 m0, s27
	s_nop 0
	global_load_lds_dwordx4 v130, s[8:9]
	s_waitcnt lgkmcnt(8)
	s_barrier
	s_setprio 1
	s_waitcnt lgkmcnt(7)
	v_mfma_f32_16x16x32_bf16 v[124:127], v[152:155], v[168:171], v[124:127]
	v_mfma_f32_16x16x32_bf16 v[120:123], v[160:163], v[168:171], v[120:123]
	s_waitcnt lgkmcnt(5)
	v_mfma_f32_16x16x32_bf16 v[108:111], v[152:155], v[176:179], v[108:111]
	v_mfma_f32_16x16x32_bf16 v[104:107], v[160:163], v[176:179], v[104:107]
	s_waitcnt lgkmcnt(3)
	v_mfma_f32_16x16x32_bf16 v[92:95], v[152:155], v[184:187], v[92:95]
	v_mfma_f32_16x16x32_bf16 v[88:91], v[160:163], v[184:187], v[88:91]
	s_waitcnt lgkmcnt(1)
	v_mfma_f32_16x16x32_bf16 v[76:79], v[152:155], v[192:195], v[76:79]
	v_mfma_f32_16x16x32_bf16 v[72:75], v[160:163], v[192:195], v[72:75]
	v_mfma_f32_16x16x32_bf16 v[124:127], v[156:159], v[172:175], v[124:127]
	v_mfma_f32_16x16x32_bf16 v[120:123], v[164:167], v[172:175], v[120:123]
	v_mfma_f32_16x16x32_bf16 v[108:111], v[156:159], v[180:183], v[108:111]
	v_mfma_f32_16x16x32_bf16 v[104:107], v[164:167], v[180:183], v[104:107]
	v_mfma_f32_16x16x32_bf16 v[92:95], v[156:159], v[188:191], v[92:95]
	v_mfma_f32_16x16x32_bf16 v[88:91], v[164:167], v[188:191], v[88:91]
	s_waitcnt lgkmcnt(0)
	v_mfma_f32_16x16x32_bf16 v[76:79], v[156:159], v[198:201], v[76:79]
	v_mfma_f32_16x16x32_bf16 v[72:75], v[164:167], v[198:201], v[72:75]
	s_setprio 0
	s_barrier
	s_add_i32 s14, 0, 0x1c000
	s_add_i32 s8, s39, s22
	v_add_u32_e32 v196, s14, v148
	v_lshl_add_u64 v[144:145], v[144:145], 0, s[52:53]
	s_mov_b32 m0, s8
	ds_read_b128 v[202:205], v196
	ds_read_b128 v[206:209], v196 offset:1024
	ds_read_b128 v[210:213], v196 offset:2048
	ds_read_b128 v[214:217], v196 offset:3072
	global_load_lds_dwordx4 v[144:145], off
	v_lshl_add_u64 v[144:145], v[218:219], 0, s[52:53]
	s_add_i32 m0, s8, 0x2000
	s_nop 0
	global_load_lds_dwordx4 v[144:145], off
	s_barrier
	s_setprio 1
	s_waitcnt lgkmcnt(3)
	v_mfma_f32_16x16x32_bf16 v[116:119], v[202:205], v[168:171], v[116:119]
	s_waitcnt lgkmcnt(1)
	v_mfma_f32_16x16x32_bf16 v[112:115], v[210:213], v[168:171], v[112:115]
	v_mfma_f32_16x16x32_bf16 v[100:103], v[202:205], v[176:179], v[100:103]
	v_mfma_f32_16x16x32_bf16 v[96:99], v[210:213], v[176:179], v[96:99]
	v_mfma_f32_16x16x32_bf16 v[84:87], v[202:205], v[184:187], v[84:87]
	v_mfma_f32_16x16x32_bf16 v[80:83], v[210:213], v[184:187], v[80:83]
	v_mfma_f32_16x16x32_bf16 v[68:71], v[202:205], v[192:195], v[68:71]
	v_mfma_f32_16x16x32_bf16 v[64:67], v[210:213], v[192:195], v[64:67]
	v_mfma_f32_16x16x32_bf16 v[116:119], v[206:209], v[172:175], v[116:119]
	s_mov_b32 m0, s30
	s_waitcnt lgkmcnt(0)
	v_mfma_f32_16x16x32_bf16 v[112:115], v[214:217], v[172:175], v[112:115]
	v_lshl_add_u64 v[144:145], v[220:221], 0, s[52:53]
	v_mfma_f32_16x16x32_bf16 v[100:103], v[206:209], v[180:183], v[100:103]
	v_mfma_f32_16x16x32_bf16 v[96:99], v[214:217], v[180:183], v[96:99]
	v_mfma_f32_16x16x32_bf16 v[84:87], v[206:209], v[188:191], v[84:87]
	v_mfma_f32_16x16x32_bf16 v[80:83], v[214:217], v[188:191], v[80:83]
	v_mfma_f32_16x16x32_bf16 v[68:71], v[206:209], v[198:201], v[68:71]
	v_mfma_f32_16x16x32_bf16 v[64:67], v[214:217], v[198:201], v[64:67]
	s_setprio 0
	s_barrier
	ds_read_b128 v[168:171], v150 offset:49152
	ds_read_b128 v[172:175], v150 offset:50176
	ds_read_b128 v[176:179], v150 offset:51200
	ds_read_b128 v[180:183], v150 offset:52224
	ds_read_b128 v[184:187], v150 offset:53248
	ds_read_b128 v[188:191], v150 offset:54272
	ds_read_b128 v[192:195], v150 offset:55296
	ds_read_b128 v[198:201], v150 offset:56320
	global_load_lds_dwordx4 v[144:145], off
	v_lshl_add_u64 v[144:145], v[222:223], 0, s[52:53]
	s_mov_b32 m0, s31
	s_nop 0
	global_load_lds_dwordx4 v[144:145], off
	s_waitcnt vmcnt(10)
	s_barrier
; DI unsigned pack2(float a, float b) { f32x2 v = {a, b}; hwbf16x2 r = __builtin_convertvector(v, hwbf16x2); return __builtin_bit_cast(unsigned, r); }
; DI float bflo(unsigned w) { return __uint_as_float(w << 16); }
; DI float bfhi(unsigned w) { return __uint_as_float(w & 0xffff0000u); }
; #define PG8_WAIT_V(n) asm volatile("s_waitcnt vmcnt(" #n ")" ::: "memory")
; #define PG8_WAIT_L(n) asm volatile("s_waitcnt lgkmcnt(" #n ")" ::: "memory")
; #define PG8_BAR __builtin_amdgcn_s_barrier()
;     DI void operator()(const f32x4 (&acc)[2][2][4][2], const Unit& u, int wr, int wc, int fr, int fq) const {
;     ...
;             for (int m = 0; m < 4; ++m) { const size_t ro = (size_t)(row0 + ai * HALF + m * 16) * D + col0;
; #pragma unroll
;                 for (int bj = 0; bj < 2; ++bj) {
;                     f32x4 x0, x1;
;                     if constexpr (IB) { const u32x4 w = *(const u32x4*)((const bf16_t*)Xin + ro + bj * HALF);
;                         x0 = (f32x4){bflo(w[0]), bfhi(w[0]), bflo(w[1]), bfhi(w[1])}; x1 = (f32x4){bflo(w[2]), bfhi(w[2]), bflo(w[3]), bfhi(w[3])}; }
;                     else { x0 = *(const f32x4*)((const float*)Xin + ro + bj * HALF); x1 = *(const f32x4*)((const float*)Xin + ro + bj * HALF + 4); }
;                     x0 += acc[ai][bj][m][0] * sc[bj][0]; x1 += acc[ai][bj][m][1] * sc[bj][1];
;                     if constexpr (OB) { u32x4 o; o[0] = pack2(x0[0], x0[1]); o[1] = pack2(x0[2], x0[3]); o[2] = pack2(x1[0], x1[1]); o[3] = pack2(x1[2], x1[3]);
;                         *(u32x4*)((bf16_t*)Xout + ro + bj * HALF) = o; }
;                     else { *(f32x4*)((float*)Xout + ro + bj * HALF) = x0; *(f32x4*)((float*)Xout + ro + bj * HALF + 4) = x1; } } }
; template <class Map, class Epi>
; DI void gemm_phase(LAS unsigned char* lds, const Map& MP, const Epi& E, const int nM, const int nN, const int K, const int lda, const int ldb) {
;     ...
;             PG8_WAIT_L(8); PG8_BAR; PG8_WAIT_L(0); PG8_MMA(0, 0, At, B0); PG8_BAR; PG8_SCHED;
;             PG8_LDB(B1, 1, 1); PG8_STAGE(PG8_SB(1, 0), b3, voffB);
;             PG8_BAR; PG8_WAIT_L(0); PG8_MMA(0, 1, At, B1); PG8_BAR;
;             PG8_LDA(At, 1, 1); PG8_STAGE(PG8_SA(1, 0), a3, voffA);
;             PG8_BAR; PG8_WAIT_L(0); PG8_MMA(1, 0, At, B0); PG8_BAR; PG8_SCHED;
;             PG8_STAGE(PG8_SB(1, 1), b3 + hstepB, voffB);
;             PG8_WAIT_V(6); PG8_BAR; PG8_MMA(1, 1, At, B1); PG8_BAR;
	s_setprio 1
	s_waitcnt lgkmcnt(7)
	v_mfma_f32_16x16x32_bf16 v[60:63], v[152:155], v[168:171], v[60:63]
	v_mfma_f32_16x16x32_bf16 v[56:59], v[160:163], v[168:171], v[56:59]
	s_waitcnt lgkmcnt(5)
	v_mfma_f32_16x16x32_bf16 v[44:47], v[152:155], v[176:179], v[44:47]
	v_mfma_f32_16x16x32_bf16 v[40:43], v[160:163], v[176:179], v[40:43]
	s_waitcnt lgkmcnt(3)
	v_mfma_f32_16x16x32_bf16 v[28:31], v[152:155], v[184:187], v[28:31]
	v_mfma_f32_16x16x32_bf16 v[24:27], v[160:163], v[184:187], v[24:27]
	s_waitcnt lgkmcnt(1)
	v_mfma_f32_16x16x32_bf16 v[12:15], v[152:155], v[192:195], v[12:15]
	v_mfma_f32_16x16x32_bf16 v[8:11], v[160:163], v[192:195], v[8:11]
	v_mfma_f32_16x16x32_bf16 v[60:63], v[156:159], v[172:175], v[60:63]
	v_mfma_f32_16x16x32_bf16 v[56:59], v[164:167], v[172:175], v[56:59]
	v_mfma_f32_16x16x32_bf16 v[44:47], v[156:159], v[180:183], v[44:47]
	v_mfma_f32_16x16x32_bf16 v[40:43], v[164:167], v[180:183], v[40:43]
	v_mfma_f32_16x16x32_bf16 v[28:31], v[156:159], v[188:191], v[28:31]
	v_mfma_f32_16x16x32_bf16 v[24:27], v[164:167], v[188:191], v[24:27]
	s_waitcnt lgkmcnt(0)
	v_mfma_f32_16x16x32_bf16 v[12:15], v[156:159], v[198:201], v[12:15]
	v_mfma_f32_16x16x32_bf16 v[8:11], v[164:167], v[198:201], v[8:11]
	s_setprio 0
	s_barrier
	s_add_u32 s8, s12, 0x160080
	s_addc_u32 s9, s13, 0
	s_add_i32 s12, s14, s22
	s_mov_b32 m0, s12
	s_nop 0
	global_load_lds_dwordx4 v132, s[8:9]
	s_add_i32 m0, s12, 0x2000
	s_nop 0
	global_load_lds_dwordx4 v128, s[8:9]
	s_waitcnt vmcnt(6)
	s_barrier
	s_setprio 1
	v_mfma_f32_16x16x32_bf16 v[52:55], v[202:205], v[168:171], v[52:55]
	v_mfma_f32_16x16x32_bf16 v[48:51], v[210:213], v[168:171], v[48:51]
	ds_read_b128 v[152:155], v149
	v_mfma_f32_16x16x32_bf16 v[36:39], v[202:205], v[176:179], v[36:39]
	v_mfma_f32_16x16x32_bf16 v[32:35], v[210:213], v[176:179], v[32:35]
	ds_read_b128 v[156:159], v149 offset:1024
	v_mfma_f32_16x16x32_bf16 v[20:23], v[202:205], v[184:187], v[20:23]
	v_mfma_f32_16x16x32_bf16 v[16:19], v[210:213], v[184:187], v[16:19]
	ds_read_b128 v[160:163], v149 offset:2048
	v_mfma_f32_16x16x32_bf16 v[4:7], v[202:205], v[192:195], v[4:7]
	v_mfma_f32_16x16x32_bf16 v[0:3], v[210:213], v[192:195], v[0:3]
	ds_read_b128 v[164:167], v149 offset:3072
	v_mfma_f32_16x16x32_bf16 v[52:55], v[206:209], v[172:175], v[52:55]
	s_add_i32 s3, s3, 2
	v_mfma_f32_16x16x32_bf16 v[48:51], v[214:217], v[172:175], v[48:51]
	s_add_u32 s5, s5, 0x100
	s_addc_u32 s38, s38, 0
	v_mfma_f32_16x16x32_bf16 v[36:39], v[206:209], v[180:183], v[36:39]
	s_cmpk_gt_u32 s3, 0x55
	v_mfma_f32_16x16x32_bf16 v[32:35], v[214:217], v[180:183], v[32:35]
	s_mov_b64 s[8:9], s[10:11]
	v_mfma_f32_16x16x32_bf16 v[20:23], v[206:209], v[188:191], v[20:23]
	v_mfma_f32_16x16x32_bf16 v[16:19], v[214:217], v[188:191], v[16:19]
	v_mfma_f32_16x16x32_bf16 v[4:7], v[206:209], v[198:201], v[4:7]
	v_mfma_f32_16x16x32_bf16 v[0:3], v[214:217], v[198:201], v[0:3]
	s_setprio 0
	s_barrier
	s_cbranch_scc0 .LBB1_550
	s_waitcnt lgkmcnt(0)
	v_mov_b32_e32 v144, v146
	v_mov_b32_e32 v152, v147
	s_lshl_b32 s2, s2, 8
	s_add_i32 s2, s2, s29
	s_lshl_b32 s3, s4, 8
	v_add_u32_e32 v152, s2, v152
	s_or_b32 s3, s3, s54
	v_ashrrev_i32_e32 v153, 31, v152
	v_lshl_add_u32 v144, v144, 3, s3
	v_lshlrev_b64 v[152:153], 12, v[152:153]
	v_ashrrev_i32_e32 v145, 31, v144
	v_lshl_add_u64 v[152:153], s[46:47], 0, v[152:153]
	v_lshl_add_u64 v[144:145], v[144:145], 1, v[152:153]
	global_load_dwordx4 v[160:163], v[144:145], off
	global_load_dwordx4 v[164:167], v[144:145], off offset:256
	s_mov_b64 s[98:99], 0x10000
	v_lshl_add_u64 v[154:155], v[144:145], 0, s[98:99]
	global_load_dwordx4 v[168:171], v[154:155], off
	global_load_dwordx4 v[172:175], v[154:155], off offset:256
	s_mov_b64 s[98:99], 0x20000
	v_lshl_add_u64 v[154:155], v[144:145], 0, s[98:99]
	global_load_dwordx4 v[176:179], v[154:155], off
	global_load_dwordx4 v[180:183], v[154:155], off offset:256
	s_mov_b64 s[98:99], 0x30000
	v_lshl_add_u64 v[154:155], v[144:145], 0, s[98:99]
	global_load_dwordx4 v[184:187], v[154:155], off
	global_load_dwordx4 v[188:191], v[154:155], off offset:256
	s_mov_b64 s[98:99], 0x80000
	v_lshl_add_u64 v[154:155], v[144:145], 0, s[98:99]
	global_load_dwordx4 v[192:195], v[154:155], off
	global_load_dwordx4 v[198:201], v[154:155], off offset:256
	s_mov_b64 s[98:99], 0x90000
	v_lshl_add_u64 v[154:155], v[144:145], 0, s[98:99]
	global_load_dwordx4 v[202:205], v[154:155], off
	global_load_dwordx4 v[206:209], v[154:155], off offset:256
	s_mov_b64 s[98:99], 0xa0000
	v_lshl_add_u64 v[154:155], v[144:145], 0, s[98:99]
	global_load_dwordx4 v[210:213], v[154:155], off
	global_load_dwordx4 v[214:217], v[154:155], off offset:256
	s_mov_b64 s[98:99], 0xb0000
	v_lshl_add_u64 v[154:155], v[144:145], 0, s[98:99]
	global_load_dwordx4 v[248:251], v[154:155], off
	global_load_dwordx4 v[252:255], v[154:155], off offset:256
	s_waitcnt vmcnt(15)
	s_nop 1
	v_mov_b32_e32 v152, v160
	v_mov_b32_e32 v153, v161
	v_mov_b32_e32 v154, v162
	v_mov_b32_e32 v155, v163
	s_mov_b64 s[2:3], 0x10000
	s_mov_b32 s4, s37
	s_mov_b64 s[10:11], s[6:7]
	s_mov_b64 s[8:9], s[42:43]
	s_waitcnt lgkmcnt(0)
	v_lshlrev_b32_e32 v156, 16, v152
	v_and_b32_e32 v157, 0xffff0000, v152
	v_lshlrev_b32_e32 v152, 16, v153
	v_and_b32_e32 v153, 0xffff0000, v153
	v_lshlrev_b32_e32 v158, 16, v154
	v_and_b32_e32 v159, 0xffff0000, v154
	v_lshlrev_b32_e32 v154, 16, v155
	v_and_b32_e32 v155, 0xffff0000, v155
	v_pk_add_f32 v[126:127], v[126:127], v[152:153]
	v_pk_add_f32 v[124:125], v[124:125], v[156:157]
	v_pk_add_f32 v[152:153], v[122:123], v[154:155]
	v_pk_add_f32 v[122:123], v[120:121], v[158:159]
	v_cvt_pk_bf16_f32 v120, v124, v125
	v_cvt_pk_bf16_f32 v121, v126, v127
	v_cvt_pk_bf16_f32 v122, v122, v123
	v_cvt_pk_bf16_f32 v123, v152, v153
	global_store_dwordx4 v[144:145], v[120:123], off
	s_waitcnt vmcnt(15)
; DI unsigned pack2(float a, float b) { f32x2 v = {a, b}; hwbf16x2 r = __builtin_convertvector(v, hwbf16x2); return __builtin_bit_cast(unsigned, r); }
; DI float bflo(unsigned w) { return __uint_as_float(w << 16); }
; DI float bfhi(unsigned w) { return __uint_as_float(w & 0xffff0000u); }
;     DI void operator()(const f32x4 (&acc)[2][2][4][2], const Unit& u, int wr, int wc, int fr, int fq) const {
;     ...
;             for (int m = 0; m < 4; ++m) { const size_t ro = (size_t)(row0 + ai * HALF + m * 16) * D + col0;
; #pragma unroll
;                 for (int bj = 0; bj < 2; ++bj) {
;                     f32x4 x0, x1;
;                     if constexpr (IB) { const u32x4 w = *(const u32x4*)((const bf16_t*)Xin + ro + bj * HALF);
;                         x0 = (f32x4){bflo(w[0]), bfhi(w[0]), bflo(w[1]), bfhi(w[1])}; x1 = (f32x4){bflo(w[2]), bfhi(w[2]), bflo(w[3]), bfhi(w[3])}; }
;                     else { x0 = *(const f32x4*)((const float*)Xin + ro + bj * HALF); x1 = *(const f32x4*)((const float*)Xin + ro + bj * HALF + 4); }
;                     x0 += acc[ai][bj][m][0] * sc[bj][0]; x1 += acc[ai][bj][m][1] * sc[bj][1];
;                     if constexpr (OB) { u32x4 o; o[0] = pack2(x0[0], x0[1]); o[1] = pack2(x0[2], x0[3]); o[2] = pack2(x1[0], x1[1]); o[3] = pack2(x1[2], x1[3]);
;                         *(u32x4*)((bf16_t*)Xout + ro + bj * HALF) = o; }
;                     else { *(f32x4*)((float*)Xout + ro + bj * HALF) = x0; *(f32x4*)((float*)Xout + ro + bj * HALF + 4) = x1; } } }
	s_nop 1
	v_mov_b32_e32 v120, v164
	v_mov_b32_e32 v121, v165
	v_mov_b32_e32 v122, v166
	v_mov_b32_e32 v123, v167
	s_waitcnt lgkmcnt(0)
	v_lshlrev_b32_e32 v124, 16, v120
	v_and_b32_e32 v125, 0xffff0000, v120
	v_lshlrev_b32_e32 v120, 16, v121
	v_and_b32_e32 v121, 0xffff0000, v121
	v_lshlrev_b32_e32 v126, 16, v122
	v_and_b32_e32 v127, 0xffff0000, v122
	v_lshlrev_b32_e32 v122, 16, v123
	v_and_b32_e32 v123, 0xffff0000, v123
	v_pk_add_f32 v[116:117], v[116:117], v[124:125]
	v_pk_add_f32 v[118:119], v[118:119], v[120:121]
	v_pk_add_f32 v[120:121], v[114:115], v[122:123]
	v_pk_add_f32 v[114:115], v[112:113], v[126:127]
	v_cvt_pk_bf16_f32 v112, v116, v117
	v_lshl_add_u64 v[116:117], v[144:145], 0, s[2:3]
	s_mov_b32 s2, 0x10000
	v_cvt_pk_bf16_f32 v113, v118, v119
	v_add_co_u32_e32 v118, vcc, s2, v144
	v_cvt_pk_bf16_f32 v114, v114, v115
	v_cvt_pk_bf16_f32 v115, v120, v121
	v_addc_co_u32_e32 v119, vcc, 0, v145, vcc
	global_store_dwordx4 v[144:145], v[112:115], off offset:256
	s_waitcnt vmcnt(15)
	s_nop 1
	v_mov_b32_e32 v112, v168
	v_mov_b32_e32 v113, v169
	v_mov_b32_e32 v114, v170
	v_mov_b32_e32 v115, v171
	s_mov_b64 s[2:3], 0x20000
	s_waitcnt lgkmcnt(0)
	v_lshlrev_b32_e32 v120, 16, v112
	v_and_b32_e32 v121, 0xffff0000, v112
	v_lshlrev_b32_e32 v112, 16, v113
	v_and_b32_e32 v113, 0xffff0000, v113
	v_lshlrev_b32_e32 v122, 16, v114
	v_and_b32_e32 v123, 0xffff0000, v114
	v_lshlrev_b32_e32 v114, 16, v115
	v_and_b32_e32 v115, 0xffff0000, v115
	v_pk_add_f32 v[110:111], v[110:111], v[112:113]
	v_pk_add_f32 v[108:109], v[108:109], v[120:121]
	v_pk_add_f32 v[112:113], v[106:107], v[114:115]
	v_pk_add_f32 v[106:107], v[104:105], v[122:123]
	v_cvt_pk_bf16_f32 v104, v108, v109
	v_cvt_pk_bf16_f32 v105, v110, v111
	v_cvt_pk_bf16_f32 v106, v106, v107
	v_cvt_pk_bf16_f32 v107, v112, v113
	global_store_dwordx4 v[118:119], v[104:107], off
	s_waitcnt vmcnt(15)
	s_nop 1
	v_mov_b32_e32 v104, v172
	v_mov_b32_e32 v105, v173
	v_mov_b32_e32 v106, v174
	v_mov_b32_e32 v107, v175
	s_waitcnt lgkmcnt(0)
	v_lshlrev_b32_e32 v108, 16, v104
	v_and_b32_e32 v109, 0xffff0000, v104
	v_lshlrev_b32_e32 v104, 16, v105
	v_and_b32_e32 v105, 0xffff0000, v105
	v_lshlrev_b32_e32 v110, 16, v106
	v_and_b32_e32 v111, 0xffff0000, v106
	v_lshlrev_b32_e32 v106, 16, v107
	v_and_b32_e32 v107, 0xffff0000, v107
	v_pk_add_f32 v[100:101], v[100:101], v[108:109]
	v_pk_add_f32 v[102:103], v[102:103], v[104:105]
	v_pk_add_f32 v[104:105], v[98:99], v[106:107]
	v_pk_add_f32 v[98:99], v[96:97], v[110:111]
	v_cvt_pk_bf16_f32 v96, v100, v101
	v_lshl_add_u64 v[100:101], v[144:145], 0, s[2:3]
	s_mov_b32 s2, 0x20000
	v_cvt_pk_bf16_f32 v97, v102, v103
	v_add_co_u32_e32 v102, vcc, s2, v144
	v_cvt_pk_bf16_f32 v98, v98, v99
	v_cvt_pk_bf16_f32 v99, v104, v105
	v_addc_co_u32_e32 v103, vcc, 0, v145, vcc
	global_store_dwordx4 v[116:117], v[96:99], off offset:256
	s_waitcnt vmcnt(15)
	s_nop 1
	v_mov_b32_e32 v96, v176
	v_mov_b32_e32 v97, v177
	v_mov_b32_e32 v98, v178
	v_mov_b32_e32 v99, v179
	s_mov_b64 s[2:3], 0x30000
	s_waitcnt lgkmcnt(0)
	v_lshlrev_b32_e32 v104, 16, v96
	v_and_b32_e32 v105, 0xffff0000, v96
	v_lshlrev_b32_e32 v96, 16, v97
	v_and_b32_e32 v97, 0xffff0000, v97
	v_lshlrev_b32_e32 v106, 16, v98
	v_and_b32_e32 v107, 0xffff0000, v98
	v_lshlrev_b32_e32 v98, 16, v99
	v_and_b32_e32 v99, 0xffff0000, v99
	v_pk_add_f32 v[94:95], v[94:95], v[96:97]
	v_pk_add_f32 v[92:93], v[92:93], v[104:105]
	v_pk_add_f32 v[96:97], v[90:91], v[98:99]
	v_pk_add_f32 v[90:91], v[88:89], v[106:107]
	v_cvt_pk_bf16_f32 v88, v92, v93
	v_cvt_pk_bf16_f32 v89, v94, v95
	v_cvt_pk_bf16_f32 v90, v90, v91
	v_cvt_pk_bf16_f32 v91, v96, v97
	global_store_dwordx4 v[102:103], v[88:91], off
	s_waitcnt vmcnt(15)
	s_nop 1
	v_mov_b32_e32 v88, v180
	v_mov_b32_e32 v89, v181
	v_mov_b32_e32 v90, v182
	v_mov_b32_e32 v91, v183
	s_waitcnt lgkmcnt(0)
	v_lshlrev_b32_e32 v92, 16, v88
	v_and_b32_e32 v93, 0xffff0000, v88
	v_lshlrev_b32_e32 v88, 16, v89
	v_and_b32_e32 v89, 0xffff0000, v89
	v_lshlrev_b32_e32 v94, 16, v90
	v_and_b32_e32 v95, 0xffff0000, v90
	v_lshlrev_b32_e32 v90, 16, v91
	v_and_b32_e32 v91, 0xffff0000, v91
	v_pk_add_f32 v[86:87], v[86:87], v[88:89]
	v_pk_add_f32 v[84:85], v[84:85], v[92:93]
	v_pk_add_f32 v[88:89], v[82:83], v[90:91]
	v_pk_add_f32 v[82:83], v[80:81], v[94:95]
	v_cvt_pk_bf16_f32 v80, v84, v85
	v_cvt_pk_bf16_f32 v81, v86, v87
	v_cvt_pk_bf16_f32 v82, v82, v83
	v_cvt_pk_bf16_f32 v83, v88, v89
	global_store_dwordx4 v[100:101], v[80:83], off offset:256
	s_nop 1
	v_lshl_add_u64 v[80:81], v[144:145], 0, s[2:3]
	s_mov_b32 s2, 0x30000
	v_add_co_u32_e32 v86, vcc, s2, v144
	s_mov_b64 s[2:3], 0x80000
	s_nop 0
	v_addc_co_u32_e32 v87, vcc, 0, v145, vcc
	s_waitcnt vmcnt(15)
	s_nop 1
	v_mov_b32_e32 v82, v184
	v_mov_b32_e32 v83, v185
	v_mov_b32_e32 v84, v186
	v_mov_b32_e32 v85, v187
	s_waitcnt lgkmcnt(0)
	v_lshlrev_b32_e32 v88, 16, v82
	v_and_b32_e32 v89, 0xffff0000, v82
	v_lshlrev_b32_e32 v82, 16, v83
	v_and_b32_e32 v83, 0xffff0000, v83
	v_lshlrev_b32_e32 v90, 16, v84
	v_and_b32_e32 v91, 0xffff0000, v84
	v_lshlrev_b32_e32 v84, 16, v85
	v_and_b32_e32 v85, 0xffff0000, v85
	v_pk_add_f32 v[78:79], v[78:79], v[82:83]
	v_pk_add_f32 v[76:77], v[76:77], v[88:89]
	v_pk_add_f32 v[82:83], v[74:75], v[84:85]
	v_pk_add_f32 v[74:75], v[72:73], v[90:91]
	v_cvt_pk_bf16_f32 v72, v76, v77
	v_cvt_pk_bf16_f32 v73, v78, v79
	v_cvt_pk_bf16_f32 v74, v74, v75
	v_cvt_pk_bf16_f32 v75, v82, v83
	global_store_dwordx4 v[86:87], v[72:75], off
	s_waitcnt vmcnt(15)
	s_nop 1
	v_mov_b32_e32 v72, v188
	v_mov_b32_e32 v73, v189
	v_mov_b32_e32 v74, v190
	v_mov_b32_e32 v75, v191
	s_waitcnt lgkmcnt(0)
; DI unsigned pack2(float a, float b) { f32x2 v = {a, b}; hwbf16x2 r = __builtin_convertvector(v, hwbf16x2); return __builtin_bit_cast(unsigned, r); }
; DI float bflo(unsigned w) { return __uint_as_float(w << 16); }
; DI float bfhi(unsigned w) { return __uint_as_float(w & 0xffff0000u); }
;     DI void operator()(const f32x4 (&acc)[2][2][4][2], const Unit& u, int wr, int wc, int fr, int fq) const {
;     ...
;             for (int m = 0; m < 4; ++m) { const size_t ro = (size_t)(row0 + ai * HALF + m * 16) * D + col0;
; #pragma unroll
;                 for (int bj = 0; bj < 2; ++bj) {
;                     f32x4 x0, x1;
;                     if constexpr (IB) { const u32x4 w = *(const u32x4*)((const bf16_t*)Xin + ro + bj * HALF);
;                         x0 = (f32x4){bflo(w[0]), bfhi(w[0]), bflo(w[1]), bfhi(w[1])}; x1 = (f32x4){bflo(w[2]), bfhi(w[2]), bflo(w[3]), bfhi(w[3])}; }
;                     else { x0 = *(const f32x4*)((const float*)Xin + ro + bj * HALF); x1 = *(const f32x4*)((const float*)Xin + ro + bj * HALF + 4); }
;                     x0 += acc[ai][bj][m][0] * sc[bj][0]; x1 += acc[ai][bj][m][1] * sc[bj][1];
;                     if constexpr (OB) { u32x4 o; o[0] = pack2(x0[0], x0[1]); o[1] = pack2(x0[2], x0[3]); o[2] = pack2(x1[0], x1[1]); o[3] = pack2(x1[2], x1[3]);
;                         *(u32x4*)((bf16_t*)Xout + ro + bj * HALF) = o; }
;                     else { *(f32x4*)((float*)Xout + ro + bj * HALF) = x0; *(f32x4*)((float*)Xout + ro + bj * HALF + 4) = x1; } } }
	v_lshlrev_b32_e32 v76, 16, v72
	v_and_b32_e32 v77, 0xffff0000, v72
	v_lshlrev_b32_e32 v72, 16, v73
	v_and_b32_e32 v73, 0xffff0000, v73
	v_lshlrev_b32_e32 v78, 16, v74
	v_and_b32_e32 v79, 0xffff0000, v74
	v_lshlrev_b32_e32 v74, 16, v75
	v_and_b32_e32 v75, 0xffff0000, v75
	v_pk_add_f32 v[70:71], v[70:71], v[72:73]
	v_pk_add_f32 v[68:69], v[68:69], v[76:77]
	v_pk_add_f32 v[72:73], v[66:67], v[74:75]
	v_pk_add_f32 v[66:67], v[64:65], v[78:79]
	v_cvt_pk_bf16_f32 v64, v68, v69
	v_cvt_pk_bf16_f32 v65, v70, v71
	v_cvt_pk_bf16_f32 v66, v66, v67
	v_cvt_pk_bf16_f32 v67, v72, v73
	global_store_dwordx4 v[80:81], v[64:67], off offset:256
	s_nop 1
	v_lshl_add_u64 v[64:65], v[144:145], 0, s[2:3]
	s_mov_b32 s2, 0x80000
	v_add_co_u32_e32 v70, vcc, s2, v144
	s_mov_b64 s[2:3], 0x90000
	s_nop 0
	v_addc_co_u32_e32 v71, vcc, 0, v145, vcc
	s_waitcnt vmcnt(15)
	s_nop 1
	v_mov_b32_e32 v66, v192
	v_mov_b32_e32 v67, v193
	v_mov_b32_e32 v68, v194
	v_mov_b32_e32 v69, v195
	s_waitcnt lgkmcnt(0)
	v_lshlrev_b32_e32 v72, 16, v66
	v_and_b32_e32 v73, 0xffff0000, v66
	v_lshlrev_b32_e32 v66, 16, v67
	v_and_b32_e32 v67, 0xffff0000, v67
	v_lshlrev_b32_e32 v74, 16, v68
	v_and_b32_e32 v75, 0xffff0000, v68
	v_lshlrev_b32_e32 v68, 16, v69
	v_and_b32_e32 v69, 0xffff0000, v69
	v_pk_add_f32 v[62:63], v[62:63], v[66:67]
	v_pk_add_f32 v[60:61], v[60:61], v[72:73]
	v_pk_add_f32 v[66:67], v[58:59], v[68:69]
	v_pk_add_f32 v[58:59], v[56:57], v[74:75]
	v_cvt_pk_bf16_f32 v56, v60, v61
	v_cvt_pk_bf16_f32 v57, v62, v63
	v_cvt_pk_bf16_f32 v58, v58, v59
	v_cvt_pk_bf16_f32 v59, v66, v67
	global_store_dwordx4 v[70:71], v[56:59], off
	s_waitcnt vmcnt(15)
	s_nop 1
	v_mov_b32_e32 v56, v198
	v_mov_b32_e32 v57, v199
	v_mov_b32_e32 v58, v200
	v_mov_b32_e32 v59, v201
	s_waitcnt lgkmcnt(0)
	v_lshlrev_b32_e32 v60, 16, v56
	v_and_b32_e32 v61, 0xffff0000, v56
	v_lshlrev_b32_e32 v56, 16, v57
	v_and_b32_e32 v57, 0xffff0000, v57
	v_lshlrev_b32_e32 v62, 16, v58
	v_and_b32_e32 v63, 0xffff0000, v58
	v_lshlrev_b32_e32 v58, 16, v59
	v_and_b32_e32 v59, 0xffff0000, v59
	v_pk_add_f32 v[54:55], v[54:55], v[56:57]
	v_pk_add_f32 v[52:53], v[52:53], v[60:61]
	v_pk_add_f32 v[56:57], v[50:51], v[58:59]
	v_pk_add_f32 v[50:51], v[48:49], v[62:63]
	v_cvt_pk_bf16_f32 v48, v52, v53
	v_cvt_pk_bf16_f32 v49, v54, v55
	v_cvt_pk_bf16_f32 v50, v50, v51
	v_cvt_pk_bf16_f32 v51, v56, v57
	global_store_dwordx4 v[64:65], v[48:51], off offset:256
	s_nop 1
	v_lshl_add_u64 v[48:49], v[144:145], 0, s[2:3]
	s_mov_b32 s2, 0x90000
	v_add_co_u32_e32 v54, vcc, s2, v144
	s_mov_b64 s[2:3], 0xa0000
	s_nop 0
	v_addc_co_u32_e32 v55, vcc, 0, v145, vcc
	s_waitcnt vmcnt(15)
	s_nop 1
	v_mov_b32_e32 v50, v202
	v_mov_b32_e32 v51, v203
	v_mov_b32_e32 v52, v204
	v_mov_b32_e32 v53, v205
	s_waitcnt lgkmcnt(0)
	v_lshlrev_b32_e32 v56, 16, v50
	v_and_b32_e32 v57, 0xffff0000, v50
	v_lshlrev_b32_e32 v50, 16, v51
	v_and_b32_e32 v51, 0xffff0000, v51
	v_lshlrev_b32_e32 v58, 16, v52
	v_and_b32_e32 v59, 0xffff0000, v52
	v_lshlrev_b32_e32 v52, 16, v53
	v_and_b32_e32 v53, 0xffff0000, v53
	v_pk_add_f32 v[46:47], v[46:47], v[50:51]
	v_pk_add_f32 v[44:45], v[44:45], v[56:57]
	v_pk_add_f32 v[50:51], v[42:43], v[52:53]
	v_pk_add_f32 v[42:43], v[40:41], v[58:59]
	v_cvt_pk_bf16_f32 v40, v44, v45
	v_cvt_pk_bf16_f32 v41, v46, v47
	v_cvt_pk_bf16_f32 v42, v42, v43
	v_cvt_pk_bf16_f32 v43, v50, v51
	global_store_dwordx4 v[54:55], v[40:43], off
	s_waitcnt vmcnt(15)
	s_nop 1
	v_mov_b32_e32 v40, v206
	v_mov_b32_e32 v41, v207
	v_mov_b32_e32 v42, v208
	v_mov_b32_e32 v43, v209
	s_waitcnt lgkmcnt(0)
; DI unsigned pack2(float a, float b) { f32x2 v = {a, b}; hwbf16x2 r = __builtin_convertvector(v, hwbf16x2); return __builtin_bit_cast(unsigned, r); }
; DI float bflo(unsigned w) { return __uint_as_float(w << 16); }
; DI float bfhi(unsigned w) { return __uint_as_float(w & 0xffff0000u); }
;     DI const char* a(const Unit& u) const { return (const char*)(A + (size_t)u.pm * BM * lda); }
;     DI const char* a(const Unit& u) const { return (const char*)(A + (size_t)u.pm * BM * 2048 + (u.pn >> 1) * 512); }
; #define PG8_BAR __builtin_amdgcn_s_barrier()
;     DI void operator()(const f32x4 (&acc)[2][2][4][2], const Unit& u, int wr, int wc, int fr, int fq) const {
;     ...
;             for (int m = 0; m < 4; ++m) { const size_t ro = (size_t)(row0 + ai * HALF + m * 16) * D + col0;
; #pragma unroll
;                 for (int bj = 0; bj < 2; ++bj) {
;                     f32x4 x0, x1;
;                     if constexpr (IB) { const u32x4 w = *(const u32x4*)((const bf16_t*)Xin + ro + bj * HALF);
;                         x0 = (f32x4){bflo(w[0]), bfhi(w[0]), bflo(w[1]), bfhi(w[1])}; x1 = (f32x4){bflo(w[2]), bfhi(w[2]), bflo(w[3]), bfhi(w[3])}; }
;                     else { x0 = *(const f32x4*)((const float*)Xin + ro + bj * HALF); x1 = *(const f32x4*)((const float*)Xin + ro + bj * HALF + 4); }
;                     x0 += acc[ai][bj][m][0] * sc[bj][0]; x1 += acc[ai][bj][m][1] * sc[bj][1];
;                     if constexpr (OB) { u32x4 o; o[0] = pack2(x0[0], x0[1]); o[1] = pack2(x0[2], x0[3]); o[2] = pack2(x1[0], x1[1]); o[3] = pack2(x1[2], x1[3]);
;                         *(u32x4*)((bf16_t*)Xout + ro + bj * HALF) = o; }
;                     else { *(f32x4*)((float*)Xout + ro + bj * HALF) = x0; *(f32x4*)((float*)Xout + ro + bj * HALF + 4) = x1; } } }
; template <class Map, class Epi>
; DI void gemm_phase(LAS unsigned char* lds, const Map& MP, const Epi& E, const int nM, const int nN, const int K, const int lda, const int ldb) {
;     ...
;         if (!has_next) break;
; #pragma unroll
;         for (int a = 0; a < 2; ++a)
; #pragma unroll
;             for (int b = 0; b < 2; ++b)
; #pragma unroll
;                 for (int m = 0; m < 4; ++m)
; #pragma unroll
;                     for (int n = 0; n < 2; ++n) acc[a][b][m][n] = (f32x4){0.f, 0.f, 0.f, 0.f};
;         cur = nxt; cA = nA; cB = nB; ++ui;
;     }
;     PG8_WAIT_V(0);
;     if (wr == 0) PG8_BAR;
;     PG8_BAR;
	v_lshlrev_b32_e32 v44, 16, v40
	v_and_b32_e32 v45, 0xffff0000, v40
	v_lshlrev_b32_e32 v40, 16, v41
	v_and_b32_e32 v41, 0xffff0000, v41
	v_lshlrev_b32_e32 v46, 16, v42
	v_and_b32_e32 v47, 0xffff0000, v42
	v_lshlrev_b32_e32 v42, 16, v43
	v_and_b32_e32 v43, 0xffff0000, v43
	v_pk_add_f32 v[38:39], v[38:39], v[40:41]
	v_pk_add_f32 v[36:37], v[36:37], v[44:45]
	v_pk_add_f32 v[40:41], v[34:35], v[42:43]
	v_pk_add_f32 v[34:35], v[32:33], v[46:47]
	v_cvt_pk_bf16_f32 v32, v36, v37
	v_cvt_pk_bf16_f32 v33, v38, v39
	v_cvt_pk_bf16_f32 v34, v34, v35
	v_cvt_pk_bf16_f32 v35, v40, v41
	global_store_dwordx4 v[48:49], v[32:35], off offset:256
	s_nop 1
	v_lshl_add_u64 v[32:33], v[144:145], 0, s[2:3]
	s_mov_b32 s2, 0xa0000
	v_add_co_u32_e32 v38, vcc, s2, v144
	s_mov_b64 s[2:3], 0xb0000
	s_nop 0
	v_addc_co_u32_e32 v39, vcc, 0, v145, vcc
	s_waitcnt vmcnt(15)
	s_nop 1
	v_mov_b32_e32 v34, v210
	v_mov_b32_e32 v35, v211
	v_mov_b32_e32 v36, v212
	v_mov_b32_e32 v37, v213
	s_waitcnt lgkmcnt(0)
	v_lshlrev_b32_e32 v40, 16, v34
	v_and_b32_e32 v41, 0xffff0000, v34
	v_lshlrev_b32_e32 v34, 16, v35
	v_and_b32_e32 v35, 0xffff0000, v35
	v_lshlrev_b32_e32 v42, 16, v36
	v_and_b32_e32 v43, 0xffff0000, v36
	v_lshlrev_b32_e32 v36, 16, v37
	v_and_b32_e32 v37, 0xffff0000, v37
	v_pk_add_f32 v[30:31], v[30:31], v[34:35]
	v_pk_add_f32 v[28:29], v[28:29], v[40:41]
	v_pk_add_f32 v[34:35], v[26:27], v[36:37]
	v_pk_add_f32 v[26:27], v[24:25], v[42:43]
	v_cvt_pk_bf16_f32 v24, v28, v29
	v_cvt_pk_bf16_f32 v25, v30, v31
	v_cvt_pk_bf16_f32 v26, v26, v27
	v_cvt_pk_bf16_f32 v27, v34, v35
	global_store_dwordx4 v[38:39], v[24:27], off
	s_waitcnt vmcnt(15)
	s_nop 1
	v_mov_b32_e32 v24, v214
	v_mov_b32_e32 v25, v215
	v_mov_b32_e32 v26, v216
	v_mov_b32_e32 v27, v217
	s_waitcnt lgkmcnt(0)
	v_lshlrev_b32_e32 v28, 16, v24
	v_and_b32_e32 v29, 0xffff0000, v24
	v_lshlrev_b32_e32 v24, 16, v25
	v_and_b32_e32 v25, 0xffff0000, v25
	v_lshlrev_b32_e32 v30, 16, v26
	v_and_b32_e32 v31, 0xffff0000, v26
	v_lshlrev_b32_e32 v26, 16, v27
	v_and_b32_e32 v27, 0xffff0000, v27
	v_pk_add_f32 v[22:23], v[22:23], v[24:25]
	v_pk_add_f32 v[20:21], v[20:21], v[28:29]
	v_pk_add_f32 v[24:25], v[18:19], v[26:27]
	v_pk_add_f32 v[18:19], v[16:17], v[30:31]
	v_cvt_pk_bf16_f32 v16, v20, v21
	v_cvt_pk_bf16_f32 v17, v22, v23
	v_cvt_pk_bf16_f32 v18, v18, v19
	v_cvt_pk_bf16_f32 v19, v24, v25
	global_store_dwordx4 v[32:33], v[16:19], off offset:256
	s_nop 1
	v_lshl_add_u64 v[16:17], v[144:145], 0, s[2:3]
	s_mov_b32 s2, 0xb0000
	v_add_co_u32_e32 v22, vcc, s2, v144
	s_mov_b32 s2, s55
	s_nop 0
	v_addc_co_u32_e32 v23, vcc, 0, v145, vcc
	s_waitcnt vmcnt(15)
	s_nop 1
	v_mov_b32_e32 v18, v248
	v_mov_b32_e32 v19, v249
	v_mov_b32_e32 v20, v250
	v_mov_b32_e32 v21, v251
	s_and_b64 vcc, exec, s[40:41]
	s_waitcnt lgkmcnt(0)
	v_lshlrev_b32_e32 v24, 16, v18
	v_and_b32_e32 v25, 0xffff0000, v18
	v_lshlrev_b32_e32 v18, 16, v19
	v_and_b32_e32 v19, 0xffff0000, v19
	v_lshlrev_b32_e32 v26, 16, v20
	v_and_b32_e32 v27, 0xffff0000, v20
	v_lshlrev_b32_e32 v20, 16, v21
	v_and_b32_e32 v21, 0xffff0000, v21
	v_pk_add_f32 v[14:15], v[14:15], v[18:19]
	v_pk_add_f32 v[12:13], v[12:13], v[24:25]
	v_pk_add_f32 v[18:19], v[10:11], v[20:21]
	v_pk_add_f32 v[10:11], v[8:9], v[26:27]
	v_cvt_pk_bf16_f32 v8, v12, v13
	v_cvt_pk_bf16_f32 v9, v14, v15
	v_cvt_pk_bf16_f32 v10, v10, v11
	v_cvt_pk_bf16_f32 v11, v18, v19
	global_store_dwordx4 v[22:23], v[8:11], off
	s_waitcnt vmcnt(15)
	s_nop 1
	v_mov_b32_e32 v8, v252
	v_mov_b32_e32 v9, v253
	v_mov_b32_e32 v10, v254
	v_mov_b32_e32 v11, v255
	s_waitcnt lgkmcnt(0)
	v_lshlrev_b32_e32 v12, 16, v8
	v_and_b32_e32 v13, 0xffff0000, v8
	v_lshlrev_b32_e32 v8, 16, v9
	v_and_b32_e32 v9, 0xffff0000, v9
	v_lshlrev_b32_e32 v14, 16, v10
	v_and_b32_e32 v15, 0xffff0000, v10
	v_lshlrev_b32_e32 v10, 16, v11
	v_and_b32_e32 v11, 0xffff0000, v11
	v_pk_add_f32 v[6:7], v[6:7], v[8:9]
	v_pk_add_f32 v[4:5], v[4:5], v[12:13]
	v_pk_add_f32 v[8:9], v[2:3], v[10:11]
	v_pk_add_f32 v[2:3], v[0:1], v[14:15]
	v_cvt_pk_bf16_f32 v0, v4, v5
	v_cvt_pk_bf16_f32 v1, v6, v7
	v_cvt_pk_bf16_f32 v2, v2, v3
	v_cvt_pk_bf16_f32 v3, v8, v9
	global_store_dwordx4 v[16:17], v[0:3], off offset:256
	s_cbranch_vccz .LBB1_543
	s_waitcnt vmcnt(0)
	s_cmpk_gt_u32 s17, 0xff
	s_cbranch_scc1 .LBB1_554
	s_barrier

; #define PG8_STAGE(bufoff, gbase, voff) do { _Pragma("unroll") for (int _i = 0; _i < 2; ++_i) \
;         __builtin_amdgcn_global_load_lds((const unsigned*)((const char*)(gbase) + (voff)[_i]), (LAS unsigned*)(lds + (bufoff) + ldsw + _i * 8192), 16, 0, 0); } while (0)
; #define PG8_LDA(dst, b, h) do { _Pragma("unroll") for (int m = 0; m < 4; ++m) _Pragma("unroll") for (int k = 0; k < 2; ++k) dst[m][k] = *(const LAS bf16x8*)(lds + PG8_SA(b, h) + aoff + m * 2048 + k * 1024); } while (0)
; #define PG8_LDB(dst, b, h) do { _Pragma("unroll") for (int n = 0; n < 2; ++n) _Pragma("unroll") for (int k = 0; k < 2; ++k) dst[n][k] = *(const LAS bf16x8*)(lds + PG8_SB(b, h) + boff + n * 2048 + k * 1024); } while (0)
; #define PG8_MMA(ai, bj, At, Bt) do { __builtin_amdgcn_s_setprio(1); _Pragma("unroll") for (int m = 0; m < 4; ++m) _Pragma("unroll") for (int n = 0; n < 2; ++n) _Pragma("unroll") for (int k = 0; k < 2; ++k) \
;         acc[ai][bj][m][n] = __builtin_amdgcn_mfma_f32_16x16x32_bf16(Bt[n][k], At[m][k], acc[ai][bj][m][n], 0, 0, 0); __builtin_amdgcn_s_setprio(0); } while (0)
; #define PG8_WAIT_V(n) asm volatile("s_waitcnt vmcnt(" #n ")" ::: "memory")
; #define PG8_WAIT_L(n) asm volatile("s_waitcnt lgkmcnt(" #n ")" ::: "memory")
; template <class Map, class Epi>
; DI void gemm_phase(LAS unsigned char* lds, const Map& MP, const Epi& E, const int nM, const int nN, const int K, const int lda, const int ldb) {
;     ...
;             const bool last = (t == nt - 2);
;             const char* a1 = cA + (size_t)(t + 1) * kstep;
;             const char* a2 = last ? nA : cA + (size_t)(t + 2) * kstep; const char* b2 = last ? nB : cB + (size_t)(t + 2) * kstep;
;             const char* a3 = a2 + kstep; const char* b3 = b2 + kstep;
;             PG8_LDB(B0, 0, 0); PG8_SCHED; PG8_LDA(At, 0, 0); PG8_STAGE(PG8_SA(1, 1), a1 + hstepA, voffA);
;             PG8_WAIT_L(8); PG8_BAR; PG8_WAIT_L(0); PG8_MMA(0, 0, At, B0); PG8_BAR; PG8_SCHED;
;             PG8_LDB(B1, 0, 1); PG8_STAGE(PG8_SB(0, 0), b2, voffB);
;             PG8_BAR; PG8_WAIT_L(0); PG8_MMA(0, 1, At, B1); PG8_BAR;
;             PG8_LDA(At, 0, 1); PG8_STAGE(PG8_SA(0, 0), a2, voffA);
;             PG8_BAR; PG8_WAIT_L(0); PG8_MMA(1, 0, At, B0); PG8_BAR; PG8_SCHED;
;             PG8_STAGE(PG8_SB(0, 1), b2 + hstepB, voffB);
;             PG8_WAIT_V(6); PG8_BAR; PG8_MMA(1, 1, At, B1); PG8_BAR;
.LBB1_693:
	s_add_u32 s3, s20, 0xfff80080
	s_addc_u32 s22, s21, -1
	s_cmp_eq_u32 s54, 28
	s_cselect_b32 s25, s15, s22
	s_cselect_b32 s24, s48, s3
	s_cselect_b32 s23, s13, s53
	s_cselect_b32 s22, s49, s52
	s_add_i32 m0, s31, 0xc000
	ds_read_b128 v[166:169], v148
	ds_read_b128 v[170:173], v148 offset:1024
	ds_read_b128 v[174:177], v148 offset:2048
	ds_read_b128 v[178:181], v148 offset:3072
	ds_read_b128 v[182:185], v148 offset:4096
	ds_read_b128 v[186:189], v148 offset:5120
	ds_read_b128 v[190:193], v148 offset:6144
	ds_read_b128 v[198:201], v148 offset:7168
	global_load_lds_dwordx4 v138, s[20:21]
	s_add_i32 m0, s31, 0xe000
	s_nop 0
	global_load_lds_dwordx4 v136, s[20:21]
	s_waitcnt lgkmcnt(8)
	s_barrier
	s_setprio 1
	s_waitcnt lgkmcnt(7)
	v_mfma_f32_16x16x32_bf16 v[124:127], v[150:153], v[166:169], v[124:127]
	v_mfma_f32_16x16x32_bf16 v[120:123], v[158:161], v[166:169], v[120:123]
	s_waitcnt lgkmcnt(5)
	v_mfma_f32_16x16x32_bf16 v[116:119], v[150:153], v[174:177], v[116:119]
	v_mfma_f32_16x16x32_bf16 v[112:115], v[158:161], v[174:177], v[112:115]
	s_waitcnt lgkmcnt(3)
	v_mfma_f32_16x16x32_bf16 v[100:103], v[150:153], v[182:185], v[100:103]
	v_mfma_f32_16x16x32_bf16 v[96:99], v[158:161], v[182:185], v[96:99]
	s_waitcnt lgkmcnt(1)
	v_mfma_f32_16x16x32_bf16 v[84:87], v[150:153], v[190:193], v[84:87]
	v_mfma_f32_16x16x32_bf16 v[80:83], v[158:161], v[190:193], v[80:83]
	v_mfma_f32_16x16x32_bf16 v[124:127], v[154:157], v[170:173], v[124:127]
	v_mfma_f32_16x16x32_bf16 v[120:123], v[162:165], v[170:173], v[120:123]
	v_mfma_f32_16x16x32_bf16 v[116:119], v[154:157], v[178:181], v[116:119]
	v_mfma_f32_16x16x32_bf16 v[112:115], v[162:165], v[178:181], v[112:115]
	v_mfma_f32_16x16x32_bf16 v[100:103], v[154:157], v[186:189], v[100:103]
	v_mfma_f32_16x16x32_bf16 v[96:99], v[162:165], v[186:189], v[96:99]
	s_waitcnt lgkmcnt(0)
	v_mfma_f32_16x16x32_bf16 v[84:87], v[154:157], v[198:201], v[84:87]
	v_mfma_f32_16x16x32_bf16 v[80:83], v[162:165], v[198:201], v[80:83]
	s_setprio 0
	s_barrier
	s_add_i32 s3, s44, s29
	v_lshl_add_u64 v[194:195], s[22:23], 0, v[132:133]
	s_mov_b32 m0, s3
	ds_read_b128 v[202:205], v149
	ds_read_b128 v[206:209], v149 offset:1024
	ds_read_b128 v[210:213], v149 offset:2048
	ds_read_b128 v[214:217], v149 offset:3072
	global_load_lds_dwordx4 v[194:195], off
	v_lshl_add_u64 v[218:219], s[22:23], 0, v[128:129]
	s_add_i32 m0, s3, 0x2000
	s_nop 0
	global_load_lds_dwordx4 v[218:219], off
	s_barrier
	s_setprio 1
	s_waitcnt lgkmcnt(3)
	v_mfma_f32_16x16x32_bf16 v[108:111], v[202:205], v[166:169], v[108:111]
	s_waitcnt lgkmcnt(1)
	v_mfma_f32_16x16x32_bf16 v[104:107], v[210:213], v[166:169], v[104:107]
	v_mfma_f32_16x16x32_bf16 v[92:95], v[202:205], v[174:177], v[92:95]
	v_mfma_f32_16x16x32_bf16 v[88:91], v[210:213], v[174:177], v[88:91]
	v_mfma_f32_16x16x32_bf16 v[76:79], v[202:205], v[182:185], v[76:79]
	v_mfma_f32_16x16x32_bf16 v[72:75], v[210:213], v[182:185], v[72:75]
	v_mfma_f32_16x16x32_bf16 v[68:71], v[202:205], v[190:193], v[68:71]
	v_mfma_f32_16x16x32_bf16 v[64:67], v[210:213], v[190:193], v[64:67]
	v_mfma_f32_16x16x32_bf16 v[108:111], v[206:209], v[170:173], v[108:111]
	s_mov_b32 m0, s31
	s_waitcnt lgkmcnt(0)
	v_mfma_f32_16x16x32_bf16 v[104:107], v[214:217], v[170:173], v[104:107]
	v_lshl_add_u64 v[220:221], s[24:25], 0, v[134:135]
	v_mfma_f32_16x16x32_bf16 v[92:95], v[206:209], v[178:181], v[92:95]
	v_mfma_f32_16x16x32_bf16 v[88:91], v[214:217], v[178:181], v[88:91]
	v_mfma_f32_16x16x32_bf16 v[76:79], v[206:209], v[186:189], v[76:79]
	v_mfma_f32_16x16x32_bf16 v[72:75], v[214:217], v[186:189], v[72:75]
	v_mfma_f32_16x16x32_bf16 v[68:71], v[206:209], v[198:201], v[68:71]
	v_mfma_f32_16x16x32_bf16 v[64:67], v[214:217], v[198:201], v[64:67]
	s_setprio 0
	s_barrier
	ds_read_b128 v[166:169], v148 offset:16384
	ds_read_b128 v[170:173], v148 offset:17408
	ds_read_b128 v[174:177], v148 offset:18432
	ds_read_b128 v[178:181], v148 offset:19456
	ds_read_b128 v[182:185], v148 offset:20480
	ds_read_b128 v[186:189], v148 offset:21504
	ds_read_b128 v[190:193], v148 offset:22528
	ds_read_b128 v[198:201], v148 offset:23552
	global_load_lds_dwordx4 v[220:221], off
	v_lshl_add_u64 v[222:223], s[24:25], 0, v[130:131]
	s_mov_b32 m0, s11
	s_nop 0
	global_load_lds_dwordx4 v[222:223], off
	s_waitcnt vmcnt(10)
	s_barrier
	s_setprio 1
	s_waitcnt lgkmcnt(7)
	v_mfma_f32_16x16x32_bf16 v[60:63], v[150:153], v[166:169], v[60:63]
	v_mfma_f32_16x16x32_bf16 v[56:59], v[158:161], v[166:169], v[56:59]
	s_waitcnt lgkmcnt(5)
	v_mfma_f32_16x16x32_bf16 v[52:55], v[150:153], v[174:177], v[52:55]
	v_mfma_f32_16x16x32_bf16 v[48:51], v[158:161], v[174:177], v[48:51]
	s_waitcnt lgkmcnt(3)
	v_mfma_f32_16x16x32_bf16 v[36:39], v[150:153], v[182:185], v[36:39]
	v_mfma_f32_16x16x32_bf16 v[32:35], v[158:161], v[182:185], v[32:35]
	s_waitcnt lgkmcnt(1)
	v_mfma_f32_16x16x32_bf16 v[20:23], v[150:153], v[190:193], v[20:23]
	v_mfma_f32_16x16x32_bf16 v[16:19], v[158:161], v[190:193], v[16:19]
	v_mfma_f32_16x16x32_bf16 v[60:63], v[154:157], v[170:173], v[60:63]
	v_mfma_f32_16x16x32_bf16 v[56:59], v[162:165], v[170:173], v[56:59]
	v_mfma_f32_16x16x32_bf16 v[52:55], v[154:157], v[178:181], v[52:55]
	v_mfma_f32_16x16x32_bf16 v[48:51], v[162:165], v[178:181], v[48:51]
	v_mfma_f32_16x16x32_bf16 v[36:39], v[154:157], v[186:189], v[36:39]
	v_mfma_f32_16x16x32_bf16 v[32:35], v[162:165], v[186:189], v[32:35]
	s_waitcnt lgkmcnt(0)
	v_mfma_f32_16x16x32_bf16 v[20:23], v[154:157], v[198:201], v[20:23]
	v_mfma_f32_16x16x32_bf16 v[16:19], v[162:165], v[198:201], v[16:19]
	s_setprio 0
	s_barrier
; #define PG8_STAGE(bufoff, gbase, voff) do { _Pragma("unroll") for (int _i = 0; _i < 2; ++_i) \
;         __builtin_amdgcn_global_load_lds((const unsigned*)((const char*)(gbase) + (voff)[_i]), (LAS unsigned*)(lds + (bufoff) + ldsw + _i * 8192), 16, 0, 0); } while (0)
; #define PG8_LDA(dst, b, h) do { _Pragma("unroll") for (int m = 0; m < 4; ++m) _Pragma("unroll") for (int k = 0; k < 2; ++k) dst[m][k] = *(const LAS bf16x8*)(lds + PG8_SA(b, h) + aoff + m * 2048 + k * 1024); } while (0)
; #define PG8_LDB(dst, b, h) do { _Pragma("unroll") for (int n = 0; n < 2; ++n) _Pragma("unroll") for (int k = 0; k < 2; ++k) dst[n][k] = *(const LAS bf16x8*)(lds + PG8_SB(b, h) + boff + n * 2048 + k * 1024); } while (0)
; #define PG8_MMA(ai, bj, At, Bt) do { __builtin_amdgcn_s_setprio(1); _Pragma("unroll") for (int m = 0; m < 4; ++m) _Pragma("unroll") for (int n = 0; n < 2; ++n) _Pragma("unroll") for (int k = 0; k < 2; ++k) \
;         acc[ai][bj][m][n] = __builtin_amdgcn_mfma_f32_16x16x32_bf16(Bt[n][k], At[m][k], acc[ai][bj][m][n], 0, 0, 0); __builtin_amdgcn_s_setprio(0); } while (0)
; #define PG8_WAIT_V(n) asm volatile("s_waitcnt vmcnt(" #n ")" ::: "memory")
; #define PG8_WAIT_L(n) asm volatile("s_waitcnt lgkmcnt(" #n ")" ::: "memory")
; #define PG8_BAR __builtin_amdgcn_s_barrier()
; #define PG8_SCHED __builtin_amdgcn_sched_barrier(0)
; template <class Map, class Epi>
; DI void gemm_phase(LAS unsigned char* lds, const Map& MP, const Epi& E, const int nM, const int nN, const int K, const int lda, const int ldb) {
;     ...
;             PG8_STAGE(PG8_SB(0, 1), b2 + hstepB, voffB);
;             PG8_WAIT_V(6); PG8_BAR; PG8_MMA(1, 1, At, B1); PG8_BAR;
;             PG8_LDB(B0, 1, 0); PG8_SCHED; PG8_LDA(At, 1, 0); PG8_STAGE(PG8_SA(0, 1), a2 + hstepA, voffA);
;             PG8_WAIT_L(8); PG8_BAR; PG8_WAIT_L(0); PG8_MMA(0, 0, At, B0); PG8_BAR; PG8_SCHED;
;             PG8_LDB(B1, 1, 1); PG8_STAGE(PG8_SB(1, 0), b3, voffB);
;             PG8_BAR; PG8_WAIT_L(0); PG8_MMA(0, 1, At, B1); PG8_BAR;
;             PG8_LDA(At, 1, 1); PG8_STAGE(PG8_SA(1, 0), a3, voffA);
;             PG8_BAR; PG8_WAIT_L(0); PG8_MMA(1, 0, At, B0); PG8_BAR; PG8_SCHED;
	s_add_u32 s56, s22, 0x80000
	s_addc_u32 s57, s23, 0
	s_add_i32 s3, s45, s29
	s_mov_b32 m0, s3
	s_nop 0
	global_load_lds_dwordx4 v132, s[56:57]
	s_add_i32 m0, s3, 0x2000
	s_nop 0
	global_load_lds_dwordx4 v128, s[56:57]
	s_waitcnt vmcnt(6)
	s_barrier
	s_setprio 1
	v_mfma_f32_16x16x32_bf16 v[44:47], v[202:205], v[166:169], v[44:47]
	v_mfma_f32_16x16x32_bf16 v[40:43], v[210:213], v[166:169], v[40:43]
	s_add_i32 s3, 0, 0x18000
	v_add_u32_e32 v162, s3, v146
	ds_read_b128 v[150:153], v162
	v_mfma_f32_16x16x32_bf16 v[28:31], v[202:205], v[174:177], v[28:31]
	v_mfma_f32_16x16x32_bf16 v[24:27], v[210:213], v[174:177], v[24:27]
	ds_read_b128 v[154:157], v162 offset:1024
	v_mfma_f32_16x16x32_bf16 v[12:15], v[202:205], v[182:185], v[12:15]
	v_mfma_f32_16x16x32_bf16 v[8:11], v[210:213], v[182:185], v[8:11]
	ds_read_b128 v[158:161], v162 offset:2048
	v_mfma_f32_16x16x32_bf16 v[4:7], v[202:205], v[190:193], v[4:7]
	v_mfma_f32_16x16x32_bf16 v[0:3], v[210:213], v[190:193], v[0:3]
	ds_read_b128 v[162:165], v162 offset:3072
	v_mfma_f32_16x16x32_bf16 v[44:47], v[206:209], v[170:173], v[44:47]
	v_mfma_f32_16x16x32_bf16 v[40:43], v[214:217], v[170:173], v[40:43]
	v_mfma_f32_16x16x32_bf16 v[28:31], v[206:209], v[178:181], v[28:31]
	v_mfma_f32_16x16x32_bf16 v[24:27], v[214:217], v[178:181], v[24:27]
	v_mfma_f32_16x16x32_bf16 v[12:15], v[206:209], v[186:189], v[12:15]
	v_mfma_f32_16x16x32_bf16 v[8:11], v[214:217], v[186:189], v[8:11]
	v_mfma_f32_16x16x32_bf16 v[4:7], v[206:209], v[198:201], v[4:7]
	v_mfma_f32_16x16x32_bf16 v[0:3], v[214:217], v[198:201], v[0:3]
	s_setprio 0
	s_barrier
	s_add_u32 s24, s24, 0x80000
	s_addc_u32 s25, s25, 0
	s_mov_b32 m0, s34
	ds_read_b128 v[166:169], v148 offset:32768
	ds_read_b128 v[170:173], v148 offset:33792
	ds_read_b128 v[174:177], v148 offset:34816
	ds_read_b128 v[178:181], v148 offset:35840
	ds_read_b128 v[182:185], v148 offset:36864
	ds_read_b128 v[186:189], v148 offset:37888
	ds_read_b128 v[190:193], v148 offset:38912
	ds_read_b128 v[198:201], v148 offset:39936
	global_load_lds_dwordx4 v134, s[24:25]
	s_mov_b32 m0, s35
	s_nop 0
	global_load_lds_dwordx4 v130, s[24:25]
	s_waitcnt lgkmcnt(8)
	s_barrier
	s_setprio 1
	s_waitcnt lgkmcnt(7)
	v_mfma_f32_16x16x32_bf16 v[124:127], v[150:153], v[166:169], v[124:127]
	v_mfma_f32_16x16x32_bf16 v[120:123], v[158:161], v[166:169], v[120:123]
	s_waitcnt lgkmcnt(5)
	v_mfma_f32_16x16x32_bf16 v[116:119], v[150:153], v[174:177], v[116:119]
	v_mfma_f32_16x16x32_bf16 v[112:115], v[158:161], v[174:177], v[112:115]
	s_waitcnt lgkmcnt(3)
	v_mfma_f32_16x16x32_bf16 v[100:103], v[150:153], v[182:185], v[100:103]
	v_mfma_f32_16x16x32_bf16 v[96:99], v[158:161], v[182:185], v[96:99]
	s_waitcnt lgkmcnt(1)
	v_mfma_f32_16x16x32_bf16 v[84:87], v[150:153], v[190:193], v[84:87]
	v_mfma_f32_16x16x32_bf16 v[80:83], v[158:161], v[190:193], v[80:83]
	v_mfma_f32_16x16x32_bf16 v[124:127], v[154:157], v[170:173], v[124:127]
	v_mfma_f32_16x16x32_bf16 v[120:123], v[162:165], v[170:173], v[120:123]
	v_mfma_f32_16x16x32_bf16 v[116:119], v[154:157], v[178:181], v[116:119]
	v_mfma_f32_16x16x32_bf16 v[112:115], v[162:165], v[178:181], v[112:115]
	v_mfma_f32_16x16x32_bf16 v[100:103], v[154:157], v[186:189], v[100:103]
	v_mfma_f32_16x16x32_bf16 v[96:99], v[162:165], v[186:189], v[96:99]
	s_waitcnt lgkmcnt(0)
	v_mfma_f32_16x16x32_bf16 v[84:87], v[154:157], v[198:201], v[84:87]
	v_mfma_f32_16x16x32_bf16 v[80:83], v[162:165], v[198:201], v[80:83]
	s_setprio 0
	s_barrier
	s_add_i32 s24, 0, 0x1c000
	s_add_i32 s3, s3, s29
	v_add_u32_e32 v196, s24, v146
	v_lshl_add_u64 v[194:195], v[194:195], 0, s[8:9]
	s_mov_b32 m0, s3
	ds_read_b128 v[202:205], v196
	ds_read_b128 v[206:209], v196 offset:1024
	ds_read_b128 v[210:213], v196 offset:2048
	ds_read_b128 v[214:217], v196 offset:3072
	global_load_lds_dwordx4 v[194:195], off
	v_lshl_add_u64 v[194:195], v[218:219], 0, s[8:9]
	s_add_i32 m0, s3, 0x2000
	s_nop 0
	global_load_lds_dwordx4 v[194:195], off
	s_barrier
	s_setprio 1
	s_waitcnt lgkmcnt(3)
	v_mfma_f32_16x16x32_bf16 v[108:111], v[202:205], v[166:169], v[108:111]
	s_waitcnt lgkmcnt(1)
	v_mfma_f32_16x16x32_bf16 v[104:107], v[210:213], v[166:169], v[104:107]
	v_mfma_f32_16x16x32_bf16 v[92:95], v[202:205], v[174:177], v[92:95]
	v_mfma_f32_16x16x32_bf16 v[88:91], v[210:213], v[174:177], v[88:91]
	v_mfma_f32_16x16x32_bf16 v[76:79], v[202:205], v[182:185], v[76:79]
	v_mfma_f32_16x16x32_bf16 v[72:75], v[210:213], v[182:185], v[72:75]
	v_mfma_f32_16x16x32_bf16 v[68:71], v[202:205], v[190:193], v[68:71]
	v_mfma_f32_16x16x32_bf16 v[64:67], v[210:213], v[190:193], v[64:67]
	v_mfma_f32_16x16x32_bf16 v[108:111], v[206:209], v[170:173], v[108:111]
	s_mov_b32 m0, s39
	s_waitcnt lgkmcnt(0)
	v_mfma_f32_16x16x32_bf16 v[104:107], v[214:217], v[170:173], v[104:107]
	v_lshl_add_u64 v[194:195], v[220:221], 0, s[8:9]
	v_mfma_f32_16x16x32_bf16 v[92:95], v[206:209], v[178:181], v[92:95]
	v_mfma_f32_16x16x32_bf16 v[88:91], v[214:217], v[178:181], v[88:91]
	v_mfma_f32_16x16x32_bf16 v[76:79], v[206:209], v[186:189], v[76:79]
	v_mfma_f32_16x16x32_bf16 v[72:75], v[214:217], v[186:189], v[72:75]
	v_mfma_f32_16x16x32_bf16 v[68:71], v[206:209], v[198:201], v[68:71]
	v_mfma_f32_16x16x32_bf16 v[64:67], v[214:217], v[198:201], v[64:67]
	s_setprio 0
	s_barrier
	ds_read_b128 v[166:169], v148 offset:49152
	ds_read_b128 v[170:173], v148 offset:50176
	ds_read_b128 v[174:177], v148 offset:51200
	ds_read_b128 v[178:181], v148 offset:52224
	ds_read_b128 v[182:185], v148 offset:53248
	ds_read_b128 v[186:189], v148 offset:54272
	ds_read_b128 v[190:193], v148 offset:55296
	ds_read_b128 v[198:201], v148 offset:56320
	global_load_lds_dwordx4 v[194:195], off
	v_lshl_add_u64 v[194:195], v[222:223], 0, s[8:9]
	s_mov_b32 m0, s42
	s_nop 0
	global_load_lds_dwordx4 v[194:195], off
	s_waitcnt vmcnt(10)
	s_barrier
; #define PG8_STAGE(bufoff, gbase, voff) do { _Pragma("unroll") for (int _i = 0; _i < 2; ++_i) \
;         __builtin_amdgcn_global_load_lds((const unsigned*)((const char*)(gbase) + (voff)[_i]), (LAS unsigned*)(lds + (bufoff) + ldsw + _i * 8192), 16, 0, 0); } while (0)
; #define PG8_LDA(dst, b, h) do { _Pragma("unroll") for (int m = 0; m < 4; ++m) _Pragma("unroll") for (int k = 0; k < 2; ++k) dst[m][k] = *(const LAS bf16x8*)(lds + PG8_SA(b, h) + aoff + m * 2048 + k * 1024); } while (0)
; #define PG8_MMA(ai, bj, At, Bt) do { __builtin_amdgcn_s_setprio(1); _Pragma("unroll") for (int m = 0; m < 4; ++m) _Pragma("unroll") for (int n = 0; n < 2; ++n) _Pragma("unroll") for (int k = 0; k < 2; ++k) \
;         acc[ai][bj][m][n] = __builtin_amdgcn_mfma_f32_16x16x32_bf16(Bt[n][k], At[m][k], acc[ai][bj][m][n], 0, 0, 0); __builtin_amdgcn_s_setprio(0); } while (0)
; #define PG8_WAIT_V(n) asm volatile("s_waitcnt vmcnt(" #n ")" ::: "memory")
; #define PG8_WAIT_L(n) asm volatile("s_waitcnt lgkmcnt(" #n ")" ::: "memory")
; #define PG8_BAR __builtin_amdgcn_s_barrier()
; #define PG8_SCHED __builtin_amdgcn_sched_barrier(0)
; template <class Map, class Epi>
; DI void gemm_phase(LAS unsigned char* lds, const Map& MP, const Epi& E, const int nM, const int nN, const int K, const int lda, const int ldb) {
;     ...
;             PG8_BAR; PG8_WAIT_L(0); PG8_MMA(0, 1, At, B1); PG8_BAR;
;             PG8_LDA(At, 1, 1); PG8_STAGE(PG8_SA(1, 0), a3, voffA);
;             PG8_BAR; PG8_WAIT_L(0); PG8_MMA(1, 0, At, B0); PG8_BAR; PG8_SCHED;
;             PG8_STAGE(PG8_SB(1, 1), b3 + hstepB, voffB);
;             PG8_WAIT_V(6); PG8_BAR; PG8_MMA(1, 1, At, B1); PG8_BAR;
	s_setprio 1
	s_waitcnt lgkmcnt(7)
	v_mfma_f32_16x16x32_bf16 v[60:63], v[150:153], v[166:169], v[60:63]
	v_mfma_f32_16x16x32_bf16 v[56:59], v[158:161], v[166:169], v[56:59]
	s_waitcnt lgkmcnt(5)
	v_mfma_f32_16x16x32_bf16 v[52:55], v[150:153], v[174:177], v[52:55]
	v_mfma_f32_16x16x32_bf16 v[48:51], v[158:161], v[174:177], v[48:51]
	s_waitcnt lgkmcnt(3)
	v_mfma_f32_16x16x32_bf16 v[36:39], v[150:153], v[182:185], v[36:39]
	v_mfma_f32_16x16x32_bf16 v[32:35], v[158:161], v[182:185], v[32:35]
	s_waitcnt lgkmcnt(1)
	v_mfma_f32_16x16x32_bf16 v[20:23], v[150:153], v[190:193], v[20:23]
	v_mfma_f32_16x16x32_bf16 v[16:19], v[158:161], v[190:193], v[16:19]
	v_mfma_f32_16x16x32_bf16 v[60:63], v[154:157], v[170:173], v[60:63]
	v_mfma_f32_16x16x32_bf16 v[56:59], v[162:165], v[170:173], v[56:59]
	v_mfma_f32_16x16x32_bf16 v[52:55], v[154:157], v[178:181], v[52:55]
	v_mfma_f32_16x16x32_bf16 v[48:51], v[162:165], v[178:181], v[48:51]
	v_mfma_f32_16x16x32_bf16 v[36:39], v[154:157], v[186:189], v[36:39]
	v_mfma_f32_16x16x32_bf16 v[32:35], v[162:165], v[186:189], v[32:35]
	s_waitcnt lgkmcnt(0)
	v_mfma_f32_16x16x32_bf16 v[20:23], v[154:157], v[198:201], v[20:23]
	v_mfma_f32_16x16x32_bf16 v[16:19], v[162:165], v[198:201], v[16:19]
	s_setprio 0
	s_barrier
	s_add_u32 s22, s22, 0x80080
	s_addc_u32 s23, s23, 0
	s_add_i32 s3, s24, s29
	s_mov_b32 m0, s3
	s_nop 0
	global_load_lds_dwordx4 v132, s[22:23]
	s_add_i32 m0, s3, 0x2000
	s_nop 0
	global_load_lds_dwordx4 v128, s[22:23]
	s_waitcnt vmcnt(6)
	s_barrier
	s_setprio 1
	v_mfma_f32_16x16x32_bf16 v[44:47], v[202:205], v[166:169], v[44:47]
	v_mfma_f32_16x16x32_bf16 v[40:43], v[210:213], v[166:169], v[40:43]
	ds_read_b128 v[150:153], v147
	v_mfma_f32_16x16x32_bf16 v[28:31], v[202:205], v[174:177], v[28:31]
	v_mfma_f32_16x16x32_bf16 v[24:27], v[210:213], v[174:177], v[24:27]
	ds_read_b128 v[154:157], v147 offset:1024
	v_mfma_f32_16x16x32_bf16 v[12:15], v[202:205], v[182:185], v[12:15]
	v_mfma_f32_16x16x32_bf16 v[8:11], v[210:213], v[182:185], v[8:11]
	ds_read_b128 v[158:161], v147 offset:2048
	v_mfma_f32_16x16x32_bf16 v[4:7], v[202:205], v[190:193], v[4:7]
	v_mfma_f32_16x16x32_bf16 v[0:3], v[210:213], v[190:193], v[0:3]
	ds_read_b128 v[162:165], v147 offset:3072
	v_mfma_f32_16x16x32_bf16 v[44:47], v[206:209], v[170:173], v[44:47]
	s_add_i32 s54, s54, 2
	v_mfma_f32_16x16x32_bf16 v[40:43], v[214:217], v[170:173], v[40:43]
	s_add_u32 s52, s52, 0x100
	s_addc_u32 s53, s53, 0
	v_mfma_f32_16x16x32_bf16 v[28:31], v[206:209], v[178:181], v[28:31]
	s_add_u32 s20, s20, 0x100
	s_addc_u32 s21, s21, 0
	v_mfma_f32_16x16x32_bf16 v[24:27], v[214:217], v[178:181], v[24:27]
	s_cmp_gt_u32 s54, 29
	v_mfma_f32_16x16x32_bf16 v[12:15], v[206:209], v[186:189], v[12:15]
	v_mfma_f32_16x16x32_bf16 v[8:11], v[214:217], v[186:189], v[8:11]
	v_mfma_f32_16x16x32_bf16 v[4:7], v[206:209], v[198:201], v[4:7]
	v_mfma_f32_16x16x32_bf16 v[0:3], v[214:217], v[198:201], v[0:3]
	s_setprio 0
	s_barrier
	s_cbranch_scc0 .LBB1_693
; DI unsigned pack2(float a, float b) { f32x2 v = {a, b}; hwbf16x2 r = __builtin_convertvector(v, hwbf16x2); return __builtin_bit_cast(unsigned, r); }
;     DI const char* a(const Unit& u) const { return (const char*)(A + (size_t)u.pm * BM * lda); }
;     DI const char* a(const Unit& u) const { return (const char*)(A + (size_t)u.pm * BM * 2048 + (u.pn >> 1) * 512); }
;     DI const char* a(const Unit& u) const { return (const char*)((u.pn < 12 ? A1 : A2) + (size_t)u.pm * BM * 512); }
; #define PG8_WAIT_V(n) asm volatile("s_waitcnt vmcnt(" #n ")" ::: "memory")
; #define PG8_BAR __builtin_amdgcn_s_barrier()
;     DI void operator()(const f32x4 (&acc)[2][2][4][2], const Unit& u, int wr, int wc, int fr, int fq) const {
;         bf16_t* O = O1; int ldc = ldc1, pn = u.pn; if (pn >= split) { O = O2; ldc = ldc2; pn -= split; }
;         const int row0 = u.pm * BM + wr * 64 + fr, col0 = pn * BM + wc * 32 + 8 * fq;
; #pragma unroll
;         for (int ai = 0; ai < 2; ++ai)
; #pragma unroll
;             for (int m = 0; m < 4; ++m) { bf16_t* rowp = O + (size_t)(row0 + ai * HALF + m * 16) * ldc + col0;
; #pragma unroll
;                 for (int bj = 0; bj < 2; ++bj) { const f32x4 v0 = acc[ai][bj][m][0], v1 = acc[ai][bj][m][1];
;                     u32x4 o; o[0] = pack2(v0[0], v0[1]); o[1] = pack2(v0[2], v0[3]); o[2] = pack2(v1[0], v1[1]); o[3] = pack2(v1[2], v1[3]);
;                     *(u32x4*)(rowp + bj * HALF) = o; } }
; template <class Map, class Epi>
; DI void gemm_phase(LAS unsigned char* lds, const Map& MP, const Epi& E, const int nM, const int nN, const int K, const int lda, const int ldb) {
;     ...
;         if (!has_next) break;
; #pragma unroll
;         for (int a = 0; a < 2; ++a)
; #pragma unroll
;             for (int b = 0; b < 2; ++b)
; #pragma unroll
;                 for (int m = 0; m < 4; ++m)
; #pragma unroll
;                     for (int n = 0; n < 2; ++n) acc[a][b][m][n] = (f32x4){0.f, 0.f, 0.f, 0.f};
;         cur = nxt; cA = nA; cB = nB; ++ui;
;     }
;     PG8_WAIT_V(0);
;     if (wr == 0) PG8_BAR;
;     PG8_BAR;
	s_waitcnt lgkmcnt(0)
	s_lshl_b32 s3, s10, 8
	v_mov_b32_e32 v150, v144
	v_mov_b32_e32 v151, v145
	s_add_i32 s3, s3, s37
	v_cvt_pk_bf16_f32 v68, v68, v69
	v_add_u32_e32 v154, s3, v150
	s_lshl_b32 s3, s47, 8
	s_or_b32 s3, s3, s38
	v_lshl_add_u32 v150, v151, 3, s3
	v_ashrrev_i32_e32 v151, 31, v150
	v_lshl_add_u64 v[150:151], v[150:151], 1, s[6:7]
	v_cvt_pk_bf16_f32 v69, v70, v71
	v_cvt_pk_bf16_f32 v70, v64, v65
	v_add_u32_e32 v64, 0x80, v154
	v_mad_i64_i32 v[152:153], s[20:21], v154, s46, v[150:151]
	v_cvt_pk_bf16_f32 v108, v108, v109
	v_cvt_pk_bf16_f32 v109, v110, v111
	v_cvt_pk_bf16_f32 v110, v104, v105
	v_cvt_pk_bf16_f32 v111, v106, v107
	v_add_u32_e32 v104, 16, v154
	v_mad_i64_i32 v[64:65], s[20:21], v64, s46, v[150:151]
	v_cvt_pk_bf16_f32 v44, v44, v45
	v_cvt_pk_bf16_f32 v45, v46, v47
	v_cvt_pk_bf16_f32 v46, v40, v41
	v_cvt_pk_bf16_f32 v47, v42, v43
	v_add_u32_e32 v40, 0x90, v154
	global_store_dwordx4 v[152:153], v[108:111], off offset:256
	v_cvt_pk_bf16_f32 v92, v92, v93
	v_cvt_pk_bf16_f32 v93, v94, v95
	v_mad_i64_i32 v[108:109], s[20:21], v104, s46, v[150:151]
	v_cvt_pk_bf16_f32 v94, v88, v89
	v_cvt_pk_bf16_f32 v95, v90, v91
	v_add_u32_e32 v88, 32, v154
	global_store_dwordx4 v[64:65], v[44:47], off offset:256
	v_cvt_pk_bf16_f32 v28, v28, v29
	v_cvt_pk_bf16_f32 v29, v30, v31
	v_mad_i64_i32 v[44:45], s[20:21], v40, s46, v[150:151]
	v_cvt_pk_bf16_f32 v30, v24, v25
	v_cvt_pk_bf16_f32 v31, v26, v27
	v_add_u32_e32 v24, 0xa0, v154
	global_store_dwordx4 v[108:109], v[92:95], off offset:256
	v_cvt_pk_bf16_f32 v76, v76, v77
	v_cvt_pk_bf16_f32 v77, v78, v79
	v_mad_i64_i32 v[92:93], s[20:21], v88, s46, v[150:151]
	v_cvt_pk_bf16_f32 v78, v72, v73
	v_cvt_pk_bf16_f32 v79, v74, v75
	v_add_u32_e32 v72, 48, v154
	global_store_dwordx4 v[44:45], v[28:31], off offset:256
	v_cvt_pk_bf16_f32 v12, v12, v13
	v_cvt_pk_bf16_f32 v13, v14, v15
	v_mad_i64_i32 v[28:29], s[20:21], v24, s46, v[150:151]
	v_cvt_pk_bf16_f32 v14, v8, v9
	v_cvt_pk_bf16_f32 v15, v10, v11
	v_add_u32_e32 v8, 0xb0, v154
	global_store_dwordx4 v[92:93], v[76:79], off offset:256
	global_store_dwordx4 v[28:29], v[12:15], off offset:256
	v_cvt_pk_bf16_f32 v124, v124, v125
	v_mad_i64_i32 v[76:77], s[20:21], v72, s46, v[150:151]
	v_mad_i64_i32 v[12:13], s[20:21], v8, s46, v[150:151]
	v_cvt_pk_bf16_f32 v125, v126, v127
	v_cvt_pk_bf16_f32 v126, v120, v121
	v_cvt_pk_bf16_f32 v127, v122, v123
	v_cvt_pk_bf16_f32 v104, v116, v117
	v_cvt_pk_bf16_f32 v105, v118, v119
	v_cvt_pk_bf16_f32 v106, v112, v113
	v_cvt_pk_bf16_f32 v107, v114, v115
	v_cvt_pk_bf16_f32 v88, v100, v101
	v_cvt_pk_bf16_f32 v89, v102, v103
	v_cvt_pk_bf16_f32 v90, v96, v97
	v_cvt_pk_bf16_f32 v91, v98, v99
	v_cvt_pk_bf16_f32 v72, v84, v85
	v_cvt_pk_bf16_f32 v73, v86, v87
	v_cvt_pk_bf16_f32 v74, v80, v81
	v_cvt_pk_bf16_f32 v75, v82, v83
	v_cvt_pk_bf16_f32 v71, v66, v67
	v_cvt_pk_bf16_f32 v60, v60, v61
	v_cvt_pk_bf16_f32 v61, v62, v63
	v_cvt_pk_bf16_f32 v62, v56, v57
	v_cvt_pk_bf16_f32 v63, v58, v59
	v_cvt_pk_bf16_f32 v40, v52, v53
	v_cvt_pk_bf16_f32 v41, v54, v55
	v_cvt_pk_bf16_f32 v42, v48, v49
	v_cvt_pk_bf16_f32 v43, v50, v51
	v_cvt_pk_bf16_f32 v24, v36, v37
	v_cvt_pk_bf16_f32 v25, v38, v39
	v_cvt_pk_bf16_f32 v26, v32, v33
	v_cvt_pk_bf16_f32 v27, v34, v35
	v_cvt_pk_bf16_f32 v8, v20, v21
	v_cvt_pk_bf16_f32 v9, v22, v23
	v_cvt_pk_bf16_f32 v10, v16, v17
	v_cvt_pk_bf16_f32 v11, v18, v19
	v_cvt_pk_bf16_f32 v4, v4, v5
	v_cvt_pk_bf16_f32 v5, v6, v7
	v_cvt_pk_bf16_f32 v6, v0, v1
	v_cvt_pk_bf16_f32 v7, v2, v3
	s_and_b64 vcc, exec, s[40:41]
	s_mov_b32 s47, s12
	s_mov_b32 s10, s14
	s_mov_b64 s[20:21], s[18:19]
	s_mov_b64 s[22:23], s[16:17]
	global_store_dwordx4 v[152:153], v[124:127], off
	global_store_dwordx4 v[108:109], v[104:107], off
	global_store_dwordx4 v[92:93], v[88:91], off
	global_store_dwordx4 v[76:77], v[72:75], off
	global_store_dwordx4 v[76:77], v[68:71], off offset:256
	global_store_dwordx4 v[64:65], v[60:63], off
	global_store_dwordx4 v[44:45], v[40:43], off
	global_store_dwordx4 v[28:29], v[24:27], off
	global_store_dwordx4 v[12:13], v[8:11], off
	global_store_dwordx4 v[12:13], v[4:7], off offset:256
	s_cbranch_vccz .LBB1_690
	s_waitcnt vmcnt(0)
	s_cmpk_gt_u32 s4, 0xff
	s_cbranch_scc1 .LBB1_697
	s_barrier

; #define PG8_STAGE(bufoff, gbase, voff) do { _Pragma("unroll") for (int _i = 0; _i < 2; ++_i) \
;         __builtin_amdgcn_global_load_lds((const unsigned*)((const char*)(gbase) + (voff)[_i]), (LAS unsigned*)(lds + (bufoff) + ldsw + _i * 8192), 16, 0, 0); } while (0)
; #define PG8_LDA(dst, b, h) do { _Pragma("unroll") for (int m = 0; m < 4; ++m) _Pragma("unroll") for (int k = 0; k < 2; ++k) dst[m][k] = *(const LAS bf16x8*)(lds + PG8_SA(b, h) + aoff + m * 2048 + k * 1024); } while (0)
; #define PG8_LDB(dst, b, h) do { _Pragma("unroll") for (int n = 0; n < 2; ++n) _Pragma("unroll") for (int k = 0; k < 2; ++k) dst[n][k] = *(const LAS bf16x8*)(lds + PG8_SB(b, h) + boff + n * 2048 + k * 1024); } while (0)
; #define PG8_MMA(ai, bj, At, Bt) do { __builtin_amdgcn_s_setprio(1); _Pragma("unroll") for (int m = 0; m < 4; ++m) _Pragma("unroll") for (int n = 0; n < 2; ++n) _Pragma("unroll") for (int k = 0; k < 2; ++k) \
;         acc[ai][bj][m][n] = __builtin_amdgcn_mfma_f32_16x16x32_bf16(Bt[n][k], At[m][k], acc[ai][bj][m][n], 0, 0, 0); __builtin_amdgcn_s_setprio(0); } while (0)
; #define PG8_WAIT_V(n) asm volatile("s_waitcnt vmcnt(" #n ")" ::: "memory")
; #define PG8_WAIT_L(n) asm volatile("s_waitcnt lgkmcnt(" #n ")" ::: "memory")
; template <class Map, class Epi>
; DI void gemm_phase(LAS unsigned char* lds, const Map& MP, const Epi& E, const int nM, const int nN, const int K, const int lda, const int ldb) {
;     ...
;             const bool last = (t == nt - 2);
;             const char* a1 = cA + (size_t)(t + 1) * kstep;
;             const char* a2 = last ? nA : cA + (size_t)(t + 2) * kstep; const char* b2 = last ? nB : cB + (size_t)(t + 2) * kstep;
;             const char* a3 = a2 + kstep; const char* b3 = b2 + kstep;
;             PG8_LDB(B0, 0, 0); PG8_SCHED; PG8_LDA(At, 0, 0); PG8_STAGE(PG8_SA(1, 1), a1 + hstepA, voffA);
;             PG8_WAIT_L(8); PG8_BAR; PG8_WAIT_L(0); PG8_MMA(0, 0, At, B0); PG8_BAR; PG8_SCHED;
;             PG8_LDB(B1, 0, 1); PG8_STAGE(PG8_SB(0, 0), b2, voffB);
;             PG8_BAR; PG8_WAIT_L(0); PG8_MMA(0, 1, At, B1); PG8_BAR;
;             PG8_LDA(At, 0, 1); PG8_STAGE(PG8_SA(0, 0), a2, voffA);
;             PG8_BAR; PG8_WAIT_L(0); PG8_MMA(1, 0, At, B0); PG8_BAR; PG8_SCHED;
;             PG8_STAGE(PG8_SB(0, 1), b2 + hstepB, voffB);
;             PG8_WAIT_V(6); PG8_BAR; PG8_MMA(1, 1, At, B1); PG8_BAR;
.LBB1_925:
	s_add_u32 s3, s10, 0xfff80080
	s_addc_u32 s12, s11, -1
	s_cmp_eq_u32 s48, 28
	s_cselect_b32 s15, s4, s12
	s_cselect_b32 s14, s5, s3
	s_cselect_b32 s13, s37, s47
	s_cselect_b32 s12, s38, s39
	s_add_i32 m0, s24, 0xc000
	ds_read_b128 v[168:171], v150
	ds_read_b128 v[172:175], v150 offset:1024
	ds_read_b128 v[176:179], v150 offset:2048
	ds_read_b128 v[180:183], v150 offset:3072
	ds_read_b128 v[184:187], v150 offset:4096
	ds_read_b128 v[188:191], v150 offset:5120
	ds_read_b128 v[192:195], v150 offset:6144
	ds_read_b128 v[198:201], v150 offset:7168
	global_load_lds_dwordx4 v138, s[10:11]
	s_add_i32 m0, s24, 0xe000
	s_nop 0
	global_load_lds_dwordx4 v136, s[10:11]
	s_waitcnt lgkmcnt(8)
	s_barrier
	s_setprio 1
	s_waitcnt lgkmcnt(7)
	v_mfma_f32_16x16x32_bf16 v[124:127], v[152:155], v[168:171], v[124:127]
	v_mfma_f32_16x16x32_bf16 v[120:123], v[160:163], v[168:171], v[120:123]
	s_waitcnt lgkmcnt(5)
	v_mfma_f32_16x16x32_bf16 v[108:111], v[152:155], v[176:179], v[108:111]
	v_mfma_f32_16x16x32_bf16 v[104:107], v[160:163], v[176:179], v[104:107]
	s_waitcnt lgkmcnt(3)
	v_mfma_f32_16x16x32_bf16 v[92:95], v[152:155], v[184:187], v[92:95]
	v_mfma_f32_16x16x32_bf16 v[88:91], v[160:163], v[184:187], v[88:91]
	s_waitcnt lgkmcnt(1)
	v_mfma_f32_16x16x32_bf16 v[76:79], v[152:155], v[192:195], v[76:79]
	v_mfma_f32_16x16x32_bf16 v[72:75], v[160:163], v[192:195], v[72:75]
	v_mfma_f32_16x16x32_bf16 v[124:127], v[156:159], v[172:175], v[124:127]
	v_mfma_f32_16x16x32_bf16 v[120:123], v[164:167], v[172:175], v[120:123]
	v_mfma_f32_16x16x32_bf16 v[108:111], v[156:159], v[180:183], v[108:111]
	v_mfma_f32_16x16x32_bf16 v[104:107], v[164:167], v[180:183], v[104:107]
	v_mfma_f32_16x16x32_bf16 v[92:95], v[156:159], v[188:191], v[92:95]
	v_mfma_f32_16x16x32_bf16 v[88:91], v[164:167], v[188:191], v[88:91]
	s_waitcnt lgkmcnt(0)
	v_mfma_f32_16x16x32_bf16 v[76:79], v[156:159], v[198:201], v[76:79]
	v_mfma_f32_16x16x32_bf16 v[72:75], v[164:167], v[198:201], v[72:75]
	s_setprio 0
	s_barrier
	s_add_i32 s3, s35, s22
	v_lshl_add_u64 v[144:145], s[12:13], 0, v[132:133]
	s_mov_b32 m0, s3
	ds_read_b128 v[202:205], v151
	ds_read_b128 v[206:209], v151 offset:1024
	ds_read_b128 v[210:213], v151 offset:2048
	ds_read_b128 v[214:217], v151 offset:3072
	global_load_lds_dwordx4 v[144:145], off
	v_lshl_add_u64 v[218:219], s[12:13], 0, v[128:129]
	s_add_i32 m0, s3, 0x2000
	s_nop 0
	global_load_lds_dwordx4 v[218:219], off
	s_barrier
	s_setprio 1
	s_waitcnt lgkmcnt(3)
	v_mfma_f32_16x16x32_bf16 v[116:119], v[202:205], v[168:171], v[116:119]
	s_waitcnt lgkmcnt(1)
	v_mfma_f32_16x16x32_bf16 v[112:115], v[210:213], v[168:171], v[112:115]
	v_mfma_f32_16x16x32_bf16 v[100:103], v[202:205], v[176:179], v[100:103]
	v_mfma_f32_16x16x32_bf16 v[96:99], v[210:213], v[176:179], v[96:99]
	v_mfma_f32_16x16x32_bf16 v[84:87], v[202:205], v[184:187], v[84:87]
	v_mfma_f32_16x16x32_bf16 v[80:83], v[210:213], v[184:187], v[80:83]
	v_mfma_f32_16x16x32_bf16 v[68:71], v[202:205], v[192:195], v[68:71]
	v_mfma_f32_16x16x32_bf16 v[64:67], v[210:213], v[192:195], v[64:67]
	v_mfma_f32_16x16x32_bf16 v[116:119], v[206:209], v[172:175], v[116:119]
	s_mov_b32 m0, s24
	s_waitcnt lgkmcnt(0)
	v_mfma_f32_16x16x32_bf16 v[112:115], v[214:217], v[172:175], v[112:115]
	v_lshl_add_u64 v[220:221], s[14:15], 0, v[134:135]
	v_mfma_f32_16x16x32_bf16 v[100:103], v[206:209], v[180:183], v[100:103]
	v_mfma_f32_16x16x32_bf16 v[96:99], v[214:217], v[180:183], v[96:99]
	v_mfma_f32_16x16x32_bf16 v[84:87], v[206:209], v[188:191], v[84:87]
	v_mfma_f32_16x16x32_bf16 v[80:83], v[214:217], v[188:191], v[80:83]
	v_mfma_f32_16x16x32_bf16 v[68:71], v[206:209], v[198:201], v[68:71]
	v_mfma_f32_16x16x32_bf16 v[64:67], v[214:217], v[198:201], v[64:67]
	s_setprio 0
	s_barrier
	ds_read_b128 v[168:171], v150 offset:16384
	ds_read_b128 v[172:175], v150 offset:17408
	ds_read_b128 v[176:179], v150 offset:18432
	ds_read_b128 v[180:183], v150 offset:19456
	ds_read_b128 v[184:187], v150 offset:20480
	ds_read_b128 v[188:191], v150 offset:21504
	ds_read_b128 v[192:195], v150 offset:22528
	ds_read_b128 v[198:201], v150 offset:23552
	global_load_lds_dwordx4 v[220:221], off
	v_lshl_add_u64 v[222:223], s[14:15], 0, v[130:131]
	s_mov_b32 m0, s9
	s_nop 0
	global_load_lds_dwordx4 v[222:223], off
	s_waitcnt vmcnt(10)
	s_barrier
	s_setprio 1
	s_waitcnt lgkmcnt(7)
	v_mfma_f32_16x16x32_bf16 v[60:63], v[152:155], v[168:171], v[60:63]
	v_mfma_f32_16x16x32_bf16 v[56:59], v[160:163], v[168:171], v[56:59]
	s_waitcnt lgkmcnt(5)
	v_mfma_f32_16x16x32_bf16 v[44:47], v[152:155], v[176:179], v[44:47]
	v_mfma_f32_16x16x32_bf16 v[40:43], v[160:163], v[176:179], v[40:43]
	s_waitcnt lgkmcnt(3)
	v_mfma_f32_16x16x32_bf16 v[28:31], v[152:155], v[184:187], v[28:31]
	v_mfma_f32_16x16x32_bf16 v[24:27], v[160:163], v[184:187], v[24:27]
	s_waitcnt lgkmcnt(1)
	v_mfma_f32_16x16x32_bf16 v[12:15], v[152:155], v[192:195], v[12:15]
	v_mfma_f32_16x16x32_bf16 v[8:11], v[160:163], v[192:195], v[8:11]
	v_mfma_f32_16x16x32_bf16 v[60:63], v[156:159], v[172:175], v[60:63]
	v_mfma_f32_16x16x32_bf16 v[56:59], v[164:167], v[172:175], v[56:59]
	v_mfma_f32_16x16x32_bf16 v[44:47], v[156:159], v[180:183], v[44:47]
	v_mfma_f32_16x16x32_bf16 v[40:43], v[164:167], v[180:183], v[40:43]
	v_mfma_f32_16x16x32_bf16 v[28:31], v[156:159], v[188:191], v[28:31]
	v_mfma_f32_16x16x32_bf16 v[24:27], v[164:167], v[188:191], v[24:27]
	s_waitcnt lgkmcnt(0)
	v_mfma_f32_16x16x32_bf16 v[12:15], v[156:159], v[198:201], v[12:15]
	v_mfma_f32_16x16x32_bf16 v[8:11], v[164:167], v[198:201], v[8:11]
	s_setprio 0
	s_barrier
; #define PG8_STAGE(bufoff, gbase, voff) do { _Pragma("unroll") for (int _i = 0; _i < 2; ++_i) \
;         __builtin_amdgcn_global_load_lds((const unsigned*)((const char*)(gbase) + (voff)[_i]), (LAS unsigned*)(lds + (bufoff) + ldsw + _i * 8192), 16, 0, 0); } while (0)
; #define PG8_LDA(dst, b, h) do { _Pragma("unroll") for (int m = 0; m < 4; ++m) _Pragma("unroll") for (int k = 0; k < 2; ++k) dst[m][k] = *(const LAS bf16x8*)(lds + PG8_SA(b, h) + aoff + m * 2048 + k * 1024); } while (0)
; #define PG8_LDB(dst, b, h) do { _Pragma("unroll") for (int n = 0; n < 2; ++n) _Pragma("unroll") for (int k = 0; k < 2; ++k) dst[n][k] = *(const LAS bf16x8*)(lds + PG8_SB(b, h) + boff + n * 2048 + k * 1024); } while (0)
; #define PG8_MMA(ai, bj, At, Bt) do { __builtin_amdgcn_s_setprio(1); _Pragma("unroll") for (int m = 0; m < 4; ++m) _Pragma("unroll") for (int n = 0; n < 2; ++n) _Pragma("unroll") for (int k = 0; k < 2; ++k) \
;         acc[ai][bj][m][n] = __builtin_amdgcn_mfma_f32_16x16x32_bf16(Bt[n][k], At[m][k], acc[ai][bj][m][n], 0, 0, 0); __builtin_amdgcn_s_setprio(0); } while (0)
; #define PG8_WAIT_V(n) asm volatile("s_waitcnt vmcnt(" #n ")" ::: "memory")
; #define PG8_WAIT_L(n) asm volatile("s_waitcnt lgkmcnt(" #n ")" ::: "memory")
; #define PG8_BAR __builtin_amdgcn_s_barrier()
; #define PG8_SCHED __builtin_amdgcn_sched_barrier(0)
; template <class Map, class Epi>
; DI void gemm_phase(LAS unsigned char* lds, const Map& MP, const Epi& E, const int nM, const int nN, const int K, const int lda, const int ldb) {
;     ...
;             PG8_STAGE(PG8_SB(0, 1), b2 + hstepB, voffB);
;             PG8_WAIT_V(6); PG8_BAR; PG8_MMA(1, 1, At, B1); PG8_BAR;
;             PG8_LDB(B0, 1, 0); PG8_SCHED; PG8_LDA(At, 1, 0); PG8_STAGE(PG8_SA(0, 1), a2 + hstepA, voffA);
;             PG8_WAIT_L(8); PG8_BAR; PG8_WAIT_L(0); PG8_MMA(0, 0, At, B0); PG8_BAR; PG8_SCHED;
;             PG8_LDB(B1, 1, 1); PG8_STAGE(PG8_SB(1, 0), b3, voffB);
;             PG8_BAR; PG8_WAIT_L(0); PG8_MMA(0, 1, At, B1); PG8_BAR;
;             PG8_LDA(At, 1, 1); PG8_STAGE(PG8_SA(1, 0), a3, voffA);
;             PG8_BAR; PG8_WAIT_L(0); PG8_MMA(1, 0, At, B0); PG8_BAR; PG8_SCHED;
	s_add_u32 s56, s12, 0x80000
	s_addc_u32 s57, s13, 0
	s_add_i32 s3, s36, s22
	s_mov_b32 m0, s3
	s_nop 0
	global_load_lds_dwordx4 v132, s[56:57]
	s_add_i32 m0, s3, 0x2000
	s_nop 0
	global_load_lds_dwordx4 v128, s[56:57]
	s_waitcnt vmcnt(6)
	s_barrier
	s_setprio 1
	v_mfma_f32_16x16x32_bf16 v[52:55], v[202:205], v[168:171], v[52:55]
	v_mfma_f32_16x16x32_bf16 v[48:51], v[210:213], v[168:171], v[48:51]
	s_add_i32 s3, 0, 0x18000
	v_add_u32_e32 v164, s3, v148
	ds_read_b128 v[152:155], v164
	v_mfma_f32_16x16x32_bf16 v[36:39], v[202:205], v[176:179], v[36:39]
	v_mfma_f32_16x16x32_bf16 v[32:35], v[210:213], v[176:179], v[32:35]
	ds_read_b128 v[156:159], v164 offset:1024
	v_mfma_f32_16x16x32_bf16 v[20:23], v[202:205], v[184:187], v[20:23]
	v_mfma_f32_16x16x32_bf16 v[16:19], v[210:213], v[184:187], v[16:19]
	ds_read_b128 v[160:163], v164 offset:2048
	v_mfma_f32_16x16x32_bf16 v[4:7], v[202:205], v[192:195], v[4:7]
	v_mfma_f32_16x16x32_bf16 v[0:3], v[210:213], v[192:195], v[0:3]
	ds_read_b128 v[164:167], v164 offset:3072
	v_mfma_f32_16x16x32_bf16 v[52:55], v[206:209], v[172:175], v[52:55]
	v_mfma_f32_16x16x32_bf16 v[48:51], v[214:217], v[172:175], v[48:51]
	v_mfma_f32_16x16x32_bf16 v[36:39], v[206:209], v[180:183], v[36:39]
	v_mfma_f32_16x16x32_bf16 v[32:35], v[214:217], v[180:183], v[32:35]
	v_mfma_f32_16x16x32_bf16 v[20:23], v[206:209], v[188:191], v[20:23]
	v_mfma_f32_16x16x32_bf16 v[16:19], v[214:217], v[188:191], v[16:19]
	v_mfma_f32_16x16x32_bf16 v[4:7], v[206:209], v[198:201], v[4:7]
	v_mfma_f32_16x16x32_bf16 v[0:3], v[214:217], v[198:201], v[0:3]
	s_setprio 0
	s_barrier
	s_add_u32 s14, s14, 0x80000
	s_addc_u32 s15, s15, 0
	s_mov_b32 m0, s25
	ds_read_b128 v[168:171], v150 offset:32768
	ds_read_b128 v[172:175], v150 offset:33792
	ds_read_b128 v[176:179], v150 offset:34816
	ds_read_b128 v[180:183], v150 offset:35840
	ds_read_b128 v[184:187], v150 offset:36864
	ds_read_b128 v[188:191], v150 offset:37888
	ds_read_b128 v[192:195], v150 offset:38912
	ds_read_b128 v[198:201], v150 offset:39936
	global_load_lds_dwordx4 v134, s[14:15]
	s_mov_b32 m0, s26
	s_nop 0
	global_load_lds_dwordx4 v130, s[14:15]
	s_waitcnt lgkmcnt(8)
	s_barrier
	s_setprio 1
	s_waitcnt lgkmcnt(7)
	v_mfma_f32_16x16x32_bf16 v[124:127], v[152:155], v[168:171], v[124:127]
	v_mfma_f32_16x16x32_bf16 v[120:123], v[160:163], v[168:171], v[120:123]
	s_waitcnt lgkmcnt(5)
	v_mfma_f32_16x16x32_bf16 v[108:111], v[152:155], v[176:179], v[108:111]
	v_mfma_f32_16x16x32_bf16 v[104:107], v[160:163], v[176:179], v[104:107]
	s_waitcnt lgkmcnt(3)
	v_mfma_f32_16x16x32_bf16 v[92:95], v[152:155], v[184:187], v[92:95]
	v_mfma_f32_16x16x32_bf16 v[88:91], v[160:163], v[184:187], v[88:91]
	s_waitcnt lgkmcnt(1)
	v_mfma_f32_16x16x32_bf16 v[76:79], v[152:155], v[192:195], v[76:79]
	v_mfma_f32_16x16x32_bf16 v[72:75], v[160:163], v[192:195], v[72:75]
	v_mfma_f32_16x16x32_bf16 v[124:127], v[156:159], v[172:175], v[124:127]
	v_mfma_f32_16x16x32_bf16 v[120:123], v[164:167], v[172:175], v[120:123]
	v_mfma_f32_16x16x32_bf16 v[108:111], v[156:159], v[180:183], v[108:111]
	v_mfma_f32_16x16x32_bf16 v[104:107], v[164:167], v[180:183], v[104:107]
	v_mfma_f32_16x16x32_bf16 v[92:95], v[156:159], v[188:191], v[92:95]
	v_mfma_f32_16x16x32_bf16 v[88:91], v[164:167], v[188:191], v[88:91]
	s_waitcnt lgkmcnt(0)
	v_mfma_f32_16x16x32_bf16 v[76:79], v[156:159], v[198:201], v[76:79]
	v_mfma_f32_16x16x32_bf16 v[72:75], v[164:167], v[198:201], v[72:75]
	s_setprio 0
	s_barrier
	s_add_i32 s14, 0, 0x1c000
	s_add_i32 s3, s3, s22
	v_add_u32_e32 v196, s14, v148
	v_lshl_add_u64 v[144:145], v[144:145], 0, s[44:45]
	s_mov_b32 m0, s3
	ds_read_b128 v[202:205], v196
	ds_read_b128 v[206:209], v196 offset:1024
	ds_read_b128 v[210:213], v196 offset:2048
	ds_read_b128 v[214:217], v196 offset:3072
	global_load_lds_dwordx4 v[144:145], off
	v_lshl_add_u64 v[144:145], v[218:219], 0, s[44:45]
	s_add_i32 m0, s3, 0x2000
	s_nop 0
	global_load_lds_dwordx4 v[144:145], off
	s_barrier
	s_setprio 1
	s_waitcnt lgkmcnt(3)
	v_mfma_f32_16x16x32_bf16 v[116:119], v[202:205], v[168:171], v[116:119]
	s_waitcnt lgkmcnt(1)
	v_mfma_f32_16x16x32_bf16 v[112:115], v[210:213], v[168:171], v[112:115]
	v_mfma_f32_16x16x32_bf16 v[100:103], v[202:205], v[176:179], v[100:103]
	v_mfma_f32_16x16x32_bf16 v[96:99], v[210:213], v[176:179], v[96:99]
	v_mfma_f32_16x16x32_bf16 v[84:87], v[202:205], v[184:187], v[84:87]
	v_mfma_f32_16x16x32_bf16 v[80:83], v[210:213], v[184:187], v[80:83]
	v_mfma_f32_16x16x32_bf16 v[68:71], v[202:205], v[192:195], v[68:71]
	v_mfma_f32_16x16x32_bf16 v[64:67], v[210:213], v[192:195], v[64:67]
	v_mfma_f32_16x16x32_bf16 v[116:119], v[206:209], v[172:175], v[116:119]
	s_mov_b32 m0, s30
	s_waitcnt lgkmcnt(0)
	v_mfma_f32_16x16x32_bf16 v[112:115], v[214:217], v[172:175], v[112:115]
	v_lshl_add_u64 v[144:145], v[220:221], 0, s[44:45]
	v_mfma_f32_16x16x32_bf16 v[100:103], v[206:209], v[180:183], v[100:103]
	v_mfma_f32_16x16x32_bf16 v[96:99], v[214:217], v[180:183], v[96:99]
	v_mfma_f32_16x16x32_bf16 v[84:87], v[206:209], v[188:191], v[84:87]
	v_mfma_f32_16x16x32_bf16 v[80:83], v[214:217], v[188:191], v[80:83]
	v_mfma_f32_16x16x32_bf16 v[68:71], v[206:209], v[198:201], v[68:71]
	v_mfma_f32_16x16x32_bf16 v[64:67], v[214:217], v[198:201], v[64:67]
	s_setprio 0
	s_barrier
	ds_read_b128 v[168:171], v150 offset:49152
	ds_read_b128 v[172:175], v150 offset:50176
	ds_read_b128 v[176:179], v150 offset:51200
	ds_read_b128 v[180:183], v150 offset:52224
	ds_read_b128 v[184:187], v150 offset:53248
	ds_read_b128 v[188:191], v150 offset:54272
	ds_read_b128 v[192:195], v150 offset:55296
	ds_read_b128 v[198:201], v150 offset:56320
	global_load_lds_dwordx4 v[144:145], off
	v_lshl_add_u64 v[144:145], v[222:223], 0, s[44:45]
	s_mov_b32 m0, s31
	s_nop 0
	global_load_lds_dwordx4 v[144:145], off
	s_waitcnt vmcnt(10)
	s_barrier
; DI unsigned pack2(float a, float b) { f32x2 v = {a, b}; hwbf16x2 r = __builtin_convertvector(v, hwbf16x2); return __builtin_bit_cast(unsigned, r); }
; DI float bflo(unsigned w) { return __uint_as_float(w << 16); }
; DI float bfhi(unsigned w) { return __uint_as_float(w & 0xffff0000u); }
; #define PG8_STAGE(bufoff, gbase, voff) do { _Pragma("unroll") for (int _i = 0; _i < 2; ++_i) \
;         __builtin_amdgcn_global_load_lds((const unsigned*)((const char*)(gbase) + (voff)[_i]), (LAS unsigned*)(lds + (bufoff) + ldsw + _i * 8192), 16, 0, 0); } while (0)
; #define PG8_WAIT_V(n) asm volatile("s_waitcnt vmcnt(" #n ")" ::: "memory")
;     DI void operator()(const f32x4 (&acc)[2][2][4][2], const Unit& u, int wr, int wc, int fr, int fq) const {
;     ...
;             for (int m = 0; m < 4; ++m) { const size_t ro = (size_t)(row0 + ai * HALF + m * 16) * D + col0;
; #pragma unroll
;                 for (int bj = 0; bj < 2; ++bj) {
;                     f32x4 x0, x1;
;                     if constexpr (IB) { const u32x4 w = *(const u32x4*)((const bf16_t*)Xin + ro + bj * HALF);
;                         x0 = (f32x4){bflo(w[0]), bfhi(w[0]), bflo(w[1]), bfhi(w[1])}; x1 = (f32x4){bflo(w[2]), bfhi(w[2]), bflo(w[3]), bfhi(w[3])}; }
;                     else { x0 = *(const f32x4*)((const float*)Xin + ro + bj * HALF); x1 = *(const f32x4*)((const float*)Xin + ro + bj * HALF + 4); }
;                     x0 += acc[ai][bj][m][0] * sc[bj][0]; x1 += acc[ai][bj][m][1] * sc[bj][1];
;                     if constexpr (OB) { u32x4 o; o[0] = pack2(x0[0], x0[1]); o[1] = pack2(x0[2], x0[3]); o[2] = pack2(x1[0], x1[1]); o[3] = pack2(x1[2], x1[3]);
;                         *(u32x4*)((bf16_t*)Xout + ro + bj * HALF) = o; }
;                     else { *(f32x4*)((float*)Xout + ro + bj * HALF) = x0; *(f32x4*)((float*)Xout + ro + bj * HALF + 4) = x1; } } }
; template <class Map, class Epi>
; DI void gemm_phase(LAS unsigned char* lds, const Map& MP, const Epi& E, const int nM, const int nN, const int K, const int lda, const int ldb) {
;     ...
;             PG8_BAR; PG8_WAIT_L(0); PG8_MMA(0, 1, At, B1); PG8_BAR;
;             PG8_LDA(At, 1, 1); PG8_STAGE(PG8_SA(1, 0), a3, voffA);
;             PG8_BAR; PG8_WAIT_L(0); PG8_MMA(1, 0, At, B0); PG8_BAR; PG8_SCHED;
;             PG8_STAGE(PG8_SB(1, 1), b3 + hstepB, voffB);
;             PG8_WAIT_V(6); PG8_BAR; PG8_MMA(1, 1, At, B1); PG8_BAR;
	s_setprio 1
	s_waitcnt lgkmcnt(7)
	v_mfma_f32_16x16x32_bf16 v[60:63], v[152:155], v[168:171], v[60:63]
	v_mfma_f32_16x16x32_bf16 v[56:59], v[160:163], v[168:171], v[56:59]
	s_waitcnt lgkmcnt(5)
	v_mfma_f32_16x16x32_bf16 v[44:47], v[152:155], v[176:179], v[44:47]
	v_mfma_f32_16x16x32_bf16 v[40:43], v[160:163], v[176:179], v[40:43]
	s_waitcnt lgkmcnt(3)
	v_mfma_f32_16x16x32_bf16 v[28:31], v[152:155], v[184:187], v[28:31]
	v_mfma_f32_16x16x32_bf16 v[24:27], v[160:163], v[184:187], v[24:27]
	s_waitcnt lgkmcnt(1)
	v_mfma_f32_16x16x32_bf16 v[12:15], v[152:155], v[192:195], v[12:15]
	v_mfma_f32_16x16x32_bf16 v[8:11], v[160:163], v[192:195], v[8:11]
	v_mfma_f32_16x16x32_bf16 v[60:63], v[156:159], v[172:175], v[60:63]
	v_mfma_f32_16x16x32_bf16 v[56:59], v[164:167], v[172:175], v[56:59]
	v_mfma_f32_16x16x32_bf16 v[44:47], v[156:159], v[180:183], v[44:47]
	v_mfma_f32_16x16x32_bf16 v[40:43], v[164:167], v[180:183], v[40:43]
	v_mfma_f32_16x16x32_bf16 v[28:31], v[156:159], v[188:191], v[28:31]
	v_mfma_f32_16x16x32_bf16 v[24:27], v[164:167], v[188:191], v[24:27]
	s_waitcnt lgkmcnt(0)
	v_mfma_f32_16x16x32_bf16 v[12:15], v[156:159], v[198:201], v[12:15]
	v_mfma_f32_16x16x32_bf16 v[8:11], v[164:167], v[198:201], v[8:11]
	s_setprio 0
	s_barrier
	s_add_u32 s12, s12, 0x80080
	s_addc_u32 s13, s13, 0
	s_add_i32 s3, s14, s22
	s_mov_b32 m0, s3
	s_nop 0
	global_load_lds_dwordx4 v132, s[12:13]
	s_add_i32 m0, s3, 0x2000
	s_nop 0
	global_load_lds_dwordx4 v128, s[12:13]
	s_waitcnt vmcnt(6)
	s_barrier
	s_setprio 1
	v_mfma_f32_16x16x32_bf16 v[52:55], v[202:205], v[168:171], v[52:55]
	v_mfma_f32_16x16x32_bf16 v[48:51], v[210:213], v[168:171], v[48:51]
	ds_read_b128 v[152:155], v149
	v_mfma_f32_16x16x32_bf16 v[36:39], v[202:205], v[176:179], v[36:39]
	v_mfma_f32_16x16x32_bf16 v[32:35], v[210:213], v[176:179], v[32:35]
	ds_read_b128 v[156:159], v149 offset:1024
	v_mfma_f32_16x16x32_bf16 v[20:23], v[202:205], v[184:187], v[20:23]
	v_mfma_f32_16x16x32_bf16 v[16:19], v[210:213], v[184:187], v[16:19]
	ds_read_b128 v[160:163], v149 offset:2048
	v_mfma_f32_16x16x32_bf16 v[4:7], v[202:205], v[192:195], v[4:7]
	v_mfma_f32_16x16x32_bf16 v[0:3], v[210:213], v[192:195], v[0:3]
	ds_read_b128 v[164:167], v149 offset:3072
	v_mfma_f32_16x16x32_bf16 v[52:55], v[206:209], v[172:175], v[52:55]
	s_add_i32 s48, s48, 2
	v_mfma_f32_16x16x32_bf16 v[48:51], v[214:217], v[172:175], v[48:51]
	s_add_u32 s39, s39, 0x100
	s_addc_u32 s47, s47, 0
	v_mfma_f32_16x16x32_bf16 v[36:39], v[206:209], v[180:183], v[36:39]
	s_add_u32 s10, s10, 0x100
	s_addc_u32 s11, s11, 0
	v_mfma_f32_16x16x32_bf16 v[32:35], v[214:217], v[180:183], v[32:35]
	s_cmp_gt_u32 s48, 29
	v_mfma_f32_16x16x32_bf16 v[20:23], v[206:209], v[188:191], v[20:23]
	v_mfma_f32_16x16x32_bf16 v[16:19], v[214:217], v[188:191], v[16:19]
	v_mfma_f32_16x16x32_bf16 v[4:7], v[206:209], v[198:201], v[4:7]
	v_mfma_f32_16x16x32_bf16 v[0:3], v[214:217], v[198:201], v[0:3]
	s_setprio 0
	s_barrier
	s_cbranch_scc0 .LBB1_925
	s_waitcnt lgkmcnt(0)
	v_mov_b32_e32 v152, v147
	v_mov_b32_e32 v144, v146
	s_lshl_b32 s2, s2, 8
	s_or_b32 s2, s2, s29
	v_lshl_add_u32 v144, v144, 3, s2
	s_lshl_b32 s2, s8, 8
	s_add_i32 s2, s2, s28
	v_add_u32_e32 v152, s2, v152
	v_ashrrev_i32_e32 v153, 31, v152
	v_lshlrev_b64 v[152:153], 12, v[152:153]
	v_ashrrev_i32_e32 v145, 31, v144
	v_lshl_add_u64 v[152:153], s[42:43], 0, v[152:153]
	v_lshl_add_u64 v[144:145], v[144:145], 1, v[152:153]
	global_load_dwordx4 v[160:163], v[144:145], off
	global_load_dwordx4 v[164:167], v[144:145], off offset:256
	s_mov_b64 s[98:99], 0x10000
	v_lshl_add_u64 v[154:155], v[144:145], 0, s[98:99]
	global_load_dwordx4 v[168:171], v[154:155], off
	global_load_dwordx4 v[172:175], v[154:155], off offset:256
	s_mov_b64 s[98:99], 0x20000
	v_lshl_add_u64 v[154:155], v[144:145], 0, s[98:99]
	global_load_dwordx4 v[176:179], v[154:155], off
	global_load_dwordx4 v[180:183], v[154:155], off offset:256
	s_mov_b64 s[98:99], 0x30000
	v_lshl_add_u64 v[154:155], v[144:145], 0, s[98:99]
	global_load_dwordx4 v[184:187], v[154:155], off
	global_load_dwordx4 v[188:191], v[154:155], off offset:256
	s_mov_b64 s[98:99], 0x80000
	v_lshl_add_u64 v[154:155], v[144:145], 0, s[98:99]
	global_load_dwordx4 v[192:195], v[154:155], off
	global_load_dwordx4 v[198:201], v[154:155], off offset:256
	s_mov_b64 s[98:99], 0x90000
	v_lshl_add_u64 v[154:155], v[144:145], 0, s[98:99]
	global_load_dwordx4 v[202:205], v[154:155], off
	global_load_dwordx4 v[206:209], v[154:155], off offset:256
	s_mov_b64 s[98:99], 0xa0000
	v_lshl_add_u64 v[154:155], v[144:145], 0, s[98:99]
	global_load_dwordx4 v[210:213], v[154:155], off
	global_load_dwordx4 v[214:217], v[154:155], off offset:256
	s_mov_b64 s[98:99], 0xb0000
	v_lshl_add_u64 v[154:155], v[144:145], 0, s[98:99]
	global_load_dwordx4 v[248:251], v[154:155], off
	global_load_dwordx4 v[252:255], v[154:155], off offset:256
	s_waitcnt vmcnt(15)
	s_nop 1
	v_mov_b32_e32 v152, v160
	v_mov_b32_e32 v153, v161
	v_mov_b32_e32 v154, v162
	v_mov_b32_e32 v155, v163
	s_mov_b64 s[2:3], 0x10000
	s_mov_b32 s8, s52
	s_mov_b64 s[10:11], s[6:7]
	s_mov_b64 s[12:13], s[54:55]
	s_waitcnt lgkmcnt(0)
	v_lshlrev_b32_e32 v156, 16, v152
	v_and_b32_e32 v157, 0xffff0000, v152
	v_lshlrev_b32_e32 v152, 16, v153
	v_and_b32_e32 v153, 0xffff0000, v153
	v_lshlrev_b32_e32 v158, 16, v154
	v_and_b32_e32 v159, 0xffff0000, v154
	v_lshlrev_b32_e32 v154, 16, v155
	v_and_b32_e32 v155, 0xffff0000, v155
	v_pk_add_f32 v[126:127], v[126:127], v[152:153]
	v_pk_add_f32 v[124:125], v[124:125], v[156:157]
	v_pk_add_f32 v[152:153], v[122:123], v[154:155]
	v_pk_add_f32 v[122:123], v[120:121], v[158:159]
	v_cvt_pk_bf16_f32 v120, v124, v125
	v_cvt_pk_bf16_f32 v121, v126, v127
	v_cvt_pk_bf16_f32 v122, v122, v123
	v_cvt_pk_bf16_f32 v123, v152, v153
	global_store_dwordx4 v[144:145], v[120:123], off
	s_waitcnt vmcnt(15)
; DI unsigned pack2(float a, float b) { f32x2 v = {a, b}; hwbf16x2 r = __builtin_convertvector(v, hwbf16x2); return __builtin_bit_cast(unsigned, r); }
; DI float bflo(unsigned w) { return __uint_as_float(w << 16); }
; DI float bfhi(unsigned w) { return __uint_as_float(w & 0xffff0000u); }
;     DI void operator()(const f32x4 (&acc)[2][2][4][2], const Unit& u, int wr, int wc, int fr, int fq) const {
;     ...
;             for (int m = 0; m < 4; ++m) { const size_t ro = (size_t)(row0 + ai * HALF + m * 16) * D + col0;
; #pragma unroll
;                 for (int bj = 0; bj < 2; ++bj) {
;                     f32x4 x0, x1;
;                     if constexpr (IB) { const u32x4 w = *(const u32x4*)((const bf16_t*)Xin + ro + bj * HALF);
;                         x0 = (f32x4){bflo(w[0]), bfhi(w[0]), bflo(w[1]), bfhi(w[1])}; x1 = (f32x4){bflo(w[2]), bfhi(w[2]), bflo(w[3]), bfhi(w[3])}; }
;                     else { x0 = *(const f32x4*)((const float*)Xin + ro + bj * HALF); x1 = *(const f32x4*)((const float*)Xin + ro + bj * HALF + 4); }
;                     x0 += acc[ai][bj][m][0] * sc[bj][0]; x1 += acc[ai][bj][m][1] * sc[bj][1];
;                     if constexpr (OB) { u32x4 o; o[0] = pack2(x0[0], x0[1]); o[1] = pack2(x0[2], x0[3]); o[2] = pack2(x1[0], x1[1]); o[3] = pack2(x1[2], x1[3]);
;                         *(u32x4*)((bf16_t*)Xout + ro + bj * HALF) = o; }
;                     else { *(f32x4*)((float*)Xout + ro + bj * HALF) = x0; *(f32x4*)((float*)Xout + ro + bj * HALF + 4) = x1; } } }
	s_nop 1
	v_mov_b32_e32 v120, v164
	v_mov_b32_e32 v121, v165
	v_mov_b32_e32 v122, v166
	v_mov_b32_e32 v123, v167
	s_waitcnt lgkmcnt(0)
	v_lshlrev_b32_e32 v124, 16, v120
	v_and_b32_e32 v125, 0xffff0000, v120
	v_lshlrev_b32_e32 v120, 16, v121
	v_and_b32_e32 v121, 0xffff0000, v121
	v_lshlrev_b32_e32 v126, 16, v122
	v_and_b32_e32 v127, 0xffff0000, v122
	v_lshlrev_b32_e32 v122, 16, v123
	v_and_b32_e32 v123, 0xffff0000, v123
	v_pk_add_f32 v[116:117], v[116:117], v[124:125]
	v_pk_add_f32 v[118:119], v[118:119], v[120:121]
	v_pk_add_f32 v[120:121], v[114:115], v[122:123]
	v_pk_add_f32 v[114:115], v[112:113], v[126:127]
	v_cvt_pk_bf16_f32 v112, v116, v117
	v_lshl_add_u64 v[116:117], v[144:145], 0, s[2:3]
	s_mov_b32 s2, 0x10000
	v_cvt_pk_bf16_f32 v113, v118, v119
	v_add_co_u32_e32 v118, vcc, s2, v144
	v_cvt_pk_bf16_f32 v114, v114, v115
	v_cvt_pk_bf16_f32 v115, v120, v121
	v_addc_co_u32_e32 v119, vcc, 0, v145, vcc
	global_store_dwordx4 v[144:145], v[112:115], off offset:256
	s_waitcnt vmcnt(15)
	s_nop 1
	v_mov_b32_e32 v112, v168
	v_mov_b32_e32 v113, v169
	v_mov_b32_e32 v114, v170
	v_mov_b32_e32 v115, v171
	s_mov_b64 s[2:3], 0x20000
	s_waitcnt lgkmcnt(0)
	v_lshlrev_b32_e32 v120, 16, v112
	v_and_b32_e32 v121, 0xffff0000, v112
	v_lshlrev_b32_e32 v112, 16, v113
	v_and_b32_e32 v113, 0xffff0000, v113
	v_lshlrev_b32_e32 v122, 16, v114
	v_and_b32_e32 v123, 0xffff0000, v114
	v_lshlrev_b32_e32 v114, 16, v115
	v_and_b32_e32 v115, 0xffff0000, v115
	v_pk_add_f32 v[110:111], v[110:111], v[112:113]
	v_pk_add_f32 v[108:109], v[108:109], v[120:121]
	v_pk_add_f32 v[112:113], v[106:107], v[114:115]
	v_pk_add_f32 v[106:107], v[104:105], v[122:123]
	v_cvt_pk_bf16_f32 v104, v108, v109
	v_cvt_pk_bf16_f32 v105, v110, v111
	v_cvt_pk_bf16_f32 v106, v106, v107
	v_cvt_pk_bf16_f32 v107, v112, v113
	global_store_dwordx4 v[118:119], v[104:107], off
	s_waitcnt vmcnt(15)
	s_nop 1
	v_mov_b32_e32 v104, v172
	v_mov_b32_e32 v105, v173
	v_mov_b32_e32 v106, v174
	v_mov_b32_e32 v107, v175
	s_waitcnt lgkmcnt(0)
	v_lshlrev_b32_e32 v108, 16, v104
	v_and_b32_e32 v109, 0xffff0000, v104
	v_lshlrev_b32_e32 v104, 16, v105
	v_and_b32_e32 v105, 0xffff0000, v105
	v_lshlrev_b32_e32 v110, 16, v106
	v_and_b32_e32 v111, 0xffff0000, v106
	v_lshlrev_b32_e32 v106, 16, v107
	v_and_b32_e32 v107, 0xffff0000, v107
	v_pk_add_f32 v[100:101], v[100:101], v[108:109]
	v_pk_add_f32 v[102:103], v[102:103], v[104:105]
	v_pk_add_f32 v[104:105], v[98:99], v[106:107]
	v_pk_add_f32 v[98:99], v[96:97], v[110:111]
	v_cvt_pk_bf16_f32 v96, v100, v101
	v_lshl_add_u64 v[100:101], v[144:145], 0, s[2:3]
	s_mov_b32 s2, 0x20000
	v_cvt_pk_bf16_f32 v97, v102, v103
	v_add_co_u32_e32 v102, vcc, s2, v144
	v_cvt_pk_bf16_f32 v98, v98, v99
	v_cvt_pk_bf16_f32 v99, v104, v105
	v_addc_co_u32_e32 v103, vcc, 0, v145, vcc
	global_store_dwordx4 v[116:117], v[96:99], off offset:256
	s_waitcnt vmcnt(15)
	s_nop 1
	v_mov_b32_e32 v96, v176
	v_mov_b32_e32 v97, v177
	v_mov_b32_e32 v98, v178
	v_mov_b32_e32 v99, v179
	s_mov_b64 s[2:3], 0x30000
	s_waitcnt lgkmcnt(0)
	v_lshlrev_b32_e32 v104, 16, v96
	v_and_b32_e32 v105, 0xffff0000, v96
	v_lshlrev_b32_e32 v96, 16, v97
	v_and_b32_e32 v97, 0xffff0000, v97
	v_lshlrev_b32_e32 v106, 16, v98
	v_and_b32_e32 v107, 0xffff0000, v98
	v_lshlrev_b32_e32 v98, 16, v99
	v_and_b32_e32 v99, 0xffff0000, v99
	v_pk_add_f32 v[94:95], v[94:95], v[96:97]
	v_pk_add_f32 v[92:93], v[92:93], v[104:105]
	v_pk_add_f32 v[96:97], v[90:91], v[98:99]
	v_pk_add_f32 v[90:91], v[88:89], v[106:107]
	v_cvt_pk_bf16_f32 v88, v92, v93
	v_cvt_pk_bf16_f32 v89, v94, v95
	v_cvt_pk_bf16_f32 v90, v90, v91
	v_cvt_pk_bf16_f32 v91, v96, v97
	global_store_dwordx4 v[102:103], v[88:91], off
	s_waitcnt vmcnt(15)
	s_nop 1
	v_mov_b32_e32 v88, v180
	v_mov_b32_e32 v89, v181
	v_mov_b32_e32 v90, v182
	v_mov_b32_e32 v91, v183
	s_waitcnt lgkmcnt(0)
	v_lshlrev_b32_e32 v92, 16, v88
	v_and_b32_e32 v93, 0xffff0000, v88
	v_lshlrev_b32_e32 v88, 16, v89
	v_and_b32_e32 v89, 0xffff0000, v89
	v_lshlrev_b32_e32 v94, 16, v90
	v_and_b32_e32 v95, 0xffff0000, v90
	v_lshlrev_b32_e32 v90, 16, v91
	v_and_b32_e32 v91, 0xffff0000, v91
	v_pk_add_f32 v[86:87], v[86:87], v[88:89]
	v_pk_add_f32 v[84:85], v[84:85], v[92:93]
	v_pk_add_f32 v[88:89], v[82:83], v[90:91]
	v_pk_add_f32 v[82:83], v[80:81], v[94:95]
	v_cvt_pk_bf16_f32 v80, v84, v85
	v_cvt_pk_bf16_f32 v81, v86, v87
	v_cvt_pk_bf16_f32 v82, v82, v83
	v_cvt_pk_bf16_f32 v83, v88, v89
	global_store_dwordx4 v[100:101], v[80:83], off offset:256
	s_nop 1
	v_lshl_add_u64 v[80:81], v[144:145], 0, s[2:3]
	s_mov_b32 s2, 0x30000
	v_add_co_u32_e32 v86, vcc, s2, v144
	s_mov_b64 s[2:3], 0x80000
	s_nop 0
	v_addc_co_u32_e32 v87, vcc, 0, v145, vcc
	s_waitcnt vmcnt(15)
	s_nop 1
	v_mov_b32_e32 v82, v184
	v_mov_b32_e32 v83, v185
	v_mov_b32_e32 v84, v186
	v_mov_b32_e32 v85, v187
	s_waitcnt lgkmcnt(0)
	v_lshlrev_b32_e32 v88, 16, v82
	v_and_b32_e32 v89, 0xffff0000, v82
	v_lshlrev_b32_e32 v82, 16, v83
	v_and_b32_e32 v83, 0xffff0000, v83
	v_lshlrev_b32_e32 v90, 16, v84
	v_and_b32_e32 v91, 0xffff0000, v84
	v_lshlrev_b32_e32 v84, 16, v85
	v_and_b32_e32 v85, 0xffff0000, v85
	v_pk_add_f32 v[78:79], v[78:79], v[82:83]
	v_pk_add_f32 v[76:77], v[76:77], v[88:89]
	v_pk_add_f32 v[82:83], v[74:75], v[84:85]
	v_pk_add_f32 v[74:75], v[72:73], v[90:91]
	v_cvt_pk_bf16_f32 v72, v76, v77
	v_cvt_pk_bf16_f32 v73, v78, v79
	v_cvt_pk_bf16_f32 v74, v74, v75
	v_cvt_pk_bf16_f32 v75, v82, v83
	global_store_dwordx4 v[86:87], v[72:75], off
	s_waitcnt vmcnt(15)
	s_nop 1
	v_mov_b32_e32 v72, v188
	v_mov_b32_e32 v73, v189
	v_mov_b32_e32 v74, v190
	v_mov_b32_e32 v75, v191
	s_waitcnt lgkmcnt(0)
; DI unsigned pack2(float a, float b) { f32x2 v = {a, b}; hwbf16x2 r = __builtin_convertvector(v, hwbf16x2); return __builtin_bit_cast(unsigned, r); }
; DI float bflo(unsigned w) { return __uint_as_float(w << 16); }
; DI float bfhi(unsigned w) { return __uint_as_float(w & 0xffff0000u); }
;     DI void operator()(const f32x4 (&acc)[2][2][4][2], const Unit& u, int wr, int wc, int fr, int fq) const {
;     ...
;             for (int m = 0; m < 4; ++m) { const size_t ro = (size_t)(row0 + ai * HALF + m * 16) * D + col0;
; #pragma unroll
;                 for (int bj = 0; bj < 2; ++bj) {
;                     f32x4 x0, x1;
;                     if constexpr (IB) { const u32x4 w = *(const u32x4*)((const bf16_t*)Xin + ro + bj * HALF);
;                         x0 = (f32x4){bflo(w[0]), bfhi(w[0]), bflo(w[1]), bfhi(w[1])}; x1 = (f32x4){bflo(w[2]), bfhi(w[2]), bflo(w[3]), bfhi(w[3])}; }
;                     else { x0 = *(const f32x4*)((const float*)Xin + ro + bj * HALF); x1 = *(const f32x4*)((const float*)Xin + ro + bj * HALF + 4); }
;                     x0 += acc[ai][bj][m][0] * sc[bj][0]; x1 += acc[ai][bj][m][1] * sc[bj][1];
;                     if constexpr (OB) { u32x4 o; o[0] = pack2(x0[0], x0[1]); o[1] = pack2(x0[2], x0[3]); o[2] = pack2(x1[0], x1[1]); o[3] = pack2(x1[2], x1[3]);
;                         *(u32x4*)((bf16_t*)Xout + ro + bj * HALF) = o; }
;                     else { *(f32x4*)((float*)Xout + ro + bj * HALF) = x0; *(f32x4*)((float*)Xout + ro + bj * HALF + 4) = x1; } } }
	v_lshlrev_b32_e32 v76, 16, v72
	v_and_b32_e32 v77, 0xffff0000, v72
	v_lshlrev_b32_e32 v72, 16, v73
	v_and_b32_e32 v73, 0xffff0000, v73
	v_lshlrev_b32_e32 v78, 16, v74
	v_and_b32_e32 v79, 0xffff0000, v74
	v_lshlrev_b32_e32 v74, 16, v75
	v_and_b32_e32 v75, 0xffff0000, v75
	v_pk_add_f32 v[70:71], v[70:71], v[72:73]
	v_pk_add_f32 v[68:69], v[68:69], v[76:77]
	v_pk_add_f32 v[72:73], v[66:67], v[74:75]
	v_pk_add_f32 v[66:67], v[64:65], v[78:79]
	v_cvt_pk_bf16_f32 v64, v68, v69
	v_cvt_pk_bf16_f32 v65, v70, v71
	v_cvt_pk_bf16_f32 v66, v66, v67
	v_cvt_pk_bf16_f32 v67, v72, v73
	global_store_dwordx4 v[80:81], v[64:67], off offset:256
	s_nop 1
	v_lshl_add_u64 v[64:65], v[144:145], 0, s[2:3]
	s_mov_b32 s2, 0x80000
	v_add_co_u32_e32 v70, vcc, s2, v144
	s_mov_b64 s[2:3], 0x90000
	s_nop 0
	v_addc_co_u32_e32 v71, vcc, 0, v145, vcc
	s_waitcnt vmcnt(15)
	s_nop 1
	v_mov_b32_e32 v66, v192
	v_mov_b32_e32 v67, v193
	v_mov_b32_e32 v68, v194
	v_mov_b32_e32 v69, v195
	s_waitcnt lgkmcnt(0)
	v_lshlrev_b32_e32 v72, 16, v66
	v_and_b32_e32 v73, 0xffff0000, v66
	v_lshlrev_b32_e32 v66, 16, v67
	v_and_b32_e32 v67, 0xffff0000, v67
	v_lshlrev_b32_e32 v74, 16, v68
	v_and_b32_e32 v75, 0xffff0000, v68
	v_lshlrev_b32_e32 v68, 16, v69
	v_and_b32_e32 v69, 0xffff0000, v69
	v_pk_add_f32 v[62:63], v[62:63], v[66:67]
	v_pk_add_f32 v[60:61], v[60:61], v[72:73]
	v_pk_add_f32 v[66:67], v[58:59], v[68:69]
	v_pk_add_f32 v[58:59], v[56:57], v[74:75]
	v_cvt_pk_bf16_f32 v56, v60, v61
	v_cvt_pk_bf16_f32 v57, v62, v63
	v_cvt_pk_bf16_f32 v58, v58, v59
	v_cvt_pk_bf16_f32 v59, v66, v67
	global_store_dwordx4 v[70:71], v[56:59], off
	s_waitcnt vmcnt(15)
	s_nop 1
	v_mov_b32_e32 v56, v198
	v_mov_b32_e32 v57, v199
	v_mov_b32_e32 v58, v200
	v_mov_b32_e32 v59, v201
	s_waitcnt lgkmcnt(0)
	v_lshlrev_b32_e32 v60, 16, v56
	v_and_b32_e32 v61, 0xffff0000, v56
	v_lshlrev_b32_e32 v56, 16, v57
	v_and_b32_e32 v57, 0xffff0000, v57
	v_lshlrev_b32_e32 v62, 16, v58
	v_and_b32_e32 v63, 0xffff0000, v58
	v_lshlrev_b32_e32 v58, 16, v59
	v_and_b32_e32 v59, 0xffff0000, v59
	v_pk_add_f32 v[54:55], v[54:55], v[56:57]
	v_pk_add_f32 v[52:53], v[52:53], v[60:61]
	v_pk_add_f32 v[56:57], v[50:51], v[58:59]
	v_pk_add_f32 v[50:51], v[48:49], v[62:63]
	v_cvt_pk_bf16_f32 v48, v52, v53
	v_cvt_pk_bf16_f32 v49, v54, v55
	v_cvt_pk_bf16_f32 v50, v50, v51
	v_cvt_pk_bf16_f32 v51, v56, v57
	global_store_dwordx4 v[64:65], v[48:51], off offset:256
	s_nop 1
	v_lshl_add_u64 v[48:49], v[144:145], 0, s[2:3]
	s_mov_b32 s2, 0x90000
	v_add_co_u32_e32 v54, vcc, s2, v144
	s_mov_b64 s[2:3], 0xa0000
	s_nop 0
	v_addc_co_u32_e32 v55, vcc, 0, v145, vcc
	s_waitcnt vmcnt(15)
	s_nop 1
	v_mov_b32_e32 v50, v202
	v_mov_b32_e32 v51, v203
	v_mov_b32_e32 v52, v204
	v_mov_b32_e32 v53, v205
	s_waitcnt lgkmcnt(0)
	v_lshlrev_b32_e32 v56, 16, v50
	v_and_b32_e32 v57, 0xffff0000, v50
	v_lshlrev_b32_e32 v50, 16, v51
	v_and_b32_e32 v51, 0xffff0000, v51
	v_lshlrev_b32_e32 v58, 16, v52
	v_and_b32_e32 v59, 0xffff0000, v52
	v_lshlrev_b32_e32 v52, 16, v53
	v_and_b32_e32 v53, 0xffff0000, v53
	v_pk_add_f32 v[46:47], v[46:47], v[50:51]
	v_pk_add_f32 v[44:45], v[44:45], v[56:57]
	v_pk_add_f32 v[50:51], v[42:43], v[52:53]
	v_pk_add_f32 v[42:43], v[40:41], v[58:59]
	v_cvt_pk_bf16_f32 v40, v44, v45
	v_cvt_pk_bf16_f32 v41, v46, v47
	v_cvt_pk_bf16_f32 v42, v42, v43
	v_cvt_pk_bf16_f32 v43, v50, v51
	global_store_dwordx4 v[54:55], v[40:43], off
	s_waitcnt vmcnt(15)
	s_nop 1
	v_mov_b32_e32 v40, v206
	v_mov_b32_e32 v41, v207
	v_mov_b32_e32 v42, v208
	v_mov_b32_e32 v43, v209
	s_waitcnt lgkmcnt(0)
; DI unsigned pack2(float a, float b) { f32x2 v = {a, b}; hwbf16x2 r = __builtin_convertvector(v, hwbf16x2); return __builtin_bit_cast(unsigned, r); }
; DI float bflo(unsigned w) { return __uint_as_float(w << 16); }
; DI float bfhi(unsigned w) { return __uint_as_float(w & 0xffff0000u); }
;     DI const char* a(const Unit& u) const { return (const char*)(A + (size_t)u.pm * BM * lda); }
;     DI const char* a(const Unit& u) const { return (const char*)(A + (size_t)u.pm * BM * 2048 + (u.pn >> 1) * 512); }
; #define PG8_BAR __builtin_amdgcn_s_barrier()
;     DI void operator()(const f32x4 (&acc)[2][2][4][2], const Unit& u, int wr, int wc, int fr, int fq) const {
;     ...
;             for (int m = 0; m < 4; ++m) { const size_t ro = (size_t)(row0 + ai * HALF + m * 16) * D + col0;
; #pragma unroll
;                 for (int bj = 0; bj < 2; ++bj) {
;                     f32x4 x0, x1;
;                     if constexpr (IB) { const u32x4 w = *(const u32x4*)((const bf16_t*)Xin + ro + bj * HALF);
;                         x0 = (f32x4){bflo(w[0]), bfhi(w[0]), bflo(w[1]), bfhi(w[1])}; x1 = (f32x4){bflo(w[2]), bfhi(w[2]), bflo(w[3]), bfhi(w[3])}; }
;                     else { x0 = *(const f32x4*)((const float*)Xin + ro + bj * HALF); x1 = *(const f32x4*)((const float*)Xin + ro + bj * HALF + 4); }
;                     x0 += acc[ai][bj][m][0] * sc[bj][0]; x1 += acc[ai][bj][m][1] * sc[bj][1];
;                     if constexpr (OB) { u32x4 o; o[0] = pack2(x0[0], x0[1]); o[1] = pack2(x0[2], x0[3]); o[2] = pack2(x1[0], x1[1]); o[3] = pack2(x1[2], x1[3]);
;                         *(u32x4*)((bf16_t*)Xout + ro + bj * HALF) = o; }
;                     else { *(f32x4*)((float*)Xout + ro + bj * HALF) = x0; *(f32x4*)((float*)Xout + ro + bj * HALF + 4) = x1; } } }
; template <class Map, class Epi>
; DI void gemm_phase(LAS unsigned char* lds, const Map& MP, const Epi& E, const int nM, const int nN, const int K, const int lda, const int ldb) {
;     ...
;         if (!has_next) break;
; #pragma unroll
;         for (int a = 0; a < 2; ++a)
; #pragma unroll
;             for (int b = 0; b < 2; ++b)
; #pragma unroll
;                 for (int m = 0; m < 4; ++m)
; #pragma unroll
;                     for (int n = 0; n < 2; ++n) acc[a][b][m][n] = (f32x4){0.f, 0.f, 0.f, 0.f};
;         cur = nxt; cA = nA; cB = nB; ++ui;
;     }
;     PG8_WAIT_V(0);
;     if (wr == 0) PG8_BAR;
;     PG8_BAR;
	v_lshlrev_b32_e32 v44, 16, v40
	v_and_b32_e32 v45, 0xffff0000, v40
	v_lshlrev_b32_e32 v40, 16, v41
	v_and_b32_e32 v41, 0xffff0000, v41
	v_lshlrev_b32_e32 v46, 16, v42
	v_and_b32_e32 v47, 0xffff0000, v42
	v_lshlrev_b32_e32 v42, 16, v43
	v_and_b32_e32 v43, 0xffff0000, v43
	v_pk_add_f32 v[38:39], v[38:39], v[40:41]
	v_pk_add_f32 v[36:37], v[36:37], v[44:45]
	v_pk_add_f32 v[40:41], v[34:35], v[42:43]
	v_pk_add_f32 v[34:35], v[32:33], v[46:47]
	v_cvt_pk_bf16_f32 v32, v36, v37
	v_cvt_pk_bf16_f32 v33, v38, v39
	v_cvt_pk_bf16_f32 v34, v34, v35
	v_cvt_pk_bf16_f32 v35, v40, v41
	global_store_dwordx4 v[48:49], v[32:35], off offset:256
	s_nop 1
	v_lshl_add_u64 v[32:33], v[144:145], 0, s[2:3]
	s_mov_b32 s2, 0xa0000
	v_add_co_u32_e32 v38, vcc, s2, v144
	s_mov_b64 s[2:3], 0xb0000
	s_nop 0
	v_addc_co_u32_e32 v39, vcc, 0, v145, vcc
	s_waitcnt vmcnt(15)
	s_nop 1
	v_mov_b32_e32 v34, v210
	v_mov_b32_e32 v35, v211
	v_mov_b32_e32 v36, v212
	v_mov_b32_e32 v37, v213
	s_waitcnt lgkmcnt(0)
	v_lshlrev_b32_e32 v40, 16, v34
	v_and_b32_e32 v41, 0xffff0000, v34
	v_lshlrev_b32_e32 v34, 16, v35
	v_and_b32_e32 v35, 0xffff0000, v35
	v_lshlrev_b32_e32 v42, 16, v36
	v_and_b32_e32 v43, 0xffff0000, v36
	v_lshlrev_b32_e32 v36, 16, v37
	v_and_b32_e32 v37, 0xffff0000, v37
	v_pk_add_f32 v[30:31], v[30:31], v[34:35]
	v_pk_add_f32 v[28:29], v[28:29], v[40:41]
	v_pk_add_f32 v[34:35], v[26:27], v[36:37]
	v_pk_add_f32 v[26:27], v[24:25], v[42:43]
	v_cvt_pk_bf16_f32 v24, v28, v29
	v_cvt_pk_bf16_f32 v25, v30, v31
	v_cvt_pk_bf16_f32 v26, v26, v27
	v_cvt_pk_bf16_f32 v27, v34, v35
	global_store_dwordx4 v[38:39], v[24:27], off
	s_waitcnt vmcnt(15)
	s_nop 1
	v_mov_b32_e32 v24, v214
	v_mov_b32_e32 v25, v215
	v_mov_b32_e32 v26, v216
	v_mov_b32_e32 v27, v217
	s_waitcnt lgkmcnt(0)
	v_lshlrev_b32_e32 v28, 16, v24
	v_and_b32_e32 v29, 0xffff0000, v24
	v_lshlrev_b32_e32 v24, 16, v25
	v_and_b32_e32 v25, 0xffff0000, v25
	v_lshlrev_b32_e32 v30, 16, v26
	v_and_b32_e32 v31, 0xffff0000, v26
	v_lshlrev_b32_e32 v26, 16, v27
	v_and_b32_e32 v27, 0xffff0000, v27
	v_pk_add_f32 v[22:23], v[22:23], v[24:25]
	v_pk_add_f32 v[20:21], v[20:21], v[28:29]
	v_pk_add_f32 v[24:25], v[18:19], v[26:27]
	v_pk_add_f32 v[18:19], v[16:17], v[30:31]
	v_cvt_pk_bf16_f32 v16, v20, v21
	v_cvt_pk_bf16_f32 v17, v22, v23
	v_cvt_pk_bf16_f32 v18, v18, v19
	v_cvt_pk_bf16_f32 v19, v24, v25
	global_store_dwordx4 v[32:33], v[16:19], off offset:256
	s_nop 1
	v_lshl_add_u64 v[16:17], v[144:145], 0, s[2:3]
	s_mov_b32 s2, 0xb0000
	v_add_co_u32_e32 v22, vcc, s2, v144
	s_mov_b32 s2, s46
	s_nop 0
	v_addc_co_u32_e32 v23, vcc, 0, v145, vcc
	s_waitcnt vmcnt(15)
	s_nop 1
	v_mov_b32_e32 v18, v248
	v_mov_b32_e32 v19, v249
	v_mov_b32_e32 v20, v250
	v_mov_b32_e32 v21, v251
	s_and_b64 vcc, exec, s[40:41]
	s_waitcnt lgkmcnt(0)
	v_lshlrev_b32_e32 v24, 16, v18
	v_and_b32_e32 v25, 0xffff0000, v18
	v_lshlrev_b32_e32 v18, 16, v19
	v_and_b32_e32 v19, 0xffff0000, v19
	v_lshlrev_b32_e32 v26, 16, v20
	v_and_b32_e32 v27, 0xffff0000, v20
	v_lshlrev_b32_e32 v20, 16, v21
	v_and_b32_e32 v21, 0xffff0000, v21
	v_pk_add_f32 v[14:15], v[14:15], v[18:19]
	v_pk_add_f32 v[12:13], v[12:13], v[24:25]
	v_pk_add_f32 v[18:19], v[10:11], v[20:21]
	v_pk_add_f32 v[10:11], v[8:9], v[26:27]
	v_cvt_pk_bf16_f32 v8, v12, v13
	v_cvt_pk_bf16_f32 v9, v14, v15
	v_cvt_pk_bf16_f32 v10, v10, v11
	v_cvt_pk_bf16_f32 v11, v18, v19
	global_store_dwordx4 v[22:23], v[8:11], off
	s_waitcnt vmcnt(15)
	s_nop 1
	v_mov_b32_e32 v8, v252
	v_mov_b32_e32 v9, v253
	v_mov_b32_e32 v10, v254
	v_mov_b32_e32 v11, v255
	s_waitcnt lgkmcnt(0)
	v_lshlrev_b32_e32 v12, 16, v8
	v_and_b32_e32 v13, 0xffff0000, v8
	v_lshlrev_b32_e32 v8, 16, v9
	v_and_b32_e32 v9, 0xffff0000, v9
	v_lshlrev_b32_e32 v14, 16, v10
	v_and_b32_e32 v15, 0xffff0000, v10
	v_lshlrev_b32_e32 v10, 16, v11
	v_and_b32_e32 v11, 0xffff0000, v11
	v_pk_add_f32 v[6:7], v[6:7], v[8:9]
	v_pk_add_f32 v[4:5], v[4:5], v[12:13]
	v_pk_add_f32 v[8:9], v[2:3], v[10:11]
	v_pk_add_f32 v[2:3], v[0:1], v[14:15]
	v_cvt_pk_bf16_f32 v0, v4, v5
	v_cvt_pk_bf16_f32 v1, v6, v7
	v_cvt_pk_bf16_f32 v2, v2, v3
	v_cvt_pk_bf16_f32 v3, v8, v9
	global_store_dwordx4 v[16:17], v[0:3], off offset:256
	s_cbranch_vccz .LBB1_922
	s_waitcnt vmcnt(0)
	s_cmpk_gt_u32 s17, 0xff
	s_cbranch_scc1 .LBB1_929
	s_barrier

; #define PG8_STAGE(bufoff, gbase, voff) do { _Pragma("unroll") for (int _i = 0; _i < 2; ++_i) \
;         __builtin_amdgcn_global_load_lds((const unsigned*)((const char*)(gbase) + (voff)[_i]), (LAS unsigned*)(lds + (bufoff) + ldsw + _i * 8192), 16, 0, 0); } while (0)
; #define PG8_LDA(dst, b, h) do { _Pragma("unroll") for (int m = 0; m < 4; ++m) _Pragma("unroll") for (int k = 0; k < 2; ++k) dst[m][k] = *(const LAS bf16x8*)(lds + PG8_SA(b, h) + aoff + m * 2048 + k * 1024); } while (0)
; #define PG8_LDB(dst, b, h) do { _Pragma("unroll") for (int n = 0; n < 2; ++n) _Pragma("unroll") for (int k = 0; k < 2; ++k) dst[n][k] = *(const LAS bf16x8*)(lds + PG8_SB(b, h) + boff + n * 2048 + k * 1024); } while (0)
; #define PG8_MMA(ai, bj, At, Bt) do { __builtin_amdgcn_s_setprio(1); _Pragma("unroll") for (int m = 0; m < 4; ++m) _Pragma("unroll") for (int n = 0; n < 2; ++n) _Pragma("unroll") for (int k = 0; k < 2; ++k) \
;         acc[ai][bj][m][n] = __builtin_amdgcn_mfma_f32_16x16x32_bf16(Bt[n][k], At[m][k], acc[ai][bj][m][n], 0, 0, 0); __builtin_amdgcn_s_setprio(0); } while (0)
; #define PG8_WAIT_V(n) asm volatile("s_waitcnt vmcnt(" #n ")" ::: "memory")
; #define PG8_WAIT_L(n) asm volatile("s_waitcnt lgkmcnt(" #n ")" ::: "memory")
; template <class Map, class Epi>
; DI void gemm_phase(LAS unsigned char* lds, const Map& MP, const Epi& E, const int nM, const int nN, const int K, const int lda, const int ldb) {
;     ...
;             const bool last = (t == nt - 2);
;             const char* a1 = cA + (size_t)(t + 1) * kstep;
;             const char* a2 = last ? nA : cA + (size_t)(t + 2) * kstep; const char* b2 = last ? nB : cB + (size_t)(t + 2) * kstep;
;             const char* a3 = a2 + kstep; const char* b3 = b2 + kstep;
;             PG8_LDB(B0, 0, 0); PG8_SCHED; PG8_LDA(At, 0, 0); PG8_STAGE(PG8_SA(1, 1), a1 + hstepA, voffA);
;             PG8_WAIT_L(8); PG8_BAR; PG8_WAIT_L(0); PG8_MMA(0, 0, At, B0); PG8_BAR; PG8_SCHED;
;             PG8_LDB(B1, 0, 1); PG8_STAGE(PG8_SB(0, 0), b2, voffB);
;             PG8_BAR; PG8_WAIT_L(0); PG8_MMA(0, 1, At, B1); PG8_BAR;
;             PG8_LDA(At, 0, 1); PG8_STAGE(PG8_SA(0, 0), a2, voffA);
;             PG8_BAR; PG8_WAIT_L(0); PG8_MMA(1, 0, At, B0); PG8_BAR; PG8_SCHED;
;             PG8_STAGE(PG8_SB(0, 1), b2 + hstepB, voffB);
;             PG8_WAIT_V(6); PG8_BAR; PG8_MMA(1, 1, At, B1); PG8_BAR;
.LBB1_1069:
	s_add_u32 s24, s42, 0xfff80080
	s_addc_u32 s25, s43, -1
	s_cmp_eq_u32 s3, 28
	s_cselect_b32 s47, s23, s25
	s_cselect_b32 s46, s58, s24
	s_cselect_b32 s25, s21, vcc_hi
	s_cselect_b32 s24, s59, vcc_lo
	s_add_i32 m0, s38, 0xc000
	ds_read_b128 v[96:99], v190
	ds_read_b128 v[100:103], v190 offset:1024
	ds_read_b128 v[108:111], v190 offset:2048
	ds_read_b128 v[112:115], v190 offset:3072
	ds_read_b128 v[160:163], v190 offset:4096
	ds_read_b128 v[164:167], v190 offset:5120
	ds_read_b128 v[198:201], v190 offset:6144
	ds_read_b128 v[202:205], v190 offset:7168
	global_load_lds_dwordx4 v178, s[42:43]
	s_add_i32 m0, s38, 0xe000
	s_nop 0
	global_load_lds_dwordx4 v176, s[42:43]
	s_waitcnt lgkmcnt(8)
	s_barrier
	s_setprio 1
	s_waitcnt lgkmcnt(7)
	v_mfma_f32_16x16x32_bf16 v[148:151], v[80:83], v[96:99], v[148:151]
	v_mfma_f32_16x16x32_bf16 v[144:147], v[88:91], v[96:99], v[144:147]
	s_waitcnt lgkmcnt(5)
	v_mfma_f32_16x16x32_bf16 v[136:139], v[80:83], v[108:111], v[136:139]
	v_mfma_f32_16x16x32_bf16 v[128:131], v[88:91], v[108:111], v[128:131]
	s_waitcnt lgkmcnt(3)
	v_mfma_f32_16x16x32_bf16 v[120:123], v[80:83], v[160:163], v[120:123]
	v_mfma_f32_16x16x32_bf16 v[104:107], v[88:91], v[160:163], v[104:107]
	s_waitcnt lgkmcnt(1)
	v_mfma_f32_16x16x32_bf16 v[76:79], v[80:83], v[198:201], v[76:79]
	v_mfma_f32_16x16x32_bf16 v[72:75], v[88:91], v[198:201], v[72:75]
	v_mfma_f32_16x16x32_bf16 v[148:151], v[84:87], v[100:103], v[148:151]
	v_mfma_f32_16x16x32_bf16 v[144:147], v[92:95], v[100:103], v[144:147]
	v_mfma_f32_16x16x32_bf16 v[136:139], v[84:87], v[112:115], v[136:139]
	v_mfma_f32_16x16x32_bf16 v[128:131], v[92:95], v[112:115], v[128:131]
	v_mfma_f32_16x16x32_bf16 v[120:123], v[84:87], v[164:167], v[120:123]
	v_mfma_f32_16x16x32_bf16 v[104:107], v[92:95], v[164:167], v[104:107]
	s_waitcnt lgkmcnt(0)
	v_mfma_f32_16x16x32_bf16 v[76:79], v[84:87], v[202:205], v[76:79]
	v_mfma_f32_16x16x32_bf16 v[72:75], v[92:95], v[202:205], v[72:75]
	s_setprio 0
	s_barrier
	s_add_i32 s68, s31, s66
	v_lshl_add_u64 v[184:185], s[24:25], 0, v[172:173]
	s_mov_b32 m0, s68
	ds_read_b128 v[206:209], v191
	ds_read_b128 v[210:213], v191 offset:1024
	ds_read_b128 v[214:217], v191 offset:2048
	ds_read_b128 v[218:221], v191 offset:3072
	global_load_lds_dwordx4 v[184:185], off
	v_lshl_add_u64 v[194:195], s[24:25], 0, v[168:169]
	s_add_i32 m0, s68, 0x2000
	s_nop 0
	global_load_lds_dwordx4 v[194:195], off
	s_barrier
	s_setprio 1
	s_waitcnt lgkmcnt(3)
	v_mfma_f32_16x16x32_bf16 v[156:159], v[206:209], v[96:99], v[156:159]
	s_waitcnt lgkmcnt(1)
	v_mfma_f32_16x16x32_bf16 v[96:99], v[214:217], v[96:99], v[152:155]
	v_mfma_f32_16x16x32_bf16 v[156:159], v[210:213], v[100:103], v[156:159]
	s_waitcnt lgkmcnt(0)
	v_mfma_f32_16x16x32_bf16 v[96:99], v[218:221], v[100:103], v[96:99]
	v_mfma_f32_16x16x32_bf16 v[100:103], v[206:209], v[108:111], v[140:143]
	v_mfma_f32_16x16x32_bf16 v[108:111], v[214:217], v[108:111], v[132:135]
	v_mfma_f32_16x16x32_bf16 v[116:119], v[214:217], v[160:163], v[116:119]
	v_mfma_f32_16x16x32_bf16 v[68:71], v[206:209], v[198:201], v[68:71]
	v_mfma_f32_16x16x32_bf16 v[64:67], v[214:217], v[198:201], v[64:67]
	s_mov_b32 m0, s38
	v_mfma_f32_16x16x32_bf16 v[100:103], v[210:213], v[112:115], v[100:103]
	v_lshl_add_u64 v[226:227], s[46:47], 0, v[174:175]
	v_mfma_f32_16x16x32_bf16 v[108:111], v[218:221], v[112:115], v[108:111]
	v_mfma_f32_16x16x32_bf16 v[112:115], v[206:209], v[160:163], v[124:127]
	v_mfma_f32_16x16x32_bf16 v[116:119], v[218:221], v[164:167], v[116:119]
	v_mfma_f32_16x16x32_bf16 v[68:71], v[210:213], v[202:205], v[68:71]
	v_mfma_f32_16x16x32_bf16 v[64:67], v[218:221], v[202:205], v[64:67]
	v_mfma_f32_16x16x32_bf16 v[112:115], v[210:213], v[164:167], v[112:115]
	s_setprio 0
	s_barrier
	ds_read_b128 v[124:127], v190 offset:16384
	ds_read_b128 v[132:135], v190 offset:17408
	ds_read_b128 v[140:143], v190 offset:18432
	ds_read_b128 v[152:155], v190 offset:19456
	ds_read_b128 v[160:163], v190 offset:20480
	ds_read_b128 v[164:167], v190 offset:21504
	ds_read_b128 v[198:201], v190 offset:22528
	ds_read_b128 v[202:205], v190 offset:23552
	global_load_lds_dwordx4 v[226:227], off
	v_lshl_add_u64 v[234:235], s[46:47], 0, v[170:171]
	s_mov_b32 m0, s39
	s_nop 0
	global_load_lds_dwordx4 v[234:235], off
	s_waitcnt vmcnt(10)
	s_barrier
	s_setprio 1
	s_waitcnt lgkmcnt(7)
	v_mfma_f32_16x16x32_bf16 v[60:63], v[80:83], v[124:127], v[60:63]
	v_mfma_f32_16x16x32_bf16 v[48:51], v[88:91], v[124:127], v[48:51]
	s_waitcnt lgkmcnt(5)
	v_mfma_f32_16x16x32_bf16 v[40:43], v[80:83], v[140:143], v[40:43]
	v_mfma_f32_16x16x32_bf16 v[32:35], v[88:91], v[140:143], v[32:35]
	s_waitcnt lgkmcnt(3)
	v_mfma_f32_16x16x32_bf16 v[24:27], v[80:83], v[160:163], v[24:27]
	v_mfma_f32_16x16x32_bf16 v[16:19], v[88:91], v[160:163], v[16:19]
	s_waitcnt lgkmcnt(1)
	v_mfma_f32_16x16x32_bf16 v[12:15], v[80:83], v[198:201], v[12:15]
	v_mfma_f32_16x16x32_bf16 v[8:11], v[88:91], v[198:201], v[8:11]
	v_mfma_f32_16x16x32_bf16 v[60:63], v[84:87], v[132:135], v[60:63]
	v_mfma_f32_16x16x32_bf16 v[48:51], v[92:95], v[132:135], v[48:51]
	v_mfma_f32_16x16x32_bf16 v[40:43], v[84:87], v[152:155], v[40:43]
	v_mfma_f32_16x16x32_bf16 v[32:35], v[92:95], v[152:155], v[32:35]
	v_mfma_f32_16x16x32_bf16 v[24:27], v[84:87], v[164:167], v[24:27]
	v_mfma_f32_16x16x32_bf16 v[16:19], v[92:95], v[164:167], v[16:19]
	s_waitcnt lgkmcnt(0)
	v_mfma_f32_16x16x32_bf16 v[12:15], v[84:87], v[202:205], v[12:15]
	v_mfma_f32_16x16x32_bf16 v[8:11], v[92:95], v[202:205], v[8:11]
	s_setprio 0
	s_barrier
	s_add_u32 s68, s24, 0x80000
	s_addc_u32 s69, s25, 0
	s_add_i32 s70, s2, s66
	s_mov_b32 m0, s70
	s_nop 0
	global_load_lds_dwordx4 v172, s[68:69]
	s_add_i32 m0, s70, 0x2000
	s_nop 0
	global_load_lds_dwordx4 v168, s[68:69]
	s_waitcnt vmcnt(6)
	s_barrier
; #define PG8_STAGE(bufoff, gbase, voff) do { _Pragma("unroll") for (int _i = 0; _i < 2; ++_i) \
;         __builtin_amdgcn_global_load_lds((const unsigned*)((const char*)(gbase) + (voff)[_i]), (LAS unsigned*)(lds + (bufoff) + ldsw + _i * 8192), 16, 0, 0); } while (0)
; #define PG8_LDA(dst, b, h) do { _Pragma("unroll") for (int m = 0; m < 4; ++m) _Pragma("unroll") for (int k = 0; k < 2; ++k) dst[m][k] = *(const LAS bf16x8*)(lds + PG8_SA(b, h) + aoff + m * 2048 + k * 1024); } while (0)
; #define PG8_LDB(dst, b, h) do { _Pragma("unroll") for (int n = 0; n < 2; ++n) _Pragma("unroll") for (int k = 0; k < 2; ++k) dst[n][k] = *(const LAS bf16x8*)(lds + PG8_SB(b, h) + boff + n * 2048 + k * 1024); } while (0)
; #define PG8_MMA(ai, bj, At, Bt) do { __builtin_amdgcn_s_setprio(1); _Pragma("unroll") for (int m = 0; m < 4; ++m) _Pragma("unroll") for (int n = 0; n < 2; ++n) _Pragma("unroll") for (int k = 0; k < 2; ++k) \
;         acc[ai][bj][m][n] = __builtin_amdgcn_mfma_f32_16x16x32_bf16(Bt[n][k], At[m][k], acc[ai][bj][m][n], 0, 0, 0); __builtin_amdgcn_s_setprio(0); } while (0)
; #define PG8_WAIT_V(n) asm volatile("s_waitcnt vmcnt(" #n ")" ::: "memory")
; #define PG8_WAIT_L(n) asm volatile("s_waitcnt lgkmcnt(" #n ")" ::: "memory")
; #define PG8_BAR __builtin_amdgcn_s_barrier()
; #define PG8_SCHED __builtin_amdgcn_sched_barrier(0)
; template <class Map, class Epi>
; DI void gemm_phase(LAS unsigned char* lds, const Map& MP, const Epi& E, const int nM, const int nN, const int K, const int lda, const int ldb) {
;     ...
;             PG8_STAGE(PG8_SB(0, 1), b2 + hstepB, voffB);
;             PG8_WAIT_V(6); PG8_BAR; PG8_MMA(1, 1, At, B1); PG8_BAR;
;             PG8_LDB(B0, 1, 0); PG8_SCHED; PG8_LDA(At, 1, 0); PG8_STAGE(PG8_SA(0, 1), a2 + hstepA, voffA);
;             PG8_WAIT_L(8); PG8_BAR; PG8_WAIT_L(0); PG8_MMA(0, 0, At, B0); PG8_BAR; PG8_SCHED;
;             PG8_LDB(B1, 1, 1); PG8_STAGE(PG8_SB(1, 0), b3, voffB);
;             PG8_BAR; PG8_WAIT_L(0); PG8_MMA(0, 1, At, B1); PG8_BAR;
;             PG8_LDA(At, 1, 1); PG8_STAGE(PG8_SA(1, 0), a3, voffA);
;             PG8_BAR; PG8_WAIT_L(0); PG8_MMA(1, 0, At, B0); PG8_BAR; PG8_SCHED;
	s_setprio 1
	v_mfma_f32_16x16x32_bf16 v[56:59], v[206:209], v[124:127], v[56:59]
	v_mfma_f32_16x16x32_bf16 v[52:55], v[214:217], v[124:127], v[52:55]
	s_add_i32 s68, 0, 0x18000
	v_add_u32_e32 v92, s68, v188
	ds_read_b128 v[80:83], v92
	v_mfma_f32_16x16x32_bf16 v[44:47], v[206:209], v[140:143], v[44:47]
	v_mfma_f32_16x16x32_bf16 v[36:39], v[214:217], v[140:143], v[36:39]
	ds_read_b128 v[84:87], v92 offset:1024
	v_mfma_f32_16x16x32_bf16 v[28:31], v[206:209], v[160:163], v[28:31]
	v_mfma_f32_16x16x32_bf16 v[20:23], v[214:217], v[160:163], v[20:23]
	ds_read_b128 v[88:91], v92 offset:2048
	v_mfma_f32_16x16x32_bf16 v[4:7], v[206:209], v[198:201], v[4:7]
	v_mfma_f32_16x16x32_bf16 v[0:3], v[214:217], v[198:201], v[0:3]
	ds_read_b128 v[92:95], v92 offset:3072
	v_mfma_f32_16x16x32_bf16 v[56:59], v[210:213], v[132:135], v[56:59]
	v_mfma_f32_16x16x32_bf16 v[52:55], v[218:221], v[132:135], v[52:55]
	v_mfma_f32_16x16x32_bf16 v[44:47], v[210:213], v[152:155], v[44:47]
	v_mfma_f32_16x16x32_bf16 v[36:39], v[218:221], v[152:155], v[36:39]
	v_mfma_f32_16x16x32_bf16 v[28:31], v[210:213], v[164:167], v[28:31]
	v_mfma_f32_16x16x32_bf16 v[20:23], v[218:221], v[164:167], v[20:23]
	v_mfma_f32_16x16x32_bf16 v[4:7], v[210:213], v[202:205], v[4:7]
	v_mfma_f32_16x16x32_bf16 v[0:3], v[218:221], v[202:205], v[0:3]
	s_setprio 0
	s_barrier
	s_add_u32 s46, s46, 0x80000
	s_addc_u32 s47, s47, 0
	s_mov_b32 m0, s56
	ds_read_b128 v[124:127], v190 offset:32768
	ds_read_b128 v[132:135], v190 offset:33792
	ds_read_b128 v[160:163], v190 offset:34816
	ds_read_b128 v[164:167], v190 offset:35840
	ds_read_b128 v[198:201], v190 offset:36864
	ds_read_b128 v[202:205], v190 offset:37888
	ds_read_b128 v[206:209], v190 offset:38912
	ds_read_b128 v[210:213], v190 offset:39936
	global_load_lds_dwordx4 v174, s[46:47]
	s_mov_b32 m0, s57
	s_nop 0
	global_load_lds_dwordx4 v170, s[46:47]
	s_waitcnt lgkmcnt(8)
	s_barrier
	s_setprio 1
	s_waitcnt lgkmcnt(7)
	v_mfma_f32_16x16x32_bf16 v[140:143], v[80:83], v[124:127], v[148:151]
	s_waitcnt lgkmcnt(6)
	v_mfma_f32_16x16x32_bf16 v[148:151], v[84:87], v[132:135], v[140:143]
	v_mfma_f32_16x16x32_bf16 v[140:143], v[88:91], v[124:127], v[144:147]
	s_waitcnt lgkmcnt(5)
	v_mfma_f32_16x16x32_bf16 v[136:139], v[80:83], v[160:163], v[136:139]
	v_mfma_f32_16x16x32_bf16 v[128:131], v[88:91], v[160:163], v[128:131]
	s_waitcnt lgkmcnt(3)
	v_mfma_f32_16x16x32_bf16 v[120:123], v[80:83], v[198:201], v[120:123]
	v_mfma_f32_16x16x32_bf16 v[104:107], v[88:91], v[198:201], v[104:107]
	s_waitcnt lgkmcnt(1)
	v_mfma_f32_16x16x32_bf16 v[76:79], v[80:83], v[206:209], v[76:79]
	v_mfma_f32_16x16x32_bf16 v[72:75], v[88:91], v[206:209], v[72:75]
	v_mfma_f32_16x16x32_bf16 v[144:147], v[92:95], v[132:135], v[140:143]
	v_mfma_f32_16x16x32_bf16 v[136:139], v[84:87], v[164:167], v[136:139]
	v_mfma_f32_16x16x32_bf16 v[128:131], v[92:95], v[164:167], v[128:131]
	v_mfma_f32_16x16x32_bf16 v[120:123], v[84:87], v[202:205], v[120:123]
	v_mfma_f32_16x16x32_bf16 v[104:107], v[92:95], v[202:205], v[104:107]
	s_waitcnt lgkmcnt(0)
	v_mfma_f32_16x16x32_bf16 v[76:79], v[84:87], v[210:213], v[76:79]
	v_mfma_f32_16x16x32_bf16 v[72:75], v[92:95], v[210:213], v[72:75]
	s_setprio 0
	s_barrier
	s_add_i32 s46, 0, 0x1c000
	v_add_u32_e32 v140, s46, v188
	s_add_i32 s47, s68, s66
	ds_read_b128 v[214:217], v140
	ds_read_b128 v[218:221], v140 offset:1024
	ds_read_b128 v[222:225], v140 offset:2048
	ds_read_b128 v[230:233], v140 offset:3072
	v_lshl_add_u64 v[140:141], v[184:185], 0, s[14:15]
	s_mov_b32 m0, s47
	s_nop 0
	global_load_lds_dwordx4 v[140:141], off
	v_lshl_add_u64 v[140:141], v[194:195], 0, s[14:15]
	s_add_i32 m0, s47, 0x2000
	s_nop 0
	global_load_lds_dwordx4 v[140:141], off
	s_barrier
	s_setprio 1
	s_waitcnt lgkmcnt(1)
	v_mfma_f32_16x16x32_bf16 v[96:99], v[222:225], v[124:127], v[96:99]
	v_mfma_f32_16x16x32_bf16 v[140:143], v[214:217], v[124:127], v[156:159]
	s_waitcnt lgkmcnt(0)
	v_mfma_f32_16x16x32_bf16 v[152:155], v[230:233], v[132:135], v[96:99]
	v_mfma_f32_16x16x32_bf16 v[96:99], v[214:217], v[160:163], v[100:103]
	v_mfma_f32_16x16x32_bf16 v[156:159], v[218:221], v[132:135], v[140:143]
	v_mfma_f32_16x16x32_bf16 v[140:143], v[218:221], v[164:167], v[96:99]
	v_mfma_f32_16x16x32_bf16 v[96:99], v[222:225], v[160:163], v[108:111]
	v_mfma_f32_16x16x32_bf16 v[132:135], v[230:233], v[164:167], v[96:99]
	v_mfma_f32_16x16x32_bf16 v[96:99], v[214:217], v[198:201], v[112:115]
	s_mov_b32 m0, s63
	v_mfma_f32_16x16x32_bf16 v[124:127], v[218:221], v[202:205], v[96:99]
	v_lshl_add_u64 v[184:185], v[226:227], 0, s[14:15]
	v_mfma_f32_16x16x32_bf16 v[96:99], v[222:225], v[198:201], v[116:119]
	v_mfma_f32_16x16x32_bf16 v[68:71], v[214:217], v[206:209], v[68:71]
	v_mfma_f32_16x16x32_bf16 v[64:67], v[222:225], v[206:209], v[64:67]
	v_mfma_f32_16x16x32_bf16 v[116:119], v[230:233], v[202:205], v[96:99]
	v_mfma_f32_16x16x32_bf16 v[68:71], v[218:221], v[210:213], v[68:71]
	v_mfma_f32_16x16x32_bf16 v[64:67], v[230:233], v[210:213], v[64:67]
	s_setprio 0
	s_barrier
	ds_read_b128 v[96:99], v190 offset:49152
	ds_read_b128 v[100:103], v190 offset:50176
	ds_read_b128 v[108:111], v190 offset:51200
	ds_read_b128 v[112:115], v190 offset:52224
	ds_read_b128 v[160:163], v190 offset:53248
	ds_read_b128 v[164:167], v190 offset:54272
	ds_read_b128 v[198:201], v190 offset:55296
	ds_read_b128 v[202:205], v190 offset:56320
	global_load_lds_dwordx4 v[184:185], off
	v_lshl_add_u64 v[184:185], v[234:235], 0, s[14:15]
	s_mov_b32 m0, s4
	s_nop 0
	global_load_lds_dwordx4 v[184:185], off
	s_waitcnt vmcnt(10)
	s_barrier
; #define PG8_STAGE(bufoff, gbase, voff) do { _Pragma("unroll") for (int _i = 0; _i < 2; ++_i) \
;         __builtin_amdgcn_global_load_lds((const unsigned*)((const char*)(gbase) + (voff)[_i]), (LAS unsigned*)(lds + (bufoff) + ldsw + _i * 8192), 16, 0, 0); } while (0)
; #define PG8_LDA(dst, b, h) do { _Pragma("unroll") for (int m = 0; m < 4; ++m) _Pragma("unroll") for (int k = 0; k < 2; ++k) dst[m][k] = *(const LAS bf16x8*)(lds + PG8_SA(b, h) + aoff + m * 2048 + k * 1024); } while (0)
; #define PG8_MMA(ai, bj, At, Bt) do { __builtin_amdgcn_s_setprio(1); _Pragma("unroll") for (int m = 0; m < 4; ++m) _Pragma("unroll") for (int n = 0; n < 2; ++n) _Pragma("unroll") for (int k = 0; k < 2; ++k) \
;         acc[ai][bj][m][n] = __builtin_amdgcn_mfma_f32_16x16x32_bf16(Bt[n][k], At[m][k], acc[ai][bj][m][n], 0, 0, 0); __builtin_amdgcn_s_setprio(0); } while (0)
; #define PG8_WAIT_V(n) asm volatile("s_waitcnt vmcnt(" #n ")" ::: "memory")
; #define PG8_WAIT_L(n) asm volatile("s_waitcnt lgkmcnt(" #n ")" ::: "memory")
; #define PG8_BAR __builtin_amdgcn_s_barrier()
; #define PG8_SCHED __builtin_amdgcn_sched_barrier(0)
; template <class Map, class Epi>
; DI void gemm_phase(LAS unsigned char* lds, const Map& MP, const Epi& E, const int nM, const int nN, const int K, const int lda, const int ldb) {
;     ...
;             PG8_BAR; PG8_WAIT_L(0); PG8_MMA(0, 1, At, B1); PG8_BAR;
;             PG8_LDA(At, 1, 1); PG8_STAGE(PG8_SA(1, 0), a3, voffA);
;             PG8_BAR; PG8_WAIT_L(0); PG8_MMA(1, 0, At, B0); PG8_BAR; PG8_SCHED;
;             PG8_STAGE(PG8_SB(1, 1), b3 + hstepB, voffB);
;             PG8_WAIT_V(6); PG8_BAR; PG8_MMA(1, 1, At, B1); PG8_BAR;
	s_setprio 1
	s_waitcnt lgkmcnt(7)
	v_mfma_f32_16x16x32_bf16 v[60:63], v[80:83], v[96:99], v[60:63]
	v_mfma_f32_16x16x32_bf16 v[48:51], v[88:91], v[96:99], v[48:51]
	s_waitcnt lgkmcnt(5)
	v_mfma_f32_16x16x32_bf16 v[40:43], v[80:83], v[108:111], v[40:43]
	v_mfma_f32_16x16x32_bf16 v[32:35], v[88:91], v[108:111], v[32:35]
	s_waitcnt lgkmcnt(3)
	v_mfma_f32_16x16x32_bf16 v[24:27], v[80:83], v[160:163], v[24:27]
	v_mfma_f32_16x16x32_bf16 v[16:19], v[88:91], v[160:163], v[16:19]
	s_waitcnt lgkmcnt(1)
	v_mfma_f32_16x16x32_bf16 v[12:15], v[80:83], v[198:201], v[12:15]
	v_mfma_f32_16x16x32_bf16 v[8:11], v[88:91], v[198:201], v[8:11]
	v_mfma_f32_16x16x32_bf16 v[60:63], v[84:87], v[100:103], v[60:63]
	v_mfma_f32_16x16x32_bf16 v[48:51], v[92:95], v[100:103], v[48:51]
	v_mfma_f32_16x16x32_bf16 v[40:43], v[84:87], v[112:115], v[40:43]
	v_mfma_f32_16x16x32_bf16 v[32:35], v[92:95], v[112:115], v[32:35]
	v_mfma_f32_16x16x32_bf16 v[24:27], v[84:87], v[164:167], v[24:27]
	v_mfma_f32_16x16x32_bf16 v[16:19], v[92:95], v[164:167], v[16:19]
	s_waitcnt lgkmcnt(0)
	v_mfma_f32_16x16x32_bf16 v[12:15], v[84:87], v[202:205], v[12:15]
	v_mfma_f32_16x16x32_bf16 v[8:11], v[92:95], v[202:205], v[8:11]
	s_setprio 0
	s_barrier
	s_add_u32 s24, s24, 0x80080
	s_addc_u32 s25, s25, 0
	s_add_i32 s46, s46, s66
	s_mov_b32 m0, s46
	s_nop 0
	global_load_lds_dwordx4 v172, s[24:25]
	s_add_i32 m0, s46, 0x2000
	s_nop 0
	global_load_lds_dwordx4 v168, s[24:25]
	s_waitcnt vmcnt(6)
	s_barrier
	s_setprio 1
	v_mfma_f32_16x16x32_bf16 v[56:59], v[214:217], v[96:99], v[56:59]
	v_mfma_f32_16x16x32_bf16 v[52:55], v[222:225], v[96:99], v[52:55]
	ds_read_b128 v[80:83], v189
	v_mfma_f32_16x16x32_bf16 v[44:47], v[214:217], v[108:111], v[44:47]
	v_mfma_f32_16x16x32_bf16 v[36:39], v[222:225], v[108:111], v[36:39]
	ds_read_b128 v[84:87], v189 offset:1024
	v_mfma_f32_16x16x32_bf16 v[28:31], v[214:217], v[160:163], v[28:31]
	v_mfma_f32_16x16x32_bf16 v[20:23], v[222:225], v[160:163], v[20:23]
	ds_read_b128 v[88:91], v189 offset:2048
	v_mfma_f32_16x16x32_bf16 v[4:7], v[214:217], v[198:201], v[4:7]
	v_mfma_f32_16x16x32_bf16 v[0:3], v[222:225], v[198:201], v[0:3]
	ds_read_b128 v[92:95], v189 offset:3072
	v_mfma_f32_16x16x32_bf16 v[56:59], v[218:221], v[100:103], v[56:59]
	s_add_i32 s3, s3, 2
	v_mfma_f32_16x16x32_bf16 v[52:55], v[230:233], v[100:103], v[52:55]
	s_add_u32 vcc_lo, vcc_lo, 0x100
	s_addc_u32 vcc_hi, vcc_hi, 0
	v_mfma_f32_16x16x32_bf16 v[44:47], v[218:221], v[112:115], v[44:47]
	s_add_u32 s42, s42, 0x100
	s_addc_u32 s43, s43, 0
	v_mfma_f32_16x16x32_bf16 v[36:39], v[230:233], v[112:115], v[36:39]
	s_cmp_gt_u32 s3, 29
	v_mfma_f32_16x16x32_bf16 v[28:31], v[218:221], v[164:167], v[28:31]
	v_mfma_f32_16x16x32_bf16 v[20:23], v[230:233], v[164:167], v[20:23]
	v_mfma_f32_16x16x32_bf16 v[4:7], v[218:221], v[202:205], v[4:7]
	v_mfma_f32_16x16x32_bf16 v[0:3], v[230:233], v[202:205], v[0:3]
	s_setprio 0
	s_barrier
	s_cbranch_scc0 .LBB1_1069
; DI float silu_mul(float g, float v) { return g * v * __builtin_amdgcn_rcpf(1.0f + __builtin_amdgcn_exp2f(-LOG2E * g)); }
;     DI void operator()(const f32x4 (&acc)[2][2][4][2], const Unit& u, int wr, int wc, int fr, int fq) const {
;         const int row0 = u.pm * BM + wr * 64 + fr, ch0 = u.pn * 128 + wc * 32 + 8 * fq;
;         f32x4 w0[2], w1[2], w2[2], bb[2];
; #pragma unroll
;         for (int n = 0; n < 2; ++n) { w0[n] = *(const f32x4*)(cw + ch0 + 4 * n); w1[n] = *(const f32x4*)(cw + DFF + ch0 + 4 * n); w2[n] = *(const f32x4*)(cw + 2 * DFF + ch0 + 4 * n); bb[n] = *(const f32x4*)(cb + ch0 + 4 * n); }
; #pragma unroll
;         for (int ai = 0; ai < 2; ++ai)
; #pragma unroll
;             for (int m = 0; m < 4; ++m) {
;                 const bool efirst = (m == 0) && (fr == 0), elast = (m == 3) && (fr == 15);
;                 const int row = row0 + ai * HALF + m * 16;
;                 f32x4 gc[2];
; #pragma unroll
;                 for (int n = 0; n < 2; ++n) {
;                     const f32x4 g = acc[ai][0][m][n];
;                     const f32x4 gprev = acc[ai][0][m > 0 ? m - 1 : 0][n], gnext = acc[ai][0][m < 3 ? m + 1 : 3][n];
;                     f32x4 up, dn;
; #pragma unroll
;                     for (int e = 0; e < 4; ++e) {
;                         const float pu = (m > 0 && fr == 15) ? gprev[e] : g[e];
;                         const float pd = (m < 3 && fr == 0) ? gnext[e] : g[e];
;                         up[e] = dpp_ror1(pu); dn[e] = dpp_ror15(pd);
;                     }
;                     if (efirst) up = (f32x4){0.f, 0.f, 0.f, 0.f};
;                     if (elast) dn = (f32x4){0.f, 0.f, 0.f, 0.f};
;                     gc[n] = w0[n] * up + w1[n] * g + w2[n] * dn + bb[n];
;                 }
;                 if (efirst || elast) {
;                     const size_t eo = (size_t)((row >> 6) * 2 + (elast ? 1 : 0)) * DFF + ch0;
; #pragma unroll
;                     for (int n = 0; n < 2; ++n) { *(f32x4*)(EP + eo + 4 * n) = gc[n]; *(f32x4*)(ER + eo + 4 * n) = acc[ai][0][m][n]; *(f32x4*)(EV + eo + 4 * n) = acc[ai][1][m][n]; }
;                 } else {
;                     const f32x4 v0 = acc[ai][1][m][0], v1 = acc[ai][1][m][1];
;                     u32x4 o;
;                     o[0] = pack2(silu_mul(gc[0][0], v0[0]), silu_mul(gc[0][1], v0[1])); o[1] = pack2(silu_mul(gc[0][2], v0[2]), silu_mul(gc[0][3], v0[3]));
	s_waitcnt lgkmcnt(0)
	s_lshl_b32 s21, s45, 7
	v_mov_b32_e32 v194, v186
	v_mov_b32_e32 v80, v187
	s_or_b32 s21, s21, s62
	v_mov_b32_e32 v160, 0
	v_lshl_add_u32 v184, v80, 3, s21
	v_ashrrev_i32_e32 v185, 31, v184
	v_lshlrev_b64 v[80:81], 2, v[184:185]
	v_lshl_add_u64 v[84:85], s[6:7], 0, v[80:81]
	v_lshl_add_u64 v[88:89], s[16:17], 0, v[80:81]
	v_lshl_add_u64 v[92:93], s[18:19], 0, v[80:81]
	v_lshl_add_u64 v[112:113], s[52:53], 0, v[80:81]
	global_load_dwordx4 v[80:83], v[84:85], off offset:16
	global_load_dwordx4 v[96:99], v[84:85], off
	s_nop 0
	global_load_dwordx4 v[84:87], v[88:89], off offset:16
	global_load_dwordx4 v[100:103], v[88:89], off
	s_nop 0
	global_load_dwordx4 v[88:91], v[92:93], off offset:16
	global_load_dwordx4 v[108:111], v[92:93], off
	s_nop 0
	global_load_dwordx4 v[92:95], v[112:113], off offset:16
	s_nop 0
	global_load_dwordx4 v[112:115], v[112:113], off
	v_cmp_eq_u32_e32 vcc, 0, v194
	v_mov_b32_e32 v164, 0
	v_mov_b32_e32 v195, 0
	v_cndmask_b32_e32 v161, v148, v136, vcc
	v_cndmask_b32_e32 v162, v149, v137, vcc
	v_cndmask_b32_e32 v163, v150, v138, vcc
	v_mov_b32_dpp v160, v161 row_ror:15 row_mask:0xf bank_mask:0xf
	v_mov_b32_e32 v161, 0
	v_mov_b32_e32 v166, 0
	v_mov_b32_e32 v167, 0
	v_mov_b32_dpp v161, v162 row_ror:15 row_mask:0xf bank_mask:0xf
	v_mov_b32_e32 v162, 0
	v_mov_b32_dpp v164, v150 row_ror:1 row_mask:0xf bank_mask:0xf
	v_cndmask_b32_e32 v165, v151, v139, vcc
	v_mov_b32_dpp v162, v163 row_ror:15 row_mask:0xf bank_mask:0xf
	v_mov_b32_dpp v195, v151 row_ror:1 row_mask:0xf bank_mask:0xf
	v_mov_b32_e32 v163, 0
	v_mov_b32_dpp v166, v148 row_ror:1 row_mask:0xf bank_mask:0xf
	v_mov_b32_dpp v167, v149 row_ror:1 row_mask:0xf bank_mask:0xf
	v_mov_b32_dpp v163, v165 row_ror:15 row_mask:0xf bank_mask:0xf
	v_cndmask_b32_e64 v165, v195, 0, vcc
	v_cndmask_b32_e64 v164, v164, 0, vcc
	v_cndmask_b32_e64 v167, v167, 0, vcc
	v_cndmask_b32_e64 v166, v166, 0, vcc
	v_mov_b32_e32 v195, 0
	v_mov_b32_e32 v196, 0
	v_mov_b32_e32 v198, 0
	v_mov_b32_e32 v200, 0
	v_mov_b32_dpp v195, v144 row_ror:1 row_mask:0xf bank_mask:0xf
	v_mov_b32_dpp v196, v145 row_ror:1 row_mask:0xf bank_mask:0xf
	v_mov_b32_dpp v198, v146 row_ror:1 row_mask:0xf bank_mask:0xf
	v_cndmask_b32_e32 v199, v147, v131, vcc
	v_mov_b32_dpp v200, v147 row_ror:1 row_mask:0xf bank_mask:0xf
	v_cndmask_b32_e64 v198, v198, 0, vcc
	v_cndmask_b32_e64 v201, v196, 0, vcc
	s_lshl_b32 s3, s44, 8
	s_add_i32 s3, s3, s49
	v_add_u32_e32 v193, s3, v194
	v_cmp_ne_u32_e64 s[46:47], 0, v194
	s_waitcnt vmcnt(0)
	v_pk_mul_f32 v[164:165], v[98:99], v[164:165]
	v_pk_mul_f32 v[166:167], v[96:97], v[166:167]
	v_pk_fma_f32 v[164:165], v[150:151], v[102:103], v[164:165]
	v_pk_fma_f32 v[166:167], v[148:149], v[100:101], v[166:167]
	v_pk_fma_f32 v[162:163], v[110:111], v[162:163], v[164:165]
	v_cndmask_b32_e32 v165, v144, v128, vcc
	v_mov_b32_e32 v164, 0
	v_pk_fma_f32 v[160:161], v[108:109], v[160:161], v[166:167]
	v_cndmask_b32_e32 v166, v145, v129, vcc
	v_mov_b32_dpp v164, v165 row_ror:15 row_mask:0xf bank_mask:0xf
	v_mov_b32_e32 v165, 0
	v_cndmask_b32_e32 v167, v146, v130, vcc
	v_pk_add_f32 v[162:163], v[114:115], v[162:163]
	v_mov_b32_dpp v165, v166 row_ror:15 row_mask:0xf bank_mask:0xf
	v_mov_b32_e32 v166, 0
	v_pk_add_f32 v[160:161], v[112:113], v[160:161]
	s_nop 0
	v_mov_b32_dpp v166, v167 row_ror:15 row_mask:0xf bank_mask:0xf
	v_mov_b32_e32 v167, 0
	s_nop 1
	v_mov_b32_dpp v167, v199 row_ror:15 row_mask:0xf bank_mask:0xf
	v_cndmask_b32_e64 v199, v200, 0, vcc
	v_cndmask_b32_e64 v200, v195, 0, vcc
	v_pk_mul_f32 v[200:201], v[80:81], v[200:201]
	v_pk_mul_f32 v[198:199], v[82:83], v[198:199]
	v_pk_fma_f32 v[200:201], v[144:145], v[84:85], v[200:201]
	v_pk_fma_f32 v[198:199], v[146:147], v[86:87], v[198:199]
	v_pk_fma_f32 v[164:165], v[88:89], v[164:165], v[200:201]
	v_pk_fma_f32 v[166:167], v[90:91], v[166:167], v[198:199]
	v_pk_add_f32 v[164:165], v[92:93], v[164:165]
	v_pk_add_f32 v[166:167], v[94:95], v[166:167]
	s_and_saveexec_b64 s[24:25], s[46:47]
	s_xor_b64 s[24:25], exec, s[24:25]
	s_cbranch_execz .LBB1_1072
	v_mul_f32_e32 v195, 0xbfb8aa3b, v160
	v_exp_f32_e32 v195, v195
	v_mul_f32_e32 v196, 0xbfb8aa3b, v161
	v_exp_f32_e32 v196, v196
	v_pk_mul_f32 v[160:161], v[156:157], v[160:161]
	v_add_f32_e32 v195, 1.0, v195
	v_rcp_f32_e32 v198, v195
	v_add_f32_e32 v196, 1.0, v196
	v_mul_f32_e32 v195, 0xbfb8aa3b, v162
	v_rcp_f32_e32 v199, v196
	v_exp_f32_e32 v195, v195
	v_mul_f32_e32 v196, 0xbfb8aa3b, v163
	v_exp_f32_e32 v196, v196
	v_pk_mul_f32 v[160:161], v[160:161], v[198:199]
	v_add_f32_e32 v195, 1.0, v195
	v_rcp_f32_e32 v200, v195
	v_add_f32_e32 v195, 1.0, v196
	v_rcp_f32_e32 v201, v195
	v_cvt_pk_bf16_f32 v160, v160, v161
	v_mul_f32_e32 v161, 0xbfb8aa3b, v164
	v_exp_f32_e32 v195, v161
	v_mul_f32_e32 v161, 0xbfb8aa3b, v165
	v_exp_f32_e32 v196, v161
	v_pk_mul_f32 v[162:163], v[158:159], v[162:163]
	v_pk_mul_f32 v[164:165], v[152:153], v[164:165]
	v_pk_mul_f32 v[162:163], v[162:163], v[200:201]
	s_nop 0
	v_cvt_pk_bf16_f32 v161, v162, v163
	v_add_f32_e32 v162, 1.0, v195
	v_mul_f32_e32 v195, 0xbfb8aa3b, v166
	v_add_f32_e32 v163, 1.0, v196
	v_exp_f32_e32 v195, v195
	v_mul_f32_e32 v196, 0xbfb8aa3b, v167
	v_exp_f32_e32 v196, v196
	v_rcp_f32_e32 v162, v162
	v_add_f32_e32 v195, 1.0, v195
	v_rcp_f32_e32 v198, v195
	v_add_f32_e32 v195, 1.0, v196
	v_rcp_f32_e32 v163, v163
	v_rcp_f32_e32 v199, v195
	v_pk_mul_f32 v[166:167], v[154:155], v[166:167]
	v_pk_mul_f32 v[162:163], v[164:165], v[162:163]
	v_pk_mul_f32 v[164:165], v[166:167], v[198:199]
	v_cvt_pk_bf16_f32 v162, v162, v163
	v_cvt_pk_bf16_f32 v163, v164, v165
	v_mov_b64_e32 v[164:165], s[54:55]
	v_mad_i64_i32 v[164:165], s[42:43], v193, s60, v[164:165]
	v_lshl_add_u64 v[164:165], v[184:185], 1, v[164:165]
	global_store_dwordx4 v[164:165], v[160:163], off

; #define PG8_STAGE(bufoff, gbase, voff) do { _Pragma("unroll") for (int _i = 0; _i < 2; ++_i) \
;         __builtin_amdgcn_global_load_lds((const unsigned*)((const char*)(gbase) + (voff)[_i]), (LAS unsigned*)(lds + (bufoff) + ldsw + _i * 8192), 16, 0, 0); } while (0)
; #define PG8_LDA(dst, b, h) do { _Pragma("unroll") for (int m = 0; m < 4; ++m) _Pragma("unroll") for (int k = 0; k < 2; ++k) dst[m][k] = *(const LAS bf16x8*)(lds + PG8_SA(b, h) + aoff + m * 2048 + k * 1024); } while (0)
; #define PG8_LDB(dst, b, h) do { _Pragma("unroll") for (int n = 0; n < 2; ++n) _Pragma("unroll") for (int k = 0; k < 2; ++k) dst[n][k] = *(const LAS bf16x8*)(lds + PG8_SB(b, h) + boff + n * 2048 + k * 1024); } while (0)
; #define PG8_MMA(ai, bj, At, Bt) do { __builtin_amdgcn_s_setprio(1); _Pragma("unroll") for (int m = 0; m < 4; ++m) _Pragma("unroll") for (int n = 0; n < 2; ++n) _Pragma("unroll") for (int k = 0; k < 2; ++k) \
;         acc[ai][bj][m][n] = __builtin_amdgcn_mfma_f32_16x16x32_bf16(Bt[n][k], At[m][k], acc[ai][bj][m][n], 0, 0, 0); __builtin_amdgcn_s_setprio(0); } while (0)
; #define PG8_WAIT_V(n) asm volatile("s_waitcnt vmcnt(" #n ")" ::: "memory")
; #define PG8_WAIT_L(n) asm volatile("s_waitcnt lgkmcnt(" #n ")" ::: "memory")
; template <class Map, class Epi>
; DI void gemm_phase(LAS unsigned char* lds, const Map& MP, const Epi& E, const int nM, const int nN, const int K, const int lda, const int ldb) {
;     ...
;             const bool last = (t == nt - 2);
;             const char* a1 = cA + (size_t)(t + 1) * kstep;
;             const char* a2 = last ? nA : cA + (size_t)(t + 2) * kstep; const char* b2 = last ? nB : cB + (size_t)(t + 2) * kstep;
;             const char* a3 = a2 + kstep; const char* b3 = b2 + kstep;
;             PG8_LDB(B0, 0, 0); PG8_SCHED; PG8_LDA(At, 0, 0); PG8_STAGE(PG8_SA(1, 1), a1 + hstepA, voffA);
;             PG8_WAIT_L(8); PG8_BAR; PG8_WAIT_L(0); PG8_MMA(0, 0, At, B0); PG8_BAR; PG8_SCHED;
;             PG8_LDB(B1, 0, 1); PG8_STAGE(PG8_SB(0, 0), b2, voffB);
;             PG8_BAR; PG8_WAIT_L(0); PG8_MMA(0, 1, At, B1); PG8_BAR;
;             PG8_LDA(At, 0, 1); PG8_STAGE(PG8_SA(0, 0), a2, voffA);
;             PG8_BAR; PG8_WAIT_L(0); PG8_MMA(1, 0, At, B0); PG8_BAR; PG8_SCHED;
;             PG8_STAGE(PG8_SB(0, 1), b2 + hstepB, voffB);
;             PG8_WAIT_V(6); PG8_BAR; PG8_MMA(1, 1, At, B1); PG8_BAR;
.LBB1_1239:
	s_add_u32 s10, s8, 0x100
	s_addc_u32 s11, s9, 0
	s_cmpk_eq_i32 s3, 0x54
	s_cselect_b32 s15, s43, s11
	s_cselect_b32 s14, s42, s10
	s_cselect_b32 s13, s7, s38
	s_cselect_b32 s12, s6, s5
	s_add_i32 m0, s24, 0xc000
	ds_read_b128 v[168:171], v150
	ds_read_b128 v[172:175], v150 offset:1024
	ds_read_b128 v[176:179], v150 offset:2048
	ds_read_b128 v[180:183], v150 offset:3072
	ds_read_b128 v[184:187], v150 offset:4096
	ds_read_b128 v[188:191], v150 offset:5120
	ds_read_b128 v[192:195], v150 offset:6144
	ds_read_b128 v[198:201], v150 offset:7168
	global_load_lds_dwordx4 v138, s[8:9]
	s_add_i32 m0, s24, 0xe000
	s_nop 0
	global_load_lds_dwordx4 v136, s[8:9]
	s_waitcnt lgkmcnt(8)
	s_barrier
	s_setprio 1
	s_waitcnt lgkmcnt(7)
	v_mfma_f32_16x16x32_bf16 v[124:127], v[152:155], v[168:171], v[124:127]
	v_mfma_f32_16x16x32_bf16 v[120:123], v[160:163], v[168:171], v[120:123]
	s_waitcnt lgkmcnt(5)
	v_mfma_f32_16x16x32_bf16 v[108:111], v[152:155], v[176:179], v[108:111]
	v_mfma_f32_16x16x32_bf16 v[104:107], v[160:163], v[176:179], v[104:107]
	s_waitcnt lgkmcnt(3)
	v_mfma_f32_16x16x32_bf16 v[92:95], v[152:155], v[184:187], v[92:95]
	v_mfma_f32_16x16x32_bf16 v[88:91], v[160:163], v[184:187], v[88:91]
	s_waitcnt lgkmcnt(1)
	v_mfma_f32_16x16x32_bf16 v[76:79], v[152:155], v[192:195], v[76:79]
	v_mfma_f32_16x16x32_bf16 v[72:75], v[160:163], v[192:195], v[72:75]
	v_mfma_f32_16x16x32_bf16 v[124:127], v[156:159], v[172:175], v[124:127]
	v_mfma_f32_16x16x32_bf16 v[120:123], v[164:167], v[172:175], v[120:123]
	v_mfma_f32_16x16x32_bf16 v[108:111], v[156:159], v[180:183], v[108:111]
	v_mfma_f32_16x16x32_bf16 v[104:107], v[164:167], v[180:183], v[104:107]
	v_mfma_f32_16x16x32_bf16 v[92:95], v[156:159], v[188:191], v[92:95]
	v_mfma_f32_16x16x32_bf16 v[88:91], v[164:167], v[188:191], v[88:91]
	s_waitcnt lgkmcnt(0)
	v_mfma_f32_16x16x32_bf16 v[76:79], v[156:159], v[198:201], v[76:79]
	v_mfma_f32_16x16x32_bf16 v[72:75], v[164:167], v[198:201], v[72:75]
	s_setprio 0
	s_barrier
	s_add_i32 s8, s35, s22
	v_lshl_add_u64 v[144:145], s[12:13], 0, v[132:133]
	s_mov_b32 m0, s8
	ds_read_b128 v[202:205], v151
	ds_read_b128 v[206:209], v151 offset:1024
	ds_read_b128 v[210:213], v151 offset:2048
	ds_read_b128 v[214:217], v151 offset:3072
	global_load_lds_dwordx4 v[144:145], off
	v_lshl_add_u64 v[218:219], s[12:13], 0, v[128:129]
	s_add_i32 m0, s8, 0x2000
	s_nop 0
	global_load_lds_dwordx4 v[218:219], off
	s_barrier
	s_setprio 1
	s_waitcnt lgkmcnt(3)
	v_mfma_f32_16x16x32_bf16 v[116:119], v[202:205], v[168:171], v[116:119]
	s_waitcnt lgkmcnt(1)
	v_mfma_f32_16x16x32_bf16 v[112:115], v[210:213], v[168:171], v[112:115]
	v_mfma_f32_16x16x32_bf16 v[100:103], v[202:205], v[176:179], v[100:103]
	v_mfma_f32_16x16x32_bf16 v[96:99], v[210:213], v[176:179], v[96:99]
	v_mfma_f32_16x16x32_bf16 v[84:87], v[202:205], v[184:187], v[84:87]
	v_mfma_f32_16x16x32_bf16 v[80:83], v[210:213], v[184:187], v[80:83]
	v_mfma_f32_16x16x32_bf16 v[68:71], v[202:205], v[192:195], v[68:71]
	v_mfma_f32_16x16x32_bf16 v[64:67], v[210:213], v[192:195], v[64:67]
	v_mfma_f32_16x16x32_bf16 v[116:119], v[206:209], v[172:175], v[116:119]
	s_mov_b32 m0, s24
	s_waitcnt lgkmcnt(0)
	v_mfma_f32_16x16x32_bf16 v[112:115], v[214:217], v[172:175], v[112:115]
	v_lshl_add_u64 v[220:221], s[14:15], 0, v[134:135]
	v_mfma_f32_16x16x32_bf16 v[100:103], v[206:209], v[180:183], v[100:103]
	v_mfma_f32_16x16x32_bf16 v[96:99], v[214:217], v[180:183], v[96:99]
	v_mfma_f32_16x16x32_bf16 v[84:87], v[206:209], v[188:191], v[84:87]
	v_mfma_f32_16x16x32_bf16 v[80:83], v[214:217], v[188:191], v[80:83]
	v_mfma_f32_16x16x32_bf16 v[68:71], v[206:209], v[198:201], v[68:71]
	v_mfma_f32_16x16x32_bf16 v[64:67], v[214:217], v[198:201], v[64:67]
	s_setprio 0
	s_barrier
	ds_read_b128 v[168:171], v150 offset:16384
	ds_read_b128 v[172:175], v150 offset:17408
	ds_read_b128 v[176:179], v150 offset:18432
	ds_read_b128 v[180:183], v150 offset:19456
	ds_read_b128 v[184:187], v150 offset:20480
	ds_read_b128 v[188:191], v150 offset:21504
	ds_read_b128 v[192:195], v150 offset:22528
	ds_read_b128 v[198:201], v150 offset:23552
	global_load_lds_dwordx4 v[220:221], off
	v_lshl_add_u64 v[222:223], s[14:15], 0, v[130:131]
	s_mov_b32 m0, s25
	s_nop 0
	global_load_lds_dwordx4 v[222:223], off
	s_waitcnt vmcnt(10)
	s_barrier
	s_setprio 1
	s_waitcnt lgkmcnt(7)
	v_mfma_f32_16x16x32_bf16 v[60:63], v[152:155], v[168:171], v[60:63]
	v_mfma_f32_16x16x32_bf16 v[56:59], v[160:163], v[168:171], v[56:59]
	s_waitcnt lgkmcnt(5)
	v_mfma_f32_16x16x32_bf16 v[44:47], v[152:155], v[176:179], v[44:47]
	v_mfma_f32_16x16x32_bf16 v[40:43], v[160:163], v[176:179], v[40:43]
	s_waitcnt lgkmcnt(3)
	v_mfma_f32_16x16x32_bf16 v[28:31], v[152:155], v[184:187], v[28:31]
	v_mfma_f32_16x16x32_bf16 v[24:27], v[160:163], v[184:187], v[24:27]
	s_waitcnt lgkmcnt(1)
	v_mfma_f32_16x16x32_bf16 v[12:15], v[152:155], v[192:195], v[12:15]
	v_mfma_f32_16x16x32_bf16 v[8:11], v[160:163], v[192:195], v[8:11]
	v_mfma_f32_16x16x32_bf16 v[60:63], v[156:159], v[172:175], v[60:63]
	v_mfma_f32_16x16x32_bf16 v[56:59], v[164:167], v[172:175], v[56:59]
	v_mfma_f32_16x16x32_bf16 v[44:47], v[156:159], v[180:183], v[44:47]
	v_mfma_f32_16x16x32_bf16 v[40:43], v[164:167], v[180:183], v[40:43]
	v_mfma_f32_16x16x32_bf16 v[28:31], v[156:159], v[188:191], v[28:31]
	v_mfma_f32_16x16x32_bf16 v[24:27], v[164:167], v[188:191], v[24:27]
	s_waitcnt lgkmcnt(0)
	v_mfma_f32_16x16x32_bf16 v[12:15], v[156:159], v[198:201], v[12:15]
	v_mfma_f32_16x16x32_bf16 v[8:11], v[164:167], v[198:201], v[8:11]
	s_setprio 0
	s_barrier
	s_add_u32 s8, s12, 0x160000
	s_addc_u32 s9, s13, 0
	s_add_i32 s39, s36, s22
	s_mov_b32 m0, s39
	s_nop 0
	global_load_lds_dwordx4 v132, s[8:9]
	s_add_i32 m0, s39, 0x2000
	s_nop 0
	global_load_lds_dwordx4 v128, s[8:9]
	s_waitcnt vmcnt(6)
	s_barrier
; #define PG8_STAGE(bufoff, gbase, voff) do { _Pragma("unroll") for (int _i = 0; _i < 2; ++_i) \
;         __builtin_amdgcn_global_load_lds((const unsigned*)((const char*)(gbase) + (voff)[_i]), (LAS unsigned*)(lds + (bufoff) + ldsw + _i * 8192), 16, 0, 0); } while (0)
; #define PG8_LDA(dst, b, h) do { _Pragma("unroll") for (int m = 0; m < 4; ++m) _Pragma("unroll") for (int k = 0; k < 2; ++k) dst[m][k] = *(const LAS bf16x8*)(lds + PG8_SA(b, h) + aoff + m * 2048 + k * 1024); } while (0)
; #define PG8_LDB(dst, b, h) do { _Pragma("unroll") for (int n = 0; n < 2; ++n) _Pragma("unroll") for (int k = 0; k < 2; ++k) dst[n][k] = *(const LAS bf16x8*)(lds + PG8_SB(b, h) + boff + n * 2048 + k * 1024); } while (0)
; #define PG8_MMA(ai, bj, At, Bt) do { __builtin_amdgcn_s_setprio(1); _Pragma("unroll") for (int m = 0; m < 4; ++m) _Pragma("unroll") for (int n = 0; n < 2; ++n) _Pragma("unroll") for (int k = 0; k < 2; ++k) \
;         acc[ai][bj][m][n] = __builtin_amdgcn_mfma_f32_16x16x32_bf16(Bt[n][k], At[m][k], acc[ai][bj][m][n], 0, 0, 0); __builtin_amdgcn_s_setprio(0); } while (0)
; #define PG8_WAIT_V(n) asm volatile("s_waitcnt vmcnt(" #n ")" ::: "memory")
; #define PG8_WAIT_L(n) asm volatile("s_waitcnt lgkmcnt(" #n ")" ::: "memory")
; #define PG8_BAR __builtin_amdgcn_s_barrier()
; #define PG8_SCHED __builtin_amdgcn_sched_barrier(0)
; template <class Map, class Epi>
; DI void gemm_phase(LAS unsigned char* lds, const Map& MP, const Epi& E, const int nM, const int nN, const int K, const int lda, const int ldb) {
;     ...
;             PG8_STAGE(PG8_SB(0, 1), b2 + hstepB, voffB);
;             PG8_WAIT_V(6); PG8_BAR; PG8_MMA(1, 1, At, B1); PG8_BAR;
;             PG8_LDB(B0, 1, 0); PG8_SCHED; PG8_LDA(At, 1, 0); PG8_STAGE(PG8_SA(0, 1), a2 + hstepA, voffA);
;             PG8_WAIT_L(8); PG8_BAR; PG8_WAIT_L(0); PG8_MMA(0, 0, At, B0); PG8_BAR; PG8_SCHED;
;             PG8_LDB(B1, 1, 1); PG8_STAGE(PG8_SB(1, 0), b3, voffB);
;             PG8_BAR; PG8_WAIT_L(0); PG8_MMA(0, 1, At, B1); PG8_BAR;
;             PG8_LDA(At, 1, 1); PG8_STAGE(PG8_SA(1, 0), a3, voffA);
;             PG8_BAR; PG8_WAIT_L(0); PG8_MMA(1, 0, At, B0); PG8_BAR; PG8_SCHED;
	s_setprio 1
	v_mfma_f32_16x16x32_bf16 v[52:55], v[202:205], v[168:171], v[52:55]
	v_mfma_f32_16x16x32_bf16 v[48:51], v[210:213], v[168:171], v[48:51]
	s_add_i32 s39, 0, 0x18000
	v_add_u32_e32 v164, s39, v148
	ds_read_b128 v[152:155], v164
	v_mfma_f32_16x16x32_bf16 v[36:39], v[202:205], v[176:179], v[36:39]
	v_mfma_f32_16x16x32_bf16 v[32:35], v[210:213], v[176:179], v[32:35]
	ds_read_b128 v[156:159], v164 offset:1024
	v_mfma_f32_16x16x32_bf16 v[20:23], v[202:205], v[184:187], v[20:23]
	v_mfma_f32_16x16x32_bf16 v[16:19], v[210:213], v[184:187], v[16:19]
	ds_read_b128 v[160:163], v164 offset:2048
	v_mfma_f32_16x16x32_bf16 v[4:7], v[202:205], v[192:195], v[4:7]
	v_mfma_f32_16x16x32_bf16 v[0:3], v[210:213], v[192:195], v[0:3]
	ds_read_b128 v[164:167], v164 offset:3072
	v_mfma_f32_16x16x32_bf16 v[52:55], v[206:209], v[172:175], v[52:55]
	v_mfma_f32_16x16x32_bf16 v[48:51], v[214:217], v[172:175], v[48:51]
	v_mfma_f32_16x16x32_bf16 v[36:39], v[206:209], v[180:183], v[36:39]
	v_mfma_f32_16x16x32_bf16 v[32:35], v[214:217], v[180:183], v[32:35]
	v_mfma_f32_16x16x32_bf16 v[20:23], v[206:209], v[188:191], v[20:23]
	v_mfma_f32_16x16x32_bf16 v[16:19], v[214:217], v[188:191], v[16:19]
	v_mfma_f32_16x16x32_bf16 v[4:7], v[206:209], v[198:201], v[4:7]
	v_mfma_f32_16x16x32_bf16 v[0:3], v[214:217], v[198:201], v[0:3]
	s_setprio 0
	s_barrier
	s_add_u32 s8, s14, 0x160000
	s_addc_u32 s9, s15, 0
	s_mov_b32 m0, s26
	ds_read_b128 v[168:171], v150 offset:32768
	ds_read_b128 v[172:175], v150 offset:33792
	ds_read_b128 v[176:179], v150 offset:34816
	ds_read_b128 v[180:183], v150 offset:35840
	ds_read_b128 v[184:187], v150 offset:36864
	ds_read_b128 v[188:191], v150 offset:37888
	ds_read_b128 v[192:195], v150 offset:38912
	ds_read_b128 v[198:201], v150 offset:39936
	global_load_lds_dwordx4 v134, s[8:9]
	s_mov_b32 m0, s27
	s_nop 0
	global_load_lds_dwordx4 v130, s[8:9]
	s_waitcnt lgkmcnt(8)
	s_barrier
	s_setprio 1
	s_waitcnt lgkmcnt(7)
	v_mfma_f32_16x16x32_bf16 v[124:127], v[152:155], v[168:171], v[124:127]
	v_mfma_f32_16x16x32_bf16 v[120:123], v[160:163], v[168:171], v[120:123]
	s_waitcnt lgkmcnt(5)
	v_mfma_f32_16x16x32_bf16 v[108:111], v[152:155], v[176:179], v[108:111]
	v_mfma_f32_16x16x32_bf16 v[104:107], v[160:163], v[176:179], v[104:107]
	s_waitcnt lgkmcnt(3)
	v_mfma_f32_16x16x32_bf16 v[92:95], v[152:155], v[184:187], v[92:95]
	v_mfma_f32_16x16x32_bf16 v[88:91], v[160:163], v[184:187], v[88:91]
	s_waitcnt lgkmcnt(1)
	v_mfma_f32_16x16x32_bf16 v[76:79], v[152:155], v[192:195], v[76:79]
	v_mfma_f32_16x16x32_bf16 v[72:75], v[160:163], v[192:195], v[72:75]
	v_mfma_f32_16x16x32_bf16 v[124:127], v[156:159], v[172:175], v[124:127]
	v_mfma_f32_16x16x32_bf16 v[120:123], v[164:167], v[172:175], v[120:123]
	v_mfma_f32_16x16x32_bf16 v[108:111], v[156:159], v[180:183], v[108:111]
	v_mfma_f32_16x16x32_bf16 v[104:107], v[164:167], v[180:183], v[104:107]
	v_mfma_f32_16x16x32_bf16 v[92:95], v[156:159], v[188:191], v[92:95]
	v_mfma_f32_16x16x32_bf16 v[88:91], v[164:167], v[188:191], v[88:91]
	s_waitcnt lgkmcnt(0)
	v_mfma_f32_16x16x32_bf16 v[76:79], v[156:159], v[198:201], v[76:79]
	v_mfma_f32_16x16x32_bf16 v[72:75], v[164:167], v[198:201], v[72:75]
	s_setprio 0
	s_barrier
	s_add_i32 s14, 0, 0x1c000
	s_add_i32 s8, s39, s22
	v_add_u32_e32 v196, s14, v148
	v_lshl_add_u64 v[144:145], v[144:145], 0, s[52:53]
	s_mov_b32 m0, s8
	ds_read_b128 v[202:205], v196
	ds_read_b128 v[206:209], v196 offset:1024
	ds_read_b128 v[210:213], v196 offset:2048
	ds_read_b128 v[214:217], v196 offset:3072
	global_load_lds_dwordx4 v[144:145], off
	v_lshl_add_u64 v[144:145], v[218:219], 0, s[52:53]
	s_add_i32 m0, s8, 0x2000
	s_nop 0
	global_load_lds_dwordx4 v[144:145], off
	s_barrier
	s_setprio 1
	s_waitcnt lgkmcnt(3)
	v_mfma_f32_16x16x32_bf16 v[116:119], v[202:205], v[168:171], v[116:119]
	s_waitcnt lgkmcnt(1)
	v_mfma_f32_16x16x32_bf16 v[112:115], v[210:213], v[168:171], v[112:115]
	v_mfma_f32_16x16x32_bf16 v[100:103], v[202:205], v[176:179], v[100:103]
	v_mfma_f32_16x16x32_bf16 v[96:99], v[210:213], v[176:179], v[96:99]
	v_mfma_f32_16x16x32_bf16 v[84:87], v[202:205], v[184:187], v[84:87]
	v_mfma_f32_16x16x32_bf16 v[80:83], v[210:213], v[184:187], v[80:83]
	v_mfma_f32_16x16x32_bf16 v[68:71], v[202:205], v[192:195], v[68:71]
	v_mfma_f32_16x16x32_bf16 v[64:67], v[210:213], v[192:195], v[64:67]
	v_mfma_f32_16x16x32_bf16 v[116:119], v[206:209], v[172:175], v[116:119]
	s_mov_b32 m0, s30
	s_waitcnt lgkmcnt(0)
	v_mfma_f32_16x16x32_bf16 v[112:115], v[214:217], v[172:175], v[112:115]
	v_lshl_add_u64 v[144:145], v[220:221], 0, s[52:53]
	v_mfma_f32_16x16x32_bf16 v[100:103], v[206:209], v[180:183], v[100:103]
	v_mfma_f32_16x16x32_bf16 v[96:99], v[214:217], v[180:183], v[96:99]
	v_mfma_f32_16x16x32_bf16 v[84:87], v[206:209], v[188:191], v[84:87]
	v_mfma_f32_16x16x32_bf16 v[80:83], v[214:217], v[188:191], v[80:83]
	v_mfma_f32_16x16x32_bf16 v[68:71], v[206:209], v[198:201], v[68:71]
	v_mfma_f32_16x16x32_bf16 v[64:67], v[214:217], v[198:201], v[64:67]
	s_setprio 0
	s_barrier
	ds_read_b128 v[168:171], v150 offset:49152
	ds_read_b128 v[172:175], v150 offset:50176
	ds_read_b128 v[176:179], v150 offset:51200
	ds_read_b128 v[180:183], v150 offset:52224
	ds_read_b128 v[184:187], v150 offset:53248
	ds_read_b128 v[188:191], v150 offset:54272
	ds_read_b128 v[192:195], v150 offset:55296
	ds_read_b128 v[198:201], v150 offset:56320
	global_load_lds_dwordx4 v[144:145], off
	v_lshl_add_u64 v[144:145], v[222:223], 0, s[52:53]
	s_mov_b32 m0, s31
	s_nop 0
	global_load_lds_dwordx4 v[144:145], off
	s_waitcnt vmcnt(10)
	s_barrier
; DI unsigned pack2(float a, float b) { f32x2 v = {a, b}; hwbf16x2 r = __builtin_convertvector(v, hwbf16x2); return __builtin_bit_cast(unsigned, r); }
; DI float bflo(unsigned w) { return __uint_as_float(w << 16); }
; DI float bfhi(unsigned w) { return __uint_as_float(w & 0xffff0000u); }
; #define PG8_STAGE(bufoff, gbase, voff) do { _Pragma("unroll") for (int _i = 0; _i < 2; ++_i) \
;         __builtin_amdgcn_global_load_lds((const unsigned*)((const char*)(gbase) + (voff)[_i]), (LAS unsigned*)(lds + (bufoff) + ldsw + _i * 8192), 16, 0, 0); } while (0)
; #define PG8_WAIT_V(n) asm volatile("s_waitcnt vmcnt(" #n ")" ::: "memory")
;     DI void operator()(const f32x4 (&acc)[2][2][4][2], const Unit& u, int wr, int wc, int fr, int fq) const {
;     ...
;             for (int m = 0; m < 4; ++m) { const size_t ro = (size_t)(row0 + ai * HALF + m * 16) * D + col0;
; #pragma unroll
;                 for (int bj = 0; bj < 2; ++bj) {
;                     f32x4 x0, x1;
;                     if constexpr (IB) { const u32x4 w = *(const u32x4*)((const bf16_t*)Xin + ro + bj * HALF);
;                         x0 = (f32x4){bflo(w[0]), bfhi(w[0]), bflo(w[1]), bfhi(w[1])}; x1 = (f32x4){bflo(w[2]), bfhi(w[2]), bflo(w[3]), bfhi(w[3])}; }
;                     else { x0 = *(const f32x4*)((const float*)Xin + ro + bj * HALF); x1 = *(const f32x4*)((const float*)Xin + ro + bj * HALF + 4); }
;                     x0 += acc[ai][bj][m][0] * sc[bj][0]; x1 += acc[ai][bj][m][1] * sc[bj][1];
;                     if constexpr (OB) { u32x4 o; o[0] = pack2(x0[0], x0[1]); o[1] = pack2(x0[2], x0[3]); o[2] = pack2(x1[0], x1[1]); o[3] = pack2(x1[2], x1[3]);
;                         *(u32x4*)((bf16_t*)Xout + ro + bj * HALF) = o; }
;                     else { *(f32x4*)((float*)Xout + ro + bj * HALF) = x0; *(f32x4*)((float*)Xout + ro + bj * HALF + 4) = x1; } } }
; template <class Map, class Epi>
; DI void gemm_phase(LAS unsigned char* lds, const Map& MP, const Epi& E, const int nM, const int nN, const int K, const int lda, const int ldb) {
;     ...
;             PG8_BAR; PG8_WAIT_L(0); PG8_MMA(0, 1, At, B1); PG8_BAR;
;             PG8_LDA(At, 1, 1); PG8_STAGE(PG8_SA(1, 0), a3, voffA);
;             PG8_BAR; PG8_WAIT_L(0); PG8_MMA(1, 0, At, B0); PG8_BAR; PG8_SCHED;
;             PG8_STAGE(PG8_SB(1, 1), b3 + hstepB, voffB);
;             PG8_WAIT_V(6); PG8_BAR; PG8_MMA(1, 1, At, B1); PG8_BAR;
	s_setprio 1
	s_waitcnt lgkmcnt(7)
	v_mfma_f32_16x16x32_bf16 v[60:63], v[152:155], v[168:171], v[60:63]
	v_mfma_f32_16x16x32_bf16 v[56:59], v[160:163], v[168:171], v[56:59]
	s_waitcnt lgkmcnt(5)
	v_mfma_f32_16x16x32_bf16 v[44:47], v[152:155], v[176:179], v[44:47]
	v_mfma_f32_16x16x32_bf16 v[40:43], v[160:163], v[176:179], v[40:43]
	s_waitcnt lgkmcnt(3)
	v_mfma_f32_16x16x32_bf16 v[28:31], v[152:155], v[184:187], v[28:31]
	v_mfma_f32_16x16x32_bf16 v[24:27], v[160:163], v[184:187], v[24:27]
	s_waitcnt lgkmcnt(1)
	v_mfma_f32_16x16x32_bf16 v[12:15], v[152:155], v[192:195], v[12:15]
	v_mfma_f32_16x16x32_bf16 v[8:11], v[160:163], v[192:195], v[8:11]
	v_mfma_f32_16x16x32_bf16 v[60:63], v[156:159], v[172:175], v[60:63]
	v_mfma_f32_16x16x32_bf16 v[56:59], v[164:167], v[172:175], v[56:59]
	v_mfma_f32_16x16x32_bf16 v[44:47], v[156:159], v[180:183], v[44:47]
	v_mfma_f32_16x16x32_bf16 v[40:43], v[164:167], v[180:183], v[40:43]
	v_mfma_f32_16x16x32_bf16 v[28:31], v[156:159], v[188:191], v[28:31]
	v_mfma_f32_16x16x32_bf16 v[24:27], v[164:167], v[188:191], v[24:27]
	s_waitcnt lgkmcnt(0)
	v_mfma_f32_16x16x32_bf16 v[12:15], v[156:159], v[198:201], v[12:15]
	v_mfma_f32_16x16x32_bf16 v[8:11], v[164:167], v[198:201], v[8:11]
	s_setprio 0
	s_barrier
	s_add_u32 s8, s12, 0x160080
	s_addc_u32 s9, s13, 0
	s_add_i32 s12, s14, s22
	s_mov_b32 m0, s12
	s_nop 0
	global_load_lds_dwordx4 v132, s[8:9]
	s_add_i32 m0, s12, 0x2000
	s_nop 0
	global_load_lds_dwordx4 v128, s[8:9]
	s_waitcnt vmcnt(6)
	s_barrier
	s_setprio 1
	v_mfma_f32_16x16x32_bf16 v[52:55], v[202:205], v[168:171], v[52:55]
	v_mfma_f32_16x16x32_bf16 v[48:51], v[210:213], v[168:171], v[48:51]
	ds_read_b128 v[152:155], v149
	v_mfma_f32_16x16x32_bf16 v[36:39], v[202:205], v[176:179], v[36:39]
	v_mfma_f32_16x16x32_bf16 v[32:35], v[210:213], v[176:179], v[32:35]
	ds_read_b128 v[156:159], v149 offset:1024
	v_mfma_f32_16x16x32_bf16 v[20:23], v[202:205], v[184:187], v[20:23]
	v_mfma_f32_16x16x32_bf16 v[16:19], v[210:213], v[184:187], v[16:19]
	ds_read_b128 v[160:163], v149 offset:2048
	v_mfma_f32_16x16x32_bf16 v[4:7], v[202:205], v[192:195], v[4:7]
	v_mfma_f32_16x16x32_bf16 v[0:3], v[210:213], v[192:195], v[0:3]
	ds_read_b128 v[164:167], v149 offset:3072
	v_mfma_f32_16x16x32_bf16 v[52:55], v[206:209], v[172:175], v[52:55]
	s_add_i32 s3, s3, 2
	v_mfma_f32_16x16x32_bf16 v[48:51], v[214:217], v[172:175], v[48:51]
	s_add_u32 s5, s5, 0x100
	s_addc_u32 s38, s38, 0
	v_mfma_f32_16x16x32_bf16 v[36:39], v[206:209], v[180:183], v[36:39]
	s_cmpk_gt_u32 s3, 0x55
	v_mfma_f32_16x16x32_bf16 v[32:35], v[214:217], v[180:183], v[32:35]
	s_mov_b64 s[8:9], s[10:11]
	v_mfma_f32_16x16x32_bf16 v[20:23], v[206:209], v[188:191], v[20:23]
	v_mfma_f32_16x16x32_bf16 v[16:19], v[214:217], v[188:191], v[16:19]
	v_mfma_f32_16x16x32_bf16 v[4:7], v[206:209], v[198:201], v[4:7]
	v_mfma_f32_16x16x32_bf16 v[0:3], v[214:217], v[198:201], v[0:3]
	s_setprio 0
	s_barrier
	s_cbranch_scc0 .LBB1_1239
	s_waitcnt lgkmcnt(0)
	v_mov_b32_e32 v152, v147
	v_mov_b32_e32 v144, v146
	s_lshl_b32 s2, s2, 8
	s_add_i32 s2, s2, s29
	s_lshl_b32 s3, s4, 8
	v_add_u32_e32 v152, s2, v152
	s_or_b32 s3, s3, s54
	v_ashrrev_i32_e32 v153, 31, v152
	v_lshl_add_u32 v144, v144, 3, s3
	v_lshlrev_b64 v[152:153], 12, v[152:153]
	v_ashrrev_i32_e32 v145, 31, v144
	v_lshl_add_u64 v[152:153], s[46:47], 0, v[152:153]
	v_lshl_add_u64 v[144:145], v[144:145], 1, v[152:153]
	global_load_dwordx4 v[160:163], v[144:145], off
	global_load_dwordx4 v[164:167], v[144:145], off offset:256
	s_mov_b64 s[98:99], 0x10000
	v_lshl_add_u64 v[154:155], v[144:145], 0, s[98:99]
	global_load_dwordx4 v[168:171], v[154:155], off
	global_load_dwordx4 v[172:175], v[154:155], off offset:256
	s_mov_b64 s[98:99], 0x20000
	v_lshl_add_u64 v[154:155], v[144:145], 0, s[98:99]
	global_load_dwordx4 v[176:179], v[154:155], off
	global_load_dwordx4 v[180:183], v[154:155], off offset:256
	s_mov_b64 s[98:99], 0x30000
	v_lshl_add_u64 v[154:155], v[144:145], 0, s[98:99]
	global_load_dwordx4 v[184:187], v[154:155], off
	global_load_dwordx4 v[188:191], v[154:155], off offset:256
	s_mov_b64 s[98:99], 0x80000
	v_lshl_add_u64 v[154:155], v[144:145], 0, s[98:99]
	global_load_dwordx4 v[192:195], v[154:155], off
	global_load_dwordx4 v[198:201], v[154:155], off offset:256
	s_mov_b64 s[98:99], 0x90000
	v_lshl_add_u64 v[154:155], v[144:145], 0, s[98:99]
	global_load_dwordx4 v[202:205], v[154:155], off
	global_load_dwordx4 v[206:209], v[154:155], off offset:256
	s_mov_b64 s[98:99], 0xa0000
	v_lshl_add_u64 v[154:155], v[144:145], 0, s[98:99]
	global_load_dwordx4 v[210:213], v[154:155], off
	global_load_dwordx4 v[214:217], v[154:155], off offset:256
	s_mov_b64 s[98:99], 0xb0000
	v_lshl_add_u64 v[154:155], v[144:145], 0, s[98:99]
	global_load_dwordx4 v[248:251], v[154:155], off
	global_load_dwordx4 v[252:255], v[154:155], off offset:256
	s_waitcnt vmcnt(15)
	s_nop 1
	v_mov_b32_e32 v152, v160
	v_mov_b32_e32 v153, v161
	v_mov_b32_e32 v154, v162
	v_mov_b32_e32 v155, v163
	s_mov_b64 s[2:3], 0x10000
	s_mov_b32 s4, s37
	s_mov_b64 s[10:11], s[6:7]
	s_mov_b64 s[8:9], s[42:43]
	s_waitcnt lgkmcnt(0)
	v_lshlrev_b32_e32 v156, 16, v152
	v_and_b32_e32 v157, 0xffff0000, v152
	v_lshlrev_b32_e32 v152, 16, v153
	v_and_b32_e32 v153, 0xffff0000, v153
	v_lshlrev_b32_e32 v158, 16, v154
	v_and_b32_e32 v159, 0xffff0000, v154
	v_lshlrev_b32_e32 v154, 16, v155
	v_and_b32_e32 v155, 0xffff0000, v155
	v_pk_add_f32 v[126:127], v[126:127], v[152:153]
	v_pk_add_f32 v[124:125], v[124:125], v[156:157]
	v_pk_add_f32 v[152:153], v[122:123], v[154:155]
	v_pk_add_f32 v[122:123], v[120:121], v[158:159]
	v_cvt_pk_bf16_f32 v120, v124, v125
	v_cvt_pk_bf16_f32 v121, v126, v127
	v_cvt_pk_bf16_f32 v122, v122, v123
	v_cvt_pk_bf16_f32 v123, v152, v153
	global_store_dwordx4 v[144:145], v[120:123], off
	s_waitcnt vmcnt(15)
; DI unsigned pack2(float a, float b) { f32x2 v = {a, b}; hwbf16x2 r = __builtin_convertvector(v, hwbf16x2); return __builtin_bit_cast(unsigned, r); }
; DI float bflo(unsigned w) { return __uint_as_float(w << 16); }
; DI float bfhi(unsigned w) { return __uint_as_float(w & 0xffff0000u); }
;     DI void operator()(const f32x4 (&acc)[2][2][4][2], const Unit& u, int wr, int wc, int fr, int fq) const {
;     ...
;             for (int m = 0; m < 4; ++m) { const size_t ro = (size_t)(row0 + ai * HALF + m * 16) * D + col0;
; #pragma unroll
;                 for (int bj = 0; bj < 2; ++bj) {
;                     f32x4 x0, x1;
;                     if constexpr (IB) { const u32x4 w = *(const u32x4*)((const bf16_t*)Xin + ro + bj * HALF);
;                         x0 = (f32x4){bflo(w[0]), bfhi(w[0]), bflo(w[1]), bfhi(w[1])}; x1 = (f32x4){bflo(w[2]), bfhi(w[2]), bflo(w[3]), bfhi(w[3])}; }
;                     else { x0 = *(const f32x4*)((const float*)Xin + ro + bj * HALF); x1 = *(const f32x4*)((const float*)Xin + ro + bj * HALF + 4); }
;                     x0 += acc[ai][bj][m][0] * sc[bj][0]; x1 += acc[ai][bj][m][1] * sc[bj][1];
;                     if constexpr (OB) { u32x4 o; o[0] = pack2(x0[0], x0[1]); o[1] = pack2(x0[2], x0[3]); o[2] = pack2(x1[0], x1[1]); o[3] = pack2(x1[2], x1[3]);
;                         *(u32x4*)((bf16_t*)Xout + ro + bj * HALF) = o; }
;                     else { *(f32x4*)((float*)Xout + ro + bj * HALF) = x0; *(f32x4*)((float*)Xout + ro + bj * HALF + 4) = x1; } } }
	s_nop 1
	v_mov_b32_e32 v120, v164
	v_mov_b32_e32 v121, v165
	v_mov_b32_e32 v122, v166
	v_mov_b32_e32 v123, v167
	s_waitcnt lgkmcnt(0)
	v_lshlrev_b32_e32 v124, 16, v120
	v_and_b32_e32 v125, 0xffff0000, v120
	v_lshlrev_b32_e32 v120, 16, v121
	v_and_b32_e32 v121, 0xffff0000, v121
	v_lshlrev_b32_e32 v126, 16, v122
	v_and_b32_e32 v127, 0xffff0000, v122
	v_lshlrev_b32_e32 v122, 16, v123
	v_and_b32_e32 v123, 0xffff0000, v123
	v_pk_add_f32 v[116:117], v[116:117], v[124:125]
	v_pk_add_f32 v[118:119], v[118:119], v[120:121]
	v_pk_add_f32 v[120:121], v[114:115], v[122:123]
	v_pk_add_f32 v[114:115], v[112:113], v[126:127]
	v_cvt_pk_bf16_f32 v112, v116, v117
	v_lshl_add_u64 v[116:117], v[144:145], 0, s[2:3]
	s_mov_b32 s2, 0x10000
	v_cvt_pk_bf16_f32 v113, v118, v119
	v_add_co_u32_e32 v118, vcc, s2, v144
	v_cvt_pk_bf16_f32 v114, v114, v115
	v_cvt_pk_bf16_f32 v115, v120, v121
	v_addc_co_u32_e32 v119, vcc, 0, v145, vcc
	global_store_dwordx4 v[144:145], v[112:115], off offset:256
	s_waitcnt vmcnt(15)
	s_nop 1
	v_mov_b32_e32 v112, v168
	v_mov_b32_e32 v113, v169
	v_mov_b32_e32 v114, v170
	v_mov_b32_e32 v115, v171
	s_mov_b64 s[2:3], 0x20000
	s_waitcnt lgkmcnt(0)
	v_lshlrev_b32_e32 v120, 16, v112
	v_and_b32_e32 v121, 0xffff0000, v112
	v_lshlrev_b32_e32 v112, 16, v113
	v_and_b32_e32 v113, 0xffff0000, v113
	v_lshlrev_b32_e32 v122, 16, v114
	v_and_b32_e32 v123, 0xffff0000, v114
	v_lshlrev_b32_e32 v114, 16, v115
	v_and_b32_e32 v115, 0xffff0000, v115
	v_pk_add_f32 v[110:111], v[110:111], v[112:113]
	v_pk_add_f32 v[108:109], v[108:109], v[120:121]
	v_pk_add_f32 v[112:113], v[106:107], v[114:115]
	v_pk_add_f32 v[106:107], v[104:105], v[122:123]
	v_cvt_pk_bf16_f32 v104, v108, v109
	v_cvt_pk_bf16_f32 v105, v110, v111
	v_cvt_pk_bf16_f32 v106, v106, v107
	v_cvt_pk_bf16_f32 v107, v112, v113
	global_store_dwordx4 v[118:119], v[104:107], off
	s_waitcnt vmcnt(15)
	s_nop 1
	v_mov_b32_e32 v104, v172
	v_mov_b32_e32 v105, v173
	v_mov_b32_e32 v106, v174
	v_mov_b32_e32 v107, v175
	s_waitcnt lgkmcnt(0)
	v_lshlrev_b32_e32 v108, 16, v104
	v_and_b32_e32 v109, 0xffff0000, v104
	v_lshlrev_b32_e32 v104, 16, v105
	v_and_b32_e32 v105, 0xffff0000, v105
	v_lshlrev_b32_e32 v110, 16, v106
	v_and_b32_e32 v111, 0xffff0000, v106
	v_lshlrev_b32_e32 v106, 16, v107
	v_and_b32_e32 v107, 0xffff0000, v107
	v_pk_add_f32 v[100:101], v[100:101], v[108:109]
	v_pk_add_f32 v[102:103], v[102:103], v[104:105]
	v_pk_add_f32 v[104:105], v[98:99], v[106:107]
	v_pk_add_f32 v[98:99], v[96:97], v[110:111]
	v_cvt_pk_bf16_f32 v96, v100, v101
	v_lshl_add_u64 v[100:101], v[144:145], 0, s[2:3]
	s_mov_b32 s2, 0x20000
	v_cvt_pk_bf16_f32 v97, v102, v103
	v_add_co_u32_e32 v102, vcc, s2, v144
	v_cvt_pk_bf16_f32 v98, v98, v99
	v_cvt_pk_bf16_f32 v99, v104, v105
	v_addc_co_u32_e32 v103, vcc, 0, v145, vcc
	global_store_dwordx4 v[116:117], v[96:99], off offset:256
	s_waitcnt vmcnt(15)
	s_nop 1
	v_mov_b32_e32 v96, v176
	v_mov_b32_e32 v97, v177
	v_mov_b32_e32 v98, v178
	v_mov_b32_e32 v99, v179
	s_mov_b64 s[2:3], 0x30000
	s_waitcnt lgkmcnt(0)
	v_lshlrev_b32_e32 v104, 16, v96
	v_and_b32_e32 v105, 0xffff0000, v96
	v_lshlrev_b32_e32 v96, 16, v97
	v_and_b32_e32 v97, 0xffff0000, v97
	v_lshlrev_b32_e32 v106, 16, v98
	v_and_b32_e32 v107, 0xffff0000, v98
	v_lshlrev_b32_e32 v98, 16, v99
	v_and_b32_e32 v99, 0xffff0000, v99
	v_pk_add_f32 v[94:95], v[94:95], v[96:97]
	v_pk_add_f32 v[92:93], v[92:93], v[104:105]
	v_pk_add_f32 v[96:97], v[90:91], v[98:99]
	v_pk_add_f32 v[90:91], v[88:89], v[106:107]
	v_cvt_pk_bf16_f32 v88, v92, v93
	v_cvt_pk_bf16_f32 v89, v94, v95
	v_cvt_pk_bf16_f32 v90, v90, v91
	v_cvt_pk_bf16_f32 v91, v96, v97
	global_store_dwordx4 v[102:103], v[88:91], off
	s_waitcnt vmcnt(15)
	s_nop 1
	v_mov_b32_e32 v88, v180
	v_mov_b32_e32 v89, v181
	v_mov_b32_e32 v90, v182
	v_mov_b32_e32 v91, v183
	s_waitcnt lgkmcnt(0)
	v_lshlrev_b32_e32 v92, 16, v88
	v_and_b32_e32 v93, 0xffff0000, v88
	v_lshlrev_b32_e32 v88, 16, v89
	v_and_b32_e32 v89, 0xffff0000, v89
	v_lshlrev_b32_e32 v94, 16, v90
	v_and_b32_e32 v95, 0xffff0000, v90
	v_lshlrev_b32_e32 v90, 16, v91
	v_and_b32_e32 v91, 0xffff0000, v91
	v_pk_add_f32 v[86:87], v[86:87], v[88:89]
	v_pk_add_f32 v[84:85], v[84:85], v[92:93]
	v_pk_add_f32 v[88:89], v[82:83], v[90:91]
	v_pk_add_f32 v[82:83], v[80:81], v[94:95]
	v_cvt_pk_bf16_f32 v80, v84, v85
	v_cvt_pk_bf16_f32 v81, v86, v87
	v_cvt_pk_bf16_f32 v82, v82, v83
	v_cvt_pk_bf16_f32 v83, v88, v89
	global_store_dwordx4 v[100:101], v[80:83], off offset:256
	s_nop 1
	v_lshl_add_u64 v[80:81], v[144:145], 0, s[2:3]
	s_mov_b32 s2, 0x30000
	v_add_co_u32_e32 v86, vcc, s2, v144
	s_mov_b64 s[2:3], 0x80000
	s_nop 0
	v_addc_co_u32_e32 v87, vcc, 0, v145, vcc
	s_waitcnt vmcnt(15)
	s_nop 1
	v_mov_b32_e32 v82, v184
	v_mov_b32_e32 v83, v185
	v_mov_b32_e32 v84, v186
	v_mov_b32_e32 v85, v187
	s_waitcnt lgkmcnt(0)
	v_lshlrev_b32_e32 v88, 16, v82
	v_and_b32_e32 v89, 0xffff0000, v82
	v_lshlrev_b32_e32 v82, 16, v83
	v_and_b32_e32 v83, 0xffff0000, v83
	v_lshlrev_b32_e32 v90, 16, v84
	v_and_b32_e32 v91, 0xffff0000, v84
	v_lshlrev_b32_e32 v84, 16, v85
	v_and_b32_e32 v85, 0xffff0000, v85
	v_pk_add_f32 v[78:79], v[78:79], v[82:83]
	v_pk_add_f32 v[76:77], v[76:77], v[88:89]
	v_pk_add_f32 v[82:83], v[74:75], v[84:85]
	v_pk_add_f32 v[74:75], v[72:73], v[90:91]
	v_cvt_pk_bf16_f32 v72, v76, v77
	v_cvt_pk_bf16_f32 v73, v78, v79
	v_cvt_pk_bf16_f32 v74, v74, v75
	v_cvt_pk_bf16_f32 v75, v82, v83
	global_store_dwordx4 v[86:87], v[72:75], off
	s_waitcnt vmcnt(15)
	s_nop 1
	v_mov_b32_e32 v72, v188
	v_mov_b32_e32 v73, v189
	v_mov_b32_e32 v74, v190
	v_mov_b32_e32 v75, v191
	s_waitcnt lgkmcnt(0)
; DI unsigned pack2(float a, float b) { f32x2 v = {a, b}; hwbf16x2 r = __builtin_convertvector(v, hwbf16x2); return __builtin_bit_cast(unsigned, r); }
; DI float bflo(unsigned w) { return __uint_as_float(w << 16); }
; DI float bfhi(unsigned w) { return __uint_as_float(w & 0xffff0000u); }
;     DI void operator()(const f32x4 (&acc)[2][2][4][2], const Unit& u, int wr, int wc, int fr, int fq) const {
;     ...
;             for (int m = 0; m < 4; ++m) { const size_t ro = (size_t)(row0 + ai * HALF + m * 16) * D + col0;
; #pragma unroll
;                 for (int bj = 0; bj < 2; ++bj) {
;                     f32x4 x0, x1;
;                     if constexpr (IB) { const u32x4 w = *(const u32x4*)((const bf16_t*)Xin + ro + bj * HALF);
;                         x0 = (f32x4){bflo(w[0]), bfhi(w[0]), bflo(w[1]), bfhi(w[1])}; x1 = (f32x4){bflo(w[2]), bfhi(w[2]), bflo(w[3]), bfhi(w[3])}; }
;                     else { x0 = *(const f32x4*)((const float*)Xin + ro + bj * HALF); x1 = *(const f32x4*)((const float*)Xin + ro + bj * HALF + 4); }
;                     x0 += acc[ai][bj][m][0] * sc[bj][0]; x1 += acc[ai][bj][m][1] * sc[bj][1];
;                     if constexpr (OB) { u32x4 o; o[0] = pack2(x0[0], x0[1]); o[1] = pack2(x0[2], x0[3]); o[2] = pack2(x1[0], x1[1]); o[3] = pack2(x1[2], x1[3]);
;                         *(u32x4*)((bf16_t*)Xout + ro + bj * HALF) = o; }
;                     else { *(f32x4*)((float*)Xout + ro + bj * HALF) = x0; *(f32x4*)((float*)Xout + ro + bj * HALF + 4) = x1; } } }
	v_lshlrev_b32_e32 v76, 16, v72
	v_and_b32_e32 v77, 0xffff0000, v72
	v_lshlrev_b32_e32 v72, 16, v73
	v_and_b32_e32 v73, 0xffff0000, v73
	v_lshlrev_b32_e32 v78, 16, v74
	v_and_b32_e32 v79, 0xffff0000, v74
	v_lshlrev_b32_e32 v74, 16, v75
	v_and_b32_e32 v75, 0xffff0000, v75
	v_pk_add_f32 v[70:71], v[70:71], v[72:73]
	v_pk_add_f32 v[68:69], v[68:69], v[76:77]
	v_pk_add_f32 v[72:73], v[66:67], v[74:75]
	v_pk_add_f32 v[66:67], v[64:65], v[78:79]
	v_cvt_pk_bf16_f32 v64, v68, v69
	v_cvt_pk_bf16_f32 v65, v70, v71
	v_cvt_pk_bf16_f32 v66, v66, v67
	v_cvt_pk_bf16_f32 v67, v72, v73
	global_store_dwordx4 v[80:81], v[64:67], off offset:256
	s_nop 1
	v_lshl_add_u64 v[64:65], v[144:145], 0, s[2:3]
	s_mov_b32 s2, 0x80000
	v_add_co_u32_e32 v70, vcc, s2, v144
	s_mov_b64 s[2:3], 0x90000
	s_nop 0
	v_addc_co_u32_e32 v71, vcc, 0, v145, vcc
	s_waitcnt vmcnt(15)
	s_nop 1
	v_mov_b32_e32 v66, v192
	v_mov_b32_e32 v67, v193
	v_mov_b32_e32 v68, v194
	v_mov_b32_e32 v69, v195
	s_waitcnt lgkmcnt(0)
	v_lshlrev_b32_e32 v72, 16, v66
	v_and_b32_e32 v73, 0xffff0000, v66
	v_lshlrev_b32_e32 v66, 16, v67
	v_and_b32_e32 v67, 0xffff0000, v67
	v_lshlrev_b32_e32 v74, 16, v68
	v_and_b32_e32 v75, 0xffff0000, v68
	v_lshlrev_b32_e32 v68, 16, v69
	v_and_b32_e32 v69, 0xffff0000, v69
	v_pk_add_f32 v[62:63], v[62:63], v[66:67]
	v_pk_add_f32 v[60:61], v[60:61], v[72:73]
	v_pk_add_f32 v[66:67], v[58:59], v[68:69]
	v_pk_add_f32 v[58:59], v[56:57], v[74:75]
	v_cvt_pk_bf16_f32 v56, v60, v61
	v_cvt_pk_bf16_f32 v57, v62, v63
	v_cvt_pk_bf16_f32 v58, v58, v59
	v_cvt_pk_bf16_f32 v59, v66, v67
	global_store_dwordx4 v[70:71], v[56:59], off
	s_waitcnt vmcnt(15)
	s_nop 1
	v_mov_b32_e32 v56, v198
	v_mov_b32_e32 v57, v199
	v_mov_b32_e32 v58, v200
	v_mov_b32_e32 v59, v201
	s_waitcnt lgkmcnt(0)
	v_lshlrev_b32_e32 v60, 16, v56
	v_and_b32_e32 v61, 0xffff0000, v56
	v_lshlrev_b32_e32 v56, 16, v57
	v_and_b32_e32 v57, 0xffff0000, v57
	v_lshlrev_b32_e32 v62, 16, v58
	v_and_b32_e32 v63, 0xffff0000, v58
	v_lshlrev_b32_e32 v58, 16, v59
	v_and_b32_e32 v59, 0xffff0000, v59
	v_pk_add_f32 v[54:55], v[54:55], v[56:57]
	v_pk_add_f32 v[52:53], v[52:53], v[60:61]
	v_pk_add_f32 v[56:57], v[50:51], v[58:59]
	v_pk_add_f32 v[50:51], v[48:49], v[62:63]
	v_cvt_pk_bf16_f32 v48, v52, v53
	v_cvt_pk_bf16_f32 v49, v54, v55
	v_cvt_pk_bf16_f32 v50, v50, v51
	v_cvt_pk_bf16_f32 v51, v56, v57
	global_store_dwordx4 v[64:65], v[48:51], off offset:256
	s_nop 1
	v_lshl_add_u64 v[48:49], v[144:145], 0, s[2:3]
	s_mov_b32 s2, 0x90000
	v_add_co_u32_e32 v54, vcc, s2, v144
	s_mov_b64 s[2:3], 0xa0000
	s_nop 0
	v_addc_co_u32_e32 v55, vcc, 0, v145, vcc
	s_waitcnt vmcnt(15)
	s_nop 1
	v_mov_b32_e32 v50, v202
	v_mov_b32_e32 v51, v203
	v_mov_b32_e32 v52, v204
	v_mov_b32_e32 v53, v205
	s_waitcnt lgkmcnt(0)
	v_lshlrev_b32_e32 v56, 16, v50
	v_and_b32_e32 v57, 0xffff0000, v50
	v_lshlrev_b32_e32 v50, 16, v51
	v_and_b32_e32 v51, 0xffff0000, v51
	v_lshlrev_b32_e32 v58, 16, v52
	v_and_b32_e32 v59, 0xffff0000, v52
	v_lshlrev_b32_e32 v52, 16, v53
	v_and_b32_e32 v53, 0xffff0000, v53
	v_pk_add_f32 v[46:47], v[46:47], v[50:51]
	v_pk_add_f32 v[44:45], v[44:45], v[56:57]
	v_pk_add_f32 v[50:51], v[42:43], v[52:53]
	v_pk_add_f32 v[42:43], v[40:41], v[58:59]
	v_cvt_pk_bf16_f32 v40, v44, v45
	v_cvt_pk_bf16_f32 v41, v46, v47
	v_cvt_pk_bf16_f32 v42, v42, v43
	v_cvt_pk_bf16_f32 v43, v50, v51
	global_store_dwordx4 v[54:55], v[40:43], off
	s_waitcnt vmcnt(15)
	s_nop 1
	v_mov_b32_e32 v40, v206
	v_mov_b32_e32 v41, v207
	v_mov_b32_e32 v42, v208
	v_mov_b32_e32 v43, v209
	s_waitcnt lgkmcnt(0)
; DI unsigned pack2(float a, float b) { f32x2 v = {a, b}; hwbf16x2 r = __builtin_convertvector(v, hwbf16x2); return __builtin_bit_cast(unsigned, r); }
; DI float bflo(unsigned w) { return __uint_as_float(w << 16); }
; DI float bfhi(unsigned w) { return __uint_as_float(w & 0xffff0000u); }
;     DI const char* a(const Unit& u) const { return (const char*)(A + (size_t)u.pm * BM * lda); }
;     DI const char* a(const Unit& u) const { return (const char*)(A + (size_t)u.pm * BM * 2048 + (u.pn >> 1) * 512); }
; #define PG8_BAR __builtin_amdgcn_s_barrier()
;     DI void operator()(const f32x4 (&acc)[2][2][4][2], const Unit& u, int wr, int wc, int fr, int fq) const {
;     ...
;             for (int m = 0; m < 4; ++m) { const size_t ro = (size_t)(row0 + ai * HALF + m * 16) * D + col0;
; #pragma unroll
;                 for (int bj = 0; bj < 2; ++bj) {
;                     f32x4 x0, x1;
;                     if constexpr (IB) { const u32x4 w = *(const u32x4*)((const bf16_t*)Xin + ro + bj * HALF);
;                         x0 = (f32x4){bflo(w[0]), bfhi(w[0]), bflo(w[1]), bfhi(w[1])}; x1 = (f32x4){bflo(w[2]), bfhi(w[2]), bflo(w[3]), bfhi(w[3])}; }
;                     else { x0 = *(const f32x4*)((const float*)Xin + ro + bj * HALF); x1 = *(const f32x4*)((const float*)Xin + ro + bj * HALF + 4); }
;                     x0 += acc[ai][bj][m][0] * sc[bj][0]; x1 += acc[ai][bj][m][1] * sc[bj][1];
;                     if constexpr (OB) { u32x4 o; o[0] = pack2(x0[0], x0[1]); o[1] = pack2(x0[2], x0[3]); o[2] = pack2(x1[0], x1[1]); o[3] = pack2(x1[2], x1[3]);
;                         *(u32x4*)((bf16_t*)Xout + ro + bj * HALF) = o; }
;                     else { *(f32x4*)((float*)Xout + ro + bj * HALF) = x0; *(f32x4*)((float*)Xout + ro + bj * HALF + 4) = x1; } } }
; template <class Map, class Epi>
; DI void gemm_phase(LAS unsigned char* lds, const Map& MP, const Epi& E, const int nM, const int nN, const int K, const int lda, const int ldb) {
;     ...
;         if (!has_next) break;
; #pragma unroll
;         for (int a = 0; a < 2; ++a)
; #pragma unroll
;             for (int b = 0; b < 2; ++b)
; #pragma unroll
;                 for (int m = 0; m < 4; ++m)
; #pragma unroll
;                     for (int n = 0; n < 2; ++n) acc[a][b][m][n] = (f32x4){0.f, 0.f, 0.f, 0.f};
;         cur = nxt; cA = nA; cB = nB; ++ui;
;     }
;     PG8_WAIT_V(0);
;     if (wr == 0) PG8_BAR;
;     PG8_BAR;
	v_lshlrev_b32_e32 v44, 16, v40
	v_and_b32_e32 v45, 0xffff0000, v40
	v_lshlrev_b32_e32 v40, 16, v41
	v_and_b32_e32 v41, 0xffff0000, v41
	v_lshlrev_b32_e32 v46, 16, v42
	v_and_b32_e32 v47, 0xffff0000, v42
	v_lshlrev_b32_e32 v42, 16, v43
	v_and_b32_e32 v43, 0xffff0000, v43
	v_pk_add_f32 v[38:39], v[38:39], v[40:41]
	v_pk_add_f32 v[36:37], v[36:37], v[44:45]
	v_pk_add_f32 v[40:41], v[34:35], v[42:43]
	v_pk_add_f32 v[34:35], v[32:33], v[46:47]
	v_cvt_pk_bf16_f32 v32, v36, v37
	v_cvt_pk_bf16_f32 v33, v38, v39
	v_cvt_pk_bf16_f32 v34, v34, v35
	v_cvt_pk_bf16_f32 v35, v40, v41
	global_store_dwordx4 v[48:49], v[32:35], off offset:256
	s_nop 1
	v_lshl_add_u64 v[32:33], v[144:145], 0, s[2:3]
	s_mov_b32 s2, 0xa0000
	v_add_co_u32_e32 v38, vcc, s2, v144
	s_mov_b64 s[2:3], 0xb0000
	s_nop 0
	v_addc_co_u32_e32 v39, vcc, 0, v145, vcc
	s_waitcnt vmcnt(15)
	s_nop 1
	v_mov_b32_e32 v34, v210
	v_mov_b32_e32 v35, v211
	v_mov_b32_e32 v36, v212
	v_mov_b32_e32 v37, v213
	s_waitcnt lgkmcnt(0)
	v_lshlrev_b32_e32 v40, 16, v34
	v_and_b32_e32 v41, 0xffff0000, v34
	v_lshlrev_b32_e32 v34, 16, v35
	v_and_b32_e32 v35, 0xffff0000, v35
	v_lshlrev_b32_e32 v42, 16, v36
	v_and_b32_e32 v43, 0xffff0000, v36
	v_lshlrev_b32_e32 v36, 16, v37
	v_and_b32_e32 v37, 0xffff0000, v37
	v_pk_add_f32 v[30:31], v[30:31], v[34:35]
	v_pk_add_f32 v[28:29], v[28:29], v[40:41]
	v_pk_add_f32 v[34:35], v[26:27], v[36:37]
	v_pk_add_f32 v[26:27], v[24:25], v[42:43]
	v_cvt_pk_bf16_f32 v24, v28, v29
	v_cvt_pk_bf16_f32 v25, v30, v31
	v_cvt_pk_bf16_f32 v26, v26, v27
	v_cvt_pk_bf16_f32 v27, v34, v35
	global_store_dwordx4 v[38:39], v[24:27], off
	s_waitcnt vmcnt(15)
	s_nop 1
	v_mov_b32_e32 v24, v214
	v_mov_b32_e32 v25, v215
	v_mov_b32_e32 v26, v216
	v_mov_b32_e32 v27, v217
	s_waitcnt lgkmcnt(0)
	v_lshlrev_b32_e32 v28, 16, v24
	v_and_b32_e32 v29, 0xffff0000, v24
	v_lshlrev_b32_e32 v24, 16, v25
	v_and_b32_e32 v25, 0xffff0000, v25
	v_lshlrev_b32_e32 v30, 16, v26
	v_and_b32_e32 v31, 0xffff0000, v26
	v_lshlrev_b32_e32 v26, 16, v27
	v_and_b32_e32 v27, 0xffff0000, v27
	v_pk_add_f32 v[22:23], v[22:23], v[24:25]
	v_pk_add_f32 v[20:21], v[20:21], v[28:29]
	v_pk_add_f32 v[24:25], v[18:19], v[26:27]
	v_pk_add_f32 v[18:19], v[16:17], v[30:31]
	v_cvt_pk_bf16_f32 v16, v20, v21
	v_cvt_pk_bf16_f32 v17, v22, v23
	v_cvt_pk_bf16_f32 v18, v18, v19
	v_cvt_pk_bf16_f32 v19, v24, v25
	global_store_dwordx4 v[32:33], v[16:19], off offset:256
	s_nop 1
	v_lshl_add_u64 v[16:17], v[144:145], 0, s[2:3]
	s_mov_b32 s2, 0xb0000
	v_add_co_u32_e32 v22, vcc, s2, v144
	s_mov_b32 s2, s55
	s_nop 0
	v_addc_co_u32_e32 v23, vcc, 0, v145, vcc
	s_waitcnt vmcnt(15)
	s_nop 1
	v_mov_b32_e32 v18, v248
	v_mov_b32_e32 v19, v249
	v_mov_b32_e32 v20, v250
	v_mov_b32_e32 v21, v251
	s_and_b64 vcc, exec, s[40:41]
	s_waitcnt lgkmcnt(0)
	v_lshlrev_b32_e32 v24, 16, v18
	v_and_b32_e32 v25, 0xffff0000, v18
	v_lshlrev_b32_e32 v18, 16, v19
	v_and_b32_e32 v19, 0xffff0000, v19
	v_lshlrev_b32_e32 v26, 16, v20
	v_and_b32_e32 v27, 0xffff0000, v20
	v_lshlrev_b32_e32 v20, 16, v21
	v_and_b32_e32 v21, 0xffff0000, v21
	v_pk_add_f32 v[14:15], v[14:15], v[18:19]
	v_pk_add_f32 v[12:13], v[12:13], v[24:25]
	v_pk_add_f32 v[18:19], v[10:11], v[20:21]
	v_pk_add_f32 v[10:11], v[8:9], v[26:27]
	v_cvt_pk_bf16_f32 v8, v12, v13
	v_cvt_pk_bf16_f32 v9, v14, v15
	v_cvt_pk_bf16_f32 v10, v10, v11
	v_cvt_pk_bf16_f32 v11, v18, v19
	global_store_dwordx4 v[22:23], v[8:11], off
	s_waitcnt vmcnt(15)
	s_nop 1
	v_mov_b32_e32 v8, v252
	v_mov_b32_e32 v9, v253
	v_mov_b32_e32 v10, v254
	v_mov_b32_e32 v11, v255
	s_waitcnt lgkmcnt(0)
	v_lshlrev_b32_e32 v12, 16, v8
	v_and_b32_e32 v13, 0xffff0000, v8
	v_lshlrev_b32_e32 v8, 16, v9
	v_and_b32_e32 v9, 0xffff0000, v9
	v_lshlrev_b32_e32 v14, 16, v10
	v_and_b32_e32 v15, 0xffff0000, v10
	v_lshlrev_b32_e32 v10, 16, v11
	v_and_b32_e32 v11, 0xffff0000, v11
	v_pk_add_f32 v[6:7], v[6:7], v[8:9]
	v_pk_add_f32 v[4:5], v[4:5], v[12:13]
	v_pk_add_f32 v[8:9], v[2:3], v[10:11]
	v_pk_add_f32 v[2:3], v[0:1], v[14:15]
	v_cvt_pk_bf16_f32 v0, v4, v5
	v_cvt_pk_bf16_f32 v1, v6, v7
	v_cvt_pk_bf16_f32 v2, v2, v3
	v_cvt_pk_bf16_f32 v3, v8, v9
	global_store_dwordx4 v[16:17], v[0:3], off offset:256
	s_cbranch_vccz .LBB1_1232
	s_waitcnt vmcnt(0)
	s_cmpk_gt_u32 s17, 0xff
	s_cbranch_scc1 .LBB1_1243
	s_barrier

; #define PG8_STAGE(bufoff, gbase, voff) do { _Pragma("unroll") for (int _i = 0; _i < 2; ++_i) \
;         __builtin_amdgcn_global_load_lds((const unsigned*)((const char*)(gbase) + (voff)[_i]), (LAS unsigned*)(lds + (bufoff) + ldsw + _i * 8192), 16, 0, 0); } while (0)
; #define PG8_LDA(dst, b, h) do { _Pragma("unroll") for (int m = 0; m < 4; ++m) _Pragma("unroll") for (int k = 0; k < 2; ++k) dst[m][k] = *(const LAS bf16x8*)(lds + PG8_SA(b, h) + aoff + m * 2048 + k * 1024); } while (0)
; #define PG8_LDB(dst, b, h) do { _Pragma("unroll") for (int n = 0; n < 2; ++n) _Pragma("unroll") for (int k = 0; k < 2; ++k) dst[n][k] = *(const LAS bf16x8*)(lds + PG8_SB(b, h) + boff + n * 2048 + k * 1024); } while (0)
; #define PG8_MMA(ai, bj, At, Bt) do { __builtin_amdgcn_s_setprio(1); _Pragma("unroll") for (int m = 0; m < 4; ++m) _Pragma("unroll") for (int n = 0; n < 2; ++n) _Pragma("unroll") for (int k = 0; k < 2; ++k) \
;         acc[ai][bj][m][n] = __builtin_amdgcn_mfma_f32_16x16x32_bf16(Bt[n][k], At[m][k], acc[ai][bj][m][n], 0, 0, 0); __builtin_amdgcn_s_setprio(0); } while (0)
; #define PG8_WAIT_L(n) asm volatile("s_waitcnt lgkmcnt(" #n ")" ::: "memory")
; #define PG8_BAR __builtin_amdgcn_s_barrier()
; #define PG8_SCHED __builtin_amdgcn_sched_barrier(0)
; template <class Map, class Epi>
; DI void gemm_phase(LAS unsigned char* lds, const Map& MP, const Epi& E, const int nM, const int nN, const int K, const int lda, const int ldb) {
;     ...
;             const bool last = (t == nt - 2);
;             const char* a1 = cA + (size_t)(t + 1) * kstep;
;             const char* a2 = last ? nA : cA + (size_t)(t + 2) * kstep; const char* b2 = last ? nB : cB + (size_t)(t + 2) * kstep;
;             const char* a3 = a2 + kstep; const char* b3 = b2 + kstep;
;             PG8_LDB(B0, 0, 0); PG8_SCHED; PG8_LDA(At, 0, 0); PG8_STAGE(PG8_SA(1, 1), a1 + hstepA, voffA);
;             PG8_WAIT_L(8); PG8_BAR; PG8_WAIT_L(0); PG8_MMA(0, 0, At, B0); PG8_BAR; PG8_SCHED;
;             PG8_LDB(B1, 0, 1); PG8_STAGE(PG8_SB(0, 0), b2, voffB);
;             PG8_BAR; PG8_WAIT_L(0); PG8_MMA(0, 1, At, B1); PG8_BAR;
;             PG8_LDA(At, 0, 1); PG8_STAGE(PG8_SA(0, 0), a2, voffA);
;             PG8_BAR; PG8_WAIT_L(0); PG8_MMA(1, 0, At, B0); PG8_BAR; PG8_SCHED;
.LBB1_1382:
	s_add_u32 s22, s20, 0xfff80080
	s_addc_u32 s23, s21, -1
	s_cmp_eq_u32 s3, 28
	s_cselect_b32 s25, s15, s23
	s_cselect_b32 s24, s48, s22
	s_cselect_b32 s23, s13, s53
	s_cselect_b32 s22, s49, s52
	s_add_i32 m0, s31, 0xc000
	ds_read_b128 v[166:169], v148
	ds_read_b128 v[170:173], v148 offset:1024
	ds_read_b128 v[174:177], v148 offset:2048
	ds_read_b128 v[178:181], v148 offset:3072
	ds_read_b128 v[182:185], v148 offset:4096
	ds_read_b128 v[186:189], v148 offset:5120
	ds_read_b128 v[190:193], v148 offset:6144
	ds_read_b128 v[198:201], v148 offset:7168
	global_load_lds_dwordx4 v138, s[20:21]
	s_add_i32 m0, s31, 0xe000
	s_nop 0
	global_load_lds_dwordx4 v136, s[20:21]
	s_waitcnt lgkmcnt(8)
	s_barrier
	s_setprio 1
	s_waitcnt lgkmcnt(7)
	v_mfma_f32_16x16x32_bf16 v[124:127], v[150:153], v[166:169], v[124:127]
	v_mfma_f32_16x16x32_bf16 v[120:123], v[158:161], v[166:169], v[120:123]
	s_waitcnt lgkmcnt(5)
	v_mfma_f32_16x16x32_bf16 v[116:119], v[150:153], v[174:177], v[116:119]
	v_mfma_f32_16x16x32_bf16 v[112:115], v[158:161], v[174:177], v[112:115]
	s_waitcnt lgkmcnt(3)
	v_mfma_f32_16x16x32_bf16 v[100:103], v[150:153], v[182:185], v[100:103]
	v_mfma_f32_16x16x32_bf16 v[96:99], v[158:161], v[182:185], v[96:99]
	s_waitcnt lgkmcnt(1)
	v_mfma_f32_16x16x32_bf16 v[84:87], v[150:153], v[190:193], v[84:87]
	v_mfma_f32_16x16x32_bf16 v[80:83], v[158:161], v[190:193], v[80:83]
	v_mfma_f32_16x16x32_bf16 v[124:127], v[154:157], v[170:173], v[124:127]
	v_mfma_f32_16x16x32_bf16 v[120:123], v[162:165], v[170:173], v[120:123]
	v_mfma_f32_16x16x32_bf16 v[116:119], v[154:157], v[178:181], v[116:119]
	v_mfma_f32_16x16x32_bf16 v[112:115], v[162:165], v[178:181], v[112:115]
	v_mfma_f32_16x16x32_bf16 v[100:103], v[154:157], v[186:189], v[100:103]
	v_mfma_f32_16x16x32_bf16 v[96:99], v[162:165], v[186:189], v[96:99]
	s_waitcnt lgkmcnt(0)
	v_mfma_f32_16x16x32_bf16 v[84:87], v[154:157], v[198:201], v[84:87]
	v_mfma_f32_16x16x32_bf16 v[80:83], v[162:165], v[198:201], v[80:83]
	s_setprio 0
	s_barrier
	s_add_i32 s54, s44, s29
	v_lshl_add_u64 v[194:195], s[22:23], 0, v[132:133]
	s_mov_b32 m0, s54
	ds_read_b128 v[202:205], v149
	ds_read_b128 v[206:209], v149 offset:1024
	ds_read_b128 v[210:213], v149 offset:2048
	ds_read_b128 v[214:217], v149 offset:3072
	global_load_lds_dwordx4 v[194:195], off
	v_lshl_add_u64 v[218:219], s[22:23], 0, v[128:129]
	s_add_i32 m0, s54, 0x2000
	s_nop 0
	global_load_lds_dwordx4 v[218:219], off
	s_barrier
	s_setprio 1
	s_waitcnt lgkmcnt(3)
	v_mfma_f32_16x16x32_bf16 v[108:111], v[202:205], v[166:169], v[108:111]
	s_waitcnt lgkmcnt(1)
	v_mfma_f32_16x16x32_bf16 v[104:107], v[210:213], v[166:169], v[104:107]
	v_mfma_f32_16x16x32_bf16 v[92:95], v[202:205], v[174:177], v[92:95]
	v_mfma_f32_16x16x32_bf16 v[88:91], v[210:213], v[174:177], v[88:91]
	v_mfma_f32_16x16x32_bf16 v[76:79], v[202:205], v[182:185], v[76:79]
	v_mfma_f32_16x16x32_bf16 v[72:75], v[210:213], v[182:185], v[72:75]
	v_mfma_f32_16x16x32_bf16 v[68:71], v[202:205], v[190:193], v[68:71]
	v_mfma_f32_16x16x32_bf16 v[64:67], v[210:213], v[190:193], v[64:67]
	v_mfma_f32_16x16x32_bf16 v[108:111], v[206:209], v[170:173], v[108:111]
	s_mov_b32 m0, s31
	s_waitcnt lgkmcnt(0)
	v_mfma_f32_16x16x32_bf16 v[104:107], v[214:217], v[170:173], v[104:107]
	v_lshl_add_u64 v[220:221], s[24:25], 0, v[134:135]
	v_mfma_f32_16x16x32_bf16 v[92:95], v[206:209], v[178:181], v[92:95]
	v_mfma_f32_16x16x32_bf16 v[88:91], v[214:217], v[178:181], v[88:91]
	v_mfma_f32_16x16x32_bf16 v[76:79], v[206:209], v[186:189], v[76:79]
	v_mfma_f32_16x16x32_bf16 v[72:75], v[214:217], v[186:189], v[72:75]
	v_mfma_f32_16x16x32_bf16 v[68:71], v[206:209], v[198:201], v[68:71]
	v_mfma_f32_16x16x32_bf16 v[64:67], v[214:217], v[198:201], v[64:67]
	s_setprio 0
	s_barrier
	ds_read_b128 v[166:169], v148 offset:16384
	ds_read_b128 v[170:173], v148 offset:17408
	ds_read_b128 v[174:177], v148 offset:18432
	ds_read_b128 v[178:181], v148 offset:19456
	ds_read_b128 v[182:185], v148 offset:20480
	ds_read_b128 v[186:189], v148 offset:21504
	ds_read_b128 v[190:193], v148 offset:22528
	ds_read_b128 v[198:201], v148 offset:23552
	global_load_lds_dwordx4 v[220:221], off
	v_lshl_add_u64 v[222:223], s[24:25], 0, v[130:131]
	s_mov_b32 m0, s11
	s_nop 0
	global_load_lds_dwordx4 v[222:223], off
	s_waitcnt vmcnt(10)
	s_barrier
	s_setprio 1
	s_waitcnt lgkmcnt(7)
	v_mfma_f32_16x16x32_bf16 v[60:63], v[150:153], v[166:169], v[60:63]
	v_mfma_f32_16x16x32_bf16 v[56:59], v[158:161], v[166:169], v[56:59]
	s_waitcnt lgkmcnt(5)
	v_mfma_f32_16x16x32_bf16 v[52:55], v[150:153], v[174:177], v[52:55]
	v_mfma_f32_16x16x32_bf16 v[48:51], v[158:161], v[174:177], v[48:51]
	s_waitcnt lgkmcnt(3)
	v_mfma_f32_16x16x32_bf16 v[36:39], v[150:153], v[182:185], v[36:39]
	v_mfma_f32_16x16x32_bf16 v[32:35], v[158:161], v[182:185], v[32:35]
	s_waitcnt lgkmcnt(1)
	v_mfma_f32_16x16x32_bf16 v[20:23], v[150:153], v[190:193], v[20:23]
	v_mfma_f32_16x16x32_bf16 v[16:19], v[158:161], v[190:193], v[16:19]
	v_mfma_f32_16x16x32_bf16 v[60:63], v[154:157], v[170:173], v[60:63]
	v_mfma_f32_16x16x32_bf16 v[56:59], v[162:165], v[170:173], v[56:59]
	v_mfma_f32_16x16x32_bf16 v[52:55], v[154:157], v[178:181], v[52:55]
	v_mfma_f32_16x16x32_bf16 v[48:51], v[162:165], v[178:181], v[48:51]
	v_mfma_f32_16x16x32_bf16 v[36:39], v[154:157], v[186:189], v[36:39]
	v_mfma_f32_16x16x32_bf16 v[32:35], v[162:165], v[186:189], v[32:35]
	s_waitcnt lgkmcnt(0)
	v_mfma_f32_16x16x32_bf16 v[20:23], v[154:157], v[198:201], v[20:23]
	v_mfma_f32_16x16x32_bf16 v[16:19], v[162:165], v[198:201], v[16:19]
	s_setprio 0
	s_barrier
; #define PG8_STAGE(bufoff, gbase, voff) do { _Pragma("unroll") for (int _i = 0; _i < 2; ++_i) \
;         __builtin_amdgcn_global_load_lds((const unsigned*)((const char*)(gbase) + (voff)[_i]), (LAS unsigned*)(lds + (bufoff) + ldsw + _i * 8192), 16, 0, 0); } while (0)
; #define PG8_LDA(dst, b, h) do { _Pragma("unroll") for (int m = 0; m < 4; ++m) _Pragma("unroll") for (int k = 0; k < 2; ++k) dst[m][k] = *(const LAS bf16x8*)(lds + PG8_SA(b, h) + aoff + m * 2048 + k * 1024); } while (0)
; #define PG8_LDB(dst, b, h) do { _Pragma("unroll") for (int n = 0; n < 2; ++n) _Pragma("unroll") for (int k = 0; k < 2; ++k) dst[n][k] = *(const LAS bf16x8*)(lds + PG8_SB(b, h) + boff + n * 2048 + k * 1024); } while (0)
; #define PG8_MMA(ai, bj, At, Bt) do { __builtin_amdgcn_s_setprio(1); _Pragma("unroll") for (int m = 0; m < 4; ++m) _Pragma("unroll") for (int n = 0; n < 2; ++n) _Pragma("unroll") for (int k = 0; k < 2; ++k) \
;         acc[ai][bj][m][n] = __builtin_amdgcn_mfma_f32_16x16x32_bf16(Bt[n][k], At[m][k], acc[ai][bj][m][n], 0, 0, 0); __builtin_amdgcn_s_setprio(0); } while (0)
; #define PG8_WAIT_V(n) asm volatile("s_waitcnt vmcnt(" #n ")" ::: "memory")
; #define PG8_WAIT_L(n) asm volatile("s_waitcnt lgkmcnt(" #n ")" ::: "memory")
; #define PG8_BAR __builtin_amdgcn_s_barrier()
; #define PG8_SCHED __builtin_amdgcn_sched_barrier(0)
; template <class Map, class Epi>
; DI void gemm_phase(LAS unsigned char* lds, const Map& MP, const Epi& E, const int nM, const int nN, const int K, const int lda, const int ldb) {
;     ...
;             PG8_STAGE(PG8_SB(0, 1), b2 + hstepB, voffB);
;             PG8_WAIT_V(6); PG8_BAR; PG8_MMA(1, 1, At, B1); PG8_BAR;
;             PG8_LDB(B0, 1, 0); PG8_SCHED; PG8_LDA(At, 1, 0); PG8_STAGE(PG8_SA(0, 1), a2 + hstepA, voffA);
;             PG8_WAIT_L(8); PG8_BAR; PG8_WAIT_L(0); PG8_MMA(0, 0, At, B0); PG8_BAR; PG8_SCHED;
;             PG8_LDB(B1, 1, 1); PG8_STAGE(PG8_SB(1, 0), b3, voffB);
;             PG8_BAR; PG8_WAIT_L(0); PG8_MMA(0, 1, At, B1); PG8_BAR;
;             PG8_LDA(At, 1, 1); PG8_STAGE(PG8_SA(1, 0), a3, voffA);
;             PG8_BAR; PG8_WAIT_L(0); PG8_MMA(1, 0, At, B0); PG8_BAR; PG8_SCHED;
	s_add_u32 s54, s22, 0x80000
	s_addc_u32 s55, s23, 0
	s_add_i32 s56, s45, s29
	s_mov_b32 m0, s56
	s_nop 0
	global_load_lds_dwordx4 v132, s[54:55]
	s_add_i32 m0, s56, 0x2000
	s_nop 0
	global_load_lds_dwordx4 v128, s[54:55]
	s_waitcnt vmcnt(6)
	s_barrier
	s_setprio 1
	v_mfma_f32_16x16x32_bf16 v[44:47], v[202:205], v[166:169], v[44:47]
	v_mfma_f32_16x16x32_bf16 v[40:43], v[210:213], v[166:169], v[40:43]
	s_add_i32 s54, 0, 0x18000
	v_add_u32_e32 v162, s54, v146
	ds_read_b128 v[150:153], v162
	v_mfma_f32_16x16x32_bf16 v[28:31], v[202:205], v[174:177], v[28:31]
	v_mfma_f32_16x16x32_bf16 v[24:27], v[210:213], v[174:177], v[24:27]
	ds_read_b128 v[154:157], v162 offset:1024
	v_mfma_f32_16x16x32_bf16 v[12:15], v[202:205], v[182:185], v[12:15]
	v_mfma_f32_16x16x32_bf16 v[8:11], v[210:213], v[182:185], v[8:11]
	ds_read_b128 v[158:161], v162 offset:2048
	v_mfma_f32_16x16x32_bf16 v[4:7], v[202:205], v[190:193], v[4:7]
	v_mfma_f32_16x16x32_bf16 v[0:3], v[210:213], v[190:193], v[0:3]
	ds_read_b128 v[162:165], v162 offset:3072
	v_mfma_f32_16x16x32_bf16 v[44:47], v[206:209], v[170:173], v[44:47]
	v_mfma_f32_16x16x32_bf16 v[40:43], v[214:217], v[170:173], v[40:43]
	v_mfma_f32_16x16x32_bf16 v[28:31], v[206:209], v[178:181], v[28:31]
	v_mfma_f32_16x16x32_bf16 v[24:27], v[214:217], v[178:181], v[24:27]
	v_mfma_f32_16x16x32_bf16 v[12:15], v[206:209], v[186:189], v[12:15]
	v_mfma_f32_16x16x32_bf16 v[8:11], v[214:217], v[186:189], v[8:11]
	v_mfma_f32_16x16x32_bf16 v[4:7], v[206:209], v[198:201], v[4:7]
	v_mfma_f32_16x16x32_bf16 v[0:3], v[214:217], v[198:201], v[0:3]
	s_setprio 0
	s_barrier
	s_add_u32 s24, s24, 0x80000
	s_addc_u32 s25, s25, 0
	s_mov_b32 m0, s34
	ds_read_b128 v[166:169], v148 offset:32768
	ds_read_b128 v[170:173], v148 offset:33792
	ds_read_b128 v[174:177], v148 offset:34816
	ds_read_b128 v[178:181], v148 offset:35840
	ds_read_b128 v[182:185], v148 offset:36864
	ds_read_b128 v[186:189], v148 offset:37888
	ds_read_b128 v[190:193], v148 offset:38912
	ds_read_b128 v[198:201], v148 offset:39936
	global_load_lds_dwordx4 v134, s[24:25]
	s_mov_b32 m0, s35
	s_nop 0
	global_load_lds_dwordx4 v130, s[24:25]
	s_waitcnt lgkmcnt(8)
	s_barrier
	s_setprio 1
	s_waitcnt lgkmcnt(7)
	v_mfma_f32_16x16x32_bf16 v[124:127], v[150:153], v[166:169], v[124:127]
	v_mfma_f32_16x16x32_bf16 v[120:123], v[158:161], v[166:169], v[120:123]
	s_waitcnt lgkmcnt(5)
	v_mfma_f32_16x16x32_bf16 v[116:119], v[150:153], v[174:177], v[116:119]
	v_mfma_f32_16x16x32_bf16 v[112:115], v[158:161], v[174:177], v[112:115]
	s_waitcnt lgkmcnt(3)
	v_mfma_f32_16x16x32_bf16 v[100:103], v[150:153], v[182:185], v[100:103]
	v_mfma_f32_16x16x32_bf16 v[96:99], v[158:161], v[182:185], v[96:99]
	s_waitcnt lgkmcnt(1)
	v_mfma_f32_16x16x32_bf16 v[84:87], v[150:153], v[190:193], v[84:87]
	v_mfma_f32_16x16x32_bf16 v[80:83], v[158:161], v[190:193], v[80:83]
	v_mfma_f32_16x16x32_bf16 v[124:127], v[154:157], v[170:173], v[124:127]
	v_mfma_f32_16x16x32_bf16 v[120:123], v[162:165], v[170:173], v[120:123]
	v_mfma_f32_16x16x32_bf16 v[116:119], v[154:157], v[178:181], v[116:119]
	v_mfma_f32_16x16x32_bf16 v[112:115], v[162:165], v[178:181], v[112:115]
	v_mfma_f32_16x16x32_bf16 v[100:103], v[154:157], v[186:189], v[100:103]
	v_mfma_f32_16x16x32_bf16 v[96:99], v[162:165], v[186:189], v[96:99]
	s_waitcnt lgkmcnt(0)
	v_mfma_f32_16x16x32_bf16 v[84:87], v[154:157], v[198:201], v[84:87]
	v_mfma_f32_16x16x32_bf16 v[80:83], v[162:165], v[198:201], v[80:83]
	s_setprio 0
	s_barrier
	s_add_i32 s24, 0, 0x1c000
	s_add_i32 s25, s54, s29
	v_add_u32_e32 v196, s24, v146
	v_lshl_add_u64 v[194:195], v[194:195], 0, s[8:9]
	s_mov_b32 m0, s25
	ds_read_b128 v[202:205], v196
	ds_read_b128 v[206:209], v196 offset:1024
	ds_read_b128 v[210:213], v196 offset:2048
	ds_read_b128 v[214:217], v196 offset:3072
	global_load_lds_dwordx4 v[194:195], off
	v_lshl_add_u64 v[194:195], v[218:219], 0, s[8:9]
	s_add_i32 m0, s25, 0x2000
	s_nop 0
	global_load_lds_dwordx4 v[194:195], off
	s_barrier
	s_setprio 1
	s_waitcnt lgkmcnt(3)
	v_mfma_f32_16x16x32_bf16 v[108:111], v[202:205], v[166:169], v[108:111]
	s_waitcnt lgkmcnt(1)
	v_mfma_f32_16x16x32_bf16 v[104:107], v[210:213], v[166:169], v[104:107]
	v_mfma_f32_16x16x32_bf16 v[92:95], v[202:205], v[174:177], v[92:95]
	v_mfma_f32_16x16x32_bf16 v[88:91], v[210:213], v[174:177], v[88:91]
	v_mfma_f32_16x16x32_bf16 v[76:79], v[202:205], v[182:185], v[76:79]
	v_mfma_f32_16x16x32_bf16 v[72:75], v[210:213], v[182:185], v[72:75]
	v_mfma_f32_16x16x32_bf16 v[68:71], v[202:205], v[190:193], v[68:71]
	v_mfma_f32_16x16x32_bf16 v[64:67], v[210:213], v[190:193], v[64:67]
	v_mfma_f32_16x16x32_bf16 v[108:111], v[206:209], v[170:173], v[108:111]
	s_mov_b32 m0, s39
	s_waitcnt lgkmcnt(0)
	v_mfma_f32_16x16x32_bf16 v[104:107], v[214:217], v[170:173], v[104:107]
	v_lshl_add_u64 v[194:195], v[220:221], 0, s[8:9]
	v_mfma_f32_16x16x32_bf16 v[92:95], v[206:209], v[178:181], v[92:95]
	v_mfma_f32_16x16x32_bf16 v[88:91], v[214:217], v[178:181], v[88:91]
	v_mfma_f32_16x16x32_bf16 v[76:79], v[206:209], v[186:189], v[76:79]
	v_mfma_f32_16x16x32_bf16 v[72:75], v[214:217], v[186:189], v[72:75]
	v_mfma_f32_16x16x32_bf16 v[68:71], v[206:209], v[198:201], v[68:71]
	v_mfma_f32_16x16x32_bf16 v[64:67], v[214:217], v[198:201], v[64:67]
	s_setprio 0
	s_barrier
	ds_read_b128 v[166:169], v148 offset:49152
	ds_read_b128 v[170:173], v148 offset:50176
	ds_read_b128 v[174:177], v148 offset:51200
	ds_read_b128 v[178:181], v148 offset:52224
	ds_read_b128 v[182:185], v148 offset:53248
	ds_read_b128 v[186:189], v148 offset:54272
	ds_read_b128 v[190:193], v148 offset:55296
	ds_read_b128 v[198:201], v148 offset:56320
	global_load_lds_dwordx4 v[194:195], off
	v_lshl_add_u64 v[194:195], v[222:223], 0, s[8:9]
	s_mov_b32 m0, s42
	s_nop 0
	global_load_lds_dwordx4 v[194:195], off
	s_waitcnt vmcnt(10)
	s_barrier
; #define PG8_STAGE(bufoff, gbase, voff) do { _Pragma("unroll") for (int _i = 0; _i < 2; ++_i) \
;         __builtin_amdgcn_global_load_lds((const unsigned*)((const char*)(gbase) + (voff)[_i]), (LAS unsigned*)(lds + (bufoff) + ldsw + _i * 8192), 16, 0, 0); } while (0)
; #define PG8_MMA(ai, bj, At, Bt) do { __builtin_amdgcn_s_setprio(1); _Pragma("unroll") for (int m = 0; m < 4; ++m) _Pragma("unroll") for (int n = 0; n < 2; ++n) _Pragma("unroll") for (int k = 0; k < 2; ++k) \
;         acc[ai][bj][m][n] = __builtin_amdgcn_mfma_f32_16x16x32_bf16(Bt[n][k], At[m][k], acc[ai][bj][m][n], 0, 0, 0); __builtin_amdgcn_s_setprio(0); } while (0)
; #define PG8_WAIT_V(n) asm volatile("s_waitcnt vmcnt(" #n ")" ::: "memory")
; #define PG8_WAIT_L(n) asm volatile("s_waitcnt lgkmcnt(" #n ")" ::: "memory")
; #define PG8_BAR __builtin_amdgcn_s_barrier()
; #define PG8_SCHED __builtin_amdgcn_sched_barrier(0)
; template <class Map, class Epi>
; DI void gemm_phase(LAS unsigned char* lds, const Map& MP, const Epi& E, const int nM, const int nN, const int K, const int lda, const int ldb) {
;     ...
;             PG8_BAR; PG8_WAIT_L(0); PG8_MMA(1, 0, At, B0); PG8_BAR; PG8_SCHED;
;             PG8_STAGE(PG8_SB(1, 1), b3 + hstepB, voffB);
;             PG8_WAIT_V(6); PG8_BAR; PG8_MMA(1, 1, At, B1); PG8_BAR;
;         }
	s_setprio 1
	s_waitcnt lgkmcnt(7)
	v_mfma_f32_16x16x32_bf16 v[60:63], v[150:153], v[166:169], v[60:63]
	v_mfma_f32_16x16x32_bf16 v[56:59], v[158:161], v[166:169], v[56:59]
	s_waitcnt lgkmcnt(5)
	v_mfma_f32_16x16x32_bf16 v[52:55], v[150:153], v[174:177], v[52:55]
	v_mfma_f32_16x16x32_bf16 v[48:51], v[158:161], v[174:177], v[48:51]
	s_waitcnt lgkmcnt(3)
	v_mfma_f32_16x16x32_bf16 v[36:39], v[150:153], v[182:185], v[36:39]
	v_mfma_f32_16x16x32_bf16 v[32:35], v[158:161], v[182:185], v[32:35]
	s_waitcnt lgkmcnt(1)
	v_mfma_f32_16x16x32_bf16 v[20:23], v[150:153], v[190:193], v[20:23]
	v_mfma_f32_16x16x32_bf16 v[16:19], v[158:161], v[190:193], v[16:19]
	v_mfma_f32_16x16x32_bf16 v[60:63], v[154:157], v[170:173], v[60:63]
	v_mfma_f32_16x16x32_bf16 v[56:59], v[162:165], v[170:173], v[56:59]
	v_mfma_f32_16x16x32_bf16 v[52:55], v[154:157], v[178:181], v[52:55]
	v_mfma_f32_16x16x32_bf16 v[48:51], v[162:165], v[178:181], v[48:51]
	v_mfma_f32_16x16x32_bf16 v[36:39], v[154:157], v[186:189], v[36:39]
	v_mfma_f32_16x16x32_bf16 v[32:35], v[162:165], v[186:189], v[32:35]
	s_waitcnt lgkmcnt(0)
	v_mfma_f32_16x16x32_bf16 v[20:23], v[154:157], v[198:201], v[20:23]
	v_mfma_f32_16x16x32_bf16 v[16:19], v[162:165], v[198:201], v[16:19]
	s_setprio 0
	s_barrier
	s_add_u32 s22, s22, 0x80080
	s_addc_u32 s23, s23, 0
	s_add_i32 s24, s24, s29
	s_mov_b32 m0, s24
	s_nop 0
	global_load_lds_dwordx4 v132, s[22:23]
	s_add_i32 m0, s24, 0x2000
	s_nop 0
	global_load_lds_dwordx4 v128, s[22:23]
	s_waitcnt vmcnt(6)
	s_barrier
	s_setprio 1
	v_mfma_f32_16x16x32_bf16 v[44:47], v[202:205], v[166:169], v[44:47]
	v_mfma_f32_16x16x32_bf16 v[40:43], v[210:213], v[166:169], v[40:43]
	ds_read_b128 v[150:153], v147
	v_mfma_f32_16x16x32_bf16 v[28:31], v[202:205], v[174:177], v[28:31]
	v_mfma_f32_16x16x32_bf16 v[24:27], v[210:213], v[174:177], v[24:27]
	ds_read_b128 v[154:157], v147 offset:1024
	v_mfma_f32_16x16x32_bf16 v[12:15], v[202:205], v[182:185], v[12:15]
	v_mfma_f32_16x16x32_bf16 v[8:11], v[210:213], v[182:185], v[8:11]
	ds_read_b128 v[158:161], v147 offset:2048
	v_mfma_f32_16x16x32_bf16 v[4:7], v[202:205], v[190:193], v[4:7]
	v_mfma_f32_16x16x32_bf16 v[0:3], v[210:213], v[190:193], v[0:3]
	ds_read_b128 v[162:165], v147 offset:3072
	v_mfma_f32_16x16x32_bf16 v[44:47], v[206:209], v[170:173], v[44:47]
	s_add_i32 s3, s3, 2
	v_mfma_f32_16x16x32_bf16 v[40:43], v[214:217], v[170:173], v[40:43]
	s_add_u32 s52, s52, 0x100
	s_addc_u32 s53, s53, 0
	v_mfma_f32_16x16x32_bf16 v[28:31], v[206:209], v[178:181], v[28:31]
	s_add_u32 s20, s20, 0x100
	s_addc_u32 s21, s21, 0
	v_mfma_f32_16x16x32_bf16 v[24:27], v[214:217], v[178:181], v[24:27]
	s_cmp_gt_u32 s3, 29
	v_mfma_f32_16x16x32_bf16 v[12:15], v[206:209], v[186:189], v[12:15]
	v_mfma_f32_16x16x32_bf16 v[8:11], v[214:217], v[186:189], v[8:11]
	v_mfma_f32_16x16x32_bf16 v[4:7], v[206:209], v[198:201], v[4:7]
	v_mfma_f32_16x16x32_bf16 v[0:3], v[214:217], v[198:201], v[0:3]
	s_setprio 0
	s_barrier
	s_cbranch_scc0 .LBB1_1382
; DI unsigned pack2(float a, float b) { f32x2 v = {a, b}; hwbf16x2 r = __builtin_convertvector(v, hwbf16x2); return __builtin_bit_cast(unsigned, r); }
;     DI const char* a(const Unit& u) const { return (const char*)(A + (size_t)u.pm * BM * lda); }
;     DI const char* a(const Unit& u) const { return (const char*)(A + (size_t)u.pm * BM * 2048 + (u.pn >> 1) * 512); }
;     DI const char* a(const Unit& u) const { return (const char*)((u.pn < 12 ? A1 : A2) + (size_t)u.pm * BM * 512); }
;     DI void operator()(const f32x4 (&acc)[2][2][4][2], const Unit& u, int wr, int wc, int fr, int fq) const {
;         bf16_t* O = O1; int ldc = ldc1, pn = u.pn; if (pn >= split) { O = O2; ldc = ldc2; pn -= split; }
;         const int row0 = u.pm * BM + wr * 64 + fr, col0 = pn * BM + wc * 32 + 8 * fq;
; #pragma unroll
;         for (int ai = 0; ai < 2; ++ai)
; #pragma unroll
;             for (int m = 0; m < 4; ++m) { bf16_t* rowp = O + (size_t)(row0 + ai * HALF + m * 16) * ldc + col0;
; #pragma unroll
;                 for (int bj = 0; bj < 2; ++bj) { const f32x4 v0 = acc[ai][bj][m][0], v1 = acc[ai][bj][m][1];
;                     u32x4 o; o[0] = pack2(v0[0], v0[1]); o[1] = pack2(v0[2], v0[3]); o[2] = pack2(v1[0], v1[1]); o[3] = pack2(v1[2], v1[3]);
;                     *(u32x4*)(rowp + bj * HALF) = o; } }
;     }
; template <class Map, class Epi>
; DI void gemm_phase(LAS unsigned char* lds, const Map& MP, const Epi& E, const int nM, const int nN, const int K, const int lda, const int ldb) {
;     ...
;         { int frr = fr, fqq = fq; asm volatile("" : "+v"(frr), "+v"(fqq)); E(acc, cur, wr, wc, frr, fqq); }
;         if (!has_next) break;
; #pragma unroll
;         for (int a = 0; a < 2; ++a)
; #pragma unroll
;             for (int b = 0; b < 2; ++b)
; #pragma unroll
;                 for (int m = 0; m < 4; ++m)
; #pragma unroll
;                     for (int n = 0; n < 2; ++n) acc[a][b][m][n] = (f32x4){0.f, 0.f, 0.f, 0.f};
;         cur = nxt; cA = nA; cB = nB; ++ui;
	s_waitcnt lgkmcnt(0)
	s_lshl_b32 s3, s10, 8
	v_mov_b32_e32 v150, v144
	v_mov_b32_e32 v151, v145
	s_add_i32 s3, s3, s37
	v_cvt_pk_bf16_f32 v68, v68, v69
	v_add_u32_e32 v154, s3, v150
	s_lshl_b32 s3, s47, 8
	s_or_b32 s3, s3, s38
	v_lshl_add_u32 v150, v151, 3, s3
	v_ashrrev_i32_e32 v151, 31, v150
	v_lshl_add_u64 v[150:151], v[150:151], 1, s[6:7]
	v_cvt_pk_bf16_f32 v69, v70, v71
	v_cvt_pk_bf16_f32 v70, v64, v65
	v_add_u32_e32 v64, 0x80, v154
	v_mad_i64_i32 v[152:153], s[20:21], v154, s46, v[150:151]
	v_cvt_pk_bf16_f32 v108, v108, v109
	v_cvt_pk_bf16_f32 v109, v110, v111
	v_cvt_pk_bf16_f32 v110, v104, v105
	v_cvt_pk_bf16_f32 v111, v106, v107
	v_add_u32_e32 v104, 16, v154
	v_mad_i64_i32 v[64:65], s[20:21], v64, s46, v[150:151]
	v_cvt_pk_bf16_f32 v44, v44, v45
	v_cvt_pk_bf16_f32 v45, v46, v47
	v_cvt_pk_bf16_f32 v46, v40, v41
	v_cvt_pk_bf16_f32 v47, v42, v43
	v_add_u32_e32 v40, 0x90, v154
	global_store_dwordx4 v[152:153], v[108:111], off offset:256
	v_cvt_pk_bf16_f32 v92, v92, v93
	v_cvt_pk_bf16_f32 v93, v94, v95
	v_mad_i64_i32 v[108:109], s[20:21], v104, s46, v[150:151]
	v_cvt_pk_bf16_f32 v94, v88, v89
	v_cvt_pk_bf16_f32 v95, v90, v91
	v_add_u32_e32 v88, 32, v154
	global_store_dwordx4 v[64:65], v[44:47], off offset:256
	v_cvt_pk_bf16_f32 v28, v28, v29
	v_cvt_pk_bf16_f32 v29, v30, v31
	v_mad_i64_i32 v[44:45], s[20:21], v40, s46, v[150:151]
	v_cvt_pk_bf16_f32 v30, v24, v25
	v_cvt_pk_bf16_f32 v31, v26, v27
	v_add_u32_e32 v24, 0xa0, v154
	global_store_dwordx4 v[108:109], v[92:95], off offset:256
	v_cvt_pk_bf16_f32 v76, v76, v77
	v_cvt_pk_bf16_f32 v77, v78, v79
	v_mad_i64_i32 v[92:93], s[20:21], v88, s46, v[150:151]
	v_cvt_pk_bf16_f32 v78, v72, v73
	v_cvt_pk_bf16_f32 v79, v74, v75
	v_add_u32_e32 v72, 48, v154
	global_store_dwordx4 v[44:45], v[28:31], off offset:256
	v_cvt_pk_bf16_f32 v12, v12, v13
	v_cvt_pk_bf16_f32 v13, v14, v15
	v_mad_i64_i32 v[28:29], s[20:21], v24, s46, v[150:151]
	v_cvt_pk_bf16_f32 v14, v8, v9
	v_cvt_pk_bf16_f32 v15, v10, v11
	v_add_u32_e32 v8, 0xb0, v154
	global_store_dwordx4 v[92:93], v[76:79], off offset:256
	global_store_dwordx4 v[28:29], v[12:15], off offset:256
	v_cvt_pk_bf16_f32 v124, v124, v125
	v_mad_i64_i32 v[76:77], s[20:21], v72, s46, v[150:151]
	v_mad_i64_i32 v[12:13], s[20:21], v8, s46, v[150:151]
	v_cvt_pk_bf16_f32 v125, v126, v127
	v_cvt_pk_bf16_f32 v126, v120, v121
	v_cvt_pk_bf16_f32 v127, v122, v123
	v_cvt_pk_bf16_f32 v104, v116, v117
	v_cvt_pk_bf16_f32 v105, v118, v119
	v_cvt_pk_bf16_f32 v106, v112, v113
	v_cvt_pk_bf16_f32 v107, v114, v115
	v_cvt_pk_bf16_f32 v88, v100, v101
	v_cvt_pk_bf16_f32 v89, v102, v103
	v_cvt_pk_bf16_f32 v90, v96, v97
	v_cvt_pk_bf16_f32 v91, v98, v99
	v_cvt_pk_bf16_f32 v72, v84, v85
	v_cvt_pk_bf16_f32 v73, v86, v87
	v_cvt_pk_bf16_f32 v74, v80, v81
	v_cvt_pk_bf16_f32 v75, v82, v83
	v_cvt_pk_bf16_f32 v71, v66, v67
	v_cvt_pk_bf16_f32 v60, v60, v61
	v_cvt_pk_bf16_f32 v61, v62, v63
	v_cvt_pk_bf16_f32 v62, v56, v57
	v_cvt_pk_bf16_f32 v63, v58, v59
	v_cvt_pk_bf16_f32 v40, v52, v53
	v_cvt_pk_bf16_f32 v41, v54, v55
	v_cvt_pk_bf16_f32 v42, v48, v49
	v_cvt_pk_bf16_f32 v43, v50, v51
	v_cvt_pk_bf16_f32 v24, v36, v37
	v_cvt_pk_bf16_f32 v25, v38, v39
	v_cvt_pk_bf16_f32 v26, v32, v33
	v_cvt_pk_bf16_f32 v27, v34, v35
	v_cvt_pk_bf16_f32 v8, v20, v21
	v_cvt_pk_bf16_f32 v9, v22, v23
	v_cvt_pk_bf16_f32 v10, v16, v17
	v_cvt_pk_bf16_f32 v11, v18, v19
	v_cvt_pk_bf16_f32 v4, v4, v5
	v_cvt_pk_bf16_f32 v5, v6, v7
	v_cvt_pk_bf16_f32 v6, v0, v1
	v_cvt_pk_bf16_f32 v7, v2, v3
	s_and_b64 vcc, exec, s[40:41]
	s_mov_b32 s47, s12
	s_mov_b32 s10, s14
	s_mov_b64 s[20:21], s[18:19]
	s_mov_b64 s[22:23], s[16:17]
	global_store_dwordx4 v[152:153], v[124:127], off
	global_store_dwordx4 v[108:109], v[104:107], off
	global_store_dwordx4 v[92:93], v[88:91], off
	global_store_dwordx4 v[76:77], v[72:75], off
	global_store_dwordx4 v[76:77], v[68:71], off offset:256
	global_store_dwordx4 v[64:65], v[60:63], off
	global_store_dwordx4 v[44:45], v[40:43], off
	global_store_dwordx4 v[28:29], v[24:27], off
	global_store_dwordx4 v[12:13], v[8:11], off
	global_store_dwordx4 v[12:13], v[4:7], off offset:256
	s_cbranch_vccz .LBB1_1379
	s_waitcnt vmcnt(0)
	s_cmpk_gt_u32 s4, 0xff
	s_cbranch_scc1 .LBB1_1386
	s_barrier

; #define PG8_STAGE(bufoff, gbase, voff) do { _Pragma("unroll") for (int _i = 0; _i < 2; ++_i) \
;         __builtin_amdgcn_global_load_lds((const unsigned*)((const char*)(gbase) + (voff)[_i]), (LAS unsigned*)(lds + (bufoff) + ldsw + _i * 8192), 16, 0, 0); } while (0)
; #define PG8_LDA(dst, b, h) do { _Pragma("unroll") for (int m = 0; m < 4; ++m) _Pragma("unroll") for (int k = 0; k < 2; ++k) dst[m][k] = *(const LAS bf16x8*)(lds + PG8_SA(b, h) + aoff + m * 2048 + k * 1024); } while (0)
; #define PG8_LDB(dst, b, h) do { _Pragma("unroll") for (int n = 0; n < 2; ++n) _Pragma("unroll") for (int k = 0; k < 2; ++k) dst[n][k] = *(const LAS bf16x8*)(lds + PG8_SB(b, h) + boff + n * 2048 + k * 1024); } while (0)
; #define PG8_MMA(ai, bj, At, Bt) do { __builtin_amdgcn_s_setprio(1); _Pragma("unroll") for (int m = 0; m < 4; ++m) _Pragma("unroll") for (int n = 0; n < 2; ++n) _Pragma("unroll") for (int k = 0; k < 2; ++k) \
;         acc[ai][bj][m][n] = __builtin_amdgcn_mfma_f32_16x16x32_bf16(Bt[n][k], At[m][k], acc[ai][bj][m][n], 0, 0, 0); __builtin_amdgcn_s_setprio(0); } while (0)
; #define PG8_WAIT_L(n) asm volatile("s_waitcnt lgkmcnt(" #n ")" ::: "memory")
; #define PG8_BAR __builtin_amdgcn_s_barrier()
; #define PG8_SCHED __builtin_amdgcn_sched_barrier(0)
; template <class Map, class Epi>
; DI void gemm_phase(LAS unsigned char* lds, const Map& MP, const Epi& E, const int nM, const int nN, const int K, const int lda, const int ldb) {
;     ...
;             const bool last = (t == nt - 2);
;             const char* a1 = cA + (size_t)(t + 1) * kstep;
;             const char* a2 = last ? nA : cA + (size_t)(t + 2) * kstep; const char* b2 = last ? nB : cB + (size_t)(t + 2) * kstep;
;             const char* a3 = a2 + kstep; const char* b3 = b2 + kstep;
;             PG8_LDB(B0, 0, 0); PG8_SCHED; PG8_LDA(At, 0, 0); PG8_STAGE(PG8_SA(1, 1), a1 + hstepA, voffA);
;             PG8_WAIT_L(8); PG8_BAR; PG8_WAIT_L(0); PG8_MMA(0, 0, At, B0); PG8_BAR; PG8_SCHED;
;             PG8_LDB(B1, 0, 1); PG8_STAGE(PG8_SB(0, 0), b2, voffB);
;             PG8_BAR; PG8_WAIT_L(0); PG8_MMA(0, 1, At, B1); PG8_BAR;
;             PG8_LDA(At, 0, 1); PG8_STAGE(PG8_SA(0, 0), a2, voffA);
;             PG8_BAR; PG8_WAIT_L(0); PG8_MMA(1, 0, At, B0); PG8_BAR; PG8_SCHED;
.LBB1_1529:
	s_add_u32 s20, s18, 0xfffe0080
	s_addc_u32 s21, s19, -1
	s_cmp_eq_u32 s3, 4
	s_cselect_b32 s23, s13, s21
	s_cselect_b32 s22, s52, s20
	s_cselect_b32 s21, s53, s56
	s_cselect_b32 s20, s54, s55
	s_add_i32 m0, s11, 0xc000
	ds_read_b128 v[166:169], v148
	ds_read_b128 v[170:173], v148 offset:1024
	ds_read_b128 v[174:177], v148 offset:2048
	ds_read_b128 v[178:181], v148 offset:3072
	ds_read_b128 v[182:185], v148 offset:4096
	ds_read_b128 v[186:189], v148 offset:5120
	ds_read_b128 v[190:193], v148 offset:6144
	ds_read_b128 v[198:201], v148 offset:7168
	global_load_lds_dwordx4 v138, s[18:19]
	s_add_i32 m0, s11, 0xe000
	s_nop 0
	global_load_lds_dwordx4 v136, s[18:19]
	s_waitcnt lgkmcnt(8)
	s_barrier
	s_setprio 1
	s_waitcnt lgkmcnt(7)
	v_mfma_f32_16x16x32_bf16 v[124:127], v[150:153], v[166:169], v[124:127]
	v_mfma_f32_16x16x32_bf16 v[120:123], v[158:161], v[166:169], v[120:123]
	s_waitcnt lgkmcnt(5)
	v_mfma_f32_16x16x32_bf16 v[116:119], v[150:153], v[174:177], v[116:119]
	v_mfma_f32_16x16x32_bf16 v[112:115], v[158:161], v[174:177], v[112:115]
	s_waitcnt lgkmcnt(3)
	v_mfma_f32_16x16x32_bf16 v[100:103], v[150:153], v[182:185], v[100:103]
	v_mfma_f32_16x16x32_bf16 v[96:99], v[158:161], v[182:185], v[96:99]
	s_waitcnt lgkmcnt(1)
	v_mfma_f32_16x16x32_bf16 v[84:87], v[150:153], v[190:193], v[84:87]
	v_mfma_f32_16x16x32_bf16 v[80:83], v[158:161], v[190:193], v[80:83]
	v_mfma_f32_16x16x32_bf16 v[124:127], v[154:157], v[170:173], v[124:127]
	v_mfma_f32_16x16x32_bf16 v[120:123], v[162:165], v[170:173], v[120:123]
	v_mfma_f32_16x16x32_bf16 v[116:119], v[154:157], v[178:181], v[116:119]
	v_mfma_f32_16x16x32_bf16 v[112:115], v[162:165], v[178:181], v[112:115]
	v_mfma_f32_16x16x32_bf16 v[100:103], v[154:157], v[186:189], v[100:103]
	v_mfma_f32_16x16x32_bf16 v[96:99], v[162:165], v[186:189], v[96:99]
	s_waitcnt lgkmcnt(0)
	v_mfma_f32_16x16x32_bf16 v[84:87], v[154:157], v[198:201], v[84:87]
	v_mfma_f32_16x16x32_bf16 v[80:83], v[162:165], v[198:201], v[80:83]
	s_setprio 0
	s_barrier
	s_add_i32 s57, s47, s31
	v_lshl_add_u64 v[194:195], s[20:21], 0, v[132:133]
	s_mov_b32 m0, s57
	ds_read_b128 v[202:205], v149
	ds_read_b128 v[206:209], v149 offset:1024
	ds_read_b128 v[210:213], v149 offset:2048
	ds_read_b128 v[214:217], v149 offset:3072
	global_load_lds_dwordx4 v[194:195], off
	v_lshl_add_u64 v[218:219], s[20:21], 0, v[128:129]
	s_add_i32 m0, s57, 0x2000
	s_nop 0
	global_load_lds_dwordx4 v[218:219], off
	s_barrier
	s_setprio 1
	s_waitcnt lgkmcnt(3)
	v_mfma_f32_16x16x32_bf16 v[108:111], v[202:205], v[166:169], v[108:111]
	s_waitcnt lgkmcnt(1)
	v_mfma_f32_16x16x32_bf16 v[104:107], v[210:213], v[166:169], v[104:107]
	v_mfma_f32_16x16x32_bf16 v[92:95], v[202:205], v[174:177], v[92:95]
	v_mfma_f32_16x16x32_bf16 v[88:91], v[210:213], v[174:177], v[88:91]
	v_mfma_f32_16x16x32_bf16 v[76:79], v[202:205], v[182:185], v[76:79]
	v_mfma_f32_16x16x32_bf16 v[72:75], v[210:213], v[182:185], v[72:75]
	v_mfma_f32_16x16x32_bf16 v[68:71], v[202:205], v[190:193], v[68:71]
	v_mfma_f32_16x16x32_bf16 v[64:67], v[210:213], v[190:193], v[64:67]
	v_mfma_f32_16x16x32_bf16 v[108:111], v[206:209], v[170:173], v[108:111]
	s_mov_b32 m0, s11
	s_waitcnt lgkmcnt(0)
	v_mfma_f32_16x16x32_bf16 v[104:107], v[214:217], v[170:173], v[104:107]
	v_lshl_add_u64 v[220:221], s[22:23], 0, v[134:135]
	v_mfma_f32_16x16x32_bf16 v[92:95], v[206:209], v[178:181], v[92:95]
	v_mfma_f32_16x16x32_bf16 v[88:91], v[214:217], v[178:181], v[88:91]
	v_mfma_f32_16x16x32_bf16 v[76:79], v[206:209], v[186:189], v[76:79]
	v_mfma_f32_16x16x32_bf16 v[72:75], v[214:217], v[186:189], v[72:75]
	v_mfma_f32_16x16x32_bf16 v[68:71], v[206:209], v[198:201], v[68:71]
	v_mfma_f32_16x16x32_bf16 v[64:67], v[214:217], v[198:201], v[64:67]
	s_setprio 0
	s_barrier
	ds_read_b128 v[166:169], v148 offset:16384
	ds_read_b128 v[170:173], v148 offset:17408
	ds_read_b128 v[174:177], v148 offset:18432
	ds_read_b128 v[178:181], v148 offset:19456
	ds_read_b128 v[182:185], v148 offset:20480
	ds_read_b128 v[186:189], v148 offset:21504
	ds_read_b128 v[190:193], v148 offset:22528
	ds_read_b128 v[198:201], v148 offset:23552
	global_load_lds_dwordx4 v[220:221], off
	v_lshl_add_u64 v[222:223], s[22:23], 0, v[130:131]
	s_mov_b32 m0, s35
	s_nop 0
	global_load_lds_dwordx4 v[222:223], off
	s_waitcnt vmcnt(10)
	s_barrier
	s_setprio 1
	s_waitcnt lgkmcnt(7)
	v_mfma_f32_16x16x32_bf16 v[60:63], v[150:153], v[166:169], v[60:63]
	v_mfma_f32_16x16x32_bf16 v[56:59], v[158:161], v[166:169], v[56:59]
	s_waitcnt lgkmcnt(5)
	v_mfma_f32_16x16x32_bf16 v[52:55], v[150:153], v[174:177], v[52:55]
	v_mfma_f32_16x16x32_bf16 v[48:51], v[158:161], v[174:177], v[48:51]
	s_waitcnt lgkmcnt(3)
	v_mfma_f32_16x16x32_bf16 v[36:39], v[150:153], v[182:185], v[36:39]
	v_mfma_f32_16x16x32_bf16 v[32:35], v[158:161], v[182:185], v[32:35]
	s_waitcnt lgkmcnt(1)
	v_mfma_f32_16x16x32_bf16 v[20:23], v[150:153], v[190:193], v[20:23]
	v_mfma_f32_16x16x32_bf16 v[16:19], v[158:161], v[190:193], v[16:19]
	v_mfma_f32_16x16x32_bf16 v[60:63], v[154:157], v[170:173], v[60:63]
	v_mfma_f32_16x16x32_bf16 v[56:59], v[162:165], v[170:173], v[56:59]
	v_mfma_f32_16x16x32_bf16 v[52:55], v[154:157], v[178:181], v[52:55]
	v_mfma_f32_16x16x32_bf16 v[48:51], v[162:165], v[178:181], v[48:51]
	v_mfma_f32_16x16x32_bf16 v[36:39], v[154:157], v[186:189], v[36:39]
	v_mfma_f32_16x16x32_bf16 v[32:35], v[162:165], v[186:189], v[32:35]
	s_waitcnt lgkmcnt(0)
	v_mfma_f32_16x16x32_bf16 v[20:23], v[154:157], v[198:201], v[20:23]
	v_mfma_f32_16x16x32_bf16 v[16:19], v[162:165], v[198:201], v[16:19]
	s_setprio 0
	s_barrier
; #define PG8_STAGE(bufoff, gbase, voff) do { _Pragma("unroll") for (int _i = 0; _i < 2; ++_i) \
;         __builtin_amdgcn_global_load_lds((const unsigned*)((const char*)(gbase) + (voff)[_i]), (LAS unsigned*)(lds + (bufoff) + ldsw + _i * 8192), 16, 0, 0); } while (0)
; #define PG8_LDA(dst, b, h) do { _Pragma("unroll") for (int m = 0; m < 4; ++m) _Pragma("unroll") for (int k = 0; k < 2; ++k) dst[m][k] = *(const LAS bf16x8*)(lds + PG8_SA(b, h) + aoff + m * 2048 + k * 1024); } while (0)
; #define PG8_LDB(dst, b, h) do { _Pragma("unroll") for (int n = 0; n < 2; ++n) _Pragma("unroll") for (int k = 0; k < 2; ++k) dst[n][k] = *(const LAS bf16x8*)(lds + PG8_SB(b, h) + boff + n * 2048 + k * 1024); } while (0)
; #define PG8_MMA(ai, bj, At, Bt) do { __builtin_amdgcn_s_setprio(1); _Pragma("unroll") for (int m = 0; m < 4; ++m) _Pragma("unroll") for (int n = 0; n < 2; ++n) _Pragma("unroll") for (int k = 0; k < 2; ++k) \
;         acc[ai][bj][m][n] = __builtin_amdgcn_mfma_f32_16x16x32_bf16(Bt[n][k], At[m][k], acc[ai][bj][m][n], 0, 0, 0); __builtin_amdgcn_s_setprio(0); } while (0)
; #define PG8_WAIT_V(n) asm volatile("s_waitcnt vmcnt(" #n ")" ::: "memory")
; #define PG8_WAIT_L(n) asm volatile("s_waitcnt lgkmcnt(" #n ")" ::: "memory")
; #define PG8_BAR __builtin_amdgcn_s_barrier()
; #define PG8_SCHED __builtin_amdgcn_sched_barrier(0)
; template <class Map, class Epi>
; DI void gemm_phase(LAS unsigned char* lds, const Map& MP, const Epi& E, const int nM, const int nN, const int K, const int lda, const int ldb) {
;     ...
;             PG8_STAGE(PG8_SB(0, 1), b2 + hstepB, voffB);
;             PG8_WAIT_V(6); PG8_BAR; PG8_MMA(1, 1, At, B1); PG8_BAR;
;             PG8_LDB(B0, 1, 0); PG8_SCHED; PG8_LDA(At, 1, 0); PG8_STAGE(PG8_SA(0, 1), a2 + hstepA, voffA);
;             PG8_WAIT_L(8); PG8_BAR; PG8_WAIT_L(0); PG8_MMA(0, 0, At, B0); PG8_BAR; PG8_SCHED;
;             PG8_LDB(B1, 1, 1); PG8_STAGE(PG8_SB(1, 0), b3, voffB);
;             PG8_BAR; PG8_WAIT_L(0); PG8_MMA(0, 1, At, B1); PG8_BAR;
;             PG8_LDA(At, 1, 1); PG8_STAGE(PG8_SA(1, 0), a3, voffA);
;             PG8_BAR; PG8_WAIT_L(0); PG8_MMA(1, 0, At, B0); PG8_BAR; PG8_SCHED;
	s_add_u32 s58, s20, 0x20000
	s_addc_u32 s59, s21, 0
	s_add_i32 s57, s48, s31
	s_mov_b32 m0, s57
	s_nop 0
	global_load_lds_dwordx4 v132, s[58:59]
	s_add_i32 m0, s57, 0x2000
	s_nop 0
	global_load_lds_dwordx4 v128, s[58:59]
	s_waitcnt vmcnt(6)
	s_barrier
	s_setprio 1
	v_mfma_f32_16x16x32_bf16 v[44:47], v[202:205], v[166:169], v[44:47]
	v_mfma_f32_16x16x32_bf16 v[40:43], v[210:213], v[166:169], v[40:43]
	s_add_i32 s57, 0, 0x18000
	v_add_u32_e32 v162, s57, v146
	ds_read_b128 v[150:153], v162
	v_mfma_f32_16x16x32_bf16 v[28:31], v[202:205], v[174:177], v[28:31]
	v_mfma_f32_16x16x32_bf16 v[24:27], v[210:213], v[174:177], v[24:27]
	ds_read_b128 v[154:157], v162 offset:1024
	v_mfma_f32_16x16x32_bf16 v[12:15], v[202:205], v[182:185], v[12:15]
	v_mfma_f32_16x16x32_bf16 v[8:11], v[210:213], v[182:185], v[8:11]
	ds_read_b128 v[158:161], v162 offset:2048
	v_mfma_f32_16x16x32_bf16 v[4:7], v[202:205], v[190:193], v[4:7]
	v_mfma_f32_16x16x32_bf16 v[0:3], v[210:213], v[190:193], v[0:3]
	ds_read_b128 v[162:165], v162 offset:3072
	v_mfma_f32_16x16x32_bf16 v[44:47], v[206:209], v[170:173], v[44:47]
	v_mfma_f32_16x16x32_bf16 v[40:43], v[214:217], v[170:173], v[40:43]
	v_mfma_f32_16x16x32_bf16 v[28:31], v[206:209], v[178:181], v[28:31]
	v_mfma_f32_16x16x32_bf16 v[24:27], v[214:217], v[178:181], v[24:27]
	v_mfma_f32_16x16x32_bf16 v[12:15], v[206:209], v[186:189], v[12:15]
	v_mfma_f32_16x16x32_bf16 v[8:11], v[214:217], v[186:189], v[8:11]
	v_mfma_f32_16x16x32_bf16 v[4:7], v[206:209], v[198:201], v[4:7]
	v_mfma_f32_16x16x32_bf16 v[0:3], v[214:217], v[198:201], v[0:3]
	s_setprio 0
	s_barrier
	s_add_u32 s22, s22, 0x20000
	s_addc_u32 s23, s23, 0
	s_mov_b32 m0, s36
	ds_read_b128 v[166:169], v148 offset:32768
	ds_read_b128 v[170:173], v148 offset:33792
	ds_read_b128 v[174:177], v148 offset:34816
	ds_read_b128 v[178:181], v148 offset:35840
	ds_read_b128 v[182:185], v148 offset:36864
	ds_read_b128 v[186:189], v148 offset:37888
	ds_read_b128 v[190:193], v148 offset:38912
	ds_read_b128 v[198:201], v148 offset:39936
	global_load_lds_dwordx4 v134, s[22:23]
	s_mov_b32 m0, s37
	s_nop 0
	global_load_lds_dwordx4 v130, s[22:23]
	s_waitcnt lgkmcnt(8)
	s_barrier
	s_setprio 1
	s_waitcnt lgkmcnt(7)
	v_mfma_f32_16x16x32_bf16 v[124:127], v[150:153], v[166:169], v[124:127]
	v_mfma_f32_16x16x32_bf16 v[120:123], v[158:161], v[166:169], v[120:123]
	s_waitcnt lgkmcnt(5)
	v_mfma_f32_16x16x32_bf16 v[116:119], v[150:153], v[174:177], v[116:119]
	v_mfma_f32_16x16x32_bf16 v[112:115], v[158:161], v[174:177], v[112:115]
	s_waitcnt lgkmcnt(3)
	v_mfma_f32_16x16x32_bf16 v[100:103], v[150:153], v[182:185], v[100:103]
	v_mfma_f32_16x16x32_bf16 v[96:99], v[158:161], v[182:185], v[96:99]
	s_waitcnt lgkmcnt(1)
	v_mfma_f32_16x16x32_bf16 v[84:87], v[150:153], v[190:193], v[84:87]
	v_mfma_f32_16x16x32_bf16 v[80:83], v[158:161], v[190:193], v[80:83]
	v_mfma_f32_16x16x32_bf16 v[124:127], v[154:157], v[170:173], v[124:127]
	v_mfma_f32_16x16x32_bf16 v[120:123], v[162:165], v[170:173], v[120:123]
	v_mfma_f32_16x16x32_bf16 v[116:119], v[154:157], v[178:181], v[116:119]
	v_mfma_f32_16x16x32_bf16 v[112:115], v[162:165], v[178:181], v[112:115]
	v_mfma_f32_16x16x32_bf16 v[100:103], v[154:157], v[186:189], v[100:103]
	v_mfma_f32_16x16x32_bf16 v[96:99], v[162:165], v[186:189], v[96:99]
	s_waitcnt lgkmcnt(0)
	v_mfma_f32_16x16x32_bf16 v[84:87], v[154:157], v[198:201], v[84:87]
	v_mfma_f32_16x16x32_bf16 v[80:83], v[162:165], v[198:201], v[80:83]
	s_setprio 0
	s_barrier
	s_add_i32 s22, 0, 0x1c000
	s_add_i32 s23, s57, s31
	v_add_u32_e32 v196, s22, v146
	v_lshl_add_u64 v[194:195], v[194:195], 0, s[8:9]
	s_mov_b32 m0, s23
	ds_read_b128 v[202:205], v196
	ds_read_b128 v[206:209], v196 offset:1024
	ds_read_b128 v[210:213], v196 offset:2048
	ds_read_b128 v[214:217], v196 offset:3072
	global_load_lds_dwordx4 v[194:195], off
	v_lshl_add_u64 v[194:195], v[218:219], 0, s[8:9]
	s_add_i32 m0, s23, 0x2000
	s_nop 0
	global_load_lds_dwordx4 v[194:195], off
	s_barrier
	s_setprio 1
	s_waitcnt lgkmcnt(3)
	v_mfma_f32_16x16x32_bf16 v[108:111], v[202:205], v[166:169], v[108:111]
	s_waitcnt lgkmcnt(1)
	v_mfma_f32_16x16x32_bf16 v[104:107], v[210:213], v[166:169], v[104:107]
	v_mfma_f32_16x16x32_bf16 v[92:95], v[202:205], v[174:177], v[92:95]
	v_mfma_f32_16x16x32_bf16 v[88:91], v[210:213], v[174:177], v[88:91]
	v_mfma_f32_16x16x32_bf16 v[76:79], v[202:205], v[182:185], v[76:79]
	v_mfma_f32_16x16x32_bf16 v[72:75], v[210:213], v[182:185], v[72:75]
	v_mfma_f32_16x16x32_bf16 v[68:71], v[202:205], v[190:193], v[68:71]
	v_mfma_f32_16x16x32_bf16 v[64:67], v[210:213], v[190:193], v[64:67]
	v_mfma_f32_16x16x32_bf16 v[108:111], v[206:209], v[170:173], v[108:111]
	s_mov_b32 m0, s43
	s_waitcnt lgkmcnt(0)
	v_mfma_f32_16x16x32_bf16 v[104:107], v[214:217], v[170:173], v[104:107]
	v_lshl_add_u64 v[194:195], v[220:221], 0, s[8:9]
	v_mfma_f32_16x16x32_bf16 v[92:95], v[206:209], v[178:181], v[92:95]
	v_mfma_f32_16x16x32_bf16 v[88:91], v[214:217], v[178:181], v[88:91]
	v_mfma_f32_16x16x32_bf16 v[76:79], v[206:209], v[186:189], v[76:79]
	v_mfma_f32_16x16x32_bf16 v[72:75], v[214:217], v[186:189], v[72:75]
	v_mfma_f32_16x16x32_bf16 v[68:71], v[206:209], v[198:201], v[68:71]
	v_mfma_f32_16x16x32_bf16 v[64:67], v[214:217], v[198:201], v[64:67]
	s_setprio 0
	s_barrier
	ds_read_b128 v[166:169], v148 offset:49152
	ds_read_b128 v[170:173], v148 offset:50176
	ds_read_b128 v[174:177], v148 offset:51200
	ds_read_b128 v[178:181], v148 offset:52224
	ds_read_b128 v[182:185], v148 offset:53248
	ds_read_b128 v[186:189], v148 offset:54272
	ds_read_b128 v[190:193], v148 offset:55296
	ds_read_b128 v[198:201], v148 offset:56320
	global_load_lds_dwordx4 v[194:195], off
	v_lshl_add_u64 v[194:195], v[222:223], 0, s[8:9]
	s_mov_b32 m0, s44
	s_nop 0
	global_load_lds_dwordx4 v[194:195], off
	s_waitcnt vmcnt(10)
	s_barrier
; #define PG8_STAGE(bufoff, gbase, voff) do { _Pragma("unroll") for (int _i = 0; _i < 2; ++_i) \
;         __builtin_amdgcn_global_load_lds((const unsigned*)((const char*)(gbase) + (voff)[_i]), (LAS unsigned*)(lds + (bufoff) + ldsw + _i * 8192), 16, 0, 0); } while (0)
; #define PG8_MMA(ai, bj, At, Bt) do { __builtin_amdgcn_s_setprio(1); _Pragma("unroll") for (int m = 0; m < 4; ++m) _Pragma("unroll") for (int n = 0; n < 2; ++n) _Pragma("unroll") for (int k = 0; k < 2; ++k) \
;         acc[ai][bj][m][n] = __builtin_amdgcn_mfma_f32_16x16x32_bf16(Bt[n][k], At[m][k], acc[ai][bj][m][n], 0, 0, 0); __builtin_amdgcn_s_setprio(0); } while (0)
; #define PG8_WAIT_V(n) asm volatile("s_waitcnt vmcnt(" #n ")" ::: "memory")
; #define PG8_WAIT_L(n) asm volatile("s_waitcnt lgkmcnt(" #n ")" ::: "memory")
; #define PG8_BAR __builtin_amdgcn_s_barrier()
; #define PG8_SCHED __builtin_amdgcn_sched_barrier(0)
; template <class Map, class Epi>
; DI void gemm_phase(LAS unsigned char* lds, const Map& MP, const Epi& E, const int nM, const int nN, const int K, const int lda, const int ldb) {
;     ...
;             PG8_BAR; PG8_WAIT_L(0); PG8_MMA(1, 0, At, B0); PG8_BAR; PG8_SCHED;
;             PG8_STAGE(PG8_SB(1, 1), b3 + hstepB, voffB);
;             PG8_WAIT_V(6); PG8_BAR; PG8_MMA(1, 1, At, B1); PG8_BAR;
;         }
	s_setprio 1
	s_waitcnt lgkmcnt(7)
	v_mfma_f32_16x16x32_bf16 v[60:63], v[150:153], v[166:169], v[60:63]
	v_mfma_f32_16x16x32_bf16 v[56:59], v[158:161], v[166:169], v[56:59]
	s_waitcnt lgkmcnt(5)
	v_mfma_f32_16x16x32_bf16 v[52:55], v[150:153], v[174:177], v[52:55]
	v_mfma_f32_16x16x32_bf16 v[48:51], v[158:161], v[174:177], v[48:51]
	s_waitcnt lgkmcnt(3)
	v_mfma_f32_16x16x32_bf16 v[36:39], v[150:153], v[182:185], v[36:39]
	v_mfma_f32_16x16x32_bf16 v[32:35], v[158:161], v[182:185], v[32:35]
	s_waitcnt lgkmcnt(1)
	v_mfma_f32_16x16x32_bf16 v[20:23], v[150:153], v[190:193], v[20:23]
	v_mfma_f32_16x16x32_bf16 v[16:19], v[158:161], v[190:193], v[16:19]
	v_mfma_f32_16x16x32_bf16 v[60:63], v[154:157], v[170:173], v[60:63]
	v_mfma_f32_16x16x32_bf16 v[56:59], v[162:165], v[170:173], v[56:59]
	v_mfma_f32_16x16x32_bf16 v[52:55], v[154:157], v[178:181], v[52:55]
	v_mfma_f32_16x16x32_bf16 v[48:51], v[162:165], v[178:181], v[48:51]
	v_mfma_f32_16x16x32_bf16 v[36:39], v[154:157], v[186:189], v[36:39]
	v_mfma_f32_16x16x32_bf16 v[32:35], v[162:165], v[186:189], v[32:35]
	s_waitcnt lgkmcnt(0)
	v_mfma_f32_16x16x32_bf16 v[20:23], v[154:157], v[198:201], v[20:23]
	v_mfma_f32_16x16x32_bf16 v[16:19], v[162:165], v[198:201], v[16:19]
	s_setprio 0
	s_barrier
	s_add_u32 s20, s20, 0x20080
	s_addc_u32 s21, s21, 0
	s_add_i32 s22, s22, s31
	s_mov_b32 m0, s22
	s_nop 0
	global_load_lds_dwordx4 v132, s[20:21]
	s_add_i32 m0, s22, 0x2000
	s_nop 0
	global_load_lds_dwordx4 v128, s[20:21]
	s_waitcnt vmcnt(6)
	s_barrier
	s_setprio 1
	v_mfma_f32_16x16x32_bf16 v[44:47], v[202:205], v[166:169], v[44:47]
	v_mfma_f32_16x16x32_bf16 v[40:43], v[210:213], v[166:169], v[40:43]
	ds_read_b128 v[150:153], v147
	v_mfma_f32_16x16x32_bf16 v[28:31], v[202:205], v[174:177], v[28:31]
	v_mfma_f32_16x16x32_bf16 v[24:27], v[210:213], v[174:177], v[24:27]
	ds_read_b128 v[154:157], v147 offset:1024
	v_mfma_f32_16x16x32_bf16 v[12:15], v[202:205], v[182:185], v[12:15]
	v_mfma_f32_16x16x32_bf16 v[8:11], v[210:213], v[182:185], v[8:11]
	ds_read_b128 v[158:161], v147 offset:2048
	v_mfma_f32_16x16x32_bf16 v[4:7], v[202:205], v[190:193], v[4:7]
	v_mfma_f32_16x16x32_bf16 v[0:3], v[210:213], v[190:193], v[0:3]
	ds_read_b128 v[162:165], v147 offset:3072
	v_mfma_f32_16x16x32_bf16 v[44:47], v[206:209], v[170:173], v[44:47]
	s_add_i32 s3, s3, 2
	v_mfma_f32_16x16x32_bf16 v[40:43], v[214:217], v[170:173], v[40:43]
	s_add_u32 s55, s55, 0x100
	s_addc_u32 s56, s56, 0
	v_mfma_f32_16x16x32_bf16 v[28:31], v[206:209], v[178:181], v[28:31]
	s_add_u32 s18, s18, 0x100
	s_addc_u32 s19, s19, 0
	v_mfma_f32_16x16x32_bf16 v[24:27], v[214:217], v[178:181], v[24:27]
	s_cmp_gt_u32 s3, 5
	v_mfma_f32_16x16x32_bf16 v[12:15], v[206:209], v[186:189], v[12:15]
	v_mfma_f32_16x16x32_bf16 v[8:11], v[214:217], v[186:189], v[8:11]
	v_mfma_f32_16x16x32_bf16 v[4:7], v[206:209], v[198:201], v[4:7]
	v_mfma_f32_16x16x32_bf16 v[0:3], v[214:217], v[198:201], v[0:3]
	s_setprio 0
	s_barrier
	s_cbranch_scc0 .LBB1_1529
; DI unsigned pack2(float a, float b) { f32x2 v = {a, b}; hwbf16x2 r = __builtin_convertvector(v, hwbf16x2); return __builtin_bit_cast(unsigned, r); }
;     DI void operator()(const f32x4 (&acc)[2][2][4][2], const Unit& u, int wr, int wc, int fr, int fq) const {
;         bf16_t* O = O1; int ldc = ldc1, pn = u.pn; if (pn >= split) { O = O2; ldc = ldc2; pn -= split; }
;         const int row0 = u.pm * BM + wr * 64 + fr, col0 = pn * BM + wc * 32 + 8 * fq;
; #pragma unroll
;         for (int ai = 0; ai < 2; ++ai)
; #pragma unroll
;             for (int m = 0; m < 4; ++m) { bf16_t* rowp = O + (size_t)(row0 + ai * HALF + m * 16) * ldc + col0;
; #pragma unroll
;                 for (int bj = 0; bj < 2; ++bj) { const f32x4 v0 = acc[ai][bj][m][0], v1 = acc[ai][bj][m][1];
;                     u32x4 o; o[0] = pack2(v0[0], v0[1]); o[1] = pack2(v0[2], v0[3]); o[2] = pack2(v1[0], v1[1]); o[3] = pack2(v1[2], v1[3]);
;                     *(u32x4*)(rowp + bj * HALF) = o; } }
;     }
	s_waitcnt lgkmcnt(0)
	s_cmp_lt_i32 s45, 12
	s_cselect_b32 s3, 0, -12
	s_mov_b32 s13, 0x1e510000
	s_movk_i32 s18, 0xc00
	s_cselect_b32 s13, s13, 0x2a510000
	s_cselect_b32 s20, s18, 0x1000
	s_add_i32 s3, s3, s45
	s_add_u32 s18, s6, s13
	v_mov_b32_e32 v150, v144
	v_mov_b32_e32 v151, v145
	s_addc_u32 s19, s7, 0
	s_lshl_b32 s10, s10, 8
	s_lshl_b32 s3, s3, 8
	s_add_i32 s10, s10, s39
	s_or_b32 s3, s3, s42
	v_add_u32_e32 v154, s10, v150
	v_lshl_add_u32 v150, v151, 3, s3
	v_ashrrev_i32_e32 v151, 31, v150
	v_lshl_add_u64 v[150:151], v[150:151], 1, s[18:19]
	v_mad_i64_i32 v[152:153], s[18:19], s20, v154, 0
	v_cvt_pk_bf16_f32 v108, v108, v109
	v_cvt_pk_bf16_f32 v109, v110, v111
	v_cvt_pk_bf16_f32 v110, v104, v105
	v_add_u32_e32 v104, 16, v154
	v_lshl_add_u64 v[152:153], v[152:153], 1, v[150:151]
	v_cvt_pk_bf16_f32 v111, v106, v107
	v_mad_i64_i32 v[104:105], s[18:19], s20, v104, 0
	v_cvt_pk_bf16_f32 v92, v92, v93
	v_cvt_pk_bf16_f32 v93, v94, v95
	v_cvt_pk_bf16_f32 v94, v88, v89
	v_add_u32_e32 v88, 32, v154
	v_cvt_pk_bf16_f32 v124, v124, v125
	v_cvt_pk_bf16_f32 v125, v126, v127
	v_cvt_pk_bf16_f32 v126, v120, v121
	v_cvt_pk_bf16_f32 v127, v122, v123
	global_store_dwordx4 v[152:153], v[108:111], off offset:256
	v_cvt_pk_bf16_f32 v95, v90, v91
	v_mad_i64_i32 v[88:89], s[18:19], s20, v88, 0
	v_lshl_add_u64 v[108:109], v[104:105], 1, v[150:151]
	v_cvt_pk_bf16_f32 v76, v76, v77
	v_cvt_pk_bf16_f32 v77, v78, v79
	v_cvt_pk_bf16_f32 v78, v72, v73
	v_add_u32_e32 v72, 48, v154
	v_cvt_pk_bf16_f32 v68, v68, v69
	v_cvt_pk_bf16_f32 v69, v70, v71
	v_cvt_pk_bf16_f32 v70, v64, v65
	v_add_u32_e32 v64, 0x80, v154
	global_store_dwordx4 v[152:153], v[124:127], off
	v_cvt_pk_bf16_f32 v104, v116, v117
	v_cvt_pk_bf16_f32 v105, v118, v119
	v_cvt_pk_bf16_f32 v106, v112, v113
	v_cvt_pk_bf16_f32 v107, v114, v115
	global_store_dwordx4 v[108:109], v[92:95], off offset:256
	v_cvt_pk_bf16_f32 v79, v74, v75
	v_mad_i64_i32 v[72:73], s[18:19], s20, v72, 0
	v_lshl_add_u64 v[92:93], v[88:89], 1, v[150:151]
	v_mad_i64_i32 v[64:65], s[18:19], s20, v64, 0
	v_cvt_pk_bf16_f32 v44, v44, v45
	v_cvt_pk_bf16_f32 v45, v46, v47
	v_cvt_pk_bf16_f32 v46, v40, v41
	v_add_u32_e32 v40, 0x90, v154
	global_store_dwordx4 v[108:109], v[104:107], off
	v_cvt_pk_bf16_f32 v88, v100, v101
	v_cvt_pk_bf16_f32 v89, v102, v103
	v_cvt_pk_bf16_f32 v90, v96, v97
	v_cvt_pk_bf16_f32 v91, v98, v99
	global_store_dwordx4 v[92:93], v[76:79], off offset:256
	v_cvt_pk_bf16_f32 v74, v80, v81
	v_cvt_pk_bf16_f32 v75, v82, v83
	v_lshl_add_u64 v[76:77], v[72:73], 1, v[150:151]
	v_cvt_pk_bf16_f32 v72, v84, v85
	v_cvt_pk_bf16_f32 v73, v86, v87
	v_cvt_pk_bf16_f32 v71, v66, v67
	v_lshl_add_u64 v[64:65], v[64:65], 1, v[150:151]
	v_cvt_pk_bf16_f32 v47, v42, v43
	v_mad_i64_i32 v[40:41], s[18:19], s20, v40, 0
	v_cvt_pk_bf16_f32 v28, v28, v29
	v_cvt_pk_bf16_f32 v29, v30, v31
	v_cvt_pk_bf16_f32 v30, v24, v25
	v_add_u32_e32 v24, 0xa0, v154
	global_store_dwordx4 v[92:93], v[88:91], off
	global_store_dwordx4 v[76:77], v[72:75], off
	global_store_dwordx4 v[76:77], v[68:71], off offset:256
	v_cvt_pk_bf16_f32 v60, v60, v61
	v_cvt_pk_bf16_f32 v61, v62, v63
	v_cvt_pk_bf16_f32 v62, v56, v57
	v_cvt_pk_bf16_f32 v63, v58, v59
	global_store_dwordx4 v[64:65], v[44:47], off offset:256
	v_cvt_pk_bf16_f32 v31, v26, v27
	v_mad_i64_i32 v[24:25], s[18:19], s20, v24, 0
	v_lshl_add_u64 v[44:45], v[40:41], 1, v[150:151]
	v_cvt_pk_bf16_f32 v12, v12, v13
	v_cvt_pk_bf16_f32 v13, v14, v15
	v_cvt_pk_bf16_f32 v14, v8, v9
	v_add_u32_e32 v8, 0xb0, v154
	global_store_dwordx4 v[64:65], v[60:63], off
	v_cvt_pk_bf16_f32 v40, v52, v53
	v_cvt_pk_bf16_f32 v41, v54, v55
	v_cvt_pk_bf16_f32 v42, v48, v49
	v_cvt_pk_bf16_f32 v43, v50, v51
	global_store_dwordx4 v[44:45], v[28:31], off offset:256
	v_cvt_pk_bf16_f32 v15, v10, v11
	v_mad_i64_i32 v[8:9], s[18:19], s20, v8, 0
	v_lshl_add_u64 v[28:29], v[24:25], 1, v[150:151]
	global_store_dwordx4 v[44:45], v[40:43], off
	v_cvt_pk_bf16_f32 v24, v36, v37
	v_cvt_pk_bf16_f32 v25, v38, v39
	v_cvt_pk_bf16_f32 v26, v32, v33
	v_cvt_pk_bf16_f32 v27, v34, v35
	global_store_dwordx4 v[28:29], v[12:15], off offset:256
	v_cvt_pk_bf16_f32 v10, v16, v17
	v_cvt_pk_bf16_f32 v11, v18, v19
	v_lshl_add_u64 v[12:13], v[8:9], 1, v[150:151]
	v_cvt_pk_bf16_f32 v8, v20, v21
	v_cvt_pk_bf16_f32 v9, v22, v23
	v_cvt_pk_bf16_f32 v4, v4, v5
	v_cvt_pk_bf16_f32 v5, v6, v7
	v_cvt_pk_bf16_f32 v6, v0, v1
	v_cvt_pk_bf16_f32 v7, v2, v3
	s_and_b64 vcc, exec, s[40:41]
	s_mov_b32 s45, s49
	s_mov_b32 s10, s12
	s_mov_b64 s[18:19], s[16:17]
	s_mov_b64 s[20:21], s[14:15]
	global_store_dwordx4 v[28:29], v[24:27], off
	global_store_dwordx4 v[12:13], v[8:11], off
	global_store_dwordx4 v[12:13], v[4:7], off offset:256
	s_cbranch_vccz .LBB1_1526
	s_waitcnt vmcnt(0)
	s_cmpk_gt_u32 s4, 0xff
	s_cbranch_scc1 .LBB1_1533
	s_barrier

; #define PG8_STAGE(bufoff, gbase, voff) do { _Pragma("unroll") for (int _i = 0; _i < 2; ++_i) \
;         __builtin_amdgcn_global_load_lds((const unsigned*)((const char*)(gbase) + (voff)[_i]), (LAS unsigned*)(lds + (bufoff) + ldsw + _i * 8192), 16, 0, 0); } while (0)
; #define PG8_LDA(dst, b, h) do { _Pragma("unroll") for (int m = 0; m < 4; ++m) _Pragma("unroll") for (int k = 0; k < 2; ++k) dst[m][k] = *(const LAS bf16x8*)(lds + PG8_SA(b, h) + aoff + m * 2048 + k * 1024); } while (0)
; #define PG8_LDB(dst, b, h) do { _Pragma("unroll") for (int n = 0; n < 2; ++n) _Pragma("unroll") for (int k = 0; k < 2; ++k) dst[n][k] = *(const LAS bf16x8*)(lds + PG8_SB(b, h) + boff + n * 2048 + k * 1024); } while (0)
; #define PG8_MMA(ai, bj, At, Bt) do { __builtin_amdgcn_s_setprio(1); _Pragma("unroll") for (int m = 0; m < 4; ++m) _Pragma("unroll") for (int n = 0; n < 2; ++n) _Pragma("unroll") for (int k = 0; k < 2; ++k) \
;         acc[ai][bj][m][n] = __builtin_amdgcn_mfma_f32_16x16x32_bf16(Bt[n][k], At[m][k], acc[ai][bj][m][n], 0, 0, 0); __builtin_amdgcn_s_setprio(0); } while (0)
; #define PG8_WAIT_L(n) asm volatile("s_waitcnt lgkmcnt(" #n ")" ::: "memory")
; #define PG8_BAR __builtin_amdgcn_s_barrier()
; #define PG8_SCHED __builtin_amdgcn_sched_barrier(0)
; template <class Map, class Epi>
; DI void gemm_phase(LAS unsigned char* lds, const Map& MP, const Epi& E, const int nM, const int nN, const int K, const int lda, const int ldb) {
;     ...
;             const bool last = (t == nt - 2);
;             const char* a1 = cA + (size_t)(t + 1) * kstep;
;             const char* a2 = last ? nA : cA + (size_t)(t + 2) * kstep; const char* b2 = last ? nB : cB + (size_t)(t + 2) * kstep;
;             const char* a3 = a2 + kstep; const char* b3 = b2 + kstep;
;             PG8_LDB(B0, 0, 0); PG8_SCHED; PG8_LDA(At, 0, 0); PG8_STAGE(PG8_SA(1, 1), a1 + hstepA, voffA);
;             PG8_WAIT_L(8); PG8_BAR; PG8_WAIT_L(0); PG8_MMA(0, 0, At, B0); PG8_BAR; PG8_SCHED;
;             PG8_LDB(B1, 0, 1); PG8_STAGE(PG8_SB(0, 0), b2, voffB);
;             PG8_BAR; PG8_WAIT_L(0); PG8_MMA(0, 1, At, B1); PG8_BAR;
;             PG8_LDA(At, 0, 1); PG8_STAGE(PG8_SA(0, 0), a2, voffA);
;             PG8_BAR; PG8_WAIT_L(0); PG8_MMA(1, 0, At, B0); PG8_BAR; PG8_SCHED;
.LBB1_1764:
	s_add_u32 s12, s10, 0xfff80080
	s_addc_u32 s13, s11, -1
	s_cmp_eq_u32 s3, 28
	s_cselect_b32 s15, s37, s13
	s_cselect_b32 s14, s38, s12
	s_cselect_b32 s13, s39, s48
	s_cselect_b32 s12, s45, s47
	s_add_i32 m0, s24, 0xc000
	ds_read_b128 v[168:171], v150
	ds_read_b128 v[172:175], v150 offset:1024
	ds_read_b128 v[176:179], v150 offset:2048
	ds_read_b128 v[180:183], v150 offset:3072
	ds_read_b128 v[184:187], v150 offset:4096
	ds_read_b128 v[188:191], v150 offset:5120
	ds_read_b128 v[192:195], v150 offset:6144
	ds_read_b128 v[198:201], v150 offset:7168
	global_load_lds_dwordx4 v138, s[10:11]
	s_add_i32 m0, s24, 0xe000
	s_nop 0
	global_load_lds_dwordx4 v136, s[10:11]
	s_waitcnt lgkmcnt(8)
	s_barrier
	s_setprio 1
	s_waitcnt lgkmcnt(7)
	v_mfma_f32_16x16x32_bf16 v[124:127], v[152:155], v[168:171], v[124:127]
	v_mfma_f32_16x16x32_bf16 v[120:123], v[160:163], v[168:171], v[120:123]
	s_waitcnt lgkmcnt(5)
	v_mfma_f32_16x16x32_bf16 v[108:111], v[152:155], v[176:179], v[108:111]
	v_mfma_f32_16x16x32_bf16 v[104:107], v[160:163], v[176:179], v[104:107]
	s_waitcnt lgkmcnt(3)
	v_mfma_f32_16x16x32_bf16 v[92:95], v[152:155], v[184:187], v[92:95]
	v_mfma_f32_16x16x32_bf16 v[88:91], v[160:163], v[184:187], v[88:91]
	s_waitcnt lgkmcnt(1)
	v_mfma_f32_16x16x32_bf16 v[76:79], v[152:155], v[192:195], v[76:79]
	v_mfma_f32_16x16x32_bf16 v[72:75], v[160:163], v[192:195], v[72:75]
	v_mfma_f32_16x16x32_bf16 v[124:127], v[156:159], v[172:175], v[124:127]
	v_mfma_f32_16x16x32_bf16 v[120:123], v[164:167], v[172:175], v[120:123]
	v_mfma_f32_16x16x32_bf16 v[108:111], v[156:159], v[180:183], v[108:111]
	v_mfma_f32_16x16x32_bf16 v[104:107], v[164:167], v[180:183], v[104:107]
	v_mfma_f32_16x16x32_bf16 v[92:95], v[156:159], v[188:191], v[92:95]
	v_mfma_f32_16x16x32_bf16 v[88:91], v[164:167], v[188:191], v[88:91]
	s_waitcnt lgkmcnt(0)
	v_mfma_f32_16x16x32_bf16 v[76:79], v[156:159], v[198:201], v[76:79]
	v_mfma_f32_16x16x32_bf16 v[72:75], v[164:167], v[198:201], v[72:75]
	s_setprio 0
	s_barrier
	s_add_i32 s49, s35, s22
	v_lshl_add_u64 v[144:145], s[12:13], 0, v[132:133]
	s_mov_b32 m0, s49
	ds_read_b128 v[202:205], v151
	ds_read_b128 v[206:209], v151 offset:1024
	ds_read_b128 v[210:213], v151 offset:2048
	ds_read_b128 v[214:217], v151 offset:3072
	global_load_lds_dwordx4 v[144:145], off
	v_lshl_add_u64 v[218:219], s[12:13], 0, v[128:129]
	s_add_i32 m0, s49, 0x2000
	s_nop 0
	global_load_lds_dwordx4 v[218:219], off
	s_barrier
	s_setprio 1
	s_waitcnt lgkmcnt(3)
	v_mfma_f32_16x16x32_bf16 v[116:119], v[202:205], v[168:171], v[116:119]
	s_waitcnt lgkmcnt(1)
	v_mfma_f32_16x16x32_bf16 v[112:115], v[210:213], v[168:171], v[112:115]
	v_mfma_f32_16x16x32_bf16 v[100:103], v[202:205], v[176:179], v[100:103]
	v_mfma_f32_16x16x32_bf16 v[96:99], v[210:213], v[176:179], v[96:99]
	v_mfma_f32_16x16x32_bf16 v[84:87], v[202:205], v[184:187], v[84:87]
	v_mfma_f32_16x16x32_bf16 v[80:83], v[210:213], v[184:187], v[80:83]
	v_mfma_f32_16x16x32_bf16 v[68:71], v[202:205], v[192:195], v[68:71]
	v_mfma_f32_16x16x32_bf16 v[64:67], v[210:213], v[192:195], v[64:67]
	v_mfma_f32_16x16x32_bf16 v[116:119], v[206:209], v[172:175], v[116:119]
	s_mov_b32 m0, s24
	s_waitcnt lgkmcnt(0)
	v_mfma_f32_16x16x32_bf16 v[112:115], v[214:217], v[172:175], v[112:115]
	v_lshl_add_u64 v[220:221], s[14:15], 0, v[134:135]
	v_mfma_f32_16x16x32_bf16 v[100:103], v[206:209], v[180:183], v[100:103]
	v_mfma_f32_16x16x32_bf16 v[96:99], v[214:217], v[180:183], v[96:99]
	v_mfma_f32_16x16x32_bf16 v[84:87], v[206:209], v[188:191], v[84:87]
	v_mfma_f32_16x16x32_bf16 v[80:83], v[214:217], v[188:191], v[80:83]
	v_mfma_f32_16x16x32_bf16 v[68:71], v[206:209], v[198:201], v[68:71]
	v_mfma_f32_16x16x32_bf16 v[64:67], v[214:217], v[198:201], v[64:67]
	s_setprio 0
	s_barrier
	ds_read_b128 v[168:171], v150 offset:16384
	ds_read_b128 v[172:175], v150 offset:17408
	ds_read_b128 v[176:179], v150 offset:18432
	ds_read_b128 v[180:183], v150 offset:19456
	ds_read_b128 v[184:187], v150 offset:20480
	ds_read_b128 v[188:191], v150 offset:21504
	ds_read_b128 v[192:195], v150 offset:22528
	ds_read_b128 v[198:201], v150 offset:23552
	global_load_lds_dwordx4 v[220:221], off
	v_lshl_add_u64 v[222:223], s[14:15], 0, v[130:131]
	s_mov_b32 m0, s9
	s_nop 0
	global_load_lds_dwordx4 v[222:223], off
	s_waitcnt vmcnt(10)
	s_barrier
	s_setprio 1
	s_waitcnt lgkmcnt(7)
	v_mfma_f32_16x16x32_bf16 v[60:63], v[152:155], v[168:171], v[60:63]
	v_mfma_f32_16x16x32_bf16 v[56:59], v[160:163], v[168:171], v[56:59]
	s_waitcnt lgkmcnt(5)
	v_mfma_f32_16x16x32_bf16 v[44:47], v[152:155], v[176:179], v[44:47]
	v_mfma_f32_16x16x32_bf16 v[40:43], v[160:163], v[176:179], v[40:43]
	s_waitcnt lgkmcnt(3)
	v_mfma_f32_16x16x32_bf16 v[28:31], v[152:155], v[184:187], v[28:31]
	v_mfma_f32_16x16x32_bf16 v[24:27], v[160:163], v[184:187], v[24:27]
	s_waitcnt lgkmcnt(1)
	v_mfma_f32_16x16x32_bf16 v[12:15], v[152:155], v[192:195], v[12:15]
	v_mfma_f32_16x16x32_bf16 v[8:11], v[160:163], v[192:195], v[8:11]
	v_mfma_f32_16x16x32_bf16 v[60:63], v[156:159], v[172:175], v[60:63]
	v_mfma_f32_16x16x32_bf16 v[56:59], v[164:167], v[172:175], v[56:59]
	v_mfma_f32_16x16x32_bf16 v[44:47], v[156:159], v[180:183], v[44:47]
	v_mfma_f32_16x16x32_bf16 v[40:43], v[164:167], v[180:183], v[40:43]
	v_mfma_f32_16x16x32_bf16 v[28:31], v[156:159], v[188:191], v[28:31]
	v_mfma_f32_16x16x32_bf16 v[24:27], v[164:167], v[188:191], v[24:27]
	s_waitcnt lgkmcnt(0)
	v_mfma_f32_16x16x32_bf16 v[12:15], v[156:159], v[198:201], v[12:15]
	v_mfma_f32_16x16x32_bf16 v[8:11], v[164:167], v[198:201], v[8:11]
	s_setprio 0
	s_barrier
; #define PG8_STAGE(bufoff, gbase, voff) do { _Pragma("unroll") for (int _i = 0; _i < 2; ++_i) \
;         __builtin_amdgcn_global_load_lds((const unsigned*)((const char*)(gbase) + (voff)[_i]), (LAS unsigned*)(lds + (bufoff) + ldsw + _i * 8192), 16, 0, 0); } while (0)
; #define PG8_LDA(dst, b, h) do { _Pragma("unroll") for (int m = 0; m < 4; ++m) _Pragma("unroll") for (int k = 0; k < 2; ++k) dst[m][k] = *(const LAS bf16x8*)(lds + PG8_SA(b, h) + aoff + m * 2048 + k * 1024); } while (0)
; #define PG8_LDB(dst, b, h) do { _Pragma("unroll") for (int n = 0; n < 2; ++n) _Pragma("unroll") for (int k = 0; k < 2; ++k) dst[n][k] = *(const LAS bf16x8*)(lds + PG8_SB(b, h) + boff + n * 2048 + k * 1024); } while (0)
; #define PG8_MMA(ai, bj, At, Bt) do { __builtin_amdgcn_s_setprio(1); _Pragma("unroll") for (int m = 0; m < 4; ++m) _Pragma("unroll") for (int n = 0; n < 2; ++n) _Pragma("unroll") for (int k = 0; k < 2; ++k) \
;         acc[ai][bj][m][n] = __builtin_amdgcn_mfma_f32_16x16x32_bf16(Bt[n][k], At[m][k], acc[ai][bj][m][n], 0, 0, 0); __builtin_amdgcn_s_setprio(0); } while (0)
; #define PG8_WAIT_V(n) asm volatile("s_waitcnt vmcnt(" #n ")" ::: "memory")
; #define PG8_WAIT_L(n) asm volatile("s_waitcnt lgkmcnt(" #n ")" ::: "memory")
; #define PG8_BAR __builtin_amdgcn_s_barrier()
; #define PG8_SCHED __builtin_amdgcn_sched_barrier(0)
; template <class Map, class Epi>
; DI void gemm_phase(LAS unsigned char* lds, const Map& MP, const Epi& E, const int nM, const int nN, const int K, const int lda, const int ldb) {
;     ...
;             PG8_STAGE(PG8_SB(0, 1), b2 + hstepB, voffB);
;             PG8_WAIT_V(6); PG8_BAR; PG8_MMA(1, 1, At, B1); PG8_BAR;
;             PG8_LDB(B0, 1, 0); PG8_SCHED; PG8_LDA(At, 1, 0); PG8_STAGE(PG8_SA(0, 1), a2 + hstepA, voffA);
;             PG8_WAIT_L(8); PG8_BAR; PG8_WAIT_L(0); PG8_MMA(0, 0, At, B0); PG8_BAR; PG8_SCHED;
;             PG8_LDB(B1, 1, 1); PG8_STAGE(PG8_SB(1, 0), b3, voffB);
;             PG8_BAR; PG8_WAIT_L(0); PG8_MMA(0, 1, At, B1); PG8_BAR;
;             PG8_LDA(At, 1, 1); PG8_STAGE(PG8_SA(1, 0), a3, voffA);
;             PG8_BAR; PG8_WAIT_L(0); PG8_MMA(1, 0, At, B0); PG8_BAR; PG8_SCHED;
	s_add_u32 s54, s12, 0x80000
	s_addc_u32 s55, s13, 0
	s_add_i32 s49, s36, s22
	s_mov_b32 m0, s49
	s_nop 0
	global_load_lds_dwordx4 v132, s[54:55]
	s_add_i32 m0, s49, 0x2000
	s_nop 0
	global_load_lds_dwordx4 v128, s[54:55]
	s_waitcnt vmcnt(6)
	s_barrier
	s_setprio 1
	v_mfma_f32_16x16x32_bf16 v[52:55], v[202:205], v[168:171], v[52:55]
	v_mfma_f32_16x16x32_bf16 v[48:51], v[210:213], v[168:171], v[48:51]
	s_add_i32 s49, 0, 0x18000
	v_add_u32_e32 v164, s49, v148
	ds_read_b128 v[152:155], v164
	v_mfma_f32_16x16x32_bf16 v[36:39], v[202:205], v[176:179], v[36:39]
	v_mfma_f32_16x16x32_bf16 v[32:35], v[210:213], v[176:179], v[32:35]
	ds_read_b128 v[156:159], v164 offset:1024
	v_mfma_f32_16x16x32_bf16 v[20:23], v[202:205], v[184:187], v[20:23]
	v_mfma_f32_16x16x32_bf16 v[16:19], v[210:213], v[184:187], v[16:19]
	ds_read_b128 v[160:163], v164 offset:2048
	v_mfma_f32_16x16x32_bf16 v[4:7], v[202:205], v[192:195], v[4:7]
	v_mfma_f32_16x16x32_bf16 v[0:3], v[210:213], v[192:195], v[0:3]
	ds_read_b128 v[164:167], v164 offset:3072
	v_mfma_f32_16x16x32_bf16 v[52:55], v[206:209], v[172:175], v[52:55]
	v_mfma_f32_16x16x32_bf16 v[48:51], v[214:217], v[172:175], v[48:51]
	v_mfma_f32_16x16x32_bf16 v[36:39], v[206:209], v[180:183], v[36:39]
	v_mfma_f32_16x16x32_bf16 v[32:35], v[214:217], v[180:183], v[32:35]
	v_mfma_f32_16x16x32_bf16 v[20:23], v[206:209], v[188:191], v[20:23]
	v_mfma_f32_16x16x32_bf16 v[16:19], v[214:217], v[188:191], v[16:19]
	v_mfma_f32_16x16x32_bf16 v[4:7], v[206:209], v[198:201], v[4:7]
	v_mfma_f32_16x16x32_bf16 v[0:3], v[214:217], v[198:201], v[0:3]
	s_setprio 0
	s_barrier
	s_add_u32 s14, s14, 0x80000
	s_addc_u32 s15, s15, 0
	s_mov_b32 m0, s25
	ds_read_b128 v[168:171], v150 offset:32768
	ds_read_b128 v[172:175], v150 offset:33792
	ds_read_b128 v[176:179], v150 offset:34816
	ds_read_b128 v[180:183], v150 offset:35840
	ds_read_b128 v[184:187], v150 offset:36864
	ds_read_b128 v[188:191], v150 offset:37888
	ds_read_b128 v[192:195], v150 offset:38912
	ds_read_b128 v[198:201], v150 offset:39936
	global_load_lds_dwordx4 v134, s[14:15]
	s_mov_b32 m0, s26
	s_nop 0
	global_load_lds_dwordx4 v130, s[14:15]
	s_waitcnt lgkmcnt(8)
	s_barrier
	s_setprio 1
	s_waitcnt lgkmcnt(7)
	v_mfma_f32_16x16x32_bf16 v[124:127], v[152:155], v[168:171], v[124:127]
	v_mfma_f32_16x16x32_bf16 v[120:123], v[160:163], v[168:171], v[120:123]
	s_waitcnt lgkmcnt(5)
	v_mfma_f32_16x16x32_bf16 v[108:111], v[152:155], v[176:179], v[108:111]
	v_mfma_f32_16x16x32_bf16 v[104:107], v[160:163], v[176:179], v[104:107]
	s_waitcnt lgkmcnt(3)
	v_mfma_f32_16x16x32_bf16 v[92:95], v[152:155], v[184:187], v[92:95]
	v_mfma_f32_16x16x32_bf16 v[88:91], v[160:163], v[184:187], v[88:91]
	s_waitcnt lgkmcnt(1)
	v_mfma_f32_16x16x32_bf16 v[76:79], v[152:155], v[192:195], v[76:79]
	v_mfma_f32_16x16x32_bf16 v[72:75], v[160:163], v[192:195], v[72:75]
	v_mfma_f32_16x16x32_bf16 v[124:127], v[156:159], v[172:175], v[124:127]
	v_mfma_f32_16x16x32_bf16 v[120:123], v[164:167], v[172:175], v[120:123]
	v_mfma_f32_16x16x32_bf16 v[108:111], v[156:159], v[180:183], v[108:111]
	v_mfma_f32_16x16x32_bf16 v[104:107], v[164:167], v[180:183], v[104:107]
	v_mfma_f32_16x16x32_bf16 v[92:95], v[156:159], v[188:191], v[92:95]
	v_mfma_f32_16x16x32_bf16 v[88:91], v[164:167], v[188:191], v[88:91]
	s_waitcnt lgkmcnt(0)
	v_mfma_f32_16x16x32_bf16 v[76:79], v[156:159], v[198:201], v[76:79]
	v_mfma_f32_16x16x32_bf16 v[72:75], v[164:167], v[198:201], v[72:75]
	s_setprio 0
	s_barrier
	s_add_i32 s14, 0, 0x1c000
	s_add_i32 s15, s49, s22
	v_add_u32_e32 v196, s14, v148
	v_lshl_add_u64 v[144:145], v[144:145], 0, s[42:43]
	s_mov_b32 m0, s15
	ds_read_b128 v[202:205], v196
	ds_read_b128 v[206:209], v196 offset:1024
	ds_read_b128 v[210:213], v196 offset:2048
	ds_read_b128 v[214:217], v196 offset:3072
	global_load_lds_dwordx4 v[144:145], off
	v_lshl_add_u64 v[144:145], v[218:219], 0, s[42:43]
	s_add_i32 m0, s15, 0x2000
	s_nop 0
	global_load_lds_dwordx4 v[144:145], off
	s_barrier
	s_setprio 1
	s_waitcnt lgkmcnt(3)
	v_mfma_f32_16x16x32_bf16 v[116:119], v[202:205], v[168:171], v[116:119]
	s_waitcnt lgkmcnt(1)
	v_mfma_f32_16x16x32_bf16 v[112:115], v[210:213], v[168:171], v[112:115]
	v_mfma_f32_16x16x32_bf16 v[100:103], v[202:205], v[176:179], v[100:103]
	v_mfma_f32_16x16x32_bf16 v[96:99], v[210:213], v[176:179], v[96:99]
	v_mfma_f32_16x16x32_bf16 v[84:87], v[202:205], v[184:187], v[84:87]
	v_mfma_f32_16x16x32_bf16 v[80:83], v[210:213], v[184:187], v[80:83]
	v_mfma_f32_16x16x32_bf16 v[68:71], v[202:205], v[192:195], v[68:71]
	v_mfma_f32_16x16x32_bf16 v[64:67], v[210:213], v[192:195], v[64:67]
	v_mfma_f32_16x16x32_bf16 v[116:119], v[206:209], v[172:175], v[116:119]
	s_mov_b32 m0, s30
	s_waitcnt lgkmcnt(0)
	v_mfma_f32_16x16x32_bf16 v[112:115], v[214:217], v[172:175], v[112:115]
	v_lshl_add_u64 v[144:145], v[220:221], 0, s[42:43]
	v_mfma_f32_16x16x32_bf16 v[100:103], v[206:209], v[180:183], v[100:103]
	v_mfma_f32_16x16x32_bf16 v[96:99], v[214:217], v[180:183], v[96:99]
	v_mfma_f32_16x16x32_bf16 v[84:87], v[206:209], v[188:191], v[84:87]
	v_mfma_f32_16x16x32_bf16 v[80:83], v[214:217], v[188:191], v[80:83]
	v_mfma_f32_16x16x32_bf16 v[68:71], v[206:209], v[198:201], v[68:71]
	v_mfma_f32_16x16x32_bf16 v[64:67], v[214:217], v[198:201], v[64:67]
	s_setprio 0
	s_barrier
	ds_read_b128 v[168:171], v150 offset:49152
	ds_read_b128 v[172:175], v150 offset:50176
	ds_read_b128 v[176:179], v150 offset:51200
	ds_read_b128 v[180:183], v150 offset:52224
	ds_read_b128 v[184:187], v150 offset:53248
	ds_read_b128 v[188:191], v150 offset:54272
	ds_read_b128 v[192:195], v150 offset:55296
	ds_read_b128 v[198:201], v150 offset:56320
	global_load_lds_dwordx4 v[144:145], off
	v_lshl_add_u64 v[144:145], v[222:223], 0, s[42:43]
	s_mov_b32 m0, s31
	s_nop 0
	global_load_lds_dwordx4 v[144:145], off
	s_waitcnt vmcnt(10)
	s_barrier
; DI unsigned pack2(float a, float b) { f32x2 v = {a, b}; hwbf16x2 r = __builtin_convertvector(v, hwbf16x2); return __builtin_bit_cast(unsigned, r); }
; DI float bflo(unsigned w) { return __uint_as_float(w << 16); }
; DI float bfhi(unsigned w) { return __uint_as_float(w & 0xffff0000u); }
; #define PG8_WAIT_V(n) asm volatile("s_waitcnt vmcnt(" #n ")" ::: "memory")
;     DI void operator()(const f32x4 (&acc)[2][2][4][2], const Unit& u, int wr, int wc, int fr, int fq) const {
;         const int row0 = u.pm * BM + wr * 64 + fr, col0 = u.pn * BM + wc * 32 + 8 * fq;
;         f32x4 sc[2][2];
; #pragma unroll
;         for (int bj = 0; bj < 2; ++bj)
; #pragma unroll
;             for (int n = 0; n < 2; ++n) sc[bj][n] = scale ? *(const f32x4*)(scale + col0 + bj * HALF + 4 * n) : (f32x4){1.f, 1.f, 1.f, 1.f};
; #pragma unroll
;         for (int ai = 0; ai < 2; ++ai)
; #pragma unroll
;             for (int m = 0; m < 4; ++m) { const size_t ro = (size_t)(row0 + ai * HALF + m * 16) * D + col0;
; #pragma unroll
;                 for (int bj = 0; bj < 2; ++bj) {
;                     f32x4 x0, x1;
;                     if constexpr (IB) { const u32x4 w = *(const u32x4*)((const bf16_t*)Xin + ro + bj * HALF);
;                         x0 = (f32x4){bflo(w[0]), bfhi(w[0]), bflo(w[1]), bfhi(w[1])}; x1 = (f32x4){bflo(w[2]), bfhi(w[2]), bflo(w[3]), bfhi(w[3])}; }
;                     else { x0 = *(const f32x4*)((const float*)Xin + ro + bj * HALF); x1 = *(const f32x4*)((const float*)Xin + ro + bj * HALF + 4); }
;                     x0 += acc[ai][bj][m][0] * sc[bj][0]; x1 += acc[ai][bj][m][1] * sc[bj][1];
;                     if constexpr (OB) { u32x4 o; o[0] = pack2(x0[0], x0[1]); o[1] = pack2(x0[2], x0[3]); o[2] = pack2(x1[0], x1[1]); o[3] = pack2(x1[2], x1[3]);
;                         *(u32x4*)((bf16_t*)Xout + ro + bj * HALF) = o; }
;                     else { *(f32x4*)((float*)Xout + ro + bj * HALF) = x0; *(f32x4*)((float*)Xout + ro + bj * HALF + 4) = x1; } } }
; template <class Map, class Epi>
; DI void gemm_phase(LAS unsigned char* lds, const Map& MP, const Epi& E, const int nM, const int nN, const int K, const int lda, const int ldb) {
;     ...
;             PG8_BAR; PG8_WAIT_L(0); PG8_MMA(1, 0, At, B0); PG8_BAR; PG8_SCHED;
;             PG8_STAGE(PG8_SB(1, 1), b3 + hstepB, voffB);
;             PG8_WAIT_V(6); PG8_BAR; PG8_MMA(1, 1, At, B1); PG8_BAR;
;         }
	s_setprio 1
	s_waitcnt lgkmcnt(7)
	v_mfma_f32_16x16x32_bf16 v[60:63], v[152:155], v[168:171], v[60:63]
	v_mfma_f32_16x16x32_bf16 v[56:59], v[160:163], v[168:171], v[56:59]
	s_waitcnt lgkmcnt(5)
	v_mfma_f32_16x16x32_bf16 v[44:47], v[152:155], v[176:179], v[44:47]
	v_mfma_f32_16x16x32_bf16 v[40:43], v[160:163], v[176:179], v[40:43]
	s_waitcnt lgkmcnt(3)
	v_mfma_f32_16x16x32_bf16 v[28:31], v[152:155], v[184:187], v[28:31]
	v_mfma_f32_16x16x32_bf16 v[24:27], v[160:163], v[184:187], v[24:27]
	s_waitcnt lgkmcnt(1)
	v_mfma_f32_16x16x32_bf16 v[12:15], v[152:155], v[192:195], v[12:15]
	v_mfma_f32_16x16x32_bf16 v[8:11], v[160:163], v[192:195], v[8:11]
	v_mfma_f32_16x16x32_bf16 v[60:63], v[156:159], v[172:175], v[60:63]
	v_mfma_f32_16x16x32_bf16 v[56:59], v[164:167], v[172:175], v[56:59]
	v_mfma_f32_16x16x32_bf16 v[44:47], v[156:159], v[180:183], v[44:47]
	v_mfma_f32_16x16x32_bf16 v[40:43], v[164:167], v[180:183], v[40:43]
	v_mfma_f32_16x16x32_bf16 v[28:31], v[156:159], v[188:191], v[28:31]
	v_mfma_f32_16x16x32_bf16 v[24:27], v[164:167], v[188:191], v[24:27]
	s_waitcnt lgkmcnt(0)
	v_mfma_f32_16x16x32_bf16 v[12:15], v[156:159], v[198:201], v[12:15]
	v_mfma_f32_16x16x32_bf16 v[8:11], v[164:167], v[198:201], v[8:11]
	s_setprio 0
	s_barrier
	s_add_u32 s12, s12, 0x80080
	s_addc_u32 s13, s13, 0
	s_add_i32 s14, s14, s22
	s_mov_b32 m0, s14
	s_nop 0
	global_load_lds_dwordx4 v132, s[12:13]
	s_add_i32 m0, s14, 0x2000
	s_nop 0
	global_load_lds_dwordx4 v128, s[12:13]
	s_waitcnt vmcnt(6)
	s_barrier
	s_setprio 1
	v_mfma_f32_16x16x32_bf16 v[52:55], v[202:205], v[168:171], v[52:55]
	v_mfma_f32_16x16x32_bf16 v[48:51], v[210:213], v[168:171], v[48:51]
	ds_read_b128 v[152:155], v149
	v_mfma_f32_16x16x32_bf16 v[36:39], v[202:205], v[176:179], v[36:39]
	v_mfma_f32_16x16x32_bf16 v[32:35], v[210:213], v[176:179], v[32:35]
	ds_read_b128 v[156:159], v149 offset:1024
	v_mfma_f32_16x16x32_bf16 v[20:23], v[202:205], v[184:187], v[20:23]
	v_mfma_f32_16x16x32_bf16 v[16:19], v[210:213], v[184:187], v[16:19]
	ds_read_b128 v[160:163], v149 offset:2048
	v_mfma_f32_16x16x32_bf16 v[4:7], v[202:205], v[192:195], v[4:7]
	v_mfma_f32_16x16x32_bf16 v[0:3], v[210:213], v[192:195], v[0:3]
	ds_read_b128 v[164:167], v149 offset:3072
	v_mfma_f32_16x16x32_bf16 v[52:55], v[206:209], v[172:175], v[52:55]
	s_add_i32 s3, s3, 2
	v_mfma_f32_16x16x32_bf16 v[48:51], v[214:217], v[172:175], v[48:51]
	s_add_u32 s47, s47, 0x100
	s_addc_u32 s48, s48, 0
	v_mfma_f32_16x16x32_bf16 v[36:39], v[206:209], v[180:183], v[36:39]
	s_add_u32 s10, s10, 0x100
	s_addc_u32 s11, s11, 0
	v_mfma_f32_16x16x32_bf16 v[32:35], v[214:217], v[180:183], v[32:35]
	s_cmp_gt_u32 s3, 29
	v_mfma_f32_16x16x32_bf16 v[20:23], v[206:209], v[188:191], v[20:23]
	v_mfma_f32_16x16x32_bf16 v[16:19], v[214:217], v[188:191], v[16:19]
	v_mfma_f32_16x16x32_bf16 v[4:7], v[206:209], v[198:201], v[4:7]
	v_mfma_f32_16x16x32_bf16 v[0:3], v[214:217], v[198:201], v[0:3]
	s_setprio 0
	s_barrier
	s_cbranch_scc0 .LBB1_1764
	s_waitcnt lgkmcnt(0)
	v_mov_b32_e32 v152, v147
	v_mov_b32_e32 v144, v146
	s_lshl_b32 s2, s2, 8
	s_or_b32 s2, s2, s29
	v_lshl_add_u32 v144, v144, 3, s2
	s_lshl_b32 s2, s8, 8
	s_add_i32 s2, s2, s28
	v_add_u32_e32 v152, s2, v152
	v_ashrrev_i32_e32 v153, 31, v152
	v_lshlrev_b64 v[152:153], 12, v[152:153]
	v_ashrrev_i32_e32 v145, 31, v144
	v_lshl_add_u64 v[152:153], s[4:5], 0, v[152:153]
	v_lshl_add_u64 v[144:145], v[144:145], 1, v[152:153]
	global_load_dwordx4 v[160:163], v[144:145], off
	global_load_dwordx4 v[164:167], v[144:145], off offset:256
	s_mov_b64 s[98:99], 0x10000
	v_lshl_add_u64 v[154:155], v[144:145], 0, s[98:99]
	global_load_dwordx4 v[168:171], v[154:155], off
	global_load_dwordx4 v[172:175], v[154:155], off offset:256
	s_mov_b64 s[98:99], 0x20000
	v_lshl_add_u64 v[154:155], v[144:145], 0, s[98:99]
	global_load_dwordx4 v[176:179], v[154:155], off
	global_load_dwordx4 v[180:183], v[154:155], off offset:256
	s_mov_b64 s[98:99], 0x30000
	v_lshl_add_u64 v[154:155], v[144:145], 0, s[98:99]
	global_load_dwordx4 v[184:187], v[154:155], off
	global_load_dwordx4 v[188:191], v[154:155], off offset:256
	s_mov_b64 s[98:99], 0x80000
	v_lshl_add_u64 v[154:155], v[144:145], 0, s[98:99]
	global_load_dwordx4 v[192:195], v[154:155], off
	global_load_dwordx4 v[198:201], v[154:155], off offset:256
	s_mov_b64 s[98:99], 0x90000
	v_lshl_add_u64 v[154:155], v[144:145], 0, s[98:99]
	global_load_dwordx4 v[202:205], v[154:155], off
	global_load_dwordx4 v[206:209], v[154:155], off offset:256
	s_mov_b64 s[98:99], 0xa0000
	v_lshl_add_u64 v[154:155], v[144:145], 0, s[98:99]
	global_load_dwordx4 v[210:213], v[154:155], off
	global_load_dwordx4 v[214:217], v[154:155], off offset:256
	s_mov_b64 s[98:99], 0xb0000
	v_lshl_add_u64 v[154:155], v[144:145], 0, s[98:99]
	global_load_dwordx4 v[248:251], v[154:155], off
	global_load_dwordx4 v[252:255], v[154:155], off offset:256
	s_waitcnt vmcnt(15)
	s_nop 1
	v_mov_b32_e32 v152, v160
	v_mov_b32_e32 v153, v161
	v_mov_b32_e32 v154, v162
	v_mov_b32_e32 v155, v163
	s_mov_b64 s[2:3], 0x10000
	s_mov_b32 s8, s46
	s_mov_b64 s[10:11], s[6:7]
	s_mov_b64 s[12:13], s[52:53]
	s_waitcnt lgkmcnt(0)
	v_lshlrev_b32_e32 v156, 16, v152
	v_and_b32_e32 v157, 0xffff0000, v152
	v_lshlrev_b32_e32 v152, 16, v153
	v_and_b32_e32 v153, 0xffff0000, v153
	v_lshlrev_b32_e32 v158, 16, v154
	v_and_b32_e32 v159, 0xffff0000, v154
	v_lshlrev_b32_e32 v154, 16, v155
	v_and_b32_e32 v155, 0xffff0000, v155
	v_pk_add_f32 v[126:127], v[126:127], v[152:153]
	v_pk_add_f32 v[124:125], v[124:125], v[156:157]
	v_pk_add_f32 v[152:153], v[122:123], v[154:155]
	v_pk_add_f32 v[122:123], v[120:121], v[158:159]
	v_cvt_pk_bf16_f32 v120, v124, v125
	v_cvt_pk_bf16_f32 v121, v126, v127
	v_cvt_pk_bf16_f32 v122, v122, v123
	v_cvt_pk_bf16_f32 v123, v152, v153
	global_store_dwordx4 v[144:145], v[120:123], off
	s_waitcnt vmcnt(15)
; DI unsigned pack2(float a, float b) { f32x2 v = {a, b}; hwbf16x2 r = __builtin_convertvector(v, hwbf16x2); return __builtin_bit_cast(unsigned, r); }
; DI float bflo(unsigned w) { return __uint_as_float(w << 16); }
; DI float bfhi(unsigned w) { return __uint_as_float(w & 0xffff0000u); }
;     DI void operator()(const f32x4 (&acc)[2][2][4][2], const Unit& u, int wr, int wc, int fr, int fq) const {
;         const int row0 = u.pm * BM + wr * 64 + fr, col0 = u.pn * BM + wc * 32 + 8 * fq;
;         f32x4 sc[2][2];
; #pragma unroll
;         for (int bj = 0; bj < 2; ++bj)
; #pragma unroll
;             for (int n = 0; n < 2; ++n) sc[bj][n] = scale ? *(const f32x4*)(scale + col0 + bj * HALF + 4 * n) : (f32x4){1.f, 1.f, 1.f, 1.f};
; #pragma unroll
;         for (int ai = 0; ai < 2; ++ai)
; #pragma unroll
;             for (int m = 0; m < 4; ++m) { const size_t ro = (size_t)(row0 + ai * HALF + m * 16) * D + col0;
; #pragma unroll
;                 for (int bj = 0; bj < 2; ++bj) {
;                     f32x4 x0, x1;
;                     if constexpr (IB) { const u32x4 w = *(const u32x4*)((const bf16_t*)Xin + ro + bj * HALF);
;                         x0 = (f32x4){bflo(w[0]), bfhi(w[0]), bflo(w[1]), bfhi(w[1])}; x1 = (f32x4){bflo(w[2]), bfhi(w[2]), bflo(w[3]), bfhi(w[3])}; }
;                     else { x0 = *(const f32x4*)((const float*)Xin + ro + bj * HALF); x1 = *(const f32x4*)((const float*)Xin + ro + bj * HALF + 4); }
;                     x0 += acc[ai][bj][m][0] * sc[bj][0]; x1 += acc[ai][bj][m][1] * sc[bj][1];
;                     if constexpr (OB) { u32x4 o; o[0] = pack2(x0[0], x0[1]); o[1] = pack2(x0[2], x0[3]); o[2] = pack2(x1[0], x1[1]); o[3] = pack2(x1[2], x1[3]);
;                         *(u32x4*)((bf16_t*)Xout + ro + bj * HALF) = o; }
;                     else { *(f32x4*)((float*)Xout + ro + bj * HALF) = x0; *(f32x4*)((float*)Xout + ro + bj * HALF + 4) = x1; } } }
	s_nop 1
	v_mov_b32_e32 v120, v164
	v_mov_b32_e32 v121, v165
	v_mov_b32_e32 v122, v166
	v_mov_b32_e32 v123, v167
	s_waitcnt lgkmcnt(0)
	v_lshlrev_b32_e32 v124, 16, v120
	v_and_b32_e32 v125, 0xffff0000, v120
	v_lshlrev_b32_e32 v120, 16, v121
	v_and_b32_e32 v121, 0xffff0000, v121
	v_lshlrev_b32_e32 v126, 16, v122
	v_and_b32_e32 v127, 0xffff0000, v122
	v_lshlrev_b32_e32 v122, 16, v123
	v_and_b32_e32 v123, 0xffff0000, v123
	v_pk_add_f32 v[116:117], v[116:117], v[124:125]
	v_pk_add_f32 v[118:119], v[118:119], v[120:121]
	v_pk_add_f32 v[120:121], v[114:115], v[122:123]
	v_pk_add_f32 v[114:115], v[112:113], v[126:127]
	v_cvt_pk_bf16_f32 v112, v116, v117
	v_lshl_add_u64 v[116:117], v[144:145], 0, s[2:3]
	s_mov_b32 s2, 0x10000
	v_cvt_pk_bf16_f32 v113, v118, v119
	v_add_co_u32_e32 v118, vcc, s2, v144
	v_cvt_pk_bf16_f32 v114, v114, v115
	v_cvt_pk_bf16_f32 v115, v120, v121
	v_addc_co_u32_e32 v119, vcc, 0, v145, vcc
	global_store_dwordx4 v[144:145], v[112:115], off offset:256
	s_waitcnt vmcnt(15)
	s_nop 1
	v_mov_b32_e32 v112, v168
	v_mov_b32_e32 v113, v169
	v_mov_b32_e32 v114, v170
	v_mov_b32_e32 v115, v171
	s_mov_b64 s[2:3], 0x20000
	s_waitcnt lgkmcnt(0)
	v_lshlrev_b32_e32 v120, 16, v112
	v_and_b32_e32 v121, 0xffff0000, v112
	v_lshlrev_b32_e32 v112, 16, v113
	v_and_b32_e32 v113, 0xffff0000, v113
	v_lshlrev_b32_e32 v122, 16, v114
	v_and_b32_e32 v123, 0xffff0000, v114
	v_lshlrev_b32_e32 v114, 16, v115
	v_and_b32_e32 v115, 0xffff0000, v115
	v_pk_add_f32 v[110:111], v[110:111], v[112:113]
	v_pk_add_f32 v[108:109], v[108:109], v[120:121]
	v_pk_add_f32 v[112:113], v[106:107], v[114:115]
	v_pk_add_f32 v[106:107], v[104:105], v[122:123]
	v_cvt_pk_bf16_f32 v104, v108, v109
	v_cvt_pk_bf16_f32 v105, v110, v111
	v_cvt_pk_bf16_f32 v106, v106, v107
	v_cvt_pk_bf16_f32 v107, v112, v113
	global_store_dwordx4 v[118:119], v[104:107], off
	s_waitcnt vmcnt(15)
	s_nop 1
	v_mov_b32_e32 v104, v172
	v_mov_b32_e32 v105, v173
	v_mov_b32_e32 v106, v174
	v_mov_b32_e32 v107, v175
	s_waitcnt lgkmcnt(0)
	v_lshlrev_b32_e32 v108, 16, v104
	v_and_b32_e32 v109, 0xffff0000, v104
	v_lshlrev_b32_e32 v104, 16, v105
	v_and_b32_e32 v105, 0xffff0000, v105
	v_lshlrev_b32_e32 v110, 16, v106
	v_and_b32_e32 v111, 0xffff0000, v106
	v_lshlrev_b32_e32 v106, 16, v107
	v_and_b32_e32 v107, 0xffff0000, v107
	v_pk_add_f32 v[100:101], v[100:101], v[108:109]
	v_pk_add_f32 v[102:103], v[102:103], v[104:105]
	v_pk_add_f32 v[104:105], v[98:99], v[106:107]
	v_pk_add_f32 v[98:99], v[96:97], v[110:111]
	v_cvt_pk_bf16_f32 v96, v100, v101
	v_lshl_add_u64 v[100:101], v[144:145], 0, s[2:3]
	s_mov_b32 s2, 0x20000
	v_cvt_pk_bf16_f32 v97, v102, v103
	v_add_co_u32_e32 v102, vcc, s2, v144
	v_cvt_pk_bf16_f32 v98, v98, v99
	v_cvt_pk_bf16_f32 v99, v104, v105
	v_addc_co_u32_e32 v103, vcc, 0, v145, vcc
	global_store_dwordx4 v[116:117], v[96:99], off offset:256
	s_waitcnt vmcnt(15)
	s_nop 1
	v_mov_b32_e32 v96, v176
	v_mov_b32_e32 v97, v177
	v_mov_b32_e32 v98, v178
	v_mov_b32_e32 v99, v179
	s_mov_b64 s[2:3], 0x30000
	s_waitcnt lgkmcnt(0)
	v_lshlrev_b32_e32 v104, 16, v96
	v_and_b32_e32 v105, 0xffff0000, v96
	v_lshlrev_b32_e32 v96, 16, v97
	v_and_b32_e32 v97, 0xffff0000, v97
	v_lshlrev_b32_e32 v106, 16, v98
	v_and_b32_e32 v107, 0xffff0000, v98
	v_lshlrev_b32_e32 v98, 16, v99
	v_and_b32_e32 v99, 0xffff0000, v99
	v_pk_add_f32 v[94:95], v[94:95], v[96:97]
	v_pk_add_f32 v[92:93], v[92:93], v[104:105]
	v_pk_add_f32 v[96:97], v[90:91], v[98:99]
	v_pk_add_f32 v[90:91], v[88:89], v[106:107]
	v_cvt_pk_bf16_f32 v88, v92, v93
	v_cvt_pk_bf16_f32 v89, v94, v95
	v_cvt_pk_bf16_f32 v90, v90, v91
	v_cvt_pk_bf16_f32 v91, v96, v97
	global_store_dwordx4 v[102:103], v[88:91], off
	s_waitcnt vmcnt(15)
	s_nop 1
	v_mov_b32_e32 v88, v180
	v_mov_b32_e32 v89, v181
	v_mov_b32_e32 v90, v182
	v_mov_b32_e32 v91, v183
	s_waitcnt lgkmcnt(0)
	v_lshlrev_b32_e32 v92, 16, v88
	v_and_b32_e32 v93, 0xffff0000, v88
	v_lshlrev_b32_e32 v88, 16, v89
	v_and_b32_e32 v89, 0xffff0000, v89
	v_lshlrev_b32_e32 v94, 16, v90
	v_and_b32_e32 v95, 0xffff0000, v90
	v_lshlrev_b32_e32 v90, 16, v91
	v_and_b32_e32 v91, 0xffff0000, v91
	v_pk_add_f32 v[86:87], v[86:87], v[88:89]
	v_pk_add_f32 v[84:85], v[84:85], v[92:93]
	v_pk_add_f32 v[88:89], v[82:83], v[90:91]
	v_pk_add_f32 v[82:83], v[80:81], v[94:95]
	v_cvt_pk_bf16_f32 v80, v84, v85
	v_cvt_pk_bf16_f32 v81, v86, v87
	v_cvt_pk_bf16_f32 v82, v82, v83
	v_cvt_pk_bf16_f32 v83, v88, v89
	global_store_dwordx4 v[100:101], v[80:83], off offset:256
	s_nop 1
	v_lshl_add_u64 v[80:81], v[144:145], 0, s[2:3]
	s_mov_b32 s2, 0x30000
	v_add_co_u32_e32 v86, vcc, s2, v144
	s_mov_b64 s[2:3], 0x80000
	s_nop 0
	v_addc_co_u32_e32 v87, vcc, 0, v145, vcc
	s_waitcnt vmcnt(15)
	s_nop 1
	v_mov_b32_e32 v82, v184
	v_mov_b32_e32 v83, v185
	v_mov_b32_e32 v84, v186
	v_mov_b32_e32 v85, v187
	s_waitcnt lgkmcnt(0)
	v_lshlrev_b32_e32 v88, 16, v82
	v_and_b32_e32 v89, 0xffff0000, v82
	v_lshlrev_b32_e32 v82, 16, v83
	v_and_b32_e32 v83, 0xffff0000, v83
	v_lshlrev_b32_e32 v90, 16, v84
	v_and_b32_e32 v91, 0xffff0000, v84
	v_lshlrev_b32_e32 v84, 16, v85
	v_and_b32_e32 v85, 0xffff0000, v85
	v_pk_add_f32 v[78:79], v[78:79], v[82:83]
	v_pk_add_f32 v[76:77], v[76:77], v[88:89]
	v_pk_add_f32 v[82:83], v[74:75], v[84:85]
	v_pk_add_f32 v[74:75], v[72:73], v[90:91]
	v_cvt_pk_bf16_f32 v72, v76, v77
	v_cvt_pk_bf16_f32 v73, v78, v79
	v_cvt_pk_bf16_f32 v74, v74, v75
	v_cvt_pk_bf16_f32 v75, v82, v83
	global_store_dwordx4 v[86:87], v[72:75], off
	s_waitcnt vmcnt(15)
	s_nop 1
	v_mov_b32_e32 v72, v188
	v_mov_b32_e32 v73, v189
	v_mov_b32_e32 v74, v190
	v_mov_b32_e32 v75, v191
	s_waitcnt lgkmcnt(0)
; DI unsigned pack2(float a, float b) { f32x2 v = {a, b}; hwbf16x2 r = __builtin_convertvector(v, hwbf16x2); return __builtin_bit_cast(unsigned, r); }
; DI float bflo(unsigned w) { return __uint_as_float(w << 16); }
; DI float bfhi(unsigned w) { return __uint_as_float(w & 0xffff0000u); }
;     DI void operator()(const f32x4 (&acc)[2][2][4][2], const Unit& u, int wr, int wc, int fr, int fq) const {
;         const int row0 = u.pm * BM + wr * 64 + fr, col0 = u.pn * BM + wc * 32 + 8 * fq;
;         f32x4 sc[2][2];
; #pragma unroll
;         for (int bj = 0; bj < 2; ++bj)
; #pragma unroll
;             for (int n = 0; n < 2; ++n) sc[bj][n] = scale ? *(const f32x4*)(scale + col0 + bj * HALF + 4 * n) : (f32x4){1.f, 1.f, 1.f, 1.f};
; #pragma unroll
;         for (int ai = 0; ai < 2; ++ai)
; #pragma unroll
;             for (int m = 0; m < 4; ++m) { const size_t ro = (size_t)(row0 + ai * HALF + m * 16) * D + col0;
; #pragma unroll
;                 for (int bj = 0; bj < 2; ++bj) {
;                     f32x4 x0, x1;
;                     if constexpr (IB) { const u32x4 w = *(const u32x4*)((const bf16_t*)Xin + ro + bj * HALF);
;                         x0 = (f32x4){bflo(w[0]), bfhi(w[0]), bflo(w[1]), bfhi(w[1])}; x1 = (f32x4){bflo(w[2]), bfhi(w[2]), bflo(w[3]), bfhi(w[3])}; }
;                     else { x0 = *(const f32x4*)((const float*)Xin + ro + bj * HALF); x1 = *(const f32x4*)((const float*)Xin + ro + bj * HALF + 4); }
;                     x0 += acc[ai][bj][m][0] * sc[bj][0]; x1 += acc[ai][bj][m][1] * sc[bj][1];
;                     if constexpr (OB) { u32x4 o; o[0] = pack2(x0[0], x0[1]); o[1] = pack2(x0[2], x0[3]); o[2] = pack2(x1[0], x1[1]); o[3] = pack2(x1[2], x1[3]);
;                         *(u32x4*)((bf16_t*)Xout + ro + bj * HALF) = o; }
;                     else { *(f32x4*)((float*)Xout + ro + bj * HALF) = x0; *(f32x4*)((float*)Xout + ro + bj * HALF + 4) = x1; } } }
	v_lshlrev_b32_e32 v76, 16, v72
	v_and_b32_e32 v77, 0xffff0000, v72
	v_lshlrev_b32_e32 v72, 16, v73
	v_and_b32_e32 v73, 0xffff0000, v73
	v_lshlrev_b32_e32 v78, 16, v74
	v_and_b32_e32 v79, 0xffff0000, v74
	v_lshlrev_b32_e32 v74, 16, v75
	v_and_b32_e32 v75, 0xffff0000, v75
	v_pk_add_f32 v[70:71], v[70:71], v[72:73]
	v_pk_add_f32 v[68:69], v[68:69], v[76:77]
	v_pk_add_f32 v[72:73], v[66:67], v[74:75]
	v_pk_add_f32 v[66:67], v[64:65], v[78:79]
	v_cvt_pk_bf16_f32 v64, v68, v69
	v_cvt_pk_bf16_f32 v65, v70, v71
	v_cvt_pk_bf16_f32 v66, v66, v67
	v_cvt_pk_bf16_f32 v67, v72, v73
	global_store_dwordx4 v[80:81], v[64:67], off offset:256
	s_nop 1
	v_lshl_add_u64 v[64:65], v[144:145], 0, s[2:3]
	s_mov_b32 s2, 0x80000
	v_add_co_u32_e32 v70, vcc, s2, v144
	s_mov_b64 s[2:3], 0x90000
	s_nop 0
	v_addc_co_u32_e32 v71, vcc, 0, v145, vcc
	s_waitcnt vmcnt(15)
	s_nop 1
	v_mov_b32_e32 v66, v192
	v_mov_b32_e32 v67, v193
	v_mov_b32_e32 v68, v194
	v_mov_b32_e32 v69, v195
	s_waitcnt lgkmcnt(0)
	v_lshlrev_b32_e32 v72, 16, v66
	v_and_b32_e32 v73, 0xffff0000, v66
	v_lshlrev_b32_e32 v66, 16, v67
	v_and_b32_e32 v67, 0xffff0000, v67
	v_lshlrev_b32_e32 v74, 16, v68
	v_and_b32_e32 v75, 0xffff0000, v68
	v_lshlrev_b32_e32 v68, 16, v69
	v_and_b32_e32 v69, 0xffff0000, v69
	v_pk_add_f32 v[62:63], v[62:63], v[66:67]
	v_pk_add_f32 v[60:61], v[60:61], v[72:73]
	v_pk_add_f32 v[66:67], v[58:59], v[68:69]
	v_pk_add_f32 v[58:59], v[56:57], v[74:75]
	v_cvt_pk_bf16_f32 v56, v60, v61
	v_cvt_pk_bf16_f32 v57, v62, v63
	v_cvt_pk_bf16_f32 v58, v58, v59
	v_cvt_pk_bf16_f32 v59, v66, v67
	global_store_dwordx4 v[70:71], v[56:59], off
	s_waitcnt vmcnt(15)
	s_nop 1
	v_mov_b32_e32 v56, v198
	v_mov_b32_e32 v57, v199
	v_mov_b32_e32 v58, v200
	v_mov_b32_e32 v59, v201
	s_waitcnt lgkmcnt(0)
	v_lshlrev_b32_e32 v60, 16, v56
	v_and_b32_e32 v61, 0xffff0000, v56
	v_lshlrev_b32_e32 v56, 16, v57
	v_and_b32_e32 v57, 0xffff0000, v57
	v_lshlrev_b32_e32 v62, 16, v58
	v_and_b32_e32 v63, 0xffff0000, v58
	v_lshlrev_b32_e32 v58, 16, v59
	v_and_b32_e32 v59, 0xffff0000, v59
	v_pk_add_f32 v[54:55], v[54:55], v[56:57]
	v_pk_add_f32 v[52:53], v[52:53], v[60:61]
	v_pk_add_f32 v[56:57], v[50:51], v[58:59]
	v_pk_add_f32 v[50:51], v[48:49], v[62:63]
	v_cvt_pk_bf16_f32 v48, v52, v53
	v_cvt_pk_bf16_f32 v49, v54, v55
	v_cvt_pk_bf16_f32 v50, v50, v51
	v_cvt_pk_bf16_f32 v51, v56, v57
	global_store_dwordx4 v[64:65], v[48:51], off offset:256
	s_nop 1
	v_lshl_add_u64 v[48:49], v[144:145], 0, s[2:3]
	s_mov_b32 s2, 0x90000
	v_add_co_u32_e32 v54, vcc, s2, v144
	s_mov_b64 s[2:3], 0xa0000
	s_nop 0
	v_addc_co_u32_e32 v55, vcc, 0, v145, vcc
	s_waitcnt vmcnt(15)
	s_nop 1
	v_mov_b32_e32 v50, v202
	v_mov_b32_e32 v51, v203
	v_mov_b32_e32 v52, v204
	v_mov_b32_e32 v53, v205
	s_waitcnt lgkmcnt(0)
	v_lshlrev_b32_e32 v56, 16, v50
	v_and_b32_e32 v57, 0xffff0000, v50
	v_lshlrev_b32_e32 v50, 16, v51
	v_and_b32_e32 v51, 0xffff0000, v51
	v_lshlrev_b32_e32 v58, 16, v52
	v_and_b32_e32 v59, 0xffff0000, v52
	v_lshlrev_b32_e32 v52, 16, v53
	v_and_b32_e32 v53, 0xffff0000, v53
	v_pk_add_f32 v[46:47], v[46:47], v[50:51]
	v_pk_add_f32 v[44:45], v[44:45], v[56:57]
	v_pk_add_f32 v[50:51], v[42:43], v[52:53]
	v_pk_add_f32 v[42:43], v[40:41], v[58:59]
	v_cvt_pk_bf16_f32 v40, v44, v45
	v_cvt_pk_bf16_f32 v41, v46, v47
	v_cvt_pk_bf16_f32 v42, v42, v43
	v_cvt_pk_bf16_f32 v43, v50, v51
	global_store_dwordx4 v[54:55], v[40:43], off
	s_waitcnt vmcnt(15)
	s_nop 1
	v_mov_b32_e32 v40, v206
	v_mov_b32_e32 v41, v207
	v_mov_b32_e32 v42, v208
	v_mov_b32_e32 v43, v209
	s_waitcnt lgkmcnt(0)
; #define PG8_BAR __builtin_amdgcn_s_barrier()
;     DI void operator()(const f32x4 (&acc)[2][2][4][2], const Unit& u, int wr, int wc, int fr, int fq) const {
;         const int row0 = u.pm * BM + wr * 64 + fr, col0 = u.pn * BM + wc * 32 + 8 * fq;
;         f32x4 sc[2][2];
; #pragma unroll
;         for (int bj = 0; bj < 2; ++bj)
; #pragma unroll
;             for (int n = 0; n < 2; ++n) sc[bj][n] = scale ? *(const f32x4*)(scale + col0 + bj * HALF + 4 * n) : (f32x4){1.f, 1.f, 1.f, 1.f};
; #pragma unroll
;         for (int ai = 0; ai < 2; ++ai)
; #pragma unroll
;             for (int m = 0; m < 4; ++m) { const size_t ro = (size_t)(row0 + ai * HALF + m * 16) * D + col0;
; #pragma unroll
;                 for (int bj = 0; bj < 2; ++bj) {
;                     f32x4 x0, x1;
;                     if constexpr (IB) { const u32x4 w = *(const u32x4*)((const bf16_t*)Xin + ro + bj * HALF);
;                         x0 = (f32x4){bflo(w[0]), bfhi(w[0]), bflo(w[1]), bfhi(w[1])}; x1 = (f32x4){bflo(w[2]), bfhi(w[2]), bflo(w[3]), bfhi(w[3])}; }
;                     else { x0 = *(const f32x4*)((const float*)Xin + ro + bj * HALF); x1 = *(const f32x4*)((const float*)Xin + ro + bj * HALF + 4); }
;                     x0 += acc[ai][bj][m][0] * sc[bj][0]; x1 += acc[ai][bj][m][1] * sc[bj][1];
;                     if constexpr (OB) { u32x4 o; o[0] = pack2(x0[0], x0[1]); o[1] = pack2(x0[2], x0[3]); o[2] = pack2(x1[0], x1[1]); o[3] = pack2(x1[2], x1[3]);
;                         *(u32x4*)((bf16_t*)Xout + ro + bj * HALF) = o; }
;                     else { *(f32x4*)((float*)Xout + ro + bj * HALF) = x0; *(f32x4*)((float*)Xout + ro + bj * HALF + 4) = x1; } } }
; template <class Map, class Epi>
; DI void gemm_phase(LAS unsigned char* lds, const Map& MP, const Epi& E, const int nM, const int nN, const int K, const int lda, const int ldb) {
;     ...
;         { int frr = fr, fqq = fq; asm volatile("" : "+v"(frr), "+v"(fqq)); E(acc, cur, wr, wc, frr, fqq); }
;         if (!has_next) break;
; #pragma unroll
;         for (int a = 0; a < 2; ++a)
; #pragma unroll
;             for (int b = 0; b < 2; ++b)
; #pragma unroll
;                 for (int m = 0; m < 4; ++m)
; #pragma unroll
;                     for (int n = 0; n < 2; ++n) acc[a][b][m][n] = (f32x4){0.f, 0.f, 0.f, 0.f};
;         cur = nxt; cA = nA; cB = nB; ++ui;
;     }
;     PG8_WAIT_V(0);
;     if (wr == 0) PG8_BAR;
;     PG8_BAR;
	v_lshlrev_b32_e32 v44, 16, v40
	v_and_b32_e32 v45, 0xffff0000, v40
	v_lshlrev_b32_e32 v40, 16, v41
	v_and_b32_e32 v41, 0xffff0000, v41
	v_lshlrev_b32_e32 v46, 16, v42
	v_and_b32_e32 v47, 0xffff0000, v42
	v_lshlrev_b32_e32 v42, 16, v43
	v_and_b32_e32 v43, 0xffff0000, v43
	v_pk_add_f32 v[38:39], v[38:39], v[40:41]
	v_pk_add_f32 v[36:37], v[36:37], v[44:45]
	v_pk_add_f32 v[40:41], v[34:35], v[42:43]
	v_pk_add_f32 v[34:35], v[32:33], v[46:47]
	v_cvt_pk_bf16_f32 v32, v36, v37
	v_cvt_pk_bf16_f32 v33, v38, v39
	v_cvt_pk_bf16_f32 v34, v34, v35
	v_cvt_pk_bf16_f32 v35, v40, v41
	global_store_dwordx4 v[48:49], v[32:35], off offset:256
	s_nop 1
	v_lshl_add_u64 v[32:33], v[144:145], 0, s[2:3]
	s_mov_b32 s2, 0xa0000
	v_add_co_u32_e32 v38, vcc, s2, v144
	s_mov_b64 s[2:3], 0xb0000
	s_nop 0
	v_addc_co_u32_e32 v39, vcc, 0, v145, vcc
	s_waitcnt vmcnt(15)
	s_nop 1
	v_mov_b32_e32 v34, v210
	v_mov_b32_e32 v35, v211
	v_mov_b32_e32 v36, v212
	v_mov_b32_e32 v37, v213
	s_waitcnt lgkmcnt(0)
	v_lshlrev_b32_e32 v40, 16, v34
	v_and_b32_e32 v41, 0xffff0000, v34
	v_lshlrev_b32_e32 v34, 16, v35
	v_and_b32_e32 v35, 0xffff0000, v35
	v_lshlrev_b32_e32 v42, 16, v36
	v_and_b32_e32 v43, 0xffff0000, v36
	v_lshlrev_b32_e32 v36, 16, v37
	v_and_b32_e32 v37, 0xffff0000, v37
	v_pk_add_f32 v[30:31], v[30:31], v[34:35]
	v_pk_add_f32 v[28:29], v[28:29], v[40:41]
	v_pk_add_f32 v[34:35], v[26:27], v[36:37]
	v_pk_add_f32 v[26:27], v[24:25], v[42:43]
	v_cvt_pk_bf16_f32 v24, v28, v29
	v_cvt_pk_bf16_f32 v25, v30, v31
	v_cvt_pk_bf16_f32 v26, v26, v27
	v_cvt_pk_bf16_f32 v27, v34, v35
	global_store_dwordx4 v[38:39], v[24:27], off
	s_waitcnt vmcnt(15)
	s_nop 1
	v_mov_b32_e32 v24, v214
	v_mov_b32_e32 v25, v215
	v_mov_b32_e32 v26, v216
	v_mov_b32_e32 v27, v217
	s_waitcnt lgkmcnt(0)
	v_lshlrev_b32_e32 v28, 16, v24
	v_and_b32_e32 v29, 0xffff0000, v24
	v_lshlrev_b32_e32 v24, 16, v25
	v_and_b32_e32 v25, 0xffff0000, v25
	v_lshlrev_b32_e32 v30, 16, v26
	v_and_b32_e32 v31, 0xffff0000, v26
	v_lshlrev_b32_e32 v26, 16, v27
	v_and_b32_e32 v27, 0xffff0000, v27
	v_pk_add_f32 v[22:23], v[22:23], v[24:25]
	v_pk_add_f32 v[20:21], v[20:21], v[28:29]
	v_pk_add_f32 v[24:25], v[18:19], v[26:27]
	v_pk_add_f32 v[18:19], v[16:17], v[30:31]
	v_cvt_pk_bf16_f32 v16, v20, v21
	v_cvt_pk_bf16_f32 v17, v22, v23
	v_cvt_pk_bf16_f32 v18, v18, v19
	v_cvt_pk_bf16_f32 v19, v24, v25
	global_store_dwordx4 v[32:33], v[16:19], off offset:256
	s_nop 1
	v_lshl_add_u64 v[16:17], v[144:145], 0, s[2:3]
	s_mov_b32 s2, 0xb0000
	v_add_co_u32_e32 v22, vcc, s2, v144
	s_mov_b32 s2, s44
	s_nop 0
	v_addc_co_u32_e32 v23, vcc, 0, v145, vcc
	s_waitcnt vmcnt(15)
	s_nop 1
	v_mov_b32_e32 v18, v248
	v_mov_b32_e32 v19, v249
	v_mov_b32_e32 v20, v250
	v_mov_b32_e32 v21, v251
	s_and_b64 vcc, exec, s[40:41]
	s_waitcnt lgkmcnt(0)
	v_lshlrev_b32_e32 v24, 16, v18
	v_and_b32_e32 v25, 0xffff0000, v18
	v_lshlrev_b32_e32 v18, 16, v19
	v_and_b32_e32 v19, 0xffff0000, v19
	v_lshlrev_b32_e32 v26, 16, v20
	v_and_b32_e32 v27, 0xffff0000, v20
	v_lshlrev_b32_e32 v20, 16, v21
	v_and_b32_e32 v21, 0xffff0000, v21
	v_pk_add_f32 v[14:15], v[14:15], v[18:19]
	v_pk_add_f32 v[12:13], v[12:13], v[24:25]
	v_pk_add_f32 v[18:19], v[10:11], v[20:21]
	v_pk_add_f32 v[10:11], v[8:9], v[26:27]
	v_cvt_pk_bf16_f32 v8, v12, v13
	v_cvt_pk_bf16_f32 v9, v14, v15
	v_cvt_pk_bf16_f32 v10, v10, v11
	v_cvt_pk_bf16_f32 v11, v18, v19
	global_store_dwordx4 v[22:23], v[8:11], off
	s_waitcnt vmcnt(15)
	s_nop 1
	v_mov_b32_e32 v8, v252
	v_mov_b32_e32 v9, v253
	v_mov_b32_e32 v10, v254
	v_mov_b32_e32 v11, v255
	s_waitcnt lgkmcnt(0)
	v_lshlrev_b32_e32 v12, 16, v8
	v_and_b32_e32 v13, 0xffff0000, v8
	v_lshlrev_b32_e32 v8, 16, v9
	v_and_b32_e32 v9, 0xffff0000, v9
	v_lshlrev_b32_e32 v14, 16, v10
	v_and_b32_e32 v15, 0xffff0000, v10
	v_lshlrev_b32_e32 v10, 16, v11
	v_and_b32_e32 v11, 0xffff0000, v11
	v_pk_add_f32 v[6:7], v[6:7], v[8:9]
	v_pk_add_f32 v[4:5], v[4:5], v[12:13]
	v_pk_add_f32 v[8:9], v[2:3], v[10:11]
	v_pk_add_f32 v[2:3], v[0:1], v[14:15]
	v_cvt_pk_bf16_f32 v0, v4, v5
	v_cvt_pk_bf16_f32 v1, v6, v7
	v_cvt_pk_bf16_f32 v2, v2, v3
	v_cvt_pk_bf16_f32 v3, v8, v9
	global_store_dwordx4 v[16:17], v[0:3], off offset:256
	s_cbranch_vccz .LBB1_1761
	s_waitcnt vmcnt(0)
	s_cmpk_gt_u32 s17, 0xff
	s_cbranch_scc1 .LBB1_1768
	s_barrier

; #define PG8_STAGE(bufoff, gbase, voff) do { _Pragma("unroll") for (int _i = 0; _i < 2; ++_i) \
;         __builtin_amdgcn_global_load_lds((const unsigned*)((const char*)(gbase) + (voff)[_i]), (LAS unsigned*)(lds + (bufoff) + ldsw + _i * 8192), 16, 0, 0); } while (0)
; #define PG8_LDA(dst, b, h) do { _Pragma("unroll") for (int m = 0; m < 4; ++m) _Pragma("unroll") for (int k = 0; k < 2; ++k) dst[m][k] = *(const LAS bf16x8*)(lds + PG8_SA(b, h) + aoff + m * 2048 + k * 1024); } while (0)
; #define PG8_LDB(dst, b, h) do { _Pragma("unroll") for (int n = 0; n < 2; ++n) _Pragma("unroll") for (int k = 0; k < 2; ++k) dst[n][k] = *(const LAS bf16x8*)(lds + PG8_SB(b, h) + boff + n * 2048 + k * 1024); } while (0)
; #define PG8_MMA(ai, bj, At, Bt) do { __builtin_amdgcn_s_setprio(1); _Pragma("unroll") for (int m = 0; m < 4; ++m) _Pragma("unroll") for (int n = 0; n < 2; ++n) _Pragma("unroll") for (int k = 0; k < 2; ++k) \
;         acc[ai][bj][m][n] = __builtin_amdgcn_mfma_f32_16x16x32_bf16(Bt[n][k], At[m][k], acc[ai][bj][m][n], 0, 0, 0); __builtin_amdgcn_s_setprio(0); } while (0)
; #define PG8_WAIT_L(n) asm volatile("s_waitcnt lgkmcnt(" #n ")" ::: "memory")
; #define PG8_BAR __builtin_amdgcn_s_barrier()
; #define PG8_SCHED __builtin_amdgcn_sched_barrier(0)
; template <class Map, class Epi>
; DI void gemm_phase(LAS unsigned char* lds, const Map& MP, const Epi& E, const int nM, const int nN, const int K, const int lda, const int ldb) {
;     ...
;             const bool last = (t == nt - 2);
;             const char* a1 = cA + (size_t)(t + 1) * kstep;
;             const char* a2 = last ? nA : cA + (size_t)(t + 2) * kstep; const char* b2 = last ? nB : cB + (size_t)(t + 2) * kstep;
;             const char* a3 = a2 + kstep; const char* b3 = b2 + kstep;
;             PG8_LDB(B0, 0, 0); PG8_SCHED; PG8_LDA(At, 0, 0); PG8_STAGE(PG8_SA(1, 1), a1 + hstepA, voffA);
;             PG8_WAIT_L(8); PG8_BAR; PG8_WAIT_L(0); PG8_MMA(0, 0, At, B0); PG8_BAR; PG8_SCHED;
;             PG8_LDB(B1, 0, 1); PG8_STAGE(PG8_SB(0, 0), b2, voffB);
;             PG8_BAR; PG8_WAIT_L(0); PG8_MMA(0, 1, At, B1); PG8_BAR;
;             PG8_LDA(At, 0, 1); PG8_STAGE(PG8_SA(0, 0), a2, voffA);
;             PG8_BAR; PG8_WAIT_L(0); PG8_MMA(1, 0, At, B0); PG8_BAR; PG8_SCHED;
.LBB1_1908:
	s_add_u32 s28, s42, 0xfff80080
	s_addc_u32 s29, s43, -1
	s_cmp_eq_u32 s3, 28
	s_cselect_b32 s47, s23, s29
	s_cselect_b32 s46, s58, s28
	s_cselect_b32 s29, s21, vcc_hi
	s_cselect_b32 s28, s59, vcc_lo
	s_add_i32 m0, s38, 0xc000
	ds_read_b128 v[96:99], v190
	ds_read_b128 v[100:103], v190 offset:1024
	ds_read_b128 v[108:111], v190 offset:2048
	ds_read_b128 v[112:115], v190 offset:3072
	ds_read_b128 v[160:163], v190 offset:4096
	ds_read_b128 v[164:167], v190 offset:5120
	ds_read_b128 v[198:201], v190 offset:6144
	ds_read_b128 v[202:205], v190 offset:7168
	global_load_lds_dwordx4 v178, s[42:43]
	s_add_i32 m0, s38, 0xe000
	s_nop 0
	global_load_lds_dwordx4 v176, s[42:43]
	s_waitcnt lgkmcnt(8)
	s_barrier
	s_setprio 1
	s_waitcnt lgkmcnt(7)
	v_mfma_f32_16x16x32_bf16 v[148:151], v[80:83], v[96:99], v[148:151]
	v_mfma_f32_16x16x32_bf16 v[144:147], v[88:91], v[96:99], v[144:147]
	s_waitcnt lgkmcnt(5)
	v_mfma_f32_16x16x32_bf16 v[136:139], v[80:83], v[108:111], v[136:139]
	v_mfma_f32_16x16x32_bf16 v[128:131], v[88:91], v[108:111], v[128:131]
	s_waitcnt lgkmcnt(3)
	v_mfma_f32_16x16x32_bf16 v[120:123], v[80:83], v[160:163], v[120:123]
	v_mfma_f32_16x16x32_bf16 v[104:107], v[88:91], v[160:163], v[104:107]
	s_waitcnt lgkmcnt(1)
	v_mfma_f32_16x16x32_bf16 v[76:79], v[80:83], v[198:201], v[76:79]
	v_mfma_f32_16x16x32_bf16 v[72:75], v[88:91], v[198:201], v[72:75]
	v_mfma_f32_16x16x32_bf16 v[148:151], v[84:87], v[100:103], v[148:151]
	v_mfma_f32_16x16x32_bf16 v[144:147], v[92:95], v[100:103], v[144:147]
	v_mfma_f32_16x16x32_bf16 v[136:139], v[84:87], v[112:115], v[136:139]
	v_mfma_f32_16x16x32_bf16 v[128:131], v[92:95], v[112:115], v[128:131]
	v_mfma_f32_16x16x32_bf16 v[120:123], v[84:87], v[164:167], v[120:123]
	v_mfma_f32_16x16x32_bf16 v[104:107], v[92:95], v[164:167], v[104:107]
	s_waitcnt lgkmcnt(0)
	v_mfma_f32_16x16x32_bf16 v[76:79], v[84:87], v[202:205], v[76:79]
	v_mfma_f32_16x16x32_bf16 v[72:75], v[92:95], v[202:205], v[72:75]
	s_setprio 0
	s_barrier
	s_add_i32 s68, s2, s54
	v_lshl_add_u64 v[184:185], s[28:29], 0, v[172:173]
	s_mov_b32 m0, s68
	ds_read_b128 v[206:209], v191
	ds_read_b128 v[210:213], v191 offset:1024
	ds_read_b128 v[214:217], v191 offset:2048
	ds_read_b128 v[218:221], v191 offset:3072
	global_load_lds_dwordx4 v[184:185], off
	v_lshl_add_u64 v[194:195], s[28:29], 0, v[168:169]
	s_add_i32 m0, s68, 0x2000
	s_nop 0
	global_load_lds_dwordx4 v[194:195], off
	s_barrier
	s_setprio 1
	s_waitcnt lgkmcnt(3)
	v_mfma_f32_16x16x32_bf16 v[156:159], v[206:209], v[96:99], v[156:159]
	s_waitcnt lgkmcnt(1)
	v_mfma_f32_16x16x32_bf16 v[96:99], v[214:217], v[96:99], v[152:155]
	v_mfma_f32_16x16x32_bf16 v[156:159], v[210:213], v[100:103], v[156:159]
	s_waitcnt lgkmcnt(0)
	v_mfma_f32_16x16x32_bf16 v[96:99], v[218:221], v[100:103], v[96:99]
	v_mfma_f32_16x16x32_bf16 v[100:103], v[206:209], v[108:111], v[140:143]
	v_mfma_f32_16x16x32_bf16 v[108:111], v[214:217], v[108:111], v[132:135]
	v_mfma_f32_16x16x32_bf16 v[116:119], v[214:217], v[160:163], v[116:119]
	v_mfma_f32_16x16x32_bf16 v[68:71], v[206:209], v[198:201], v[68:71]
	v_mfma_f32_16x16x32_bf16 v[64:67], v[214:217], v[198:201], v[64:67]
	s_mov_b32 m0, s38
	v_mfma_f32_16x16x32_bf16 v[100:103], v[210:213], v[112:115], v[100:103]
	v_lshl_add_u64 v[226:227], s[46:47], 0, v[174:175]
	v_mfma_f32_16x16x32_bf16 v[108:111], v[218:221], v[112:115], v[108:111]
	v_mfma_f32_16x16x32_bf16 v[112:115], v[206:209], v[160:163], v[124:127]
	v_mfma_f32_16x16x32_bf16 v[116:119], v[218:221], v[164:167], v[116:119]
	v_mfma_f32_16x16x32_bf16 v[68:71], v[210:213], v[202:205], v[68:71]
	v_mfma_f32_16x16x32_bf16 v[64:67], v[218:221], v[202:205], v[64:67]
	v_mfma_f32_16x16x32_bf16 v[112:115], v[210:213], v[164:167], v[112:115]
	s_setprio 0
	s_barrier
	ds_read_b128 v[124:127], v190 offset:16384
	ds_read_b128 v[132:135], v190 offset:17408
	ds_read_b128 v[140:143], v190 offset:18432
	ds_read_b128 v[152:155], v190 offset:19456
	ds_read_b128 v[160:163], v190 offset:20480
	ds_read_b128 v[164:167], v190 offset:21504
	ds_read_b128 v[198:201], v190 offset:22528
	ds_read_b128 v[202:205], v190 offset:23552
	global_load_lds_dwordx4 v[226:227], off
	v_lshl_add_u64 v[234:235], s[46:47], 0, v[170:171]
	s_mov_b32 m0, s39
	s_nop 0
	global_load_lds_dwordx4 v[234:235], off
	s_waitcnt vmcnt(10)
	s_barrier
	s_setprio 1
	s_waitcnt lgkmcnt(7)
	v_mfma_f32_16x16x32_bf16 v[60:63], v[80:83], v[124:127], v[60:63]
	v_mfma_f32_16x16x32_bf16 v[48:51], v[88:91], v[124:127], v[48:51]
	s_waitcnt lgkmcnt(5)
	v_mfma_f32_16x16x32_bf16 v[40:43], v[80:83], v[140:143], v[40:43]
	v_mfma_f32_16x16x32_bf16 v[32:35], v[88:91], v[140:143], v[32:35]
	s_waitcnt lgkmcnt(3)
	v_mfma_f32_16x16x32_bf16 v[24:27], v[80:83], v[160:163], v[24:27]
	v_mfma_f32_16x16x32_bf16 v[16:19], v[88:91], v[160:163], v[16:19]
	s_waitcnt lgkmcnt(1)
	v_mfma_f32_16x16x32_bf16 v[12:15], v[80:83], v[198:201], v[12:15]
	v_mfma_f32_16x16x32_bf16 v[8:11], v[88:91], v[198:201], v[8:11]
	v_mfma_f32_16x16x32_bf16 v[60:63], v[84:87], v[132:135], v[60:63]
	v_mfma_f32_16x16x32_bf16 v[48:51], v[92:95], v[132:135], v[48:51]
	v_mfma_f32_16x16x32_bf16 v[40:43], v[84:87], v[152:155], v[40:43]
	v_mfma_f32_16x16x32_bf16 v[32:35], v[92:95], v[152:155], v[32:35]
	v_mfma_f32_16x16x32_bf16 v[24:27], v[84:87], v[164:167], v[24:27]
	v_mfma_f32_16x16x32_bf16 v[16:19], v[92:95], v[164:167], v[16:19]
	s_waitcnt lgkmcnt(0)
	v_mfma_f32_16x16x32_bf16 v[12:15], v[84:87], v[202:205], v[12:15]
	v_mfma_f32_16x16x32_bf16 v[8:11], v[92:95], v[202:205], v[8:11]
	s_setprio 0
	s_barrier
	s_add_u32 s68, s28, 0x80000
	s_addc_u32 s69, s29, 0
	s_add_i32 s70, s31, s54
	s_mov_b32 m0, s70
	s_nop 0
	global_load_lds_dwordx4 v172, s[68:69]
	s_add_i32 m0, s70, 0x2000
	s_nop 0
	global_load_lds_dwordx4 v168, s[68:69]
	s_waitcnt vmcnt(6)
	s_barrier
; #define PG8_STAGE(bufoff, gbase, voff) do { _Pragma("unroll") for (int _i = 0; _i < 2; ++_i) \
;         __builtin_amdgcn_global_load_lds((const unsigned*)((const char*)(gbase) + (voff)[_i]), (LAS unsigned*)(lds + (bufoff) + ldsw + _i * 8192), 16, 0, 0); } while (0)
; #define PG8_LDA(dst, b, h) do { _Pragma("unroll") for (int m = 0; m < 4; ++m) _Pragma("unroll") for (int k = 0; k < 2; ++k) dst[m][k] = *(const LAS bf16x8*)(lds + PG8_SA(b, h) + aoff + m * 2048 + k * 1024); } while (0)
; #define PG8_LDB(dst, b, h) do { _Pragma("unroll") for (int n = 0; n < 2; ++n) _Pragma("unroll") for (int k = 0; k < 2; ++k) dst[n][k] = *(const LAS bf16x8*)(lds + PG8_SB(b, h) + boff + n * 2048 + k * 1024); } while (0)
; #define PG8_MMA(ai, bj, At, Bt) do { __builtin_amdgcn_s_setprio(1); _Pragma("unroll") for (int m = 0; m < 4; ++m) _Pragma("unroll") for (int n = 0; n < 2; ++n) _Pragma("unroll") for (int k = 0; k < 2; ++k) \
;         acc[ai][bj][m][n] = __builtin_amdgcn_mfma_f32_16x16x32_bf16(Bt[n][k], At[m][k], acc[ai][bj][m][n], 0, 0, 0); __builtin_amdgcn_s_setprio(0); } while (0)
; #define PG8_WAIT_V(n) asm volatile("s_waitcnt vmcnt(" #n ")" ::: "memory")
; #define PG8_WAIT_L(n) asm volatile("s_waitcnt lgkmcnt(" #n ")" ::: "memory")
; #define PG8_BAR __builtin_amdgcn_s_barrier()
; #define PG8_SCHED __builtin_amdgcn_sched_barrier(0)
; template <class Map, class Epi>
; DI void gemm_phase(LAS unsigned char* lds, const Map& MP, const Epi& E, const int nM, const int nN, const int K, const int lda, const int ldb) {
;     ...
;             PG8_STAGE(PG8_SB(0, 1), b2 + hstepB, voffB);
;             PG8_WAIT_V(6); PG8_BAR; PG8_MMA(1, 1, At, B1); PG8_BAR;
;             PG8_LDB(B0, 1, 0); PG8_SCHED; PG8_LDA(At, 1, 0); PG8_STAGE(PG8_SA(0, 1), a2 + hstepA, voffA);
;             PG8_WAIT_L(8); PG8_BAR; PG8_WAIT_L(0); PG8_MMA(0, 0, At, B0); PG8_BAR; PG8_SCHED;
;             PG8_LDB(B1, 1, 1); PG8_STAGE(PG8_SB(1, 0), b3, voffB);
;             PG8_BAR; PG8_WAIT_L(0); PG8_MMA(0, 1, At, B1); PG8_BAR;
;             PG8_LDA(At, 1, 1); PG8_STAGE(PG8_SA(1, 0), a3, voffA);
;             PG8_BAR; PG8_WAIT_L(0); PG8_MMA(1, 0, At, B0); PG8_BAR; PG8_SCHED;
	s_setprio 1
	v_mfma_f32_16x16x32_bf16 v[56:59], v[206:209], v[124:127], v[56:59]
	v_mfma_f32_16x16x32_bf16 v[52:55], v[214:217], v[124:127], v[52:55]
	s_add_i32 s68, 0, 0x18000
	v_add_u32_e32 v92, s68, v188
	ds_read_b128 v[80:83], v92
	v_mfma_f32_16x16x32_bf16 v[44:47], v[206:209], v[140:143], v[44:47]
	v_mfma_f32_16x16x32_bf16 v[36:39], v[214:217], v[140:143], v[36:39]
	ds_read_b128 v[84:87], v92 offset:1024
	v_mfma_f32_16x16x32_bf16 v[28:31], v[206:209], v[160:163], v[28:31]
	v_mfma_f32_16x16x32_bf16 v[20:23], v[214:217], v[160:163], v[20:23]
	ds_read_b128 v[88:91], v92 offset:2048
	v_mfma_f32_16x16x32_bf16 v[4:7], v[206:209], v[198:201], v[4:7]
	v_mfma_f32_16x16x32_bf16 v[0:3], v[214:217], v[198:201], v[0:3]
	ds_read_b128 v[92:95], v92 offset:3072
	v_mfma_f32_16x16x32_bf16 v[56:59], v[210:213], v[132:135], v[56:59]
	v_mfma_f32_16x16x32_bf16 v[52:55], v[218:221], v[132:135], v[52:55]
	v_mfma_f32_16x16x32_bf16 v[44:47], v[210:213], v[152:155], v[44:47]
	v_mfma_f32_16x16x32_bf16 v[36:39], v[218:221], v[152:155], v[36:39]
	v_mfma_f32_16x16x32_bf16 v[28:31], v[210:213], v[164:167], v[28:31]
	v_mfma_f32_16x16x32_bf16 v[20:23], v[218:221], v[164:167], v[20:23]
	v_mfma_f32_16x16x32_bf16 v[4:7], v[210:213], v[202:205], v[4:7]
	v_mfma_f32_16x16x32_bf16 v[0:3], v[218:221], v[202:205], v[0:3]
	s_setprio 0
	s_barrier
	s_add_u32 s46, s46, 0x80000
	s_addc_u32 s47, s47, 0
	s_mov_b32 m0, s56
	ds_read_b128 v[124:127], v190 offset:32768
	ds_read_b128 v[132:135], v190 offset:33792
	ds_read_b128 v[160:163], v190 offset:34816
	ds_read_b128 v[164:167], v190 offset:35840
	ds_read_b128 v[198:201], v190 offset:36864
	ds_read_b128 v[202:205], v190 offset:37888
	ds_read_b128 v[206:209], v190 offset:38912
	ds_read_b128 v[210:213], v190 offset:39936
	global_load_lds_dwordx4 v174, s[46:47]
	s_mov_b32 m0, s57
	s_nop 0
	global_load_lds_dwordx4 v170, s[46:47]
	s_waitcnt lgkmcnt(8)
	s_barrier
	s_setprio 1
	s_waitcnt lgkmcnt(7)
	v_mfma_f32_16x16x32_bf16 v[140:143], v[80:83], v[124:127], v[148:151]
	s_waitcnt lgkmcnt(6)
	v_mfma_f32_16x16x32_bf16 v[148:151], v[84:87], v[132:135], v[140:143]
	v_mfma_f32_16x16x32_bf16 v[140:143], v[88:91], v[124:127], v[144:147]
	s_waitcnt lgkmcnt(5)
	v_mfma_f32_16x16x32_bf16 v[136:139], v[80:83], v[160:163], v[136:139]
	v_mfma_f32_16x16x32_bf16 v[128:131], v[88:91], v[160:163], v[128:131]
	s_waitcnt lgkmcnt(3)
	v_mfma_f32_16x16x32_bf16 v[120:123], v[80:83], v[198:201], v[120:123]
	v_mfma_f32_16x16x32_bf16 v[104:107], v[88:91], v[198:201], v[104:107]
	s_waitcnt lgkmcnt(1)
	v_mfma_f32_16x16x32_bf16 v[76:79], v[80:83], v[206:209], v[76:79]
	v_mfma_f32_16x16x32_bf16 v[72:75], v[88:91], v[206:209], v[72:75]
	v_mfma_f32_16x16x32_bf16 v[144:147], v[92:95], v[132:135], v[140:143]
	v_mfma_f32_16x16x32_bf16 v[136:139], v[84:87], v[164:167], v[136:139]
	v_mfma_f32_16x16x32_bf16 v[128:131], v[92:95], v[164:167], v[128:131]
	v_mfma_f32_16x16x32_bf16 v[120:123], v[84:87], v[202:205], v[120:123]
	v_mfma_f32_16x16x32_bf16 v[104:107], v[92:95], v[202:205], v[104:107]
	s_waitcnt lgkmcnt(0)
	v_mfma_f32_16x16x32_bf16 v[76:79], v[84:87], v[210:213], v[76:79]
	v_mfma_f32_16x16x32_bf16 v[72:75], v[92:95], v[210:213], v[72:75]
	s_setprio 0
	s_barrier
	s_add_i32 s46, 0, 0x1c000
	v_add_u32_e32 v140, s46, v188
	s_add_i32 s47, s68, s54
	ds_read_b128 v[214:217], v140
	ds_read_b128 v[218:221], v140 offset:1024
	ds_read_b128 v[222:225], v140 offset:2048
	ds_read_b128 v[230:233], v140 offset:3072
	v_lshl_add_u64 v[140:141], v[184:185], 0, s[14:15]
	s_mov_b32 m0, s47
	s_nop 0
	global_load_lds_dwordx4 v[140:141], off
	v_lshl_add_u64 v[140:141], v[194:195], 0, s[14:15]
	s_add_i32 m0, s47, 0x2000
	s_nop 0
	global_load_lds_dwordx4 v[140:141], off
	s_barrier
	s_setprio 1
	s_waitcnt lgkmcnt(1)
	v_mfma_f32_16x16x32_bf16 v[96:99], v[222:225], v[124:127], v[96:99]
	v_mfma_f32_16x16x32_bf16 v[140:143], v[214:217], v[124:127], v[156:159]
	s_waitcnt lgkmcnt(0)
	v_mfma_f32_16x16x32_bf16 v[152:155], v[230:233], v[132:135], v[96:99]
	v_mfma_f32_16x16x32_bf16 v[96:99], v[214:217], v[160:163], v[100:103]
	v_mfma_f32_16x16x32_bf16 v[156:159], v[218:221], v[132:135], v[140:143]
	v_mfma_f32_16x16x32_bf16 v[140:143], v[218:221], v[164:167], v[96:99]
	v_mfma_f32_16x16x32_bf16 v[96:99], v[222:225], v[160:163], v[108:111]
	v_mfma_f32_16x16x32_bf16 v[132:135], v[230:233], v[164:167], v[96:99]
	v_mfma_f32_16x16x32_bf16 v[96:99], v[214:217], v[198:201], v[112:115]
	s_mov_b32 m0, s63
	v_mfma_f32_16x16x32_bf16 v[124:127], v[218:221], v[202:205], v[96:99]
	v_lshl_add_u64 v[184:185], v[226:227], 0, s[14:15]
	v_mfma_f32_16x16x32_bf16 v[96:99], v[222:225], v[198:201], v[116:119]
	v_mfma_f32_16x16x32_bf16 v[68:71], v[214:217], v[206:209], v[68:71]
	v_mfma_f32_16x16x32_bf16 v[64:67], v[222:225], v[206:209], v[64:67]
	v_mfma_f32_16x16x32_bf16 v[116:119], v[230:233], v[202:205], v[96:99]
	v_mfma_f32_16x16x32_bf16 v[68:71], v[218:221], v[210:213], v[68:71]
	v_mfma_f32_16x16x32_bf16 v[64:67], v[230:233], v[210:213], v[64:67]
	s_setprio 0
	s_barrier
	ds_read_b128 v[96:99], v190 offset:49152
	ds_read_b128 v[100:103], v190 offset:50176
	ds_read_b128 v[108:111], v190 offset:51200
	ds_read_b128 v[112:115], v190 offset:52224
	ds_read_b128 v[160:163], v190 offset:53248
	ds_read_b128 v[164:167], v190 offset:54272
	ds_read_b128 v[198:201], v190 offset:55296
	ds_read_b128 v[202:205], v190 offset:56320
	global_load_lds_dwordx4 v[184:185], off
	v_lshl_add_u64 v[184:185], v[234:235], 0, s[14:15]
	s_mov_b32 m0, s66
	s_nop 0
	global_load_lds_dwordx4 v[184:185], off
	s_waitcnt vmcnt(10)
	s_barrier
; #define PG8_STAGE(bufoff, gbase, voff) do { _Pragma("unroll") for (int _i = 0; _i < 2; ++_i) \
;         __builtin_amdgcn_global_load_lds((const unsigned*)((const char*)(gbase) + (voff)[_i]), (LAS unsigned*)(lds + (bufoff) + ldsw + _i * 8192), 16, 0, 0); } while (0)
; #define PG8_MMA(ai, bj, At, Bt) do { __builtin_amdgcn_s_setprio(1); _Pragma("unroll") for (int m = 0; m < 4; ++m) _Pragma("unroll") for (int n = 0; n < 2; ++n) _Pragma("unroll") for (int k = 0; k < 2; ++k) \
;         acc[ai][bj][m][n] = __builtin_amdgcn_mfma_f32_16x16x32_bf16(Bt[n][k], At[m][k], acc[ai][bj][m][n], 0, 0, 0); __builtin_amdgcn_s_setprio(0); } while (0)
; #define PG8_WAIT_V(n) asm volatile("s_waitcnt vmcnt(" #n ")" ::: "memory")
; #define PG8_WAIT_L(n) asm volatile("s_waitcnt lgkmcnt(" #n ")" ::: "memory")
; #define PG8_BAR __builtin_amdgcn_s_barrier()
; #define PG8_SCHED __builtin_amdgcn_sched_barrier(0)
; template <class Map, class Epi>
; DI void gemm_phase(LAS unsigned char* lds, const Map& MP, const Epi& E, const int nM, const int nN, const int K, const int lda, const int ldb) {
;     ...
;             PG8_BAR; PG8_WAIT_L(0); PG8_MMA(1, 0, At, B0); PG8_BAR; PG8_SCHED;
;             PG8_STAGE(PG8_SB(1, 1), b3 + hstepB, voffB);
;             PG8_WAIT_V(6); PG8_BAR; PG8_MMA(1, 1, At, B1); PG8_BAR;
;         }
	s_setprio 1
	s_waitcnt lgkmcnt(7)
	v_mfma_f32_16x16x32_bf16 v[60:63], v[80:83], v[96:99], v[60:63]
	v_mfma_f32_16x16x32_bf16 v[48:51], v[88:91], v[96:99], v[48:51]
	s_waitcnt lgkmcnt(5)
	v_mfma_f32_16x16x32_bf16 v[40:43], v[80:83], v[108:111], v[40:43]
	v_mfma_f32_16x16x32_bf16 v[32:35], v[88:91], v[108:111], v[32:35]
	s_waitcnt lgkmcnt(3)
	v_mfma_f32_16x16x32_bf16 v[24:27], v[80:83], v[160:163], v[24:27]
	v_mfma_f32_16x16x32_bf16 v[16:19], v[88:91], v[160:163], v[16:19]
	s_waitcnt lgkmcnt(1)
	v_mfma_f32_16x16x32_bf16 v[12:15], v[80:83], v[198:201], v[12:15]
	v_mfma_f32_16x16x32_bf16 v[8:11], v[88:91], v[198:201], v[8:11]
	v_mfma_f32_16x16x32_bf16 v[60:63], v[84:87], v[100:103], v[60:63]
	v_mfma_f32_16x16x32_bf16 v[48:51], v[92:95], v[100:103], v[48:51]
	v_mfma_f32_16x16x32_bf16 v[40:43], v[84:87], v[112:115], v[40:43]
	v_mfma_f32_16x16x32_bf16 v[32:35], v[92:95], v[112:115], v[32:35]
	v_mfma_f32_16x16x32_bf16 v[24:27], v[84:87], v[164:167], v[24:27]
	v_mfma_f32_16x16x32_bf16 v[16:19], v[92:95], v[164:167], v[16:19]
	s_waitcnt lgkmcnt(0)
	v_mfma_f32_16x16x32_bf16 v[12:15], v[84:87], v[202:205], v[12:15]
	v_mfma_f32_16x16x32_bf16 v[8:11], v[92:95], v[202:205], v[8:11]
	s_setprio 0
	s_barrier
	s_add_u32 s28, s28, 0x80080
	s_addc_u32 s29, s29, 0
	s_add_i32 s46, s46, s54
	s_mov_b32 m0, s46
	s_nop 0
	global_load_lds_dwordx4 v172, s[28:29]
	s_add_i32 m0, s46, 0x2000
	s_nop 0
	global_load_lds_dwordx4 v168, s[28:29]
	s_waitcnt vmcnt(6)
	s_barrier
	s_setprio 1
	v_mfma_f32_16x16x32_bf16 v[56:59], v[214:217], v[96:99], v[56:59]
	v_mfma_f32_16x16x32_bf16 v[52:55], v[222:225], v[96:99], v[52:55]
	ds_read_b128 v[80:83], v189
	v_mfma_f32_16x16x32_bf16 v[44:47], v[214:217], v[108:111], v[44:47]
	v_mfma_f32_16x16x32_bf16 v[36:39], v[222:225], v[108:111], v[36:39]
	ds_read_b128 v[84:87], v189 offset:1024
	v_mfma_f32_16x16x32_bf16 v[28:31], v[214:217], v[160:163], v[28:31]
	v_mfma_f32_16x16x32_bf16 v[20:23], v[222:225], v[160:163], v[20:23]
	ds_read_b128 v[88:91], v189 offset:2048
	v_mfma_f32_16x16x32_bf16 v[4:7], v[214:217], v[198:201], v[4:7]
	v_mfma_f32_16x16x32_bf16 v[0:3], v[222:225], v[198:201], v[0:3]
	ds_read_b128 v[92:95], v189 offset:3072
	v_mfma_f32_16x16x32_bf16 v[56:59], v[218:221], v[100:103], v[56:59]
	s_add_i32 s3, s3, 2
	v_mfma_f32_16x16x32_bf16 v[52:55], v[230:233], v[100:103], v[52:55]
	s_add_u32 vcc_lo, vcc_lo, 0x100
	s_addc_u32 vcc_hi, vcc_hi, 0
	v_mfma_f32_16x16x32_bf16 v[44:47], v[218:221], v[112:115], v[44:47]
	s_add_u32 s42, s42, 0x100
	s_addc_u32 s43, s43, 0
	v_mfma_f32_16x16x32_bf16 v[36:39], v[230:233], v[112:115], v[36:39]
	s_cmp_gt_u32 s3, 29
	v_mfma_f32_16x16x32_bf16 v[28:31], v[218:221], v[164:167], v[28:31]
	v_mfma_f32_16x16x32_bf16 v[20:23], v[230:233], v[164:167], v[20:23]
	v_mfma_f32_16x16x32_bf16 v[4:7], v[218:221], v[202:205], v[4:7]
	v_mfma_f32_16x16x32_bf16 v[0:3], v[230:233], v[202:205], v[0:3]
	s_setprio 0
	s_barrier
	s_cbranch_scc0 .LBB1_1908
; DI float silu_mul(float g, float v) { return g * v * __builtin_amdgcn_rcpf(1.0f + __builtin_amdgcn_exp2f(-LOG2E * g)); }
;     DI void operator()(const f32x4 (&acc)[2][2][4][2], const Unit& u, int wr, int wc, int fr, int fq) const {
;         const int row0 = u.pm * BM + wr * 64 + fr, ch0 = u.pn * 128 + wc * 32 + 8 * fq;
;         f32x4 w0[2], w1[2], w2[2], bb[2];
; #pragma unroll
;         for (int n = 0; n < 2; ++n) { w0[n] = *(const f32x4*)(cw + ch0 + 4 * n); w1[n] = *(const f32x4*)(cw + DFF + ch0 + 4 * n); w2[n] = *(const f32x4*)(cw + 2 * DFF + ch0 + 4 * n); bb[n] = *(const f32x4*)(cb + ch0 + 4 * n); }
; #pragma unroll
;         for (int ai = 0; ai < 2; ++ai)
; #pragma unroll
;             for (int m = 0; m < 4; ++m) {
;                 const bool efirst = (m == 0) && (fr == 0), elast = (m == 3) && (fr == 15);
;                 const int row = row0 + ai * HALF + m * 16;
;                 f32x4 gc[2];
; #pragma unroll
;                 for (int n = 0; n < 2; ++n) {
;                     const f32x4 g = acc[ai][0][m][n];
;                     const f32x4 gprev = acc[ai][0][m > 0 ? m - 1 : 0][n], gnext = acc[ai][0][m < 3 ? m + 1 : 3][n];
;                     f32x4 up, dn;
; #pragma unroll
;                     for (int e = 0; e < 4; ++e) {
;                         const float pu = (m > 0 && fr == 15) ? gprev[e] : g[e];
;                         const float pd = (m < 3 && fr == 0) ? gnext[e] : g[e];
;                         up[e] = dpp_ror1(pu); dn[e] = dpp_ror15(pd);
;                     }
;                     if (efirst) up = (f32x4){0.f, 0.f, 0.f, 0.f};
;                     if (elast) dn = (f32x4){0.f, 0.f, 0.f, 0.f};
;                     gc[n] = w0[n] * up + w1[n] * g + w2[n] * dn + bb[n];
;                 }
;                 if (efirst || elast) {
;                     const size_t eo = (size_t)((row >> 6) * 2 + (elast ? 1 : 0)) * DFF + ch0;
; #pragma unroll
;                     for (int n = 0; n < 2; ++n) { *(f32x4*)(EP + eo + 4 * n) = gc[n]; *(f32x4*)(ER + eo + 4 * n) = acc[ai][0][m][n]; *(f32x4*)(EV + eo + 4 * n) = acc[ai][1][m][n]; }
;                 } else {
;                     const f32x4 v0 = acc[ai][1][m][0], v1 = acc[ai][1][m][1];
;                     u32x4 o;
;                     o[0] = pack2(silu_mul(gc[0][0], v0[0]), silu_mul(gc[0][1], v0[1])); o[1] = pack2(silu_mul(gc[0][2], v0[2]), silu_mul(gc[0][3], v0[3]));
	s_waitcnt lgkmcnt(0)
	s_lshl_b32 s21, s45, 7
	v_mov_b32_e32 v194, v186
	v_mov_b32_e32 v80, v187
	s_or_b32 s21, s21, s62
	v_mov_b32_e32 v160, 0
	v_lshl_add_u32 v184, v80, 3, s21
	v_ashrrev_i32_e32 v185, 31, v184
	v_lshlrev_b64 v[80:81], 2, v[184:185]
	v_lshl_add_u64 v[84:85], s[4:5], 0, v[80:81]
	v_lshl_add_u64 v[88:89], s[16:17], 0, v[80:81]
	v_lshl_add_u64 v[92:93], s[18:19], 0, v[80:81]
	v_lshl_add_u64 v[112:113], s[6:7], 0, v[80:81]
	global_load_dwordx4 v[80:83], v[84:85], off offset:16
	global_load_dwordx4 v[96:99], v[84:85], off
	s_nop 0
	global_load_dwordx4 v[84:87], v[88:89], off offset:16
	global_load_dwordx4 v[100:103], v[88:89], off
	s_nop 0
	global_load_dwordx4 v[88:91], v[92:93], off offset:16
	global_load_dwordx4 v[108:111], v[92:93], off
	s_nop 0
	global_load_dwordx4 v[92:95], v[112:113], off offset:16
	s_nop 0
	global_load_dwordx4 v[112:115], v[112:113], off
	v_cmp_eq_u32_e32 vcc, 0, v194
	v_mov_b32_e32 v164, 0
	v_mov_b32_e32 v195, 0
	v_cndmask_b32_e32 v161, v148, v136, vcc
	v_cndmask_b32_e32 v162, v149, v137, vcc
	v_cndmask_b32_e32 v163, v150, v138, vcc
	v_mov_b32_dpp v160, v161 row_ror:15 row_mask:0xf bank_mask:0xf
	v_mov_b32_e32 v161, 0
	v_mov_b32_e32 v166, 0
	v_mov_b32_e32 v167, 0
	v_mov_b32_dpp v161, v162 row_ror:15 row_mask:0xf bank_mask:0xf
	v_mov_b32_e32 v162, 0
	v_mov_b32_dpp v164, v150 row_ror:1 row_mask:0xf bank_mask:0xf
	v_cndmask_b32_e32 v165, v151, v139, vcc
	v_mov_b32_dpp v162, v163 row_ror:15 row_mask:0xf bank_mask:0xf
	v_mov_b32_dpp v195, v151 row_ror:1 row_mask:0xf bank_mask:0xf
	v_mov_b32_e32 v163, 0
	v_mov_b32_dpp v166, v148 row_ror:1 row_mask:0xf bank_mask:0xf
	v_mov_b32_dpp v167, v149 row_ror:1 row_mask:0xf bank_mask:0xf
	v_mov_b32_dpp v163, v165 row_ror:15 row_mask:0xf bank_mask:0xf
	v_cndmask_b32_e64 v165, v195, 0, vcc
	v_cndmask_b32_e64 v164, v164, 0, vcc
	v_cndmask_b32_e64 v167, v167, 0, vcc
	v_cndmask_b32_e64 v166, v166, 0, vcc
	v_mov_b32_e32 v195, 0
	v_mov_b32_e32 v196, 0
	v_mov_b32_e32 v198, 0
	v_mov_b32_e32 v200, 0
	v_mov_b32_dpp v195, v144 row_ror:1 row_mask:0xf bank_mask:0xf
	v_mov_b32_dpp v196, v145 row_ror:1 row_mask:0xf bank_mask:0xf
	v_mov_b32_dpp v198, v146 row_ror:1 row_mask:0xf bank_mask:0xf
	v_cndmask_b32_e32 v199, v147, v131, vcc
	v_mov_b32_dpp v200, v147 row_ror:1 row_mask:0xf bank_mask:0xf
	v_cndmask_b32_e64 v198, v198, 0, vcc
	v_cndmask_b32_e64 v201, v196, 0, vcc
	s_lshl_b32 s3, s44, 8
	s_add_i32 s3, s3, s49
	v_add_u32_e32 v193, s3, v194
	v_cmp_ne_u32_e64 s[46:47], 0, v194
	s_waitcnt vmcnt(0)
	v_pk_mul_f32 v[164:165], v[98:99], v[164:165]
	v_pk_mul_f32 v[166:167], v[96:97], v[166:167]
	v_pk_fma_f32 v[164:165], v[150:151], v[102:103], v[164:165]
	v_pk_fma_f32 v[166:167], v[148:149], v[100:101], v[166:167]
	v_pk_fma_f32 v[162:163], v[110:111], v[162:163], v[164:165]
	v_cndmask_b32_e32 v165, v144, v128, vcc
	v_mov_b32_e32 v164, 0
	v_pk_fma_f32 v[160:161], v[108:109], v[160:161], v[166:167]
	v_cndmask_b32_e32 v166, v145, v129, vcc
	v_mov_b32_dpp v164, v165 row_ror:15 row_mask:0xf bank_mask:0xf
	v_mov_b32_e32 v165, 0
	v_cndmask_b32_e32 v167, v146, v130, vcc
	v_pk_add_f32 v[162:163], v[114:115], v[162:163]
	v_mov_b32_dpp v165, v166 row_ror:15 row_mask:0xf bank_mask:0xf
	v_mov_b32_e32 v166, 0
	v_pk_add_f32 v[160:161], v[112:113], v[160:161]
	s_nop 0
	v_mov_b32_dpp v166, v167 row_ror:15 row_mask:0xf bank_mask:0xf
	v_mov_b32_e32 v167, 0
	s_nop 1
	v_mov_b32_dpp v167, v199 row_ror:15 row_mask:0xf bank_mask:0xf
	v_cndmask_b32_e64 v199, v200, 0, vcc
	v_cndmask_b32_e64 v200, v195, 0, vcc
	v_pk_mul_f32 v[200:201], v[80:81], v[200:201]
	v_pk_mul_f32 v[198:199], v[82:83], v[198:199]
	v_pk_fma_f32 v[200:201], v[144:145], v[84:85], v[200:201]
	v_pk_fma_f32 v[198:199], v[146:147], v[86:87], v[198:199]
	v_pk_fma_f32 v[164:165], v[88:89], v[164:165], v[200:201]
	v_pk_fma_f32 v[166:167], v[90:91], v[166:167], v[198:199]
	v_pk_add_f32 v[164:165], v[92:93], v[164:165]
	v_pk_add_f32 v[166:167], v[94:95], v[166:167]
	s_and_saveexec_b64 s[28:29], s[46:47]
	s_xor_b64 s[28:29], exec, s[28:29]
	s_cbranch_execz .LBB1_1911
	v_mul_f32_e32 v195, 0xbfb8aa3b, v160
	v_exp_f32_e32 v195, v195
	v_mul_f32_e32 v196, 0xbfb8aa3b, v161
	v_exp_f32_e32 v196, v196
	v_pk_mul_f32 v[160:161], v[156:157], v[160:161]
	v_add_f32_e32 v195, 1.0, v195
	v_rcp_f32_e32 v198, v195
	v_add_f32_e32 v196, 1.0, v196
	v_mul_f32_e32 v195, 0xbfb8aa3b, v162
	v_rcp_f32_e32 v199, v196
	v_exp_f32_e32 v195, v195
	v_mul_f32_e32 v196, 0xbfb8aa3b, v163
	v_exp_f32_e32 v196, v196
	v_pk_mul_f32 v[160:161], v[160:161], v[198:199]
	v_add_f32_e32 v195, 1.0, v195
	v_rcp_f32_e32 v200, v195
	v_add_f32_e32 v195, 1.0, v196
	v_rcp_f32_e32 v201, v195
	v_cvt_pk_bf16_f32 v160, v160, v161
	v_mul_f32_e32 v161, 0xbfb8aa3b, v164
	v_exp_f32_e32 v195, v161
	v_mul_f32_e32 v161, 0xbfb8aa3b, v165
	v_exp_f32_e32 v196, v161
	v_pk_mul_f32 v[162:163], v[158:159], v[162:163]
	v_pk_mul_f32 v[164:165], v[152:153], v[164:165]
	v_pk_mul_f32 v[162:163], v[162:163], v[200:201]
	s_nop 0
	v_cvt_pk_bf16_f32 v161, v162, v163
	v_add_f32_e32 v162, 1.0, v195
	v_mul_f32_e32 v195, 0xbfb8aa3b, v166
	v_add_f32_e32 v163, 1.0, v196
	v_exp_f32_e32 v195, v195
	v_mul_f32_e32 v196, 0xbfb8aa3b, v167
	v_exp_f32_e32 v196, v196
	v_rcp_f32_e32 v162, v162
	v_add_f32_e32 v195, 1.0, v195
	v_rcp_f32_e32 v198, v195
	v_add_f32_e32 v195, 1.0, v196
	v_rcp_f32_e32 v163, v163
	v_rcp_f32_e32 v199, v195
	v_pk_mul_f32 v[166:167], v[154:155], v[166:167]
	v_pk_mul_f32 v[162:163], v[164:165], v[162:163]
	v_pk_mul_f32 v[164:165], v[166:167], v[198:199]
	v_cvt_pk_bf16_f32 v162, v162, v163
	v_cvt_pk_bf16_f32 v163, v164, v165
	v_mov_b64_e32 v[164:165], s[52:53]
	v_mad_i64_i32 v[164:165], s[42:43], v193, s60, v[164:165]
	v_lshl_add_u64 v[164:165], v[184:185], 1, v[164:165]
	global_store_dwordx4 v[164:165], v[160:163], off

; #define PG8_STAGE(bufoff, gbase, voff) do { _Pragma("unroll") for (int _i = 0; _i < 2; ++_i) \
;         __builtin_amdgcn_global_load_lds((const unsigned*)((const char*)(gbase) + (voff)[_i]), (LAS unsigned*)(lds + (bufoff) + ldsw + _i * 8192), 16, 0, 0); } while (0)
; #define PG8_LDA(dst, b, h) do { _Pragma("unroll") for (int m = 0; m < 4; ++m) _Pragma("unroll") for (int k = 0; k < 2; ++k) dst[m][k] = *(const LAS bf16x8*)(lds + PG8_SA(b, h) + aoff + m * 2048 + k * 1024); } while (0)
; #define PG8_LDB(dst, b, h) do { _Pragma("unroll") for (int n = 0; n < 2; ++n) _Pragma("unroll") for (int k = 0; k < 2; ++k) dst[n][k] = *(const LAS bf16x8*)(lds + PG8_SB(b, h) + boff + n * 2048 + k * 1024); } while (0)
; #define PG8_MMA(ai, bj, At, Bt) do { __builtin_amdgcn_s_setprio(1); _Pragma("unroll") for (int m = 0; m < 4; ++m) _Pragma("unroll") for (int n = 0; n < 2; ++n) _Pragma("unroll") for (int k = 0; k < 2; ++k) \
;         acc[ai][bj][m][n] = __builtin_amdgcn_mfma_f32_16x16x32_bf16(Bt[n][k], At[m][k], acc[ai][bj][m][n], 0, 0, 0); __builtin_amdgcn_s_setprio(0); } while (0)
; #define PG8_WAIT_L(n) asm volatile("s_waitcnt lgkmcnt(" #n ")" ::: "memory")
; #define PG8_BAR __builtin_amdgcn_s_barrier()
; #define PG8_SCHED __builtin_amdgcn_sched_barrier(0)
; template <class Map, class Epi>
; DI void gemm_phase(LAS unsigned char* lds, const Map& MP, const Epi& E, const int nM, const int nN, const int K, const int lda, const int ldb) {
;     ...
;             const bool last = (t == nt - 2);
;             const char* a1 = cA + (size_t)(t + 1) * kstep;
;             const char* a2 = last ? nA : cA + (size_t)(t + 2) * kstep; const char* b2 = last ? nB : cB + (size_t)(t + 2) * kstep;
;             const char* a3 = a2 + kstep; const char* b3 = b2 + kstep;
;             PG8_LDB(B0, 0, 0); PG8_SCHED; PG8_LDA(At, 0, 0); PG8_STAGE(PG8_SA(1, 1), a1 + hstepA, voffA);
;             PG8_WAIT_L(8); PG8_BAR; PG8_WAIT_L(0); PG8_MMA(0, 0, At, B0); PG8_BAR; PG8_SCHED;
;             PG8_LDB(B1, 0, 1); PG8_STAGE(PG8_SB(0, 0), b2, voffB);
;             PG8_BAR; PG8_WAIT_L(0); PG8_MMA(0, 1, At, B1); PG8_BAR;
;             PG8_LDA(At, 0, 1); PG8_STAGE(PG8_SA(0, 0), a2, voffA);
;             PG8_BAR; PG8_WAIT_L(0); PG8_MMA(1, 0, At, B0); PG8_BAR; PG8_SCHED;
.LBB1_2078:
	s_add_u32 s10, s8, 0x100
	s_addc_u32 s11, s9, 0
	s_cmpk_eq_i32 s3, 0x54
	s_cselect_b32 s15, s43, s11
	s_cselect_b32 s14, s42, s10
	s_cselect_b32 s13, s7, s44
	s_cselect_b32 s12, s6, s39
	s_add_i32 m0, s24, 0xc000
	ds_read_b128 v[168:171], v150
	ds_read_b128 v[172:175], v150 offset:1024
	ds_read_b128 v[176:179], v150 offset:2048
	ds_read_b128 v[180:183], v150 offset:3072
	ds_read_b128 v[184:187], v150 offset:4096
	ds_read_b128 v[188:191], v150 offset:5120
	ds_read_b128 v[192:195], v150 offset:6144
	ds_read_b128 v[198:201], v150 offset:7168
	global_load_lds_dwordx4 v138, s[8:9]
	s_add_i32 m0, s24, 0xe000
	s_nop 0
	global_load_lds_dwordx4 v136, s[8:9]
	s_waitcnt lgkmcnt(8)
	s_barrier
	s_setprio 1
	s_waitcnt lgkmcnt(7)
	v_mfma_f32_16x16x32_bf16 v[124:127], v[152:155], v[168:171], v[124:127]
	v_mfma_f32_16x16x32_bf16 v[120:123], v[160:163], v[168:171], v[120:123]
	s_waitcnt lgkmcnt(5)
	v_mfma_f32_16x16x32_bf16 v[108:111], v[152:155], v[176:179], v[108:111]
	v_mfma_f32_16x16x32_bf16 v[104:107], v[160:163], v[176:179], v[104:107]
	s_waitcnt lgkmcnt(3)
	v_mfma_f32_16x16x32_bf16 v[92:95], v[152:155], v[184:187], v[92:95]
	v_mfma_f32_16x16x32_bf16 v[88:91], v[160:163], v[184:187], v[88:91]
	s_waitcnt lgkmcnt(1)
	v_mfma_f32_16x16x32_bf16 v[76:79], v[152:155], v[192:195], v[76:79]
	v_mfma_f32_16x16x32_bf16 v[72:75], v[160:163], v[192:195], v[72:75]
	v_mfma_f32_16x16x32_bf16 v[124:127], v[156:159], v[172:175], v[124:127]
	v_mfma_f32_16x16x32_bf16 v[120:123], v[164:167], v[172:175], v[120:123]
	v_mfma_f32_16x16x32_bf16 v[108:111], v[156:159], v[180:183], v[108:111]
	v_mfma_f32_16x16x32_bf16 v[104:107], v[164:167], v[180:183], v[104:107]
	v_mfma_f32_16x16x32_bf16 v[92:95], v[156:159], v[188:191], v[92:95]
	v_mfma_f32_16x16x32_bf16 v[88:91], v[164:167], v[188:191], v[88:91]
	s_waitcnt lgkmcnt(0)
	v_mfma_f32_16x16x32_bf16 v[76:79], v[156:159], v[198:201], v[76:79]
	v_mfma_f32_16x16x32_bf16 v[72:75], v[164:167], v[198:201], v[72:75]
	s_setprio 0
	s_barrier
	s_add_i32 s8, s35, s22
	v_lshl_add_u64 v[144:145], s[12:13], 0, v[132:133]
	s_mov_b32 m0, s8
	ds_read_b128 v[202:205], v151
	ds_read_b128 v[206:209], v151 offset:1024
	ds_read_b128 v[210:213], v151 offset:2048
	ds_read_b128 v[214:217], v151 offset:3072
	global_load_lds_dwordx4 v[144:145], off
	v_lshl_add_u64 v[218:219], s[12:13], 0, v[128:129]
	s_add_i32 m0, s8, 0x2000
	s_nop 0
	global_load_lds_dwordx4 v[218:219], off
	s_barrier
	s_setprio 1
	s_waitcnt lgkmcnt(3)
	v_mfma_f32_16x16x32_bf16 v[116:119], v[202:205], v[168:171], v[116:119]
	s_waitcnt lgkmcnt(1)
	v_mfma_f32_16x16x32_bf16 v[112:115], v[210:213], v[168:171], v[112:115]
	v_mfma_f32_16x16x32_bf16 v[100:103], v[202:205], v[176:179], v[100:103]
	v_mfma_f32_16x16x32_bf16 v[96:99], v[210:213], v[176:179], v[96:99]
	v_mfma_f32_16x16x32_bf16 v[84:87], v[202:205], v[184:187], v[84:87]
	v_mfma_f32_16x16x32_bf16 v[80:83], v[210:213], v[184:187], v[80:83]
	v_mfma_f32_16x16x32_bf16 v[68:71], v[202:205], v[192:195], v[68:71]
	v_mfma_f32_16x16x32_bf16 v[64:67], v[210:213], v[192:195], v[64:67]
	v_mfma_f32_16x16x32_bf16 v[116:119], v[206:209], v[172:175], v[116:119]
	s_mov_b32 m0, s24
	s_waitcnt lgkmcnt(0)
	v_mfma_f32_16x16x32_bf16 v[112:115], v[214:217], v[172:175], v[112:115]
	v_lshl_add_u64 v[220:221], s[14:15], 0, v[134:135]
	v_mfma_f32_16x16x32_bf16 v[100:103], v[206:209], v[180:183], v[100:103]
	v_mfma_f32_16x16x32_bf16 v[96:99], v[214:217], v[180:183], v[96:99]
	v_mfma_f32_16x16x32_bf16 v[84:87], v[206:209], v[188:191], v[84:87]
	v_mfma_f32_16x16x32_bf16 v[80:83], v[214:217], v[188:191], v[80:83]
	v_mfma_f32_16x16x32_bf16 v[68:71], v[206:209], v[198:201], v[68:71]
	v_mfma_f32_16x16x32_bf16 v[64:67], v[214:217], v[198:201], v[64:67]
	s_setprio 0
	s_barrier
	ds_read_b128 v[168:171], v150 offset:16384
	ds_read_b128 v[172:175], v150 offset:17408
	ds_read_b128 v[176:179], v150 offset:18432
	ds_read_b128 v[180:183], v150 offset:19456
	ds_read_b128 v[184:187], v150 offset:20480
	ds_read_b128 v[188:191], v150 offset:21504
	ds_read_b128 v[192:195], v150 offset:22528
	ds_read_b128 v[198:201], v150 offset:23552
	global_load_lds_dwordx4 v[220:221], off
	v_lshl_add_u64 v[222:223], s[14:15], 0, v[130:131]
	s_mov_b32 m0, s25
	s_nop 0
	global_load_lds_dwordx4 v[222:223], off
	s_waitcnt vmcnt(10)
	s_barrier
	s_setprio 1
	s_waitcnt lgkmcnt(7)
	v_mfma_f32_16x16x32_bf16 v[60:63], v[152:155], v[168:171], v[60:63]
	v_mfma_f32_16x16x32_bf16 v[56:59], v[160:163], v[168:171], v[56:59]
	s_waitcnt lgkmcnt(5)
	v_mfma_f32_16x16x32_bf16 v[44:47], v[152:155], v[176:179], v[44:47]
	v_mfma_f32_16x16x32_bf16 v[40:43], v[160:163], v[176:179], v[40:43]
	s_waitcnt lgkmcnt(3)
	v_mfma_f32_16x16x32_bf16 v[28:31], v[152:155], v[184:187], v[28:31]
	v_mfma_f32_16x16x32_bf16 v[24:27], v[160:163], v[184:187], v[24:27]
	s_waitcnt lgkmcnt(1)
	v_mfma_f32_16x16x32_bf16 v[12:15], v[152:155], v[192:195], v[12:15]
	v_mfma_f32_16x16x32_bf16 v[8:11], v[160:163], v[192:195], v[8:11]
	v_mfma_f32_16x16x32_bf16 v[60:63], v[156:159], v[172:175], v[60:63]
	v_mfma_f32_16x16x32_bf16 v[56:59], v[164:167], v[172:175], v[56:59]
	v_mfma_f32_16x16x32_bf16 v[44:47], v[156:159], v[180:183], v[44:47]
	v_mfma_f32_16x16x32_bf16 v[40:43], v[164:167], v[180:183], v[40:43]
	v_mfma_f32_16x16x32_bf16 v[28:31], v[156:159], v[188:191], v[28:31]
	v_mfma_f32_16x16x32_bf16 v[24:27], v[164:167], v[188:191], v[24:27]
	s_waitcnt lgkmcnt(0)
	v_mfma_f32_16x16x32_bf16 v[12:15], v[156:159], v[198:201], v[12:15]
	v_mfma_f32_16x16x32_bf16 v[8:11], v[164:167], v[198:201], v[8:11]
	s_setprio 0
	s_barrier
	s_add_u32 s8, s12, 0x160000
	s_addc_u32 s9, s13, 0
	s_add_i32 s45, s36, s22
	s_mov_b32 m0, s45
	s_nop 0
	global_load_lds_dwordx4 v132, s[8:9]
	s_add_i32 m0, s45, 0x2000
	s_nop 0
	global_load_lds_dwordx4 v128, s[8:9]
	s_waitcnt vmcnt(6)
	s_barrier
; #define PG8_STAGE(bufoff, gbase, voff) do { _Pragma("unroll") for (int _i = 0; _i < 2; ++_i) \
;         __builtin_amdgcn_global_load_lds((const unsigned*)((const char*)(gbase) + (voff)[_i]), (LAS unsigned*)(lds + (bufoff) + ldsw + _i * 8192), 16, 0, 0); } while (0)
; #define PG8_LDA(dst, b, h) do { _Pragma("unroll") for (int m = 0; m < 4; ++m) _Pragma("unroll") for (int k = 0; k < 2; ++k) dst[m][k] = *(const LAS bf16x8*)(lds + PG8_SA(b, h) + aoff + m * 2048 + k * 1024); } while (0)
; #define PG8_LDB(dst, b, h) do { _Pragma("unroll") for (int n = 0; n < 2; ++n) _Pragma("unroll") for (int k = 0; k < 2; ++k) dst[n][k] = *(const LAS bf16x8*)(lds + PG8_SB(b, h) + boff + n * 2048 + k * 1024); } while (0)
; #define PG8_MMA(ai, bj, At, Bt) do { __builtin_amdgcn_s_setprio(1); _Pragma("unroll") for (int m = 0; m < 4; ++m) _Pragma("unroll") for (int n = 0; n < 2; ++n) _Pragma("unroll") for (int k = 0; k < 2; ++k) \
;         acc[ai][bj][m][n] = __builtin_amdgcn_mfma_f32_16x16x32_bf16(Bt[n][k], At[m][k], acc[ai][bj][m][n], 0, 0, 0); __builtin_amdgcn_s_setprio(0); } while (0)
; #define PG8_WAIT_V(n) asm volatile("s_waitcnt vmcnt(" #n ")" ::: "memory")
; #define PG8_WAIT_L(n) asm volatile("s_waitcnt lgkmcnt(" #n ")" ::: "memory")
; #define PG8_BAR __builtin_amdgcn_s_barrier()
; #define PG8_SCHED __builtin_amdgcn_sched_barrier(0)
; template <class Map, class Epi>
; DI void gemm_phase(LAS unsigned char* lds, const Map& MP, const Epi& E, const int nM, const int nN, const int K, const int lda, const int ldb) {
;     ...
;             PG8_STAGE(PG8_SB(0, 1), b2 + hstepB, voffB);
;             PG8_WAIT_V(6); PG8_BAR; PG8_MMA(1, 1, At, B1); PG8_BAR;
;             PG8_LDB(B0, 1, 0); PG8_SCHED; PG8_LDA(At, 1, 0); PG8_STAGE(PG8_SA(0, 1), a2 + hstepA, voffA);
;             PG8_WAIT_L(8); PG8_BAR; PG8_WAIT_L(0); PG8_MMA(0, 0, At, B0); PG8_BAR; PG8_SCHED;
;             PG8_LDB(B1, 1, 1); PG8_STAGE(PG8_SB(1, 0), b3, voffB);
;             PG8_BAR; PG8_WAIT_L(0); PG8_MMA(0, 1, At, B1); PG8_BAR;
;             PG8_LDA(At, 1, 1); PG8_STAGE(PG8_SA(1, 0), a3, voffA);
;             PG8_BAR; PG8_WAIT_L(0); PG8_MMA(1, 0, At, B0); PG8_BAR; PG8_SCHED;
	s_setprio 1
	v_mfma_f32_16x16x32_bf16 v[52:55], v[202:205], v[168:171], v[52:55]
	v_mfma_f32_16x16x32_bf16 v[48:51], v[210:213], v[168:171], v[48:51]
	s_add_i32 s45, 0, 0x18000
	v_add_u32_e32 v164, s45, v148
	ds_read_b128 v[152:155], v164
	v_mfma_f32_16x16x32_bf16 v[36:39], v[202:205], v[176:179], v[36:39]
	v_mfma_f32_16x16x32_bf16 v[32:35], v[210:213], v[176:179], v[32:35]
	ds_read_b128 v[156:159], v164 offset:1024
	v_mfma_f32_16x16x32_bf16 v[20:23], v[202:205], v[184:187], v[20:23]
	v_mfma_f32_16x16x32_bf16 v[16:19], v[210:213], v[184:187], v[16:19]
	ds_read_b128 v[160:163], v164 offset:2048
	v_mfma_f32_16x16x32_bf16 v[4:7], v[202:205], v[192:195], v[4:7]
	v_mfma_f32_16x16x32_bf16 v[0:3], v[210:213], v[192:195], v[0:3]
	ds_read_b128 v[164:167], v164 offset:3072
	v_mfma_f32_16x16x32_bf16 v[52:55], v[206:209], v[172:175], v[52:55]
	v_mfma_f32_16x16x32_bf16 v[48:51], v[214:217], v[172:175], v[48:51]
	v_mfma_f32_16x16x32_bf16 v[36:39], v[206:209], v[180:183], v[36:39]
	v_mfma_f32_16x16x32_bf16 v[32:35], v[214:217], v[180:183], v[32:35]
	v_mfma_f32_16x16x32_bf16 v[20:23], v[206:209], v[188:191], v[20:23]
	v_mfma_f32_16x16x32_bf16 v[16:19], v[214:217], v[188:191], v[16:19]
	v_mfma_f32_16x16x32_bf16 v[4:7], v[206:209], v[198:201], v[4:7]
	v_mfma_f32_16x16x32_bf16 v[0:3], v[214:217], v[198:201], v[0:3]
	s_setprio 0
	s_barrier
	s_add_u32 s8, s14, 0x160000
	s_addc_u32 s9, s15, 0
	s_mov_b32 m0, s26
	ds_read_b128 v[168:171], v150 offset:32768
	ds_read_b128 v[172:175], v150 offset:33792
	ds_read_b128 v[176:179], v150 offset:34816
	ds_read_b128 v[180:183], v150 offset:35840
	ds_read_b128 v[184:187], v150 offset:36864
	ds_read_b128 v[188:191], v150 offset:37888
	ds_read_b128 v[192:195], v150 offset:38912
	ds_read_b128 v[198:201], v150 offset:39936
	global_load_lds_dwordx4 v134, s[8:9]
	s_mov_b32 m0, s27
	s_nop 0
	global_load_lds_dwordx4 v130, s[8:9]
	s_waitcnt lgkmcnt(8)
	s_barrier
	s_setprio 1
	s_waitcnt lgkmcnt(7)
	v_mfma_f32_16x16x32_bf16 v[124:127], v[152:155], v[168:171], v[124:127]
	v_mfma_f32_16x16x32_bf16 v[120:123], v[160:163], v[168:171], v[120:123]
	s_waitcnt lgkmcnt(5)
	v_mfma_f32_16x16x32_bf16 v[108:111], v[152:155], v[176:179], v[108:111]
	v_mfma_f32_16x16x32_bf16 v[104:107], v[160:163], v[176:179], v[104:107]
	s_waitcnt lgkmcnt(3)
	v_mfma_f32_16x16x32_bf16 v[92:95], v[152:155], v[184:187], v[92:95]
	v_mfma_f32_16x16x32_bf16 v[88:91], v[160:163], v[184:187], v[88:91]
	s_waitcnt lgkmcnt(1)
	v_mfma_f32_16x16x32_bf16 v[76:79], v[152:155], v[192:195], v[76:79]
	v_mfma_f32_16x16x32_bf16 v[72:75], v[160:163], v[192:195], v[72:75]
	v_mfma_f32_16x16x32_bf16 v[124:127], v[156:159], v[172:175], v[124:127]
	v_mfma_f32_16x16x32_bf16 v[120:123], v[164:167], v[172:175], v[120:123]
	v_mfma_f32_16x16x32_bf16 v[108:111], v[156:159], v[180:183], v[108:111]
	v_mfma_f32_16x16x32_bf16 v[104:107], v[164:167], v[180:183], v[104:107]
	v_mfma_f32_16x16x32_bf16 v[92:95], v[156:159], v[188:191], v[92:95]
	v_mfma_f32_16x16x32_bf16 v[88:91], v[164:167], v[188:191], v[88:91]
	s_waitcnt lgkmcnt(0)
	v_mfma_f32_16x16x32_bf16 v[76:79], v[156:159], v[198:201], v[76:79]
	v_mfma_f32_16x16x32_bf16 v[72:75], v[164:167], v[198:201], v[72:75]
	s_setprio 0
	s_barrier
	s_add_i32 s14, 0, 0x1c000
	s_add_i32 s8, s45, s22
	v_add_u32_e32 v196, s14, v148
	v_lshl_add_u64 v[144:145], v[144:145], 0, s[46:47]
	s_mov_b32 m0, s8
	ds_read_b128 v[202:205], v196
	ds_read_b128 v[206:209], v196 offset:1024
	ds_read_b128 v[210:213], v196 offset:2048
	ds_read_b128 v[214:217], v196 offset:3072
	global_load_lds_dwordx4 v[144:145], off
	v_lshl_add_u64 v[144:145], v[218:219], 0, s[46:47]
	s_add_i32 m0, s8, 0x2000
	s_nop 0
	global_load_lds_dwordx4 v[144:145], off
	s_barrier
	s_setprio 1
	s_waitcnt lgkmcnt(3)
	v_mfma_f32_16x16x32_bf16 v[116:119], v[202:205], v[168:171], v[116:119]
	s_waitcnt lgkmcnt(1)
	v_mfma_f32_16x16x32_bf16 v[112:115], v[210:213], v[168:171], v[112:115]
	v_mfma_f32_16x16x32_bf16 v[100:103], v[202:205], v[176:179], v[100:103]
	v_mfma_f32_16x16x32_bf16 v[96:99], v[210:213], v[176:179], v[96:99]
	v_mfma_f32_16x16x32_bf16 v[84:87], v[202:205], v[184:187], v[84:87]
	v_mfma_f32_16x16x32_bf16 v[80:83], v[210:213], v[184:187], v[80:83]
	v_mfma_f32_16x16x32_bf16 v[68:71], v[202:205], v[192:195], v[68:71]
	v_mfma_f32_16x16x32_bf16 v[64:67], v[210:213], v[192:195], v[64:67]
	v_mfma_f32_16x16x32_bf16 v[116:119], v[206:209], v[172:175], v[116:119]
	s_mov_b32 m0, s30
	s_waitcnt lgkmcnt(0)
	v_mfma_f32_16x16x32_bf16 v[112:115], v[214:217], v[172:175], v[112:115]
	v_lshl_add_u64 v[144:145], v[220:221], 0, s[46:47]
	v_mfma_f32_16x16x32_bf16 v[100:103], v[206:209], v[180:183], v[100:103]
	v_mfma_f32_16x16x32_bf16 v[96:99], v[214:217], v[180:183], v[96:99]
	v_mfma_f32_16x16x32_bf16 v[84:87], v[206:209], v[188:191], v[84:87]
	v_mfma_f32_16x16x32_bf16 v[80:83], v[214:217], v[188:191], v[80:83]
	v_mfma_f32_16x16x32_bf16 v[68:71], v[206:209], v[198:201], v[68:71]
	v_mfma_f32_16x16x32_bf16 v[64:67], v[214:217], v[198:201], v[64:67]
	s_setprio 0
	s_barrier
	ds_read_b128 v[168:171], v150 offset:49152
	ds_read_b128 v[172:175], v150 offset:50176
	ds_read_b128 v[176:179], v150 offset:51200
	ds_read_b128 v[180:183], v150 offset:52224
	ds_read_b128 v[184:187], v150 offset:53248
	ds_read_b128 v[188:191], v150 offset:54272
	ds_read_b128 v[192:195], v150 offset:55296
	ds_read_b128 v[198:201], v150 offset:56320
	global_load_lds_dwordx4 v[144:145], off
	v_lshl_add_u64 v[144:145], v[222:223], 0, s[46:47]
	s_mov_b32 m0, s31
	s_nop 0
	global_load_lds_dwordx4 v[144:145], off
	s_waitcnt vmcnt(10)
	s_barrier
; DI unsigned pack2(float a, float b) { f32x2 v = {a, b}; hwbf16x2 r = __builtin_convertvector(v, hwbf16x2); return __builtin_bit_cast(unsigned, r); }
; DI float bflo(unsigned w) { return __uint_as_float(w << 16); }
; DI float bfhi(unsigned w) { return __uint_as_float(w & 0xffff0000u); }
; #define PG8_WAIT_V(n) asm volatile("s_waitcnt vmcnt(" #n ")" ::: "memory")
;     DI void operator()(const f32x4 (&acc)[2][2][4][2], const Unit& u, int wr, int wc, int fr, int fq) const {
;         const int row0 = u.pm * BM + wr * 64 + fr, col0 = u.pn * BM + wc * 32 + 8 * fq;
;         f32x4 sc[2][2];
; #pragma unroll
;         for (int bj = 0; bj < 2; ++bj)
; #pragma unroll
;             for (int n = 0; n < 2; ++n) sc[bj][n] = scale ? *(const f32x4*)(scale + col0 + bj * HALF + 4 * n) : (f32x4){1.f, 1.f, 1.f, 1.f};
; #pragma unroll
;         for (int ai = 0; ai < 2; ++ai)
; #pragma unroll
;             for (int m = 0; m < 4; ++m) { const size_t ro = (size_t)(row0 + ai * HALF + m * 16) * D + col0;
; #pragma unroll
;                 for (int bj = 0; bj < 2; ++bj) {
;                     f32x4 x0, x1;
;                     if constexpr (IB) { const u32x4 w = *(const u32x4*)((const bf16_t*)Xin + ro + bj * HALF);
;                         x0 = (f32x4){bflo(w[0]), bfhi(w[0]), bflo(w[1]), bfhi(w[1])}; x1 = (f32x4){bflo(w[2]), bfhi(w[2]), bflo(w[3]), bfhi(w[3])}; }
;                     else { x0 = *(const f32x4*)((const float*)Xin + ro + bj * HALF); x1 = *(const f32x4*)((const float*)Xin + ro + bj * HALF + 4); }
;                     x0 += acc[ai][bj][m][0] * sc[bj][0]; x1 += acc[ai][bj][m][1] * sc[bj][1];
;                     if constexpr (OB) { u32x4 o; o[0] = pack2(x0[0], x0[1]); o[1] = pack2(x0[2], x0[3]); o[2] = pack2(x1[0], x1[1]); o[3] = pack2(x1[2], x1[3]);
;                         *(u32x4*)((bf16_t*)Xout + ro + bj * HALF) = o; }
;                     else { *(f32x4*)((float*)Xout + ro + bj * HALF) = x0; *(f32x4*)((float*)Xout + ro + bj * HALF + 4) = x1; } } }
; template <class Map, class Epi>
; DI void gemm_phase(LAS unsigned char* lds, const Map& MP, const Epi& E, const int nM, const int nN, const int K, const int lda, const int ldb) {
;     ...
;             PG8_BAR; PG8_WAIT_L(0); PG8_MMA(1, 0, At, B0); PG8_BAR; PG8_SCHED;
;             PG8_STAGE(PG8_SB(1, 1), b3 + hstepB, voffB);
;             PG8_WAIT_V(6); PG8_BAR; PG8_MMA(1, 1, At, B1); PG8_BAR;
;         }
	s_setprio 1
	s_waitcnt lgkmcnt(7)
	v_mfma_f32_16x16x32_bf16 v[60:63], v[152:155], v[168:171], v[60:63]
	v_mfma_f32_16x16x32_bf16 v[56:59], v[160:163], v[168:171], v[56:59]
	s_waitcnt lgkmcnt(5)
	v_mfma_f32_16x16x32_bf16 v[44:47], v[152:155], v[176:179], v[44:47]
	v_mfma_f32_16x16x32_bf16 v[40:43], v[160:163], v[176:179], v[40:43]
	s_waitcnt lgkmcnt(3)
	v_mfma_f32_16x16x32_bf16 v[28:31], v[152:155], v[184:187], v[28:31]
	v_mfma_f32_16x16x32_bf16 v[24:27], v[160:163], v[184:187], v[24:27]
	s_waitcnt lgkmcnt(1)
	v_mfma_f32_16x16x32_bf16 v[12:15], v[152:155], v[192:195], v[12:15]
	v_mfma_f32_16x16x32_bf16 v[8:11], v[160:163], v[192:195], v[8:11]
	v_mfma_f32_16x16x32_bf16 v[60:63], v[156:159], v[172:175], v[60:63]
	v_mfma_f32_16x16x32_bf16 v[56:59], v[164:167], v[172:175], v[56:59]
	v_mfma_f32_16x16x32_bf16 v[44:47], v[156:159], v[180:183], v[44:47]
	v_mfma_f32_16x16x32_bf16 v[40:43], v[164:167], v[180:183], v[40:43]
	v_mfma_f32_16x16x32_bf16 v[28:31], v[156:159], v[188:191], v[28:31]
	v_mfma_f32_16x16x32_bf16 v[24:27], v[164:167], v[188:191], v[24:27]
	s_waitcnt lgkmcnt(0)
	v_mfma_f32_16x16x32_bf16 v[12:15], v[156:159], v[198:201], v[12:15]
	v_mfma_f32_16x16x32_bf16 v[8:11], v[164:167], v[198:201], v[8:11]
	s_setprio 0
	s_barrier
	s_add_u32 s8, s12, 0x160080
	s_addc_u32 s9, s13, 0
	s_add_i32 s12, s14, s22
	s_mov_b32 m0, s12
	s_nop 0
	global_load_lds_dwordx4 v132, s[8:9]
	s_add_i32 m0, s12, 0x2000
	s_nop 0
	global_load_lds_dwordx4 v128, s[8:9]
	s_waitcnt vmcnt(6)
	s_barrier
	s_setprio 1
	v_mfma_f32_16x16x32_bf16 v[52:55], v[202:205], v[168:171], v[52:55]
	v_mfma_f32_16x16x32_bf16 v[48:51], v[210:213], v[168:171], v[48:51]
	ds_read_b128 v[152:155], v149
	v_mfma_f32_16x16x32_bf16 v[36:39], v[202:205], v[176:179], v[36:39]
	v_mfma_f32_16x16x32_bf16 v[32:35], v[210:213], v[176:179], v[32:35]
	ds_read_b128 v[156:159], v149 offset:1024
	v_mfma_f32_16x16x32_bf16 v[20:23], v[202:205], v[184:187], v[20:23]
	v_mfma_f32_16x16x32_bf16 v[16:19], v[210:213], v[184:187], v[16:19]
	ds_read_b128 v[160:163], v149 offset:2048
	v_mfma_f32_16x16x32_bf16 v[4:7], v[202:205], v[192:195], v[4:7]
	v_mfma_f32_16x16x32_bf16 v[0:3], v[210:213], v[192:195], v[0:3]
	ds_read_b128 v[164:167], v149 offset:3072
	v_mfma_f32_16x16x32_bf16 v[52:55], v[206:209], v[172:175], v[52:55]
	s_add_i32 s3, s3, 2
	v_mfma_f32_16x16x32_bf16 v[48:51], v[214:217], v[172:175], v[48:51]
	s_add_u32 s39, s39, 0x100
	s_addc_u32 s44, s44, 0
	v_mfma_f32_16x16x32_bf16 v[36:39], v[206:209], v[180:183], v[36:39]
	s_cmpk_gt_u32 s3, 0x55
	v_mfma_f32_16x16x32_bf16 v[32:35], v[214:217], v[180:183], v[32:35]
	s_mov_b64 s[8:9], s[10:11]
	v_mfma_f32_16x16x32_bf16 v[20:23], v[206:209], v[188:191], v[20:23]
	v_mfma_f32_16x16x32_bf16 v[16:19], v[214:217], v[188:191], v[16:19]
	v_mfma_f32_16x16x32_bf16 v[4:7], v[206:209], v[198:201], v[4:7]
	v_mfma_f32_16x16x32_bf16 v[0:3], v[214:217], v[198:201], v[0:3]
	s_setprio 0
	s_barrier
	s_cbranch_scc0 .LBB1_2078
	s_waitcnt lgkmcnt(0)
	v_mov_b32_e32 v152, v147
	v_mov_b32_e32 v144, v146
	s_lshl_b32 s2, s2, 8
	s_add_i32 s2, s2, s29
	s_lshl_b32 s3, s38, 8
	v_add_u32_e32 v152, s2, v152
	s_or_b32 s3, s3, s52
	v_ashrrev_i32_e32 v153, 31, v152
	v_lshl_add_u32 v144, v144, 3, s3
	v_lshlrev_b64 v[152:153], 12, v[152:153]
	v_ashrrev_i32_e32 v145, 31, v144
	v_lshl_add_u64 v[152:153], s[4:5], 0, v[152:153]
	v_lshl_add_u64 v[144:145], v[144:145], 1, v[152:153]
	global_load_dwordx4 v[160:163], v[144:145], off
	global_load_dwordx4 v[164:167], v[144:145], off offset:256
	s_mov_b64 s[98:99], 0x10000
	v_lshl_add_u64 v[154:155], v[144:145], 0, s[98:99]
	global_load_dwordx4 v[168:171], v[154:155], off
	global_load_dwordx4 v[172:175], v[154:155], off offset:256
	s_mov_b64 s[98:99], 0x20000
	v_lshl_add_u64 v[154:155], v[144:145], 0, s[98:99]
	global_load_dwordx4 v[176:179], v[154:155], off
	global_load_dwordx4 v[180:183], v[154:155], off offset:256
	s_mov_b64 s[98:99], 0x30000
	v_lshl_add_u64 v[154:155], v[144:145], 0, s[98:99]
	global_load_dwordx4 v[184:187], v[154:155], off
	global_load_dwordx4 v[188:191], v[154:155], off offset:256
	s_mov_b64 s[98:99], 0x80000
	v_lshl_add_u64 v[154:155], v[144:145], 0, s[98:99]
	global_load_dwordx4 v[192:195], v[154:155], off
	global_load_dwordx4 v[198:201], v[154:155], off offset:256
	s_mov_b64 s[98:99], 0x90000
	v_lshl_add_u64 v[154:155], v[144:145], 0, s[98:99]
	global_load_dwordx4 v[202:205], v[154:155], off
	global_load_dwordx4 v[206:209], v[154:155], off offset:256
	s_mov_b64 s[98:99], 0xa0000
	v_lshl_add_u64 v[154:155], v[144:145], 0, s[98:99]
	global_load_dwordx4 v[210:213], v[154:155], off
	global_load_dwordx4 v[214:217], v[154:155], off offset:256
	s_mov_b64 s[98:99], 0xb0000
	v_lshl_add_u64 v[154:155], v[144:145], 0, s[98:99]
	global_load_dwordx4 v[248:251], v[154:155], off
	global_load_dwordx4 v[252:255], v[154:155], off offset:256
	s_waitcnt vmcnt(15)
	s_nop 1
	v_mov_b32_e32 v152, v160
	v_mov_b32_e32 v153, v161
	v_mov_b32_e32 v154, v162
	v_mov_b32_e32 v155, v163
	s_mov_b64 s[2:3], 0x10000
	s_mov_b32 s38, s37
	s_mov_b64 s[10:11], s[6:7]
	s_mov_b64 s[8:9], s[42:43]
	s_waitcnt lgkmcnt(0)
	v_lshlrev_b32_e32 v156, 16, v152
	v_and_b32_e32 v157, 0xffff0000, v152
	v_lshlrev_b32_e32 v152, 16, v153
	v_and_b32_e32 v153, 0xffff0000, v153
	v_lshlrev_b32_e32 v158, 16, v154
	v_and_b32_e32 v159, 0xffff0000, v154
	v_lshlrev_b32_e32 v154, 16, v155
	v_and_b32_e32 v155, 0xffff0000, v155
	v_pk_add_f32 v[126:127], v[126:127], v[152:153]
	v_pk_add_f32 v[124:125], v[124:125], v[156:157]
	v_pk_add_f32 v[152:153], v[122:123], v[154:155]
	v_pk_add_f32 v[122:123], v[120:121], v[158:159]
	v_cvt_pk_bf16_f32 v120, v124, v125
	v_cvt_pk_bf16_f32 v121, v126, v127
	v_cvt_pk_bf16_f32 v122, v122, v123
	v_cvt_pk_bf16_f32 v123, v152, v153
	global_store_dwordx4 v[144:145], v[120:123], off
	s_waitcnt vmcnt(15)
; DI unsigned pack2(float a, float b) { f32x2 v = {a, b}; hwbf16x2 r = __builtin_convertvector(v, hwbf16x2); return __builtin_bit_cast(unsigned, r); }
; DI float bflo(unsigned w) { return __uint_as_float(w << 16); }
; DI float bfhi(unsigned w) { return __uint_as_float(w & 0xffff0000u); }
;     DI void operator()(const f32x4 (&acc)[2][2][4][2], const Unit& u, int wr, int wc, int fr, int fq) const {
;         const int row0 = u.pm * BM + wr * 64 + fr, col0 = u.pn * BM + wc * 32 + 8 * fq;
;         f32x4 sc[2][2];
; #pragma unroll
;         for (int bj = 0; bj < 2; ++bj)
; #pragma unroll
;             for (int n = 0; n < 2; ++n) sc[bj][n] = scale ? *(const f32x4*)(scale + col0 + bj * HALF + 4 * n) : (f32x4){1.f, 1.f, 1.f, 1.f};
; #pragma unroll
;         for (int ai = 0; ai < 2; ++ai)
; #pragma unroll
;             for (int m = 0; m < 4; ++m) { const size_t ro = (size_t)(row0 + ai * HALF + m * 16) * D + col0;
; #pragma unroll
;                 for (int bj = 0; bj < 2; ++bj) {
;                     f32x4 x0, x1;
;                     if constexpr (IB) { const u32x4 w = *(const u32x4*)((const bf16_t*)Xin + ro + bj * HALF);
;                         x0 = (f32x4){bflo(w[0]), bfhi(w[0]), bflo(w[1]), bfhi(w[1])}; x1 = (f32x4){bflo(w[2]), bfhi(w[2]), bflo(w[3]), bfhi(w[3])}; }
;                     else { x0 = *(const f32x4*)((const float*)Xin + ro + bj * HALF); x1 = *(const f32x4*)((const float*)Xin + ro + bj * HALF + 4); }
;                     x0 += acc[ai][bj][m][0] * sc[bj][0]; x1 += acc[ai][bj][m][1] * sc[bj][1];
;                     if constexpr (OB) { u32x4 o; o[0] = pack2(x0[0], x0[1]); o[1] = pack2(x0[2], x0[3]); o[2] = pack2(x1[0], x1[1]); o[3] = pack2(x1[2], x1[3]);
;                         *(u32x4*)((bf16_t*)Xout + ro + bj * HALF) = o; }
;                     else { *(f32x4*)((float*)Xout + ro + bj * HALF) = x0; *(f32x4*)((float*)Xout + ro + bj * HALF + 4) = x1; } } }
	s_nop 1
	v_mov_b32_e32 v120, v164
	v_mov_b32_e32 v121, v165
	v_mov_b32_e32 v122, v166
	v_mov_b32_e32 v123, v167
	s_waitcnt lgkmcnt(0)
	v_lshlrev_b32_e32 v124, 16, v120
	v_and_b32_e32 v125, 0xffff0000, v120
	v_lshlrev_b32_e32 v120, 16, v121
	v_and_b32_e32 v121, 0xffff0000, v121
	v_lshlrev_b32_e32 v126, 16, v122
	v_and_b32_e32 v127, 0xffff0000, v122
	v_lshlrev_b32_e32 v122, 16, v123
	v_and_b32_e32 v123, 0xffff0000, v123
	v_pk_add_f32 v[116:117], v[116:117], v[124:125]
	v_pk_add_f32 v[118:119], v[118:119], v[120:121]
	v_pk_add_f32 v[120:121], v[114:115], v[122:123]
	v_pk_add_f32 v[114:115], v[112:113], v[126:127]
	v_cvt_pk_bf16_f32 v112, v116, v117
	v_lshl_add_u64 v[116:117], v[144:145], 0, s[2:3]
	s_mov_b32 s2, 0x10000
	v_cvt_pk_bf16_f32 v113, v118, v119
	v_add_co_u32_e32 v118, vcc, s2, v144
	v_cvt_pk_bf16_f32 v114, v114, v115
	v_cvt_pk_bf16_f32 v115, v120, v121
	v_addc_co_u32_e32 v119, vcc, 0, v145, vcc
	global_store_dwordx4 v[144:145], v[112:115], off offset:256
	s_waitcnt vmcnt(15)
	s_nop 1
	v_mov_b32_e32 v112, v168
	v_mov_b32_e32 v113, v169
	v_mov_b32_e32 v114, v170
	v_mov_b32_e32 v115, v171
	s_mov_b64 s[2:3], 0x20000
	s_waitcnt lgkmcnt(0)
	v_lshlrev_b32_e32 v120, 16, v112
	v_and_b32_e32 v121, 0xffff0000, v112
	v_lshlrev_b32_e32 v112, 16, v113
	v_and_b32_e32 v113, 0xffff0000, v113
	v_lshlrev_b32_e32 v122, 16, v114
	v_and_b32_e32 v123, 0xffff0000, v114
	v_lshlrev_b32_e32 v114, 16, v115
	v_and_b32_e32 v115, 0xffff0000, v115
	v_pk_add_f32 v[110:111], v[110:111], v[112:113]
	v_pk_add_f32 v[108:109], v[108:109], v[120:121]
	v_pk_add_f32 v[112:113], v[106:107], v[114:115]
	v_pk_add_f32 v[106:107], v[104:105], v[122:123]
	v_cvt_pk_bf16_f32 v104, v108, v109
	v_cvt_pk_bf16_f32 v105, v110, v111
	v_cvt_pk_bf16_f32 v106, v106, v107
	v_cvt_pk_bf16_f32 v107, v112, v113
	global_store_dwordx4 v[118:119], v[104:107], off
	s_waitcnt vmcnt(15)
	s_nop 1
	v_mov_b32_e32 v104, v172
	v_mov_b32_e32 v105, v173
	v_mov_b32_e32 v106, v174
	v_mov_b32_e32 v107, v175
	s_waitcnt lgkmcnt(0)
	v_lshlrev_b32_e32 v108, 16, v104
	v_and_b32_e32 v109, 0xffff0000, v104
	v_lshlrev_b32_e32 v104, 16, v105
	v_and_b32_e32 v105, 0xffff0000, v105
	v_lshlrev_b32_e32 v110, 16, v106
	v_and_b32_e32 v111, 0xffff0000, v106
	v_lshlrev_b32_e32 v106, 16, v107
	v_and_b32_e32 v107, 0xffff0000, v107
	v_pk_add_f32 v[100:101], v[100:101], v[108:109]
	v_pk_add_f32 v[102:103], v[102:103], v[104:105]
	v_pk_add_f32 v[104:105], v[98:99], v[106:107]
	v_pk_add_f32 v[98:99], v[96:97], v[110:111]
	v_cvt_pk_bf16_f32 v96, v100, v101
	v_lshl_add_u64 v[100:101], v[144:145], 0, s[2:3]
	s_mov_b32 s2, 0x20000
	v_cvt_pk_bf16_f32 v97, v102, v103
	v_add_co_u32_e32 v102, vcc, s2, v144
	v_cvt_pk_bf16_f32 v98, v98, v99
	v_cvt_pk_bf16_f32 v99, v104, v105
	v_addc_co_u32_e32 v103, vcc, 0, v145, vcc
	global_store_dwordx4 v[116:117], v[96:99], off offset:256
	s_waitcnt vmcnt(15)
	s_nop 1
	v_mov_b32_e32 v96, v176
	v_mov_b32_e32 v97, v177
	v_mov_b32_e32 v98, v178
	v_mov_b32_e32 v99, v179
	s_mov_b64 s[2:3], 0x30000
	s_waitcnt lgkmcnt(0)
	v_lshlrev_b32_e32 v104, 16, v96
	v_and_b32_e32 v105, 0xffff0000, v96
	v_lshlrev_b32_e32 v96, 16, v97
	v_and_b32_e32 v97, 0xffff0000, v97
	v_lshlrev_b32_e32 v106, 16, v98
	v_and_b32_e32 v107, 0xffff0000, v98
	v_lshlrev_b32_e32 v98, 16, v99
	v_and_b32_e32 v99, 0xffff0000, v99
	v_pk_add_f32 v[94:95], v[94:95], v[96:97]
	v_pk_add_f32 v[92:93], v[92:93], v[104:105]
	v_pk_add_f32 v[96:97], v[90:91], v[98:99]
	v_pk_add_f32 v[90:91], v[88:89], v[106:107]
	v_cvt_pk_bf16_f32 v88, v92, v93
	v_cvt_pk_bf16_f32 v89, v94, v95
	v_cvt_pk_bf16_f32 v90, v90, v91
	v_cvt_pk_bf16_f32 v91, v96, v97
	global_store_dwordx4 v[102:103], v[88:91], off
	s_waitcnt vmcnt(15)
	s_nop 1
	v_mov_b32_e32 v88, v180
	v_mov_b32_e32 v89, v181
	v_mov_b32_e32 v90, v182
	v_mov_b32_e32 v91, v183
	s_waitcnt lgkmcnt(0)
	v_lshlrev_b32_e32 v92, 16, v88
	v_and_b32_e32 v93, 0xffff0000, v88
	v_lshlrev_b32_e32 v88, 16, v89
	v_and_b32_e32 v89, 0xffff0000, v89
	v_lshlrev_b32_e32 v94, 16, v90
	v_and_b32_e32 v95, 0xffff0000, v90
	v_lshlrev_b32_e32 v90, 16, v91
	v_and_b32_e32 v91, 0xffff0000, v91
	v_pk_add_f32 v[86:87], v[86:87], v[88:89]
	v_pk_add_f32 v[84:85], v[84:85], v[92:93]
	v_pk_add_f32 v[88:89], v[82:83], v[90:91]
	v_pk_add_f32 v[82:83], v[80:81], v[94:95]
	v_cvt_pk_bf16_f32 v80, v84, v85
	v_cvt_pk_bf16_f32 v81, v86, v87
	v_cvt_pk_bf16_f32 v82, v82, v83
	v_cvt_pk_bf16_f32 v83, v88, v89
	global_store_dwordx4 v[100:101], v[80:83], off offset:256
	s_nop 1
	v_lshl_add_u64 v[80:81], v[144:145], 0, s[2:3]
	s_mov_b32 s2, 0x30000
	v_add_co_u32_e32 v86, vcc, s2, v144
	s_mov_b64 s[2:3], 0x80000
	s_nop 0
	v_addc_co_u32_e32 v87, vcc, 0, v145, vcc
	s_waitcnt vmcnt(15)
	s_nop 1
	v_mov_b32_e32 v82, v184
	v_mov_b32_e32 v83, v185
	v_mov_b32_e32 v84, v186
	v_mov_b32_e32 v85, v187
	s_waitcnt lgkmcnt(0)
	v_lshlrev_b32_e32 v88, 16, v82
	v_and_b32_e32 v89, 0xffff0000, v82
	v_lshlrev_b32_e32 v82, 16, v83
	v_and_b32_e32 v83, 0xffff0000, v83
	v_lshlrev_b32_e32 v90, 16, v84
	v_and_b32_e32 v91, 0xffff0000, v84
	v_lshlrev_b32_e32 v84, 16, v85
	v_and_b32_e32 v85, 0xffff0000, v85
	v_pk_add_f32 v[78:79], v[78:79], v[82:83]
	v_pk_add_f32 v[76:77], v[76:77], v[88:89]
	v_pk_add_f32 v[82:83], v[74:75], v[84:85]
	v_pk_add_f32 v[74:75], v[72:73], v[90:91]
	v_cvt_pk_bf16_f32 v72, v76, v77
	v_cvt_pk_bf16_f32 v73, v78, v79
	v_cvt_pk_bf16_f32 v74, v74, v75
	v_cvt_pk_bf16_f32 v75, v82, v83
	global_store_dwordx4 v[86:87], v[72:75], off
	s_waitcnt vmcnt(15)
	s_nop 1
	v_mov_b32_e32 v72, v188
	v_mov_b32_e32 v73, v189
	v_mov_b32_e32 v74, v190
	v_mov_b32_e32 v75, v191
	s_waitcnt lgkmcnt(0)
; DI unsigned pack2(float a, float b) { f32x2 v = {a, b}; hwbf16x2 r = __builtin_convertvector(v, hwbf16x2); return __builtin_bit_cast(unsigned, r); }
; DI float bflo(unsigned w) { return __uint_as_float(w << 16); }
; DI float bfhi(unsigned w) { return __uint_as_float(w & 0xffff0000u); }
;     DI void operator()(const f32x4 (&acc)[2][2][4][2], const Unit& u, int wr, int wc, int fr, int fq) const {
;         const int row0 = u.pm * BM + wr * 64 + fr, col0 = u.pn * BM + wc * 32 + 8 * fq;
;         f32x4 sc[2][2];
; #pragma unroll
;         for (int bj = 0; bj < 2; ++bj)
; #pragma unroll
;             for (int n = 0; n < 2; ++n) sc[bj][n] = scale ? *(const f32x4*)(scale + col0 + bj * HALF + 4 * n) : (f32x4){1.f, 1.f, 1.f, 1.f};
; #pragma unroll
;         for (int ai = 0; ai < 2; ++ai)
; #pragma unroll
;             for (int m = 0; m < 4; ++m) { const size_t ro = (size_t)(row0 + ai * HALF + m * 16) * D + col0;
; #pragma unroll
;                 for (int bj = 0; bj < 2; ++bj) {
;                     f32x4 x0, x1;
;                     if constexpr (IB) { const u32x4 w = *(const u32x4*)((const bf16_t*)Xin + ro + bj * HALF);
;                         x0 = (f32x4){bflo(w[0]), bfhi(w[0]), bflo(w[1]), bfhi(w[1])}; x1 = (f32x4){bflo(w[2]), bfhi(w[2]), bflo(w[3]), bfhi(w[3])}; }
;                     else { x0 = *(const f32x4*)((const float*)Xin + ro + bj * HALF); x1 = *(const f32x4*)((const float*)Xin + ro + bj * HALF + 4); }
;                     x0 += acc[ai][bj][m][0] * sc[bj][0]; x1 += acc[ai][bj][m][1] * sc[bj][1];
;                     if constexpr (OB) { u32x4 o; o[0] = pack2(x0[0], x0[1]); o[1] = pack2(x0[2], x0[3]); o[2] = pack2(x1[0], x1[1]); o[3] = pack2(x1[2], x1[3]);
;                         *(u32x4*)((bf16_t*)Xout + ro + bj * HALF) = o; }
;                     else { *(f32x4*)((float*)Xout + ro + bj * HALF) = x0; *(f32x4*)((float*)Xout + ro + bj * HALF + 4) = x1; } } }
	v_lshlrev_b32_e32 v76, 16, v72
	v_and_b32_e32 v77, 0xffff0000, v72
	v_lshlrev_b32_e32 v72, 16, v73
	v_and_b32_e32 v73, 0xffff0000, v73
	v_lshlrev_b32_e32 v78, 16, v74
	v_and_b32_e32 v79, 0xffff0000, v74
	v_lshlrev_b32_e32 v74, 16, v75
	v_and_b32_e32 v75, 0xffff0000, v75
	v_pk_add_f32 v[70:71], v[70:71], v[72:73]
	v_pk_add_f32 v[68:69], v[68:69], v[76:77]
	v_pk_add_f32 v[72:73], v[66:67], v[74:75]
	v_pk_add_f32 v[66:67], v[64:65], v[78:79]
	v_cvt_pk_bf16_f32 v64, v68, v69
	v_cvt_pk_bf16_f32 v65, v70, v71
	v_cvt_pk_bf16_f32 v66, v66, v67
	v_cvt_pk_bf16_f32 v67, v72, v73
	global_store_dwordx4 v[80:81], v[64:67], off offset:256
	s_nop 1
	v_lshl_add_u64 v[64:65], v[144:145], 0, s[2:3]
	s_mov_b32 s2, 0x80000
	v_add_co_u32_e32 v70, vcc, s2, v144
	s_mov_b64 s[2:3], 0x90000
	s_nop 0
	v_addc_co_u32_e32 v71, vcc, 0, v145, vcc
	s_waitcnt vmcnt(15)
	s_nop 1
	v_mov_b32_e32 v66, v192
	v_mov_b32_e32 v67, v193
	v_mov_b32_e32 v68, v194
	v_mov_b32_e32 v69, v195
	s_waitcnt lgkmcnt(0)
	v_lshlrev_b32_e32 v72, 16, v66
	v_and_b32_e32 v73, 0xffff0000, v66
	v_lshlrev_b32_e32 v66, 16, v67
	v_and_b32_e32 v67, 0xffff0000, v67
	v_lshlrev_b32_e32 v74, 16, v68
	v_and_b32_e32 v75, 0xffff0000, v68
	v_lshlrev_b32_e32 v68, 16, v69
	v_and_b32_e32 v69, 0xffff0000, v69
	v_pk_add_f32 v[62:63], v[62:63], v[66:67]
	v_pk_add_f32 v[60:61], v[60:61], v[72:73]
	v_pk_add_f32 v[66:67], v[58:59], v[68:69]
	v_pk_add_f32 v[58:59], v[56:57], v[74:75]
	v_cvt_pk_bf16_f32 v56, v60, v61
	v_cvt_pk_bf16_f32 v57, v62, v63
	v_cvt_pk_bf16_f32 v58, v58, v59
	v_cvt_pk_bf16_f32 v59, v66, v67
	global_store_dwordx4 v[70:71], v[56:59], off
	s_waitcnt vmcnt(15)
	s_nop 1
	v_mov_b32_e32 v56, v198
	v_mov_b32_e32 v57, v199
	v_mov_b32_e32 v58, v200
	v_mov_b32_e32 v59, v201
	s_waitcnt lgkmcnt(0)
	v_lshlrev_b32_e32 v60, 16, v56
	v_and_b32_e32 v61, 0xffff0000, v56
	v_lshlrev_b32_e32 v56, 16, v57
	v_and_b32_e32 v57, 0xffff0000, v57
	v_lshlrev_b32_e32 v62, 16, v58
	v_and_b32_e32 v63, 0xffff0000, v58
	v_lshlrev_b32_e32 v58, 16, v59
	v_and_b32_e32 v59, 0xffff0000, v59
	v_pk_add_f32 v[54:55], v[54:55], v[56:57]
	v_pk_add_f32 v[52:53], v[52:53], v[60:61]
	v_pk_add_f32 v[56:57], v[50:51], v[58:59]
	v_pk_add_f32 v[50:51], v[48:49], v[62:63]
	v_cvt_pk_bf16_f32 v48, v52, v53
	v_cvt_pk_bf16_f32 v49, v54, v55
	v_cvt_pk_bf16_f32 v50, v50, v51
	v_cvt_pk_bf16_f32 v51, v56, v57
	global_store_dwordx4 v[64:65], v[48:51], off offset:256
	s_nop 1
	v_lshl_add_u64 v[48:49], v[144:145], 0, s[2:3]
	s_mov_b32 s2, 0x90000
	v_add_co_u32_e32 v54, vcc, s2, v144
	s_mov_b64 s[2:3], 0xa0000
	s_nop 0
	v_addc_co_u32_e32 v55, vcc, 0, v145, vcc
	s_waitcnt vmcnt(15)
	s_nop 1
	v_mov_b32_e32 v50, v202
	v_mov_b32_e32 v51, v203
	v_mov_b32_e32 v52, v204
	v_mov_b32_e32 v53, v205
	s_waitcnt lgkmcnt(0)
	v_lshlrev_b32_e32 v56, 16, v50
	v_and_b32_e32 v57, 0xffff0000, v50
	v_lshlrev_b32_e32 v50, 16, v51
	v_and_b32_e32 v51, 0xffff0000, v51
	v_lshlrev_b32_e32 v58, 16, v52
	v_and_b32_e32 v59, 0xffff0000, v52
	v_lshlrev_b32_e32 v52, 16, v53
	v_and_b32_e32 v53, 0xffff0000, v53
	v_pk_add_f32 v[46:47], v[46:47], v[50:51]
	v_pk_add_f32 v[44:45], v[44:45], v[56:57]
	v_pk_add_f32 v[50:51], v[42:43], v[52:53]
	v_pk_add_f32 v[42:43], v[40:41], v[58:59]
	v_cvt_pk_bf16_f32 v40, v44, v45
	v_cvt_pk_bf16_f32 v41, v46, v47
	v_cvt_pk_bf16_f32 v42, v42, v43
	v_cvt_pk_bf16_f32 v43, v50, v51
	global_store_dwordx4 v[54:55], v[40:43], off
	s_waitcnt vmcnt(15)
	s_nop 1
	v_mov_b32_e32 v40, v206
	v_mov_b32_e32 v41, v207
	v_mov_b32_e32 v42, v208
	v_mov_b32_e32 v43, v209
	s_waitcnt lgkmcnt(0)
; #define PG8_BAR __builtin_amdgcn_s_barrier()
;     DI void operator()(const f32x4 (&acc)[2][2][4][2], const Unit& u, int wr, int wc, int fr, int fq) const {
;         const int row0 = u.pm * BM + wr * 64 + fr, col0 = u.pn * BM + wc * 32 + 8 * fq;
;         f32x4 sc[2][2];
; #pragma unroll
;         for (int bj = 0; bj < 2; ++bj)
; #pragma unroll
;             for (int n = 0; n < 2; ++n) sc[bj][n] = scale ? *(const f32x4*)(scale + col0 + bj * HALF + 4 * n) : (f32x4){1.f, 1.f, 1.f, 1.f};
; #pragma unroll
;         for (int ai = 0; ai < 2; ++ai)
; #pragma unroll
;             for (int m = 0; m < 4; ++m) { const size_t ro = (size_t)(row0 + ai * HALF + m * 16) * D + col0;
; #pragma unroll
;                 for (int bj = 0; bj < 2; ++bj) {
;                     f32x4 x0, x1;
;                     if constexpr (IB) { const u32x4 w = *(const u32x4*)((const bf16_t*)Xin + ro + bj * HALF);
;                         x0 = (f32x4){bflo(w[0]), bfhi(w[0]), bflo(w[1]), bfhi(w[1])}; x1 = (f32x4){bflo(w[2]), bfhi(w[2]), bflo(w[3]), bfhi(w[3])}; }
;                     else { x0 = *(const f32x4*)((const float*)Xin + ro + bj * HALF); x1 = *(const f32x4*)((const float*)Xin + ro + bj * HALF + 4); }
;                     x0 += acc[ai][bj][m][0] * sc[bj][0]; x1 += acc[ai][bj][m][1] * sc[bj][1];
;                     if constexpr (OB) { u32x4 o; o[0] = pack2(x0[0], x0[1]); o[1] = pack2(x0[2], x0[3]); o[2] = pack2(x1[0], x1[1]); o[3] = pack2(x1[2], x1[3]);
;                         *(u32x4*)((bf16_t*)Xout + ro + bj * HALF) = o; }
;                     else { *(f32x4*)((float*)Xout + ro + bj * HALF) = x0; *(f32x4*)((float*)Xout + ro + bj * HALF + 4) = x1; } } }
; template <class Map, class Epi>
; DI void gemm_phase(LAS unsigned char* lds, const Map& MP, const Epi& E, const int nM, const int nN, const int K, const int lda, const int ldb) {
;     ...
;         { int frr = fr, fqq = fq; asm volatile("" : "+v"(frr), "+v"(fqq)); E(acc, cur, wr, wc, frr, fqq); }
;         if (!has_next) break;
; #pragma unroll
;         for (int a = 0; a < 2; ++a)
; #pragma unroll
;             for (int b = 0; b < 2; ++b)
; #pragma unroll
;                 for (int m = 0; m < 4; ++m)
; #pragma unroll
;                     for (int n = 0; n < 2; ++n) acc[a][b][m][n] = (f32x4){0.f, 0.f, 0.f, 0.f};
;         cur = nxt; cA = nA; cB = nB; ++ui;
;     }
;     PG8_WAIT_V(0);
;     if (wr == 0) PG8_BAR;
;     PG8_BAR;
	v_lshlrev_b32_e32 v44, 16, v40
	v_and_b32_e32 v45, 0xffff0000, v40
	v_lshlrev_b32_e32 v40, 16, v41
	v_and_b32_e32 v41, 0xffff0000, v41
	v_lshlrev_b32_e32 v46, 16, v42
	v_and_b32_e32 v47, 0xffff0000, v42
	v_lshlrev_b32_e32 v42, 16, v43
	v_and_b32_e32 v43, 0xffff0000, v43
	v_pk_add_f32 v[38:39], v[38:39], v[40:41]
	v_pk_add_f32 v[36:37], v[36:37], v[44:45]
	v_pk_add_f32 v[40:41], v[34:35], v[42:43]
	v_pk_add_f32 v[34:35], v[32:33], v[46:47]
	v_cvt_pk_bf16_f32 v32, v36, v37
	v_cvt_pk_bf16_f32 v33, v38, v39
	v_cvt_pk_bf16_f32 v34, v34, v35
	v_cvt_pk_bf16_f32 v35, v40, v41
	global_store_dwordx4 v[48:49], v[32:35], off offset:256
	s_nop 1
	v_lshl_add_u64 v[32:33], v[144:145], 0, s[2:3]
	s_mov_b32 s2, 0xa0000
	v_add_co_u32_e32 v38, vcc, s2, v144
	s_mov_b64 s[2:3], 0xb0000
	s_nop 0
	v_addc_co_u32_e32 v39, vcc, 0, v145, vcc
	s_waitcnt vmcnt(15)
	s_nop 1
	v_mov_b32_e32 v34, v210
	v_mov_b32_e32 v35, v211
	v_mov_b32_e32 v36, v212
	v_mov_b32_e32 v37, v213
	s_waitcnt lgkmcnt(0)
	v_lshlrev_b32_e32 v40, 16, v34
	v_and_b32_e32 v41, 0xffff0000, v34
	v_lshlrev_b32_e32 v34, 16, v35
	v_and_b32_e32 v35, 0xffff0000, v35
	v_lshlrev_b32_e32 v42, 16, v36
	v_and_b32_e32 v43, 0xffff0000, v36
	v_lshlrev_b32_e32 v36, 16, v37
	v_and_b32_e32 v37, 0xffff0000, v37
	v_pk_add_f32 v[30:31], v[30:31], v[34:35]
	v_pk_add_f32 v[28:29], v[28:29], v[40:41]
	v_pk_add_f32 v[34:35], v[26:27], v[36:37]
	v_pk_add_f32 v[26:27], v[24:25], v[42:43]
	v_cvt_pk_bf16_f32 v24, v28, v29
	v_cvt_pk_bf16_f32 v25, v30, v31
	v_cvt_pk_bf16_f32 v26, v26, v27
	v_cvt_pk_bf16_f32 v27, v34, v35
	global_store_dwordx4 v[38:39], v[24:27], off
	s_waitcnt vmcnt(15)
	s_nop 1
	v_mov_b32_e32 v24, v214
	v_mov_b32_e32 v25, v215
	v_mov_b32_e32 v26, v216
	v_mov_b32_e32 v27, v217
	s_waitcnt lgkmcnt(0)
	v_lshlrev_b32_e32 v28, 16, v24
	v_and_b32_e32 v29, 0xffff0000, v24
	v_lshlrev_b32_e32 v24, 16, v25
	v_and_b32_e32 v25, 0xffff0000, v25
	v_lshlrev_b32_e32 v30, 16, v26
	v_and_b32_e32 v31, 0xffff0000, v26
	v_lshlrev_b32_e32 v26, 16, v27
	v_and_b32_e32 v27, 0xffff0000, v27
	v_pk_add_f32 v[22:23], v[22:23], v[24:25]
	v_pk_add_f32 v[20:21], v[20:21], v[28:29]
	v_pk_add_f32 v[24:25], v[18:19], v[26:27]
	v_pk_add_f32 v[18:19], v[16:17], v[30:31]
	v_cvt_pk_bf16_f32 v16, v20, v21
	v_cvt_pk_bf16_f32 v17, v22, v23
	v_cvt_pk_bf16_f32 v18, v18, v19
	v_cvt_pk_bf16_f32 v19, v24, v25
	global_store_dwordx4 v[32:33], v[16:19], off offset:256
	s_nop 1
	v_lshl_add_u64 v[16:17], v[144:145], 0, s[2:3]
	s_mov_b32 s2, 0xb0000
	v_add_co_u32_e32 v22, vcc, s2, v144
	s_mov_b32 s2, s53
	s_nop 0
	v_addc_co_u32_e32 v23, vcc, 0, v145, vcc
	s_waitcnt vmcnt(15)
	s_nop 1
	v_mov_b32_e32 v18, v248
	v_mov_b32_e32 v19, v249
	v_mov_b32_e32 v20, v250
	v_mov_b32_e32 v21, v251
	s_and_b64 vcc, exec, s[40:41]
	s_waitcnt lgkmcnt(0)
	v_lshlrev_b32_e32 v24, 16, v18
	v_and_b32_e32 v25, 0xffff0000, v18
	v_lshlrev_b32_e32 v18, 16, v19
	v_and_b32_e32 v19, 0xffff0000, v19
	v_lshlrev_b32_e32 v26, 16, v20
	v_and_b32_e32 v27, 0xffff0000, v20
	v_lshlrev_b32_e32 v20, 16, v21
	v_and_b32_e32 v21, 0xffff0000, v21
	v_pk_add_f32 v[14:15], v[14:15], v[18:19]
	v_pk_add_f32 v[12:13], v[12:13], v[24:25]
	v_pk_add_f32 v[18:19], v[10:11], v[20:21]
	v_pk_add_f32 v[10:11], v[8:9], v[26:27]
	v_cvt_pk_bf16_f32 v8, v12, v13
	v_cvt_pk_bf16_f32 v9, v14, v15
	v_cvt_pk_bf16_f32 v10, v10, v11
	v_cvt_pk_bf16_f32 v11, v18, v19
	global_store_dwordx4 v[22:23], v[8:11], off
	s_waitcnt vmcnt(15)
	s_nop 1
	v_mov_b32_e32 v8, v252
	v_mov_b32_e32 v9, v253
	v_mov_b32_e32 v10, v254
	v_mov_b32_e32 v11, v255
	s_waitcnt lgkmcnt(0)
	v_lshlrev_b32_e32 v12, 16, v8
	v_and_b32_e32 v13, 0xffff0000, v8
	v_lshlrev_b32_e32 v8, 16, v9
	v_and_b32_e32 v9, 0xffff0000, v9
	v_lshlrev_b32_e32 v14, 16, v10
	v_and_b32_e32 v15, 0xffff0000, v10
	v_lshlrev_b32_e32 v10, 16, v11
	v_and_b32_e32 v11, 0xffff0000, v11
	v_pk_add_f32 v[6:7], v[6:7], v[8:9]
	v_pk_add_f32 v[4:5], v[4:5], v[12:13]
	v_pk_add_f32 v[8:9], v[2:3], v[10:11]
	v_pk_add_f32 v[2:3], v[0:1], v[14:15]
	v_cvt_pk_bf16_f32 v0, v4, v5
	v_cvt_pk_bf16_f32 v1, v6, v7
	v_cvt_pk_bf16_f32 v2, v2, v3
	v_cvt_pk_bf16_f32 v3, v8, v9
	global_store_dwordx4 v[16:17], v[0:3], off offset:256
	s_cbranch_vccz .LBB1_2071
	s_waitcnt vmcnt(0)
	s_cmpk_gt_u32 s17, 0xff
	s_cbranch_scc1 .LBB1_2082
	s_barrier

; #define PG8_STAGE(bufoff, gbase, voff) do { _Pragma("unroll") for (int _i = 0; _i < 2; ++_i) \
;         __builtin_amdgcn_global_load_lds((const unsigned*)((const char*)(gbase) + (voff)[_i]), (LAS unsigned*)(lds + (bufoff) + ldsw + _i * 8192), 16, 0, 0); } while (0)
; #define PG8_LDA(dst, b, h) do { _Pragma("unroll") for (int m = 0; m < 4; ++m) _Pragma("unroll") for (int k = 0; k < 2; ++k) dst[m][k] = *(const LAS bf16x8*)(lds + PG8_SA(b, h) + aoff + m * 2048 + k * 1024); } while (0)
; #define PG8_LDB(dst, b, h) do { _Pragma("unroll") for (int n = 0; n < 2; ++n) _Pragma("unroll") for (int k = 0; k < 2; ++k) dst[n][k] = *(const LAS bf16x8*)(lds + PG8_SB(b, h) + boff + n * 2048 + k * 1024); } while (0)
; #define PG8_MMA(ai, bj, At, Bt) do { __builtin_amdgcn_s_setprio(1); _Pragma("unroll") for (int m = 0; m < 4; ++m) _Pragma("unroll") for (int n = 0; n < 2; ++n) _Pragma("unroll") for (int k = 0; k < 2; ++k) \
;         acc[ai][bj][m][n] = __builtin_amdgcn_mfma_f32_16x16x32_bf16(Bt[n][k], At[m][k], acc[ai][bj][m][n], 0, 0, 0); __builtin_amdgcn_s_setprio(0); } while (0)
; #define PG8_WAIT_V(n) asm volatile("s_waitcnt vmcnt(" #n ")" ::: "memory")
; #define PG8_WAIT_L(n) asm volatile("s_waitcnt lgkmcnt(" #n ")" ::: "memory")
; template <class Map, class Epi>
; DI void gemm_phase(LAS unsigned char* lds, const Map& MP, const Epi& E, const int nM, const int nN, const int K, const int lda, const int ldb) {
;     ...
;         for (int t = 0; t < nt; t += 2) {
;             const bool last = (t == nt - 2);
;             const char* a1 = cA + (size_t)(t + 1) * kstep;
;             const char* a2 = last ? nA : cA + (size_t)(t + 2) * kstep; const char* b2 = last ? nB : cB + (size_t)(t + 2) * kstep;
;             const char* a3 = a2 + kstep; const char* b3 = b2 + kstep;
;             PG8_LDB(B0, 0, 0); PG8_SCHED; PG8_LDA(At, 0, 0); PG8_STAGE(PG8_SA(1, 1), a1 + hstepA, voffA);
;             PG8_WAIT_L(8); PG8_BAR; PG8_WAIT_L(0); PG8_MMA(0, 0, At, B0); PG8_BAR; PG8_SCHED;
;             PG8_LDB(B1, 0, 1); PG8_STAGE(PG8_SB(0, 0), b2, voffB);
;             PG8_BAR; PG8_WAIT_L(0); PG8_MMA(0, 1, At, B1); PG8_BAR;
;             PG8_LDA(At, 0, 1); PG8_STAGE(PG8_SA(0, 0), a2, voffA);
;             PG8_BAR; PG8_WAIT_L(0); PG8_MMA(1, 0, At, B0); PG8_BAR; PG8_SCHED;
;             PG8_STAGE(PG8_SB(0, 1), b2 + hstepB, voffB);
;             PG8_WAIT_V(6); PG8_BAR; PG8_MMA(1, 1, At, B1); PG8_BAR;
.LBB1_2339:
	s_add_u32 s12, s10, 0xfff80080
	s_addc_u32 s13, s11, -1
	s_cmp_eq_u32 s3, 4
	s_cselect_b32 s15, s38, s13
	s_cselect_b32 s14, s39, s12
	s_cselect_b32 s13, s48, s56
	s_cselect_b32 s12, s49, s53
	s_add_i32 m0, s9, 0xc000
	ds_read_b128 v[168:171], v166
	ds_read_b128 v[172:175], v166 offset:1024
	ds_read_b128 v[176:179], v166 offset:2048
	ds_read_b128 v[180:183], v166 offset:3072
	ds_read_b128 v[184:187], v166 offset:4096
	ds_read_b128 v[188:191], v166 offset:5120
	ds_read_b128 v[192:195], v166 offset:6144
	ds_read_b128 v[198:201], v166 offset:7168
	global_load_lds_dwordx4 v154, s[10:11]
	s_add_i32 m0, s9, 0xe000
	s_nop 0
	global_load_lds_dwordx4 v152, s[10:11]
	s_waitcnt lgkmcnt(8)
	s_barrier
	s_setprio 1
	s_waitcnt lgkmcnt(7)
	v_mfma_f32_16x16x32_bf16 v[140:143], v[40:43], v[168:171], v[140:143]
	v_mfma_f32_16x16x32_bf16 v[136:139], v[56:59], v[168:171], v[136:139]
	s_waitcnt lgkmcnt(5)
	v_mfma_f32_16x16x32_bf16 v[124:127], v[40:43], v[176:179], v[124:127]
	v_mfma_f32_16x16x32_bf16 v[120:123], v[56:59], v[176:179], v[120:123]
	s_waitcnt lgkmcnt(3)
	v_mfma_f32_16x16x32_bf16 v[108:111], v[40:43], v[184:187], v[108:111]
	v_mfma_f32_16x16x32_bf16 v[104:107], v[56:59], v[184:187], v[104:107]
	s_waitcnt lgkmcnt(1)
	v_mfma_f32_16x16x32_bf16 v[92:95], v[40:43], v[192:195], v[92:95]
	v_mfma_f32_16x16x32_bf16 v[88:91], v[56:59], v[192:195], v[88:91]
	v_mfma_f32_16x16x32_bf16 v[140:143], v[44:47], v[172:175], v[140:143]
	v_mfma_f32_16x16x32_bf16 v[136:139], v[60:63], v[172:175], v[136:139]
	v_mfma_f32_16x16x32_bf16 v[124:127], v[44:47], v[180:183], v[124:127]
	v_mfma_f32_16x16x32_bf16 v[120:123], v[60:63], v[180:183], v[120:123]
	v_mfma_f32_16x16x32_bf16 v[108:111], v[44:47], v[188:191], v[108:111]
	v_mfma_f32_16x16x32_bf16 v[104:107], v[60:63], v[188:191], v[104:107]
	s_waitcnt lgkmcnt(0)
	v_mfma_f32_16x16x32_bf16 v[92:95], v[44:47], v[198:201], v[92:95]
	v_mfma_f32_16x16x32_bf16 v[88:91], v[60:63], v[198:201], v[88:91]
	s_setprio 0
	s_barrier
	s_add_i32 s57, s35, s22
	v_lshl_add_u64 v[160:161], s[12:13], 0, v[148:149]
	s_mov_b32 m0, s57
	ds_read_b128 v[202:205], v167
	ds_read_b128 v[206:209], v167 offset:1024
	ds_read_b128 v[210:213], v167 offset:2048
	ds_read_b128 v[214:217], v167 offset:3072
	global_load_lds_dwordx4 v[160:161], off
	v_lshl_add_u64 v[218:219], s[12:13], 0, v[144:145]
	s_add_i32 m0, s57, 0x2000
	s_nop 0
	global_load_lds_dwordx4 v[218:219], off
	s_barrier
	s_setprio 1
	s_waitcnt lgkmcnt(3)
	v_mfma_f32_16x16x32_bf16 v[132:135], v[202:205], v[168:171], v[132:135]
	s_waitcnt lgkmcnt(1)
	v_mfma_f32_16x16x32_bf16 v[128:131], v[210:213], v[168:171], v[128:131]
	v_mfma_f32_16x16x32_bf16 v[116:119], v[202:205], v[176:179], v[116:119]
	v_mfma_f32_16x16x32_bf16 v[112:115], v[210:213], v[176:179], v[112:115]
	v_mfma_f32_16x16x32_bf16 v[100:103], v[202:205], v[184:187], v[100:103]
	v_mfma_f32_16x16x32_bf16 v[96:99], v[210:213], v[184:187], v[96:99]
	v_mfma_f32_16x16x32_bf16 v[84:87], v[202:205], v[192:195], v[84:87]
	v_mfma_f32_16x16x32_bf16 v[80:83], v[210:213], v[192:195], v[80:83]
	v_mfma_f32_16x16x32_bf16 v[132:135], v[206:209], v[172:175], v[132:135]
	s_mov_b32 m0, s9
	s_waitcnt lgkmcnt(0)
	v_mfma_f32_16x16x32_bf16 v[128:131], v[214:217], v[172:175], v[128:131]
	v_lshl_add_u64 v[220:221], s[14:15], 0, v[150:151]
	v_mfma_f32_16x16x32_bf16 v[116:119], v[206:209], v[180:183], v[116:119]
	v_mfma_f32_16x16x32_bf16 v[112:115], v[214:217], v[180:183], v[112:115]
	v_mfma_f32_16x16x32_bf16 v[100:103], v[206:209], v[188:191], v[100:103]
	v_mfma_f32_16x16x32_bf16 v[96:99], v[214:217], v[188:191], v[96:99]
	v_mfma_f32_16x16x32_bf16 v[84:87], v[206:209], v[198:201], v[84:87]
	v_mfma_f32_16x16x32_bf16 v[80:83], v[214:217], v[198:201], v[80:83]
	s_setprio 0
	s_barrier
	ds_read_b128 v[168:171], v166 offset:16384
	ds_read_b128 v[172:175], v166 offset:17408
	ds_read_b128 v[176:179], v166 offset:18432
	ds_read_b128 v[180:183], v166 offset:19456
	ds_read_b128 v[184:187], v166 offset:20480
	ds_read_b128 v[188:191], v166 offset:21504
	ds_read_b128 v[192:195], v166 offset:22528
	ds_read_b128 v[198:201], v166 offset:23552
	global_load_lds_dwordx4 v[220:221], off
	v_lshl_add_u64 v[222:223], s[14:15], 0, v[146:147]
	s_mov_b32 m0, s24
	s_nop 0
	global_load_lds_dwordx4 v[222:223], off
	s_waitcnt vmcnt(10)
	s_barrier
	s_setprio 1
	s_waitcnt lgkmcnt(7)
	v_mfma_f32_16x16x32_bf16 v[76:79], v[40:43], v[168:171], v[76:79]
	v_mfma_f32_16x16x32_bf16 v[72:75], v[56:59], v[168:171], v[72:75]
	s_waitcnt lgkmcnt(5)
	v_mfma_f32_16x16x32_bf16 v[52:55], v[40:43], v[176:179], v[52:55]
	v_mfma_f32_16x16x32_bf16 v[48:51], v[56:59], v[176:179], v[48:51]
	s_waitcnt lgkmcnt(3)
	v_mfma_f32_16x16x32_bf16 v[28:31], v[40:43], v[184:187], v[28:31]
	v_mfma_f32_16x16x32_bf16 v[24:27], v[56:59], v[184:187], v[24:27]
	s_waitcnt lgkmcnt(1)
	v_mfma_f32_16x16x32_bf16 v[12:15], v[40:43], v[192:195], v[12:15]
	v_mfma_f32_16x16x32_bf16 v[8:11], v[56:59], v[192:195], v[8:11]
	v_mfma_f32_16x16x32_bf16 v[76:79], v[44:47], v[172:175], v[76:79]
	v_mfma_f32_16x16x32_bf16 v[72:75], v[60:63], v[172:175], v[72:75]
	v_mfma_f32_16x16x32_bf16 v[52:55], v[44:47], v[180:183], v[52:55]
	v_mfma_f32_16x16x32_bf16 v[48:51], v[60:63], v[180:183], v[48:51]
	v_mfma_f32_16x16x32_bf16 v[28:31], v[44:47], v[188:191], v[28:31]
	v_mfma_f32_16x16x32_bf16 v[24:27], v[60:63], v[188:191], v[24:27]
	s_waitcnt lgkmcnt(0)
	v_mfma_f32_16x16x32_bf16 v[12:15], v[44:47], v[198:201], v[12:15]
	v_mfma_f32_16x16x32_bf16 v[8:11], v[60:63], v[198:201], v[8:11]
	s_setprio 0
	s_barrier
	s_add_u32 s58, s12, 0x20000
	s_addc_u32 s59, s13, 0
	s_add_i32 s57, s36, s22
	s_mov_b32 m0, s57
	s_nop 0
	global_load_lds_dwordx4 v148, s[58:59]
	s_add_i32 m0, s57, 0x2000
	s_nop 0
	global_load_lds_dwordx4 v144, s[58:59]
	s_waitcnt vmcnt(6)
	s_barrier
; #define PG8_STAGE(bufoff, gbase, voff) do { _Pragma("unroll") for (int _i = 0; _i < 2; ++_i) \
;         __builtin_amdgcn_global_load_lds((const unsigned*)((const char*)(gbase) + (voff)[_i]), (LAS unsigned*)(lds + (bufoff) + ldsw + _i * 8192), 16, 0, 0); } while (0)
; #define PG8_LDA(dst, b, h) do { _Pragma("unroll") for (int m = 0; m < 4; ++m) _Pragma("unroll") for (int k = 0; k < 2; ++k) dst[m][k] = *(const LAS bf16x8*)(lds + PG8_SA(b, h) + aoff + m * 2048 + k * 1024); } while (0)
; #define PG8_LDB(dst, b, h) do { _Pragma("unroll") for (int n = 0; n < 2; ++n) _Pragma("unroll") for (int k = 0; k < 2; ++k) dst[n][k] = *(const LAS bf16x8*)(lds + PG8_SB(b, h) + boff + n * 2048 + k * 1024); } while (0)
; #define PG8_MMA(ai, bj, At, Bt) do { __builtin_amdgcn_s_setprio(1); _Pragma("unroll") for (int m = 0; m < 4; ++m) _Pragma("unroll") for (int n = 0; n < 2; ++n) _Pragma("unroll") for (int k = 0; k < 2; ++k) \
;         acc[ai][bj][m][n] = __builtin_amdgcn_mfma_f32_16x16x32_bf16(Bt[n][k], At[m][k], acc[ai][bj][m][n], 0, 0, 0); __builtin_amdgcn_s_setprio(0); } while (0)
; #define PG8_WAIT_V(n) asm volatile("s_waitcnt vmcnt(" #n ")" ::: "memory")
; #define PG8_WAIT_L(n) asm volatile("s_waitcnt lgkmcnt(" #n ")" ::: "memory")
; #define PG8_BAR __builtin_amdgcn_s_barrier()
; #define PG8_SCHED __builtin_amdgcn_sched_barrier(0)
; template <class Map, class Epi>
; DI void gemm_phase(LAS unsigned char* lds, const Map& MP, const Epi& E, const int nM, const int nN, const int K, const int lda, const int ldb) {
;     ...
;             PG8_BAR; PG8_WAIT_L(0); PG8_MMA(1, 0, At, B0); PG8_BAR; PG8_SCHED;
;             PG8_STAGE(PG8_SB(0, 1), b2 + hstepB, voffB);
;             PG8_WAIT_V(6); PG8_BAR; PG8_MMA(1, 1, At, B1); PG8_BAR;
;             PG8_LDB(B0, 1, 0); PG8_SCHED; PG8_LDA(At, 1, 0); PG8_STAGE(PG8_SA(0, 1), a2 + hstepA, voffA);
;             PG8_WAIT_L(8); PG8_BAR; PG8_WAIT_L(0); PG8_MMA(0, 0, At, B0); PG8_BAR; PG8_SCHED;
;             PG8_LDB(B1, 1, 1); PG8_STAGE(PG8_SB(1, 0), b3, voffB);
;             PG8_BAR; PG8_WAIT_L(0); PG8_MMA(0, 1, At, B1); PG8_BAR;
;             PG8_LDA(At, 1, 1); PG8_STAGE(PG8_SA(1, 0), a3, voffA);
;             PG8_BAR; PG8_WAIT_L(0); PG8_MMA(1, 0, At, B0); PG8_BAR; PG8_SCHED;
;             PG8_STAGE(PG8_SB(1, 1), b3 + hstepB, voffB);
	s_setprio 1
	v_mfma_f32_16x16x32_bf16 v[36:39], v[202:205], v[176:179], v[36:39]
	v_mfma_f32_16x16x32_bf16 v[32:35], v[210:213], v[176:179], v[32:35]
	v_mfma_f32_16x16x32_bf16 v[20:23], v[202:205], v[184:187], v[20:23]
	v_mfma_f32_16x16x32_bf16 v[16:19], v[210:213], v[184:187], v[16:19]
	v_mfma_f32_16x16x32_bf16 v[4:7], v[202:205], v[192:195], v[4:7]
	v_mfma_f32_16x16x32_bf16 v[0:3], v[210:213], v[192:195], v[0:3]
	v_mfma_f32_16x16x32_bf16 v[40:43], v[202:205], v[168:171], v[68:71]
	s_add_i32 s57, 0, 0x18000
	v_add_u32_e32 v68, s57, v164
	ds_read_b128 v[56:59], v68
	ds_read_b128 v[60:63], v68 offset:1024
	v_mfma_f32_16x16x32_bf16 v[44:47], v[210:213], v[168:171], v[64:67]
	ds_read_b128 v[64:67], v68 offset:2048
	ds_read_b128 v[68:71], v68 offset:3072
	v_mfma_f32_16x16x32_bf16 v[36:39], v[206:209], v[180:183], v[36:39]
	v_mfma_f32_16x16x32_bf16 v[32:35], v[214:217], v[180:183], v[32:35]
	v_mfma_f32_16x16x32_bf16 v[20:23], v[206:209], v[188:191], v[20:23]
	v_mfma_f32_16x16x32_bf16 v[16:19], v[214:217], v[188:191], v[16:19]
	v_mfma_f32_16x16x32_bf16 v[4:7], v[206:209], v[198:201], v[4:7]
	v_mfma_f32_16x16x32_bf16 v[0:3], v[214:217], v[198:201], v[0:3]
	v_mfma_f32_16x16x32_bf16 v[40:43], v[206:209], v[172:175], v[40:43]
	v_mfma_f32_16x16x32_bf16 v[44:47], v[214:217], v[172:175], v[44:47]
	s_setprio 0
	s_barrier
	s_add_u32 s14, s14, 0x80000
	s_addc_u32 s15, s15, 0
	s_mov_b32 m0, s25
	ds_read_b128 v[168:171], v166 offset:32768
	ds_read_b128 v[172:175], v166 offset:33792
	ds_read_b128 v[176:179], v166 offset:34816
	ds_read_b128 v[180:183], v166 offset:35840
	ds_read_b128 v[184:187], v166 offset:36864
	ds_read_b128 v[188:191], v166 offset:37888
	ds_read_b128 v[192:195], v166 offset:38912
	ds_read_b128 v[198:201], v166 offset:39936
	global_load_lds_dwordx4 v150, s[14:15]
	s_mov_b32 m0, s26
	s_nop 0
	global_load_lds_dwordx4 v146, s[14:15]
	s_waitcnt lgkmcnt(8)
	s_barrier
	s_setprio 1
	s_waitcnt lgkmcnt(7)
	v_mfma_f32_16x16x32_bf16 v[140:143], v[56:59], v[168:171], v[140:143]
	v_mfma_f32_16x16x32_bf16 v[136:139], v[64:67], v[168:171], v[136:139]
	s_waitcnt lgkmcnt(5)
	v_mfma_f32_16x16x32_bf16 v[124:127], v[56:59], v[176:179], v[124:127]
	v_mfma_f32_16x16x32_bf16 v[120:123], v[64:67], v[176:179], v[120:123]
	s_waitcnt lgkmcnt(3)
	v_mfma_f32_16x16x32_bf16 v[108:111], v[56:59], v[184:187], v[108:111]
	v_mfma_f32_16x16x32_bf16 v[104:107], v[64:67], v[184:187], v[104:107]
	s_waitcnt lgkmcnt(1)
	v_mfma_f32_16x16x32_bf16 v[92:95], v[56:59], v[192:195], v[92:95]
	v_mfma_f32_16x16x32_bf16 v[88:91], v[64:67], v[192:195], v[88:91]
	v_mfma_f32_16x16x32_bf16 v[140:143], v[60:63], v[172:175], v[140:143]
	v_mfma_f32_16x16x32_bf16 v[136:139], v[68:71], v[172:175], v[136:139]
	v_mfma_f32_16x16x32_bf16 v[124:127], v[60:63], v[180:183], v[124:127]
	v_mfma_f32_16x16x32_bf16 v[120:123], v[68:71], v[180:183], v[120:123]
	v_mfma_f32_16x16x32_bf16 v[108:111], v[60:63], v[188:191], v[108:111]
	v_mfma_f32_16x16x32_bf16 v[104:107], v[68:71], v[188:191], v[104:107]
	s_waitcnt lgkmcnt(0)
	v_mfma_f32_16x16x32_bf16 v[92:95], v[60:63], v[198:201], v[92:95]
	v_mfma_f32_16x16x32_bf16 v[88:91], v[68:71], v[198:201], v[88:91]
	s_setprio 0
	s_barrier
	s_add_i32 s14, 0, 0x1c000
	s_add_i32 s15, s57, s22
	v_add_u32_e32 v196, s14, v164
	v_lshl_add_u64 v[160:161], v[160:161], 0, s[46:47]
	s_mov_b32 m0, s15
	ds_read_b128 v[202:205], v196
	ds_read_b128 v[206:209], v196 offset:1024
	ds_read_b128 v[210:213], v196 offset:2048
	ds_read_b128 v[214:217], v196 offset:3072
	global_load_lds_dwordx4 v[160:161], off
	v_lshl_add_u64 v[160:161], v[218:219], 0, s[46:47]
	s_add_i32 m0, s15, 0x2000
	s_nop 0
	global_load_lds_dwordx4 v[160:161], off
	s_barrier
	s_setprio 1
	s_waitcnt lgkmcnt(3)
	v_mfma_f32_16x16x32_bf16 v[132:135], v[202:205], v[168:171], v[132:135]
	s_waitcnt lgkmcnt(1)
	v_mfma_f32_16x16x32_bf16 v[128:131], v[210:213], v[168:171], v[128:131]
	v_mfma_f32_16x16x32_bf16 v[116:119], v[202:205], v[176:179], v[116:119]
	v_mfma_f32_16x16x32_bf16 v[112:115], v[210:213], v[176:179], v[112:115]
	v_mfma_f32_16x16x32_bf16 v[100:103], v[202:205], v[184:187], v[100:103]
	v_mfma_f32_16x16x32_bf16 v[96:99], v[210:213], v[184:187], v[96:99]
	v_mfma_f32_16x16x32_bf16 v[84:87], v[202:205], v[192:195], v[84:87]
	v_mfma_f32_16x16x32_bf16 v[80:83], v[210:213], v[192:195], v[80:83]
	v_mfma_f32_16x16x32_bf16 v[132:135], v[206:209], v[172:175], v[132:135]
	s_mov_b32 m0, s30
	s_waitcnt lgkmcnt(0)
	v_mfma_f32_16x16x32_bf16 v[128:131], v[214:217], v[172:175], v[128:131]
	v_lshl_add_u64 v[160:161], v[220:221], 0, s[46:47]
	v_mfma_f32_16x16x32_bf16 v[116:119], v[206:209], v[180:183], v[116:119]
	v_mfma_f32_16x16x32_bf16 v[112:115], v[214:217], v[180:183], v[112:115]
	v_mfma_f32_16x16x32_bf16 v[100:103], v[206:209], v[188:191], v[100:103]
	v_mfma_f32_16x16x32_bf16 v[96:99], v[214:217], v[188:191], v[96:99]
	v_mfma_f32_16x16x32_bf16 v[84:87], v[206:209], v[198:201], v[84:87]
	v_mfma_f32_16x16x32_bf16 v[80:83], v[214:217], v[198:201], v[80:83]
	s_setprio 0
	s_barrier
	ds_read_b128 v[168:171], v166 offset:49152
	ds_read_b128 v[172:175], v166 offset:50176
	ds_read_b128 v[176:179], v166 offset:51200
	ds_read_b128 v[180:183], v166 offset:52224
	ds_read_b128 v[184:187], v166 offset:53248
	ds_read_b128 v[188:191], v166 offset:54272
	ds_read_b128 v[192:195], v166 offset:55296
	ds_read_b128 v[198:201], v166 offset:56320
	global_load_lds_dwordx4 v[160:161], off
	v_lshl_add_u64 v[160:161], v[222:223], 0, s[46:47]
	s_mov_b32 m0, s31
	s_nop 0
	global_load_lds_dwordx4 v[160:161], off
	s_waitcnt vmcnt(10)
	s_barrier
; DI unsigned pack2(float a, float b) { f32x2 v = {a, b}; hwbf16x2 r = __builtin_convertvector(v, hwbf16x2); return __builtin_bit_cast(unsigned, r); }
; DI float bflo(unsigned w) { return __uint_as_float(w << 16); }
; DI float bfhi(unsigned w) { return __uint_as_float(w & 0xffff0000u); }
; #define PG8_WAIT_V(n) asm volatile("s_waitcnt vmcnt(" #n ")" ::: "memory")
; #define PG8_WAIT_L(n) asm volatile("s_waitcnt lgkmcnt(" #n ")" ::: "memory")
;     DI void operator()(const f32x4 (&acc)[2][2][4][2], const Unit& u, int wr, int wc, int fr, int fq) const {
;         const int row0 = u.pm * BM + wr * 64 + fr, col0 = u.pn * BM + wc * 32 + 8 * fq;
;         f32x4 sc[2][2];
; #pragma unroll
;         for (int bj = 0; bj < 2; ++bj)
; #pragma unroll
;             for (int n = 0; n < 2; ++n) sc[bj][n] = scale ? *(const f32x4*)(scale + col0 + bj * HALF + 4 * n) : (f32x4){1.f, 1.f, 1.f, 1.f};
; #pragma unroll
;         for (int ai = 0; ai < 2; ++ai)
; #pragma unroll
;             for (int m = 0; m < 4; ++m) { const size_t ro = (size_t)(row0 + ai * HALF + m * 16) * D + col0;
; #pragma unroll
;                 for (int bj = 0; bj < 2; ++bj) {
;                     f32x4 x0, x1;
;                     if constexpr (IB) { const u32x4 w = *(const u32x4*)((const bf16_t*)Xin + ro + bj * HALF);
;                         x0 = (f32x4){bflo(w[0]), bfhi(w[0]), bflo(w[1]), bfhi(w[1])}; x1 = (f32x4){bflo(w[2]), bfhi(w[2]), bflo(w[3]), bfhi(w[3])}; }
;                     else { x0 = *(const f32x4*)((const float*)Xin + ro + bj * HALF); x1 = *(const f32x4*)((const float*)Xin + ro + bj * HALF + 4); }
;                     x0 += acc[ai][bj][m][0] * sc[bj][0]; x1 += acc[ai][bj][m][1] * sc[bj][1];
;                     if constexpr (OB) { u32x4 o; o[0] = pack2(x0[0], x0[1]); o[1] = pack2(x0[2], x0[3]); o[2] = pack2(x1[0], x1[1]); o[3] = pack2(x1[2], x1[3]);
; template <class Map, class Epi>
; DI void gemm_phase(LAS unsigned char* lds, const Map& MP, const Epi& E, const int nM, const int nN, const int K, const int lda, const int ldb) {
;     ...
;             PG8_BAR; PG8_WAIT_L(0); PG8_MMA(0, 1, At, B1); PG8_BAR;
;             PG8_LDA(At, 1, 1); PG8_STAGE(PG8_SA(1, 0), a3, voffA);
;             PG8_BAR; PG8_WAIT_L(0); PG8_MMA(1, 0, At, B0); PG8_BAR; PG8_SCHED;
;             PG8_STAGE(PG8_SB(1, 1), b3 + hstepB, voffB);
;             PG8_WAIT_V(6); PG8_BAR; PG8_MMA(1, 1, At, B1); PG8_BAR;
;         }
	s_setprio 1
	s_waitcnt lgkmcnt(7)
	v_mfma_f32_16x16x32_bf16 v[76:79], v[56:59], v[168:171], v[76:79]
	v_mfma_f32_16x16x32_bf16 v[72:75], v[64:67], v[168:171], v[72:75]
	s_waitcnt lgkmcnt(5)
	v_mfma_f32_16x16x32_bf16 v[52:55], v[56:59], v[176:179], v[52:55]
	v_mfma_f32_16x16x32_bf16 v[48:51], v[64:67], v[176:179], v[48:51]
	s_waitcnt lgkmcnt(3)
	v_mfma_f32_16x16x32_bf16 v[28:31], v[56:59], v[184:187], v[28:31]
	v_mfma_f32_16x16x32_bf16 v[24:27], v[64:67], v[184:187], v[24:27]
	s_waitcnt lgkmcnt(1)
	v_mfma_f32_16x16x32_bf16 v[12:15], v[56:59], v[192:195], v[12:15]
	v_mfma_f32_16x16x32_bf16 v[8:11], v[64:67], v[192:195], v[8:11]
	v_mfma_f32_16x16x32_bf16 v[76:79], v[60:63], v[172:175], v[76:79]
	v_mfma_f32_16x16x32_bf16 v[72:75], v[68:71], v[172:175], v[72:75]
	v_mfma_f32_16x16x32_bf16 v[52:55], v[60:63], v[180:183], v[52:55]
	v_mfma_f32_16x16x32_bf16 v[48:51], v[68:71], v[180:183], v[48:51]
	v_mfma_f32_16x16x32_bf16 v[28:31], v[60:63], v[188:191], v[28:31]
	v_mfma_f32_16x16x32_bf16 v[24:27], v[68:71], v[188:191], v[24:27]
	s_waitcnt lgkmcnt(0)
	v_mfma_f32_16x16x32_bf16 v[12:15], v[60:63], v[198:201], v[12:15]
	v_mfma_f32_16x16x32_bf16 v[8:11], v[68:71], v[198:201], v[8:11]
	s_setprio 0
	s_barrier
	s_add_u32 s12, s12, 0x20080
	s_addc_u32 s13, s13, 0
	s_add_i32 s14, s14, s22
	s_mov_b32 m0, s14
	s_nop 0
	global_load_lds_dwordx4 v148, s[12:13]
	s_add_i32 m0, s14, 0x2000
	s_nop 0
	global_load_lds_dwordx4 v144, s[12:13]
	s_waitcnt vmcnt(6)
	s_barrier
	s_setprio 1
	v_mfma_f32_16x16x32_bf16 v[40:43], v[202:205], v[168:171], v[40:43]
	v_mfma_f32_16x16x32_bf16 v[68:71], v[206:209], v[172:175], v[40:43]
	v_mfma_f32_16x16x32_bf16 v[40:43], v[210:213], v[168:171], v[44:47]
	v_mfma_f32_16x16x32_bf16 v[36:39], v[202:205], v[176:179], v[36:39]
	v_mfma_f32_16x16x32_bf16 v[32:35], v[210:213], v[176:179], v[32:35]
	v_mfma_f32_16x16x32_bf16 v[20:23], v[202:205], v[184:187], v[20:23]
	v_mfma_f32_16x16x32_bf16 v[16:19], v[210:213], v[184:187], v[16:19]
	v_mfma_f32_16x16x32_bf16 v[4:7], v[202:205], v[192:195], v[4:7]
	v_mfma_f32_16x16x32_bf16 v[0:3], v[210:213], v[192:195], v[0:3]
	s_add_i32 s3, s3, 2
	v_mfma_f32_16x16x32_bf16 v[64:67], v[214:217], v[172:175], v[40:43]
	s_add_u32 s53, s53, 0x100
	s_addc_u32 s56, s56, 0
	ds_read_b128 v[40:43], v165
	ds_read_b128 v[44:47], v165 offset:1024
	ds_read_b128 v[56:59], v165 offset:2048
	ds_read_b128 v[60:63], v165 offset:3072
	v_mfma_f32_16x16x32_bf16 v[36:39], v[206:209], v[180:183], v[36:39]
	s_add_u32 s10, s10, 0x100
	s_addc_u32 s11, s11, 0
	v_mfma_f32_16x16x32_bf16 v[32:35], v[214:217], v[180:183], v[32:35]
	s_cmp_gt_u32 s3, 5
	v_mfma_f32_16x16x32_bf16 v[20:23], v[206:209], v[188:191], v[20:23]
	v_mfma_f32_16x16x32_bf16 v[16:19], v[214:217], v[188:191], v[16:19]
	v_mfma_f32_16x16x32_bf16 v[4:7], v[206:209], v[198:201], v[4:7]
	v_mfma_f32_16x16x32_bf16 v[0:3], v[214:217], v[198:201], v[0:3]
	s_setprio 0
	s_barrier
	s_cbranch_scc0 .LBB1_2339
	s_waitcnt lgkmcnt(0)
	s_lshl_b32 s2, s2, 8
	v_mov_b32_e32 v40, v163
	v_mov_b32_e32 v168, v162
	s_or_b32 s2, s2, s29
	s_and_b64 vcc, exec, s[40:41]
	v_lshl_add_u32 v160, v40, 3, s2
	s_lshl_b32 s2, s8, 8
	s_add_i32 s2, s2, s28
	v_add_u32_e32 v168, s2, v168
	v_ashrrev_i32_e32 v169, 31, v168
	v_ashrrev_i32_e32 v161, 31, v160
	v_lshlrev_b64 v[168:169], 11, v[168:169]
	v_lshl_add_u64 v[44:45], v[160:161], 2, s[44:45]
	v_lshl_add_u64 v[160:161], v[168:169], 0, v[160:161]
	v_lshlrev_b64 v[160:161], 1, v[160:161]
	v_lshl_add_u64 v[172:173], s[4:5], 0, v[160:161]
	global_load_dwordx4 v[56:59], v[44:45], off offset:16
	global_load_dwordx4 v[60:63], v[44:45], off
	global_load_dwordx4 v[40:43], v[44:45], off offset:528
	s_nop 0
	global_load_dwordx4 v[44:47], v[44:45], off offset:512
	s_mov_b64 s[2:3], 0x10000
	global_load_dwordx4 v[178:181], v[172:173], off
	global_load_dwordx4 v[182:185], v[172:173], off offset:256
	s_mov_b64 s[98:99], 0x10000
	v_lshl_add_u64 v[170:171], v[172:173], 0, s[98:99]
	global_load_dwordx4 v[186:189], v[170:171], off
	global_load_dwordx4 v[190:193], v[170:171], off offset:256
	s_mov_b64 s[98:99], 0x20000
	v_lshl_add_u64 v[170:171], v[172:173], 0, s[98:99]
	global_load_dwordx4 v[198:201], v[170:171], off
	global_load_dwordx4 v[202:205], v[170:171], off offset:256
	s_mov_b64 s[98:99], 0x30000
	v_lshl_add_u64 v[170:171], v[172:173], 0, s[98:99]
	global_load_dwordx4 v[206:209], v[170:171], off
	global_load_dwordx4 v[210:213], v[170:171], off offset:256
	s_mov_b64 s[98:99], 0x80000
	v_lshl_add_u64 v[170:171], v[172:173], 0, s[98:99]
	global_load_dwordx4 v[214:217], v[170:171], off
	global_load_dwordx4 v[248:251], v[170:171], off offset:256
	s_mov_b64 s[98:99], 0x90000
	v_lshl_add_u64 v[170:171], v[172:173], 0, s[98:99]
	global_load_dwordx4 v[252:255], v[170:171], off
	s_waitcnt vmcnt(10)
	s_nop 1
	v_mov_b32_e32 v168, v178
	v_mov_b32_e32 v169, v179
	v_mov_b32_e32 v170, v180
	v_mov_b32_e32 v171, v181
	s_mov_b32 s8, s52
	s_mov_b64 s[10:11], s[54:55]
	s_mov_b64 s[12:13], s[6:7]
	s_waitcnt lgkmcnt(0)
	v_lshlrev_b32_e32 v174, 16, v168
	v_and_b32_e32 v175, 0xffff0000, v168
	v_lshlrev_b32_e32 v168, 16, v169
	v_and_b32_e32 v169, 0xffff0000, v169
	v_lshlrev_b32_e32 v176, 16, v170
	v_and_b32_e32 v177, 0xffff0000, v170
	v_lshlrev_b32_e32 v170, 16, v171
	v_and_b32_e32 v171, 0xffff0000, v171
	v_pk_fma_f32 v[142:143], v[142:143], v[62:63], v[168:169]
	v_pk_fma_f32 v[140:141], v[140:141], v[60:61], v[174:175]
	v_pk_fma_f32 v[168:169], v[138:139], v[58:59], v[170:171]
	v_pk_fma_f32 v[138:139], v[136:137], v[56:57], v[176:177]
	v_cvt_pk_bf16_f32 v136, v140, v141
	v_cvt_pk_bf16_f32 v137, v142, v143
	v_cvt_pk_bf16_f32 v138, v138, v139
	v_cvt_pk_bf16_f32 v139, v168, v169
	v_lshl_add_u64 v[140:141], s[42:43], 0, v[160:161]
	global_store_dwordx4 v[140:141], v[136:139], off
	s_waitcnt vmcnt(10)
; DI unsigned pack2(float a, float b) { f32x2 v = {a, b}; hwbf16x2 r = __builtin_convertvector(v, hwbf16x2); return __builtin_bit_cast(unsigned, r); }
; DI float bflo(unsigned w) { return __uint_as_float(w << 16); }
; DI float bfhi(unsigned w) { return __uint_as_float(w & 0xffff0000u); }
;     DI void operator()(const f32x4 (&acc)[2][2][4][2], const Unit& u, int wr, int wc, int fr, int fq) const {
;     ...
;         for (int ai = 0; ai < 2; ++ai)
; #pragma unroll
;             for (int m = 0; m < 4; ++m) { const size_t ro = (size_t)(row0 + ai * HALF + m * 16) * D + col0;
; #pragma unroll
;                 for (int bj = 0; bj < 2; ++bj) {
;                     f32x4 x0, x1;
;                     if constexpr (IB) { const u32x4 w = *(const u32x4*)((const bf16_t*)Xin + ro + bj * HALF);
;                         x0 = (f32x4){bflo(w[0]), bfhi(w[0]), bflo(w[1]), bfhi(w[1])}; x1 = (f32x4){bflo(w[2]), bfhi(w[2]), bflo(w[3]), bfhi(w[3])}; }
;                     else { x0 = *(const f32x4*)((const float*)Xin + ro + bj * HALF); x1 = *(const f32x4*)((const float*)Xin + ro + bj * HALF + 4); }
;                     x0 += acc[ai][bj][m][0] * sc[bj][0]; x1 += acc[ai][bj][m][1] * sc[bj][1];
;                     if constexpr (OB) { u32x4 o; o[0] = pack2(x0[0], x0[1]); o[1] = pack2(x0[2], x0[3]); o[2] = pack2(x1[0], x1[1]); o[3] = pack2(x1[2], x1[3]);
;                         *(u32x4*)((bf16_t*)Xout + ro + bj * HALF) = o; }
;                     else { *(f32x4*)((float*)Xout + ro + bj * HALF) = x0; *(f32x4*)((float*)Xout + ro + bj * HALF + 4) = x1; } } }
	s_nop 1
	v_mov_b32_e32 v136, v182
	v_mov_b32_e32 v137, v183
	v_mov_b32_e32 v138, v184
	v_mov_b32_e32 v139, v185
	s_waitcnt lgkmcnt(0)
	v_lshlrev_b32_e32 v142, 16, v136
	v_and_b32_e32 v143, 0xffff0000, v136
	v_lshlrev_b32_e32 v136, 16, v137
	v_and_b32_e32 v137, 0xffff0000, v137
	v_lshlrev_b32_e32 v168, 16, v138
	v_and_b32_e32 v169, 0xffff0000, v138
	v_lshlrev_b32_e32 v138, 16, v139
	v_and_b32_e32 v139, 0xffff0000, v139
	v_pk_fma_f32 v[134:135], v[134:135], v[46:47], v[136:137]
	v_pk_fma_f32 v[132:133], v[132:133], v[44:45], v[142:143]
	v_pk_fma_f32 v[136:137], v[130:131], v[42:43], v[138:139]
	v_pk_fma_f32 v[130:131], v[128:129], v[40:41], v[168:169]
	v_cvt_pk_bf16_f32 v128, v132, v133
	v_cvt_pk_bf16_f32 v129, v134, v135
	v_cvt_pk_bf16_f32 v130, v130, v131
	v_cvt_pk_bf16_f32 v131, v136, v137
	v_lshl_add_u64 v[132:133], v[160:161], 0, s[2:3]
	global_store_dwordx4 v[140:141], v[128:131], off offset:256
	v_lshl_add_u64 v[134:135], s[4:5], 0, v[132:133]
	s_waitcnt vmcnt(10)
	s_nop 1
	v_mov_b32_e32 v128, v186
	v_mov_b32_e32 v129, v187
	v_mov_b32_e32 v130, v188
	v_mov_b32_e32 v131, v189
	s_mov_b64 s[2:3], 0x20000
	s_waitcnt lgkmcnt(0)
	v_lshlrev_b32_e32 v136, 16, v128
	v_and_b32_e32 v137, 0xffff0000, v128
	v_lshlrev_b32_e32 v128, 16, v129
	v_and_b32_e32 v129, 0xffff0000, v129
	v_lshlrev_b32_e32 v138, 16, v130
	v_and_b32_e32 v139, 0xffff0000, v130
	v_lshlrev_b32_e32 v130, 16, v131
	v_and_b32_e32 v131, 0xffff0000, v131
	v_pk_fma_f32 v[126:127], v[126:127], v[62:63], v[128:129]
	v_pk_fma_f32 v[124:125], v[124:125], v[60:61], v[136:137]
	v_pk_fma_f32 v[128:129], v[122:123], v[58:59], v[130:131]
	v_pk_fma_f32 v[122:123], v[120:121], v[56:57], v[138:139]
	v_cvt_pk_bf16_f32 v120, v124, v125
	v_cvt_pk_bf16_f32 v121, v126, v127
	v_cvt_pk_bf16_f32 v122, v122, v123
	v_cvt_pk_bf16_f32 v123, v128, v129
	v_lshl_add_u64 v[124:125], s[42:43], 0, v[132:133]
	global_store_dwordx4 v[124:125], v[120:123], off
	s_waitcnt vmcnt(10)
	s_nop 1
	v_mov_b32_e32 v120, v190
	v_mov_b32_e32 v121, v191
	v_mov_b32_e32 v122, v192
	v_mov_b32_e32 v123, v193
	s_waitcnt lgkmcnt(0)
	v_lshlrev_b32_e32 v126, 16, v120
	v_and_b32_e32 v127, 0xffff0000, v120
	v_lshlrev_b32_e32 v120, 16, v121
	v_and_b32_e32 v121, 0xffff0000, v121
	v_lshlrev_b32_e32 v128, 16, v122
	v_and_b32_e32 v129, 0xffff0000, v122
	v_lshlrev_b32_e32 v122, 16, v123
	v_and_b32_e32 v123, 0xffff0000, v123
	v_pk_fma_f32 v[118:119], v[118:119], v[46:47], v[120:121]
	v_pk_fma_f32 v[116:117], v[116:117], v[44:45], v[126:127]
	v_pk_fma_f32 v[120:121], v[114:115], v[42:43], v[122:123]
	v_pk_fma_f32 v[114:115], v[112:113], v[40:41], v[128:129]
	v_cvt_pk_bf16_f32 v112, v116, v117
	v_cvt_pk_bf16_f32 v113, v118, v119
	v_cvt_pk_bf16_f32 v114, v114, v115
	v_cvt_pk_bf16_f32 v115, v120, v121
	v_lshl_add_u64 v[116:117], v[160:161], 0, s[2:3]
	global_store_dwordx4 v[124:125], v[112:115], off offset:256
	v_lshl_add_u64 v[118:119], s[4:5], 0, v[116:117]
	s_waitcnt vmcnt(10)
	s_nop 1
	v_mov_b32_e32 v112, v198
	v_mov_b32_e32 v113, v199
	v_mov_b32_e32 v114, v200
	v_mov_b32_e32 v115, v201
	s_mov_b64 s[2:3], 0x30000
	s_waitcnt lgkmcnt(0)
	v_lshlrev_b32_e32 v120, 16, v112
	v_and_b32_e32 v121, 0xffff0000, v112
	v_lshlrev_b32_e32 v112, 16, v113
	v_and_b32_e32 v113, 0xffff0000, v113
	v_lshlrev_b32_e32 v122, 16, v114
	v_and_b32_e32 v123, 0xffff0000, v114
	v_lshlrev_b32_e32 v114, 16, v115
	v_and_b32_e32 v115, 0xffff0000, v115
	v_pk_fma_f32 v[110:111], v[110:111], v[62:63], v[112:113]
	v_pk_fma_f32 v[108:109], v[108:109], v[60:61], v[120:121]
	v_pk_fma_f32 v[112:113], v[106:107], v[58:59], v[114:115]
	v_pk_fma_f32 v[106:107], v[104:105], v[56:57], v[122:123]
	v_cvt_pk_bf16_f32 v104, v108, v109
	v_cvt_pk_bf16_f32 v105, v110, v111
	v_cvt_pk_bf16_f32 v106, v106, v107
	v_cvt_pk_bf16_f32 v107, v112, v113
	v_lshl_add_u64 v[108:109], s[42:43], 0, v[116:117]
	global_store_dwordx4 v[108:109], v[104:107], off
	s_waitcnt vmcnt(10)
	s_nop 1
	v_mov_b32_e32 v104, v202
	v_mov_b32_e32 v105, v203
	v_mov_b32_e32 v106, v204
	v_mov_b32_e32 v107, v205
	s_waitcnt lgkmcnt(0)
	v_lshlrev_b32_e32 v110, 16, v104
	v_and_b32_e32 v111, 0xffff0000, v104
	v_lshlrev_b32_e32 v104, 16, v105
	v_and_b32_e32 v105, 0xffff0000, v105
	v_lshlrev_b32_e32 v112, 16, v106
	v_and_b32_e32 v113, 0xffff0000, v106
	v_lshlrev_b32_e32 v106, 16, v107
	v_and_b32_e32 v107, 0xffff0000, v107
	v_pk_fma_f32 v[102:103], v[102:103], v[46:47], v[104:105]
	v_pk_fma_f32 v[100:101], v[100:101], v[44:45], v[110:111]
	v_pk_fma_f32 v[104:105], v[98:99], v[42:43], v[106:107]
	v_pk_fma_f32 v[98:99], v[96:97], v[40:41], v[112:113]
	v_cvt_pk_bf16_f32 v96, v100, v101
	v_cvt_pk_bf16_f32 v97, v102, v103
	v_cvt_pk_bf16_f32 v98, v98, v99
	v_cvt_pk_bf16_f32 v99, v104, v105
	v_lshl_add_u64 v[100:101], v[160:161], 0, s[2:3]
	global_store_dwordx4 v[108:109], v[96:99], off offset:256
	v_lshl_add_u64 v[102:103], s[4:5], 0, v[100:101]
	s_waitcnt vmcnt(10)
	s_nop 1
	v_mov_b32_e32 v96, v206
	v_mov_b32_e32 v97, v207
	v_mov_b32_e32 v98, v208
	v_mov_b32_e32 v99, v209
	s_mov_b64 s[2:3], 0x80000
	s_waitcnt lgkmcnt(0)
	v_lshlrev_b32_e32 v104, 16, v96
	v_and_b32_e32 v105, 0xffff0000, v96
	v_lshlrev_b32_e32 v96, 16, v97
	v_and_b32_e32 v97, 0xffff0000, v97
	v_lshlrev_b32_e32 v106, 16, v98
	v_and_b32_e32 v107, 0xffff0000, v98
	v_lshlrev_b32_e32 v98, 16, v99
	v_and_b32_e32 v99, 0xffff0000, v99
	v_pk_fma_f32 v[94:95], v[94:95], v[62:63], v[96:97]
	v_pk_fma_f32 v[92:93], v[92:93], v[60:61], v[104:105]
	v_pk_fma_f32 v[96:97], v[90:91], v[58:59], v[98:99]
	v_pk_fma_f32 v[90:91], v[88:89], v[56:57], v[106:107]
	v_cvt_pk_bf16_f32 v88, v92, v93
	v_cvt_pk_bf16_f32 v89, v94, v95
	v_cvt_pk_bf16_f32 v90, v90, v91
	v_cvt_pk_bf16_f32 v91, v96, v97
	v_lshl_add_u64 v[92:93], s[42:43], 0, v[100:101]
	global_store_dwordx4 v[92:93], v[88:91], off
	s_waitcnt vmcnt(10)
; DI unsigned pack2(float a, float b) { f32x2 v = {a, b}; hwbf16x2 r = __builtin_convertvector(v, hwbf16x2); return __builtin_bit_cast(unsigned, r); }
; DI float bflo(unsigned w) { return __uint_as_float(w << 16); }
; DI float bfhi(unsigned w) { return __uint_as_float(w & 0xffff0000u); }
;     DI void operator()(const f32x4 (&acc)[2][2][4][2], const Unit& u, int wr, int wc, int fr, int fq) const {
;     ...
;         for (int ai = 0; ai < 2; ++ai)
; #pragma unroll
;             for (int m = 0; m < 4; ++m) { const size_t ro = (size_t)(row0 + ai * HALF + m * 16) * D + col0;
; #pragma unroll
;                 for (int bj = 0; bj < 2; ++bj) {
;                     f32x4 x0, x1;
;                     if constexpr (IB) { const u32x4 w = *(const u32x4*)((const bf16_t*)Xin + ro + bj * HALF);
;                         x0 = (f32x4){bflo(w[0]), bfhi(w[0]), bflo(w[1]), bfhi(w[1])}; x1 = (f32x4){bflo(w[2]), bfhi(w[2]), bflo(w[3]), bfhi(w[3])}; }
;                     else { x0 = *(const f32x4*)((const float*)Xin + ro + bj * HALF); x1 = *(const f32x4*)((const float*)Xin + ro + bj * HALF + 4); }
;                     x0 += acc[ai][bj][m][0] * sc[bj][0]; x1 += acc[ai][bj][m][1] * sc[bj][1];
;                     if constexpr (OB) { u32x4 o; o[0] = pack2(x0[0], x0[1]); o[1] = pack2(x0[2], x0[3]); o[2] = pack2(x1[0], x1[1]); o[3] = pack2(x1[2], x1[3]);
;                         *(u32x4*)((bf16_t*)Xout + ro + bj * HALF) = o; }
;                     else { *(f32x4*)((float*)Xout + ro + bj * HALF) = x0; *(f32x4*)((float*)Xout + ro + bj * HALF + 4) = x1; } } }
	s_nop 1
	v_mov_b32_e32 v88, v210
	v_mov_b32_e32 v89, v211
	v_mov_b32_e32 v90, v212
	v_mov_b32_e32 v91, v213
	s_waitcnt lgkmcnt(0)
	v_lshlrev_b32_e32 v94, 16, v88
	v_and_b32_e32 v95, 0xffff0000, v88
	v_lshlrev_b32_e32 v88, 16, v89
	v_and_b32_e32 v89, 0xffff0000, v89
	v_lshlrev_b32_e32 v96, 16, v90
	v_and_b32_e32 v97, 0xffff0000, v90
	v_lshlrev_b32_e32 v90, 16, v91
	v_and_b32_e32 v91, 0xffff0000, v91
	v_pk_fma_f32 v[86:87], v[86:87], v[46:47], v[88:89]
	v_pk_fma_f32 v[84:85], v[84:85], v[44:45], v[94:95]
	v_pk_fma_f32 v[88:89], v[82:83], v[42:43], v[90:91]
	v_pk_fma_f32 v[82:83], v[80:81], v[40:41], v[96:97]
	v_cvt_pk_bf16_f32 v80, v84, v85
	v_cvt_pk_bf16_f32 v81, v86, v87
	v_cvt_pk_bf16_f32 v82, v82, v83
	v_cvt_pk_bf16_f32 v83, v88, v89
	v_lshl_add_u64 v[84:85], v[160:161], 0, s[2:3]
	global_store_dwordx4 v[92:93], v[80:83], off offset:256
	v_lshl_add_u64 v[86:87], s[4:5], 0, v[84:85]
	s_waitcnt vmcnt(10)
	s_nop 1
	v_mov_b32_e32 v80, v214
	v_mov_b32_e32 v81, v215
	v_mov_b32_e32 v82, v216
	v_mov_b32_e32 v83, v217
	s_mov_b64 s[2:3], 0x90000
	s_waitcnt lgkmcnt(0)
	v_lshlrev_b32_e32 v88, 16, v80
	v_and_b32_e32 v89, 0xffff0000, v80
	v_lshlrev_b32_e32 v80, 16, v81
	v_and_b32_e32 v81, 0xffff0000, v81
	v_lshlrev_b32_e32 v90, 16, v82
	v_and_b32_e32 v91, 0xffff0000, v82
	v_lshlrev_b32_e32 v82, 16, v83
	v_and_b32_e32 v83, 0xffff0000, v83
	v_pk_fma_f32 v[78:79], v[78:79], v[62:63], v[80:81]
	v_pk_fma_f32 v[76:77], v[76:77], v[60:61], v[88:89]
	v_pk_fma_f32 v[80:81], v[74:75], v[58:59], v[82:83]
	v_pk_fma_f32 v[74:75], v[72:73], v[56:57], v[90:91]
	v_cvt_pk_bf16_f32 v72, v76, v77
	v_cvt_pk_bf16_f32 v73, v78, v79
	v_cvt_pk_bf16_f32 v74, v74, v75
	v_cvt_pk_bf16_f32 v75, v80, v81
	v_lshl_add_u64 v[76:77], s[42:43], 0, v[84:85]
	global_store_dwordx4 v[76:77], v[72:75], off
	s_waitcnt vmcnt(10)
	s_nop 1
	v_mov_b32_e32 v72, v248
	v_mov_b32_e32 v73, v249
	v_mov_b32_e32 v74, v250
	v_mov_b32_e32 v75, v251
	s_waitcnt lgkmcnt(0)
	v_lshlrev_b32_e32 v78, 16, v72
	v_and_b32_e32 v79, 0xffff0000, v72
	v_lshlrev_b32_e32 v72, 16, v73
	v_and_b32_e32 v73, 0xffff0000, v73
	v_lshlrev_b32_e32 v80, 16, v74
	v_and_b32_e32 v81, 0xffff0000, v74
	v_lshlrev_b32_e32 v74, 16, v75
	v_and_b32_e32 v75, 0xffff0000, v75
	v_pk_fma_f32 v[70:71], v[70:71], v[46:47], v[72:73]
	v_pk_fma_f32 v[68:69], v[68:69], v[44:45], v[78:79]
	v_pk_fma_f32 v[72:73], v[66:67], v[42:43], v[74:75]
	v_pk_fma_f32 v[66:67], v[64:65], v[40:41], v[80:81]
	v_cvt_pk_bf16_f32 v64, v68, v69
	v_cvt_pk_bf16_f32 v65, v70, v71
	v_cvt_pk_bf16_f32 v66, v66, v67
	v_cvt_pk_bf16_f32 v67, v72, v73
	v_lshl_add_u64 v[68:69], v[160:161], 0, s[2:3]
	global_store_dwordx4 v[76:77], v[64:67], off offset:256
	v_lshl_add_u64 v[70:71], s[4:5], 0, v[68:69]
	s_waitcnt vmcnt(10)
	s_nop 1
	v_mov_b32_e32 v64, v252
	v_mov_b32_e32 v65, v253
	v_mov_b32_e32 v66, v254
	v_mov_b32_e32 v67, v255
	s_mov_b64 s[2:3], 0xa0000
	s_waitcnt lgkmcnt(0)
	v_lshlrev_b32_e32 v72, 16, v64
	v_and_b32_e32 v73, 0xffff0000, v64
	v_lshlrev_b32_e32 v64, 16, v65
	v_and_b32_e32 v65, 0xffff0000, v65
	v_lshlrev_b32_e32 v74, 16, v66
	v_and_b32_e32 v75, 0xffff0000, v66
	v_lshlrev_b32_e32 v66, 16, v67
	v_and_b32_e32 v67, 0xffff0000, v67
	v_pk_fma_f32 v[54:55], v[54:55], v[62:63], v[64:65]
	v_pk_fma_f32 v[52:53], v[52:53], v[60:61], v[72:73]
	v_pk_fma_f32 v[64:65], v[50:51], v[58:59], v[66:67]
	v_pk_fma_f32 v[50:51], v[48:49], v[56:57], v[74:75]
	v_cvt_pk_bf16_f32 v48, v52, v53
	v_cvt_pk_bf16_f32 v49, v54, v55
	v_cvt_pk_bf16_f32 v50, v50, v51
	v_cvt_pk_bf16_f32 v51, v64, v65
	v_lshl_add_u64 v[52:53], s[42:43], 0, v[68:69]
	global_store_dwordx4 v[52:53], v[48:51], off
	global_load_dwordx4 v[48:51], v[70:71], off offset:256
	s_waitcnt vmcnt(0) lgkmcnt(0)
; DI unsigned pack2(float a, float b) { f32x2 v = {a, b}; hwbf16x2 r = __builtin_convertvector(v, hwbf16x2); return __builtin_bit_cast(unsigned, r); }
; DI float bflo(unsigned w) { return __uint_as_float(w << 16); }
; DI float bfhi(unsigned w) { return __uint_as_float(w & 0xffff0000u); }
;     DI const char* a(const Unit& u) const { return (const char*)(A + (size_t)u.pm * BM * lda); }
;     DI const char* a(const Unit& u) const { return (const char*)(A + (size_t)u.pm * BM * 2048 + (u.pn >> 1) * 512); }
;     DI void operator()(const f32x4 (&acc)[2][2][4][2], const Unit& u, int wr, int wc, int fr, int fq) const {
;     ...
;         for (int ai = 0; ai < 2; ++ai)
; #pragma unroll
;             for (int m = 0; m < 4; ++m) { const size_t ro = (size_t)(row0 + ai * HALF + m * 16) * D + col0;
; #pragma unroll
;                 for (int bj = 0; bj < 2; ++bj) {
;                     f32x4 x0, x1;
;                     if constexpr (IB) { const u32x4 w = *(const u32x4*)((const bf16_t*)Xin + ro + bj * HALF);
;                         x0 = (f32x4){bflo(w[0]), bfhi(w[0]), bflo(w[1]), bfhi(w[1])}; x1 = (f32x4){bflo(w[2]), bfhi(w[2]), bflo(w[3]), bfhi(w[3])}; }
;                     else { x0 = *(const f32x4*)((const float*)Xin + ro + bj * HALF); x1 = *(const f32x4*)((const float*)Xin + ro + bj * HALF + 4); }
;                     x0 += acc[ai][bj][m][0] * sc[bj][0]; x1 += acc[ai][bj][m][1] * sc[bj][1];
;                     if constexpr (OB) { u32x4 o; o[0] = pack2(x0[0], x0[1]); o[1] = pack2(x0[2], x0[3]); o[2] = pack2(x1[0], x1[1]); o[3] = pack2(x1[2], x1[3]);
;                         *(u32x4*)((bf16_t*)Xout + ro + bj * HALF) = o; }
;                     else { *(f32x4*)((float*)Xout + ro + bj * HALF) = x0; *(f32x4*)((float*)Xout + ro + bj * HALF + 4) = x1; } } }
; template <class Map, class Epi>
; DI void gemm_phase(LAS unsigned char* lds, const Map& MP, const Epi& E, const int nM, const int nN, const int K, const int lda, const int ldb) {
;     ...
;         if (!has_next) break;
; #pragma unroll
;         for (int a = 0; a < 2; ++a)
; #pragma unroll
;             for (int b = 0; b < 2; ++b)
; #pragma unroll
;                 for (int m = 0; m < 4; ++m)
; #pragma unroll
;                     for (int n = 0; n < 2; ++n) acc[a][b][m][n] = (f32x4){0.f, 0.f, 0.f, 0.f};
;         cur = nxt; cA = nA; cB = nB; ++ui;
;     }
;     PG8_WAIT_V(0);
;     if (wr == 0) PG8_BAR;
;     PG8_BAR;
	v_lshlrev_b32_e32 v54, 16, v48
	v_and_b32_e32 v55, 0xffff0000, v48
	v_lshlrev_b32_e32 v48, 16, v49
	v_and_b32_e32 v49, 0xffff0000, v49
	v_lshlrev_b32_e32 v64, 16, v50
	v_and_b32_e32 v65, 0xffff0000, v50
	v_lshlrev_b32_e32 v50, 16, v51
	v_and_b32_e32 v51, 0xffff0000, v51
	v_pk_fma_f32 v[38:39], v[38:39], v[46:47], v[48:49]
	v_pk_fma_f32 v[36:37], v[36:37], v[44:45], v[54:55]
	v_pk_fma_f32 v[48:49], v[34:35], v[42:43], v[50:51]
	v_pk_fma_f32 v[34:35], v[32:33], v[40:41], v[64:65]
	v_cvt_pk_bf16_f32 v32, v36, v37
	v_cvt_pk_bf16_f32 v33, v38, v39
	v_cvt_pk_bf16_f32 v34, v34, v35
	v_cvt_pk_bf16_f32 v35, v48, v49
	v_lshl_add_u64 v[36:37], v[160:161], 0, s[2:3]
	global_store_dwordx4 v[52:53], v[32:35], off offset:256
	v_lshl_add_u64 v[38:39], s[4:5], 0, v[36:37]
	global_load_dwordx4 v[32:35], v[38:39], off
	s_mov_b64 s[2:3], 0xb0000
	s_waitcnt vmcnt(0) lgkmcnt(0)
	v_lshlrev_b32_e32 v48, 16, v32
	v_and_b32_e32 v49, 0xffff0000, v32
	v_lshlrev_b32_e32 v32, 16, v33
	v_and_b32_e32 v33, 0xffff0000, v33
	v_lshlrev_b32_e32 v50, 16, v34
	v_and_b32_e32 v51, 0xffff0000, v34
	v_lshlrev_b32_e32 v34, 16, v35
	v_and_b32_e32 v35, 0xffff0000, v35
	v_pk_fma_f32 v[30:31], v[30:31], v[62:63], v[32:33]
	v_pk_fma_f32 v[28:29], v[28:29], v[60:61], v[48:49]
	v_pk_fma_f32 v[32:33], v[26:27], v[58:59], v[34:35]
	v_pk_fma_f32 v[26:27], v[24:25], v[56:57], v[50:51]
	v_cvt_pk_bf16_f32 v24, v28, v29
	v_cvt_pk_bf16_f32 v25, v30, v31
	v_cvt_pk_bf16_f32 v26, v26, v27
	v_cvt_pk_bf16_f32 v27, v32, v33
	v_lshl_add_u64 v[28:29], s[42:43], 0, v[36:37]
	global_store_dwordx4 v[28:29], v[24:27], off
	global_load_dwordx4 v[24:27], v[38:39], off offset:256
	s_waitcnt vmcnt(0) lgkmcnt(0)
	v_lshlrev_b32_e32 v30, 16, v24
	v_and_b32_e32 v31, 0xffff0000, v24
	v_lshlrev_b32_e32 v24, 16, v25
	v_and_b32_e32 v25, 0xffff0000, v25
	v_lshlrev_b32_e32 v32, 16, v26
	v_and_b32_e32 v33, 0xffff0000, v26
	v_lshlrev_b32_e32 v26, 16, v27
	v_and_b32_e32 v27, 0xffff0000, v27
	v_pk_fma_f32 v[22:23], v[22:23], v[46:47], v[24:25]
	v_pk_fma_f32 v[20:21], v[20:21], v[44:45], v[30:31]
	v_pk_fma_f32 v[24:25], v[18:19], v[42:43], v[26:27]
	v_pk_fma_f32 v[18:19], v[16:17], v[40:41], v[32:33]
	v_cvt_pk_bf16_f32 v16, v20, v21
	v_cvt_pk_bf16_f32 v17, v22, v23
	v_cvt_pk_bf16_f32 v18, v18, v19
	v_cvt_pk_bf16_f32 v19, v24, v25
	v_lshl_add_u64 v[20:21], v[160:161], 0, s[2:3]
	global_store_dwordx4 v[28:29], v[16:19], off offset:256
	v_lshl_add_u64 v[22:23], s[4:5], 0, v[20:21]
	global_load_dwordx4 v[16:19], v[22:23], off
	s_mov_b32 s2, s37
	s_waitcnt vmcnt(0) lgkmcnt(0)
	v_lshlrev_b32_e32 v24, 16, v16
	v_and_b32_e32 v25, 0xffff0000, v16
	v_lshlrev_b32_e32 v16, 16, v17
	v_and_b32_e32 v17, 0xffff0000, v17
	v_lshlrev_b32_e32 v26, 16, v18
	v_and_b32_e32 v27, 0xffff0000, v18
	v_lshlrev_b32_e32 v18, 16, v19
	v_and_b32_e32 v19, 0xffff0000, v19
	v_pk_fma_f32 v[14:15], v[14:15], v[62:63], v[16:17]
	v_pk_fma_f32 v[12:13], v[12:13], v[60:61], v[24:25]
	v_pk_fma_f32 v[16:17], v[10:11], v[58:59], v[18:19]
	v_pk_fma_f32 v[10:11], v[8:9], v[56:57], v[26:27]
	v_cvt_pk_bf16_f32 v8, v12, v13
	v_cvt_pk_bf16_f32 v9, v14, v15
	v_cvt_pk_bf16_f32 v10, v10, v11
	v_cvt_pk_bf16_f32 v11, v16, v17
	v_lshl_add_u64 v[12:13], s[42:43], 0, v[20:21]
	global_store_dwordx4 v[12:13], v[8:11], off
	global_load_dwordx4 v[8:11], v[22:23], off offset:256
	s_waitcnt vmcnt(0) lgkmcnt(0)
	v_lshlrev_b32_e32 v14, 16, v8
	v_and_b32_e32 v15, 0xffff0000, v8
	v_lshlrev_b32_e32 v8, 16, v9
	v_and_b32_e32 v9, 0xffff0000, v9
	v_lshlrev_b32_e32 v16, 16, v10
	v_and_b32_e32 v17, 0xffff0000, v10
	v_lshlrev_b32_e32 v10, 16, v11
	v_and_b32_e32 v11, 0xffff0000, v11
	v_pk_fma_f32 v[6:7], v[6:7], v[46:47], v[8:9]
	v_pk_fma_f32 v[4:5], v[4:5], v[44:45], v[14:15]
	v_pk_fma_f32 v[8:9], v[2:3], v[42:43], v[10:11]
	v_pk_fma_f32 v[2:3], v[0:1], v[40:41], v[16:17]
	v_cvt_pk_bf16_f32 v0, v4, v5
	v_cvt_pk_bf16_f32 v1, v6, v7
	v_cvt_pk_bf16_f32 v2, v2, v3
	v_cvt_pk_bf16_f32 v3, v8, v9
	global_store_dwordx4 v[12:13], v[0:3], off offset:256
	s_cbranch_vccz .LBB1_2336
	s_waitcnt vmcnt(0)
	s_cmpk_gt_u32 s17, 0xff
	s_cbranch_scc1 .LBB1_2343
	s_barrier

; #define PG8_STAGE(bufoff, gbase, voff) do { _Pragma("unroll") for (int _i = 0; _i < 2; ++_i) \
;         __builtin_amdgcn_global_load_lds((const unsigned*)((const char*)(gbase) + (voff)[_i]), (LAS unsigned*)(lds + (bufoff) + ldsw + _i * 8192), 16, 0, 0); } while (0)
; #define PG8_LDA(dst, b, h) do { _Pragma("unroll") for (int m = 0; m < 4; ++m) _Pragma("unroll") for (int k = 0; k < 2; ++k) dst[m][k] = *(const LAS bf16x8*)(lds + PG8_SA(b, h) + aoff + m * 2048 + k * 1024); } while (0)
; #define PG8_LDB(dst, b, h) do { _Pragma("unroll") for (int n = 0; n < 2; ++n) _Pragma("unroll") for (int k = 0; k < 2; ++k) dst[n][k] = *(const LAS bf16x8*)(lds + PG8_SB(b, h) + boff + n * 2048 + k * 1024); } while (0)
; #define PG8_MMA(ai, bj, At, Bt) do { __builtin_amdgcn_s_setprio(1); _Pragma("unroll") for (int m = 0; m < 4; ++m) _Pragma("unroll") for (int n = 0; n < 2; ++n) _Pragma("unroll") for (int k = 0; k < 2; ++k) \
;         acc[ai][bj][m][n] = __builtin_amdgcn_mfma_f32_16x16x32_bf16(Bt[n][k], At[m][k], acc[ai][bj][m][n], 0, 0, 0); __builtin_amdgcn_s_setprio(0); } while (0)
; #define PG8_WAIT_V(n) asm volatile("s_waitcnt vmcnt(" #n ")" ::: "memory")
; #define PG8_WAIT_L(n) asm volatile("s_waitcnt lgkmcnt(" #n ")" ::: "memory")
; template <class Map, class Epi>
; DI void gemm_phase(LAS unsigned char* lds, const Map& MP, const Epi& E, const int nM, const int nN, const int K, const int lda, const int ldb) {
;     ...
;         for (int t = 0; t < nt; t += 2) {
;             const bool last = (t == nt - 2);
;             const char* a1 = cA + (size_t)(t + 1) * kstep;
;             const char* a2 = last ? nA : cA + (size_t)(t + 2) * kstep; const char* b2 = last ? nB : cB + (size_t)(t + 2) * kstep;
;             const char* a3 = a2 + kstep; const char* b3 = b2 + kstep;
;             PG8_LDB(B0, 0, 0); PG8_SCHED; PG8_LDA(At, 0, 0); PG8_STAGE(PG8_SA(1, 1), a1 + hstepA, voffA);
;             PG8_WAIT_L(8); PG8_BAR; PG8_WAIT_L(0); PG8_MMA(0, 0, At, B0); PG8_BAR; PG8_SCHED;
;             PG8_LDB(B1, 0, 1); PG8_STAGE(PG8_SB(0, 0), b2, voffB);
;             PG8_BAR; PG8_WAIT_L(0); PG8_MMA(0, 1, At, B1); PG8_BAR;
;             PG8_LDA(At, 0, 1); PG8_STAGE(PG8_SA(0, 0), a2, voffA);
;             PG8_BAR; PG8_WAIT_L(0); PG8_MMA(1, 0, At, B0); PG8_BAR; PG8_SCHED;
;             PG8_STAGE(PG8_SB(0, 1), b2 + hstepB, voffB);
;             PG8_WAIT_V(6); PG8_BAR; PG8_MMA(1, 1, At, B1); PG8_BAR;
.LBB1_2483:
	s_add_u32 s28, s42, 0xfff80080
	s_addc_u32 s29, s43, -1
	s_cmp_eq_u32 s3, 28
	s_cselect_b32 s47, s23, s29
	s_cselect_b32 s46, s58, s28
	s_cselect_b32 s29, s21, vcc_hi
	s_cselect_b32 s28, s59, vcc_lo
	s_add_i32 m0, s38, 0xc000
	ds_read_b128 v[96:99], v190
	ds_read_b128 v[100:103], v190 offset:1024
	ds_read_b128 v[108:111], v190 offset:2048
	ds_read_b128 v[112:115], v190 offset:3072
	ds_read_b128 v[160:163], v190 offset:4096
	ds_read_b128 v[164:167], v190 offset:5120
	ds_read_b128 v[198:201], v190 offset:6144
	ds_read_b128 v[202:205], v190 offset:7168
	global_load_lds_dwordx4 v178, s[42:43]
	s_add_i32 m0, s38, 0xe000
	s_nop 0
	global_load_lds_dwordx4 v176, s[42:43]
	s_waitcnt lgkmcnt(8)
	s_barrier
	s_setprio 1
	s_waitcnt lgkmcnt(7)
	v_mfma_f32_16x16x32_bf16 v[148:151], v[80:83], v[96:99], v[148:151]
	v_mfma_f32_16x16x32_bf16 v[144:147], v[88:91], v[96:99], v[144:147]
	s_waitcnt lgkmcnt(5)
	v_mfma_f32_16x16x32_bf16 v[136:139], v[80:83], v[108:111], v[136:139]
	v_mfma_f32_16x16x32_bf16 v[128:131], v[88:91], v[108:111], v[128:131]
	s_waitcnt lgkmcnt(3)
	v_mfma_f32_16x16x32_bf16 v[120:123], v[80:83], v[160:163], v[120:123]
	v_mfma_f32_16x16x32_bf16 v[104:107], v[88:91], v[160:163], v[104:107]
	s_waitcnt lgkmcnt(1)
	v_mfma_f32_16x16x32_bf16 v[76:79], v[80:83], v[198:201], v[76:79]
	v_mfma_f32_16x16x32_bf16 v[72:75], v[88:91], v[198:201], v[72:75]
	v_mfma_f32_16x16x32_bf16 v[148:151], v[84:87], v[100:103], v[148:151]
	v_mfma_f32_16x16x32_bf16 v[144:147], v[92:95], v[100:103], v[144:147]
	v_mfma_f32_16x16x32_bf16 v[136:139], v[84:87], v[112:115], v[136:139]
	v_mfma_f32_16x16x32_bf16 v[128:131], v[92:95], v[112:115], v[128:131]
	v_mfma_f32_16x16x32_bf16 v[120:123], v[84:87], v[164:167], v[120:123]
	v_mfma_f32_16x16x32_bf16 v[104:107], v[92:95], v[164:167], v[104:107]
	s_waitcnt lgkmcnt(0)
	v_mfma_f32_16x16x32_bf16 v[76:79], v[84:87], v[202:205], v[76:79]
	v_mfma_f32_16x16x32_bf16 v[72:75], v[92:95], v[202:205], v[72:75]
	s_setprio 0
	s_barrier
	s_add_i32 s68, s2, s37
	v_lshl_add_u64 v[184:185], s[28:29], 0, v[172:173]
	s_mov_b32 m0, s68
	ds_read_b128 v[206:209], v191
	ds_read_b128 v[210:213], v191 offset:1024
	ds_read_b128 v[214:217], v191 offset:2048
	ds_read_b128 v[218:221], v191 offset:3072
	global_load_lds_dwordx4 v[184:185], off
	v_lshl_add_u64 v[194:195], s[28:29], 0, v[168:169]
	s_add_i32 m0, s68, 0x2000
	s_nop 0
	global_load_lds_dwordx4 v[194:195], off
	s_barrier
	s_setprio 1
	s_waitcnt lgkmcnt(3)
	v_mfma_f32_16x16x32_bf16 v[156:159], v[206:209], v[96:99], v[156:159]
	s_waitcnt lgkmcnt(1)
	v_mfma_f32_16x16x32_bf16 v[96:99], v[214:217], v[96:99], v[152:155]
	v_mfma_f32_16x16x32_bf16 v[156:159], v[210:213], v[100:103], v[156:159]
	s_waitcnt lgkmcnt(0)
	v_mfma_f32_16x16x32_bf16 v[96:99], v[218:221], v[100:103], v[96:99]
	v_mfma_f32_16x16x32_bf16 v[100:103], v[206:209], v[108:111], v[140:143]
	v_mfma_f32_16x16x32_bf16 v[108:111], v[214:217], v[108:111], v[132:135]
	v_mfma_f32_16x16x32_bf16 v[116:119], v[214:217], v[160:163], v[116:119]
	v_mfma_f32_16x16x32_bf16 v[68:71], v[206:209], v[198:201], v[68:71]
	v_mfma_f32_16x16x32_bf16 v[64:67], v[214:217], v[198:201], v[64:67]
	s_mov_b32 m0, s38
	v_mfma_f32_16x16x32_bf16 v[100:103], v[210:213], v[112:115], v[100:103]
	v_lshl_add_u64 v[230:231], s[46:47], 0, v[174:175]
	v_mfma_f32_16x16x32_bf16 v[108:111], v[218:221], v[112:115], v[108:111]
	v_mfma_f32_16x16x32_bf16 v[112:115], v[206:209], v[160:163], v[124:127]
	v_mfma_f32_16x16x32_bf16 v[116:119], v[218:221], v[164:167], v[116:119]
	v_mfma_f32_16x16x32_bf16 v[68:71], v[210:213], v[202:205], v[68:71]
	v_mfma_f32_16x16x32_bf16 v[64:67], v[218:221], v[202:205], v[64:67]
	v_mfma_f32_16x16x32_bf16 v[112:115], v[210:213], v[164:167], v[112:115]
	s_setprio 0
	s_barrier
	ds_read_b128 v[124:127], v190 offset:16384
	ds_read_b128 v[132:135], v190 offset:17408
	ds_read_b128 v[140:143], v190 offset:18432
	ds_read_b128 v[152:155], v190 offset:19456
	ds_read_b128 v[160:163], v190 offset:20480
	ds_read_b128 v[164:167], v190 offset:21504
	ds_read_b128 v[198:201], v190 offset:22528
	ds_read_b128 v[202:205], v190 offset:23552
	global_load_lds_dwordx4 v[230:231], off
	v_lshl_add_u64 v[232:233], s[46:47], 0, v[170:171]
	s_mov_b32 m0, s39
	s_nop 0
	global_load_lds_dwordx4 v[232:233], off
	s_waitcnt vmcnt(10)
	s_barrier
	s_setprio 1
	s_waitcnt lgkmcnt(7)
	v_mfma_f32_16x16x32_bf16 v[60:63], v[80:83], v[124:127], v[60:63]
	v_mfma_f32_16x16x32_bf16 v[48:51], v[88:91], v[124:127], v[48:51]
	s_waitcnt lgkmcnt(5)
	v_mfma_f32_16x16x32_bf16 v[40:43], v[80:83], v[140:143], v[40:43]
	v_mfma_f32_16x16x32_bf16 v[32:35], v[88:91], v[140:143], v[32:35]
	s_waitcnt lgkmcnt(3)
	v_mfma_f32_16x16x32_bf16 v[24:27], v[80:83], v[160:163], v[24:27]
	v_mfma_f32_16x16x32_bf16 v[16:19], v[88:91], v[160:163], v[16:19]
	s_waitcnt lgkmcnt(1)
	v_mfma_f32_16x16x32_bf16 v[12:15], v[80:83], v[198:201], v[12:15]
	v_mfma_f32_16x16x32_bf16 v[8:11], v[88:91], v[198:201], v[8:11]
	v_mfma_f32_16x16x32_bf16 v[60:63], v[84:87], v[132:135], v[60:63]
	v_mfma_f32_16x16x32_bf16 v[48:51], v[92:95], v[132:135], v[48:51]
	v_mfma_f32_16x16x32_bf16 v[40:43], v[84:87], v[152:155], v[40:43]
	v_mfma_f32_16x16x32_bf16 v[32:35], v[92:95], v[152:155], v[32:35]
	v_mfma_f32_16x16x32_bf16 v[24:27], v[84:87], v[164:167], v[24:27]
	v_mfma_f32_16x16x32_bf16 v[16:19], v[92:95], v[164:167], v[16:19]
	s_waitcnt lgkmcnt(0)
	v_mfma_f32_16x16x32_bf16 v[12:15], v[84:87], v[202:205], v[12:15]
	v_mfma_f32_16x16x32_bf16 v[8:11], v[92:95], v[202:205], v[8:11]
	s_setprio 0
	s_barrier
	s_add_u32 s68, s28, 0x80000
	s_addc_u32 s69, s29, 0
	s_add_i32 s70, s67, s37
	s_mov_b32 m0, s70
	s_nop 0
	global_load_lds_dwordx4 v172, s[68:69]
	s_add_i32 m0, s70, 0x2000
	s_nop 0
	global_load_lds_dwordx4 v168, s[68:69]
	s_waitcnt vmcnt(6)
	s_barrier
; #define PG8_STAGE(bufoff, gbase, voff) do { _Pragma("unroll") for (int _i = 0; _i < 2; ++_i) \
;         __builtin_amdgcn_global_load_lds((const unsigned*)((const char*)(gbase) + (voff)[_i]), (LAS unsigned*)(lds + (bufoff) + ldsw + _i * 8192), 16, 0, 0); } while (0)
; #define PG8_LDA(dst, b, h) do { _Pragma("unroll") for (int m = 0; m < 4; ++m) _Pragma("unroll") for (int k = 0; k < 2; ++k) dst[m][k] = *(const LAS bf16x8*)(lds + PG8_SA(b, h) + aoff + m * 2048 + k * 1024); } while (0)
; #define PG8_LDB(dst, b, h) do { _Pragma("unroll") for (int n = 0; n < 2; ++n) _Pragma("unroll") for (int k = 0; k < 2; ++k) dst[n][k] = *(const LAS bf16x8*)(lds + PG8_SB(b, h) + boff + n * 2048 + k * 1024); } while (0)
; #define PG8_MMA(ai, bj, At, Bt) do { __builtin_amdgcn_s_setprio(1); _Pragma("unroll") for (int m = 0; m < 4; ++m) _Pragma("unroll") for (int n = 0; n < 2; ++n) _Pragma("unroll") for (int k = 0; k < 2; ++k) \
;         acc[ai][bj][m][n] = __builtin_amdgcn_mfma_f32_16x16x32_bf16(Bt[n][k], At[m][k], acc[ai][bj][m][n], 0, 0, 0); __builtin_amdgcn_s_setprio(0); } while (0)
; #define PG8_WAIT_V(n) asm volatile("s_waitcnt vmcnt(" #n ")" ::: "memory")
; #define PG8_WAIT_L(n) asm volatile("s_waitcnt lgkmcnt(" #n ")" ::: "memory")
; #define PG8_BAR __builtin_amdgcn_s_barrier()
; #define PG8_SCHED __builtin_amdgcn_sched_barrier(0)
; template <class Map, class Epi>
; DI void gemm_phase(LAS unsigned char* lds, const Map& MP, const Epi& E, const int nM, const int nN, const int K, const int lda, const int ldb) {
;     ...
;             PG8_BAR; PG8_WAIT_L(0); PG8_MMA(1, 0, At, B0); PG8_BAR; PG8_SCHED;
;             PG8_STAGE(PG8_SB(0, 1), b2 + hstepB, voffB);
;             PG8_WAIT_V(6); PG8_BAR; PG8_MMA(1, 1, At, B1); PG8_BAR;
;             PG8_LDB(B0, 1, 0); PG8_SCHED; PG8_LDA(At, 1, 0); PG8_STAGE(PG8_SA(0, 1), a2 + hstepA, voffA);
;             PG8_WAIT_L(8); PG8_BAR; PG8_WAIT_L(0); PG8_MMA(0, 0, At, B0); PG8_BAR; PG8_SCHED;
;             PG8_LDB(B1, 1, 1); PG8_STAGE(PG8_SB(1, 0), b3, voffB);
;             PG8_BAR; PG8_WAIT_L(0); PG8_MMA(0, 1, At, B1); PG8_BAR;
;             PG8_LDA(At, 1, 1); PG8_STAGE(PG8_SA(1, 0), a3, voffA);
;             PG8_BAR; PG8_WAIT_L(0); PG8_MMA(1, 0, At, B0); PG8_BAR; PG8_SCHED;
;             PG8_STAGE(PG8_SB(1, 1), b3 + hstepB, voffB);
	s_setprio 1
	v_mfma_f32_16x16x32_bf16 v[56:59], v[206:209], v[124:127], v[56:59]
	v_mfma_f32_16x16x32_bf16 v[52:55], v[214:217], v[124:127], v[52:55]
	s_add_i32 s68, 0, 0x18000
	v_add_u32_e32 v92, s68, v188
	ds_read_b128 v[80:83], v92
	v_mfma_f32_16x16x32_bf16 v[44:47], v[206:209], v[140:143], v[44:47]
	v_mfma_f32_16x16x32_bf16 v[36:39], v[214:217], v[140:143], v[36:39]
	ds_read_b128 v[84:87], v92 offset:1024
	v_mfma_f32_16x16x32_bf16 v[28:31], v[206:209], v[160:163], v[28:31]
	v_mfma_f32_16x16x32_bf16 v[20:23], v[214:217], v[160:163], v[20:23]
	ds_read_b128 v[88:91], v92 offset:2048
	v_mfma_f32_16x16x32_bf16 v[4:7], v[206:209], v[198:201], v[4:7]
	v_mfma_f32_16x16x32_bf16 v[0:3], v[214:217], v[198:201], v[0:3]
	ds_read_b128 v[92:95], v92 offset:3072
	v_mfma_f32_16x16x32_bf16 v[56:59], v[210:213], v[132:135], v[56:59]
	v_mfma_f32_16x16x32_bf16 v[52:55], v[218:221], v[132:135], v[52:55]
	v_mfma_f32_16x16x32_bf16 v[44:47], v[210:213], v[152:155], v[44:47]
	v_mfma_f32_16x16x32_bf16 v[36:39], v[218:221], v[152:155], v[36:39]
	v_mfma_f32_16x16x32_bf16 v[28:31], v[210:213], v[164:167], v[28:31]
	v_mfma_f32_16x16x32_bf16 v[20:23], v[218:221], v[164:167], v[20:23]
	v_mfma_f32_16x16x32_bf16 v[4:7], v[210:213], v[202:205], v[4:7]
	v_mfma_f32_16x16x32_bf16 v[0:3], v[218:221], v[202:205], v[0:3]
	s_setprio 0
	s_barrier
	s_add_u32 s46, s46, 0x80000
	s_addc_u32 s47, s47, 0
	s_mov_b32 m0, s55
	ds_read_b128 v[124:127], v190 offset:32768
	ds_read_b128 v[132:135], v190 offset:33792
	ds_read_b128 v[160:163], v190 offset:34816
	ds_read_b128 v[164:167], v190 offset:35840
	ds_read_b128 v[198:201], v190 offset:36864
	ds_read_b128 v[202:205], v190 offset:37888
	ds_read_b128 v[206:209], v190 offset:38912
	ds_read_b128 v[210:213], v190 offset:39936
	global_load_lds_dwordx4 v174, s[46:47]
	s_mov_b32 m0, s56
	s_nop 0
	global_load_lds_dwordx4 v170, s[46:47]
	s_waitcnt lgkmcnt(8)
	s_barrier
	s_setprio 1
	s_waitcnt lgkmcnt(7)
	v_mfma_f32_16x16x32_bf16 v[140:143], v[80:83], v[124:127], v[148:151]
	s_waitcnt lgkmcnt(6)
	v_mfma_f32_16x16x32_bf16 v[148:151], v[84:87], v[132:135], v[140:143]
	v_mfma_f32_16x16x32_bf16 v[140:143], v[88:91], v[124:127], v[144:147]
	s_waitcnt lgkmcnt(5)
	v_mfma_f32_16x16x32_bf16 v[136:139], v[80:83], v[160:163], v[136:139]
	v_mfma_f32_16x16x32_bf16 v[128:131], v[88:91], v[160:163], v[128:131]
	s_waitcnt lgkmcnt(3)
	v_mfma_f32_16x16x32_bf16 v[120:123], v[80:83], v[198:201], v[120:123]
	v_mfma_f32_16x16x32_bf16 v[104:107], v[88:91], v[198:201], v[104:107]
	s_waitcnt lgkmcnt(1)
	v_mfma_f32_16x16x32_bf16 v[76:79], v[80:83], v[206:209], v[76:79]
	v_mfma_f32_16x16x32_bf16 v[72:75], v[88:91], v[206:209], v[72:75]
	v_mfma_f32_16x16x32_bf16 v[144:147], v[92:95], v[132:135], v[140:143]
	v_mfma_f32_16x16x32_bf16 v[136:139], v[84:87], v[164:167], v[136:139]
	v_mfma_f32_16x16x32_bf16 v[128:131], v[92:95], v[164:167], v[128:131]
	v_mfma_f32_16x16x32_bf16 v[120:123], v[84:87], v[202:205], v[120:123]
	v_mfma_f32_16x16x32_bf16 v[104:107], v[92:95], v[202:205], v[104:107]
	s_waitcnt lgkmcnt(0)
	v_mfma_f32_16x16x32_bf16 v[76:79], v[84:87], v[210:213], v[76:79]
	v_mfma_f32_16x16x32_bf16 v[72:75], v[92:95], v[210:213], v[72:75]
	s_setprio 0
	s_barrier
	s_add_i32 s46, 0, 0x1c000
	v_add_u32_e32 v140, s46, v188
	s_add_i32 s47, s68, s37
	ds_read_b128 v[214:217], v140
	ds_read_b128 v[218:221], v140 offset:1024
	ds_read_b128 v[222:225], v140 offset:2048
	ds_read_b128 v[226:229], v140 offset:3072
	v_lshl_add_u64 v[140:141], v[184:185], 0, s[14:15]
	s_mov_b32 m0, s47
	s_nop 0
	global_load_lds_dwordx4 v[140:141], off
	v_lshl_add_u64 v[140:141], v[194:195], 0, s[14:15]
	s_add_i32 m0, s47, 0x2000
	s_nop 0
	global_load_lds_dwordx4 v[140:141], off
	s_barrier
	s_setprio 1
	s_waitcnt lgkmcnt(1)
	v_mfma_f32_16x16x32_bf16 v[96:99], v[222:225], v[124:127], v[96:99]
	v_mfma_f32_16x16x32_bf16 v[140:143], v[214:217], v[124:127], v[156:159]
	s_waitcnt lgkmcnt(0)
	v_mfma_f32_16x16x32_bf16 v[152:155], v[226:229], v[132:135], v[96:99]
	v_mfma_f32_16x16x32_bf16 v[96:99], v[214:217], v[160:163], v[100:103]
	v_mfma_f32_16x16x32_bf16 v[156:159], v[218:221], v[132:135], v[140:143]
	v_mfma_f32_16x16x32_bf16 v[140:143], v[218:221], v[164:167], v[96:99]
	v_mfma_f32_16x16x32_bf16 v[96:99], v[222:225], v[160:163], v[108:111]
	v_mfma_f32_16x16x32_bf16 v[132:135], v[226:229], v[164:167], v[96:99]
	v_mfma_f32_16x16x32_bf16 v[96:99], v[214:217], v[198:201], v[112:115]
	s_mov_b32 m0, s62
	v_mfma_f32_16x16x32_bf16 v[124:127], v[218:221], v[202:205], v[96:99]
	v_lshl_add_u64 v[184:185], v[230:231], 0, s[14:15]
	v_mfma_f32_16x16x32_bf16 v[96:99], v[222:225], v[198:201], v[116:119]
	v_mfma_f32_16x16x32_bf16 v[68:71], v[214:217], v[206:209], v[68:71]
	v_mfma_f32_16x16x32_bf16 v[64:67], v[222:225], v[206:209], v[64:67]
	v_mfma_f32_16x16x32_bf16 v[116:119], v[226:229], v[202:205], v[96:99]
	v_mfma_f32_16x16x32_bf16 v[68:71], v[218:221], v[210:213], v[68:71]
	v_mfma_f32_16x16x32_bf16 v[64:67], v[226:229], v[210:213], v[64:67]
	s_setprio 0
	s_barrier
	ds_read_b128 v[96:99], v190 offset:49152
	ds_read_b128 v[100:103], v190 offset:50176
	ds_read_b128 v[108:111], v190 offset:51200
	ds_read_b128 v[112:115], v190 offset:52224
	ds_read_b128 v[160:163], v190 offset:53248
	ds_read_b128 v[164:167], v190 offset:54272
	ds_read_b128 v[198:201], v190 offset:55296
	ds_read_b128 v[202:205], v190 offset:56320
	global_load_lds_dwordx4 v[184:185], off
	v_lshl_add_u64 v[184:185], v[232:233], 0, s[14:15]
	s_mov_b32 m0, s63
	s_nop 0
	global_load_lds_dwordx4 v[184:185], off
	s_waitcnt vmcnt(10)
	s_barrier
; #define PG8_STAGE(bufoff, gbase, voff) do { _Pragma("unroll") for (int _i = 0; _i < 2; ++_i) \
;         __builtin_amdgcn_global_load_lds((const unsigned*)((const char*)(gbase) + (voff)[_i]), (LAS unsigned*)(lds + (bufoff) + ldsw + _i * 8192), 16, 0, 0); } while (0)
; #define PG8_LDA(dst, b, h) do { _Pragma("unroll") for (int m = 0; m < 4; ++m) _Pragma("unroll") for (int k = 0; k < 2; ++k) dst[m][k] = *(const LAS bf16x8*)(lds + PG8_SA(b, h) + aoff + m * 2048 + k * 1024); } while (0)
; #define PG8_MMA(ai, bj, At, Bt) do { __builtin_amdgcn_s_setprio(1); _Pragma("unroll") for (int m = 0; m < 4; ++m) _Pragma("unroll") for (int n = 0; n < 2; ++n) _Pragma("unroll") for (int k = 0; k < 2; ++k) \
;         acc[ai][bj][m][n] = __builtin_amdgcn_mfma_f32_16x16x32_bf16(Bt[n][k], At[m][k], acc[ai][bj][m][n], 0, 0, 0); __builtin_amdgcn_s_setprio(0); } while (0)
; #define PG8_WAIT_V(n) asm volatile("s_waitcnt vmcnt(" #n ")" ::: "memory")
; #define PG8_WAIT_L(n) asm volatile("s_waitcnt lgkmcnt(" #n ")" ::: "memory")
; #define PG8_BAR __builtin_amdgcn_s_barrier()
; #define PG8_SCHED __builtin_amdgcn_sched_barrier(0)
; template <class Map, class Epi>
; DI void gemm_phase(LAS unsigned char* lds, const Map& MP, const Epi& E, const int nM, const int nN, const int K, const int lda, const int ldb) {
;     ...
;             PG8_BAR; PG8_WAIT_L(0); PG8_MMA(0, 1, At, B1); PG8_BAR;
;             PG8_LDA(At, 1, 1); PG8_STAGE(PG8_SA(1, 0), a3, voffA);
;             PG8_BAR; PG8_WAIT_L(0); PG8_MMA(1, 0, At, B0); PG8_BAR; PG8_SCHED;
;             PG8_STAGE(PG8_SB(1, 1), b3 + hstepB, voffB);
;             PG8_WAIT_V(6); PG8_BAR; PG8_MMA(1, 1, At, B1); PG8_BAR;
;         }
	s_setprio 1
	s_waitcnt lgkmcnt(7)
	v_mfma_f32_16x16x32_bf16 v[60:63], v[80:83], v[96:99], v[60:63]
	v_mfma_f32_16x16x32_bf16 v[48:51], v[88:91], v[96:99], v[48:51]
	s_waitcnt lgkmcnt(5)
	v_mfma_f32_16x16x32_bf16 v[40:43], v[80:83], v[108:111], v[40:43]
	v_mfma_f32_16x16x32_bf16 v[32:35], v[88:91], v[108:111], v[32:35]
	s_waitcnt lgkmcnt(3)
	v_mfma_f32_16x16x32_bf16 v[24:27], v[80:83], v[160:163], v[24:27]
	v_mfma_f32_16x16x32_bf16 v[16:19], v[88:91], v[160:163], v[16:19]
	s_waitcnt lgkmcnt(1)
	v_mfma_f32_16x16x32_bf16 v[12:15], v[80:83], v[198:201], v[12:15]
	v_mfma_f32_16x16x32_bf16 v[8:11], v[88:91], v[198:201], v[8:11]
	v_mfma_f32_16x16x32_bf16 v[60:63], v[84:87], v[100:103], v[60:63]
	v_mfma_f32_16x16x32_bf16 v[48:51], v[92:95], v[100:103], v[48:51]
	v_mfma_f32_16x16x32_bf16 v[40:43], v[84:87], v[112:115], v[40:43]
	v_mfma_f32_16x16x32_bf16 v[32:35], v[92:95], v[112:115], v[32:35]
	v_mfma_f32_16x16x32_bf16 v[24:27], v[84:87], v[164:167], v[24:27]
	v_mfma_f32_16x16x32_bf16 v[16:19], v[92:95], v[164:167], v[16:19]
	s_waitcnt lgkmcnt(0)
	v_mfma_f32_16x16x32_bf16 v[12:15], v[84:87], v[202:205], v[12:15]
	v_mfma_f32_16x16x32_bf16 v[8:11], v[92:95], v[202:205], v[8:11]
	s_setprio 0
	s_barrier
	s_add_u32 s28, s28, 0x80080
	s_addc_u32 s29, s29, 0
	s_add_i32 s46, s46, s37
	s_mov_b32 m0, s46
	s_nop 0
	global_load_lds_dwordx4 v172, s[28:29]
	s_add_i32 m0, s46, 0x2000
	s_nop 0
	global_load_lds_dwordx4 v168, s[28:29]
	s_waitcnt vmcnt(6)
	s_barrier
	s_setprio 1
	v_mfma_f32_16x16x32_bf16 v[56:59], v[214:217], v[96:99], v[56:59]
	v_mfma_f32_16x16x32_bf16 v[52:55], v[222:225], v[96:99], v[52:55]
	ds_read_b128 v[80:83], v189
	v_mfma_f32_16x16x32_bf16 v[44:47], v[214:217], v[108:111], v[44:47]
	v_mfma_f32_16x16x32_bf16 v[36:39], v[222:225], v[108:111], v[36:39]
	ds_read_b128 v[84:87], v189 offset:1024
	v_mfma_f32_16x16x32_bf16 v[28:31], v[214:217], v[160:163], v[28:31]
	v_mfma_f32_16x16x32_bf16 v[20:23], v[222:225], v[160:163], v[20:23]
	ds_read_b128 v[88:91], v189 offset:2048
	v_mfma_f32_16x16x32_bf16 v[4:7], v[214:217], v[198:201], v[4:7]
	v_mfma_f32_16x16x32_bf16 v[0:3], v[222:225], v[198:201], v[0:3]
	ds_read_b128 v[92:95], v189 offset:3072
	v_mfma_f32_16x16x32_bf16 v[56:59], v[218:221], v[100:103], v[56:59]
	s_add_i32 s3, s3, 2
	v_mfma_f32_16x16x32_bf16 v[52:55], v[226:229], v[100:103], v[52:55]
	s_add_u32 vcc_lo, vcc_lo, 0x100
	s_addc_u32 vcc_hi, vcc_hi, 0
	v_mfma_f32_16x16x32_bf16 v[44:47], v[218:221], v[112:115], v[44:47]
	s_add_u32 s42, s42, 0x100
	s_addc_u32 s43, s43, 0
	v_mfma_f32_16x16x32_bf16 v[36:39], v[226:229], v[112:115], v[36:39]
	s_cmp_gt_u32 s3, 29
	v_mfma_f32_16x16x32_bf16 v[28:31], v[218:221], v[164:167], v[28:31]
	v_mfma_f32_16x16x32_bf16 v[20:23], v[226:229], v[164:167], v[20:23]
	v_mfma_f32_16x16x32_bf16 v[4:7], v[218:221], v[202:205], v[4:7]
	v_mfma_f32_16x16x32_bf16 v[0:3], v[226:229], v[202:205], v[0:3]
	s_setprio 0
	s_barrier
	s_cbranch_scc0 .LBB1_2483
; DI float silu_mul(float g, float v) { return g * v * __builtin_amdgcn_rcpf(1.0f + __builtin_amdgcn_exp2f(-LOG2E * g)); }
;     DI void operator()(const f32x4 (&acc)[2][2][4][2], const Unit& u, int wr, int wc, int fr, int fq) const {
;         const int row0 = u.pm * BM + wr * 64 + fr, ch0 = u.pn * 128 + wc * 32 + 8 * fq;
;         f32x4 w0[2], w1[2], w2[2], bb[2];
; #pragma unroll
;         for (int n = 0; n < 2; ++n) { w0[n] = *(const f32x4*)(cw + ch0 + 4 * n); w1[n] = *(const f32x4*)(cw + DFF + ch0 + 4 * n); w2[n] = *(const f32x4*)(cw + 2 * DFF + ch0 + 4 * n); bb[n] = *(const f32x4*)(cb + ch0 + 4 * n); }
; #pragma unroll
;         for (int ai = 0; ai < 2; ++ai)
; #pragma unroll
;             for (int m = 0; m < 4; ++m) {
;                 const bool efirst = (m == 0) && (fr == 0), elast = (m == 3) && (fr == 15);
;                 const int row = row0 + ai * HALF + m * 16;
;                 f32x4 gc[2];
; #pragma unroll
;                 for (int n = 0; n < 2; ++n) {
;                     const f32x4 g = acc[ai][0][m][n];
;                     const f32x4 gprev = acc[ai][0][m > 0 ? m - 1 : 0][n], gnext = acc[ai][0][m < 3 ? m + 1 : 3][n];
;                     f32x4 up, dn;
; #pragma unroll
;                     for (int e = 0; e < 4; ++e) {
;                         const float pu = (m > 0 && fr == 15) ? gprev[e] : g[e];
;                         const float pd = (m < 3 && fr == 0) ? gnext[e] : g[e];
;                         up[e] = dpp_ror1(pu); dn[e] = dpp_ror15(pd);
;                     }
;                     if (efirst) up = (f32x4){0.f, 0.f, 0.f, 0.f};
;                     if (elast) dn = (f32x4){0.f, 0.f, 0.f, 0.f};
;                     gc[n] = w0[n] * up + w1[n] * g + w2[n] * dn + bb[n];
;                 }
;                 if (efirst || elast) {
;                     const size_t eo = (size_t)((row >> 6) * 2 + (elast ? 1 : 0)) * DFF + ch0;
; #pragma unroll
;                     for (int n = 0; n < 2; ++n) { *(f32x4*)(EP + eo + 4 * n) = gc[n]; *(f32x4*)(ER + eo + 4 * n) = acc[ai][0][m][n]; *(f32x4*)(EV + eo + 4 * n) = acc[ai][1][m][n]; }
;                 } else {
;                     const f32x4 v0 = acc[ai][1][m][0], v1 = acc[ai][1][m][1];
;                     u32x4 o;
;                     o[0] = pack2(silu_mul(gc[0][0], v0[0]), silu_mul(gc[0][1], v0[1])); o[1] = pack2(silu_mul(gc[0][2], v0[2]), silu_mul(gc[0][3], v0[3]));
	s_waitcnt lgkmcnt(0)
	s_lshl_b32 s21, s45, 7
	v_mov_b32_e32 v80, v187
	v_mov_b32_e32 v194, v186
	s_or_b32 s21, s21, s57
	v_mov_b32_e32 v160, 0
	v_lshl_add_u32 v184, v80, 3, s21
	v_ashrrev_i32_e32 v185, 31, v184
	v_lshlrev_b64 v[80:81], 2, v[184:185]
	v_lshl_add_u64 v[84:85], s[4:5], 0, v[80:81]
	v_lshl_add_u64 v[88:89], s[16:17], 0, v[80:81]
	v_lshl_add_u64 v[92:93], s[18:19], 0, v[80:81]
	v_lshl_add_u64 v[112:113], s[6:7], 0, v[80:81]
	global_load_dwordx4 v[80:83], v[84:85], off offset:16
	global_load_dwordx4 v[96:99], v[84:85], off
	s_nop 0
	global_load_dwordx4 v[84:87], v[88:89], off offset:16
	global_load_dwordx4 v[100:103], v[88:89], off
	s_nop 0
	global_load_dwordx4 v[88:91], v[92:93], off offset:16
	global_load_dwordx4 v[108:111], v[92:93], off
	s_nop 0
	global_load_dwordx4 v[92:95], v[112:113], off offset:16
	s_nop 0
	global_load_dwordx4 v[112:115], v[112:113], off
	v_cmp_eq_u32_e32 vcc, 0, v194
	v_mov_b32_e32 v164, 0
	v_mov_b32_e32 v195, 0
	v_cndmask_b32_e32 v161, v148, v136, vcc
	v_cndmask_b32_e32 v162, v149, v137, vcc
	v_cndmask_b32_e32 v163, v150, v138, vcc
	v_mov_b32_dpp v160, v161 row_ror:15 row_mask:0xf bank_mask:0xf
	v_mov_b32_e32 v161, 0
	v_mov_b32_e32 v166, 0
	v_mov_b32_e32 v167, 0
	v_mov_b32_dpp v161, v162 row_ror:15 row_mask:0xf bank_mask:0xf
	v_mov_b32_e32 v162, 0
	v_mov_b32_dpp v164, v150 row_ror:1 row_mask:0xf bank_mask:0xf
	v_cndmask_b32_e32 v165, v151, v139, vcc
	v_mov_b32_dpp v162, v163 row_ror:15 row_mask:0xf bank_mask:0xf
	v_mov_b32_dpp v195, v151 row_ror:1 row_mask:0xf bank_mask:0xf
	v_mov_b32_e32 v163, 0
	v_mov_b32_dpp v166, v148 row_ror:1 row_mask:0xf bank_mask:0xf
	v_mov_b32_dpp v167, v149 row_ror:1 row_mask:0xf bank_mask:0xf
	v_mov_b32_dpp v163, v165 row_ror:15 row_mask:0xf bank_mask:0xf
	v_cndmask_b32_e64 v165, v195, 0, vcc
	v_cndmask_b32_e64 v164, v164, 0, vcc
	v_cndmask_b32_e64 v167, v167, 0, vcc
	v_cndmask_b32_e64 v166, v166, 0, vcc
	v_mov_b32_e32 v195, 0
	v_mov_b32_e32 v196, 0
	v_mov_b32_e32 v198, 0
	v_mov_b32_e32 v200, 0
	v_mov_b32_dpp v195, v144 row_ror:1 row_mask:0xf bank_mask:0xf
	v_mov_b32_dpp v196, v145 row_ror:1 row_mask:0xf bank_mask:0xf
	v_mov_b32_dpp v198, v146 row_ror:1 row_mask:0xf bank_mask:0xf
	v_cndmask_b32_e32 v199, v147, v131, vcc
	v_mov_b32_dpp v200, v147 row_ror:1 row_mask:0xf bank_mask:0xf
	v_cndmask_b32_e64 v198, v198, 0, vcc
	v_cndmask_b32_e64 v201, v196, 0, vcc
	s_lshl_b32 s3, s44, 8
	s_add_i32 s3, s3, s49
	v_add_u32_e32 v193, s3, v194
	v_cmp_ne_u32_e64 s[46:47], 0, v194
	s_waitcnt vmcnt(0)
	v_pk_mul_f32 v[164:165], v[98:99], v[164:165]
	v_pk_mul_f32 v[166:167], v[96:97], v[166:167]
	v_pk_fma_f32 v[164:165], v[150:151], v[102:103], v[164:165]
	v_pk_fma_f32 v[166:167], v[148:149], v[100:101], v[166:167]
	v_pk_fma_f32 v[162:163], v[110:111], v[162:163], v[164:165]
	v_cndmask_b32_e32 v165, v144, v128, vcc
	v_mov_b32_e32 v164, 0
	v_pk_fma_f32 v[160:161], v[108:109], v[160:161], v[166:167]
	v_cndmask_b32_e32 v166, v145, v129, vcc
	v_mov_b32_dpp v164, v165 row_ror:15 row_mask:0xf bank_mask:0xf
	v_mov_b32_e32 v165, 0
	v_cndmask_b32_e32 v167, v146, v130, vcc
	v_pk_add_f32 v[162:163], v[114:115], v[162:163]
	v_mov_b32_dpp v165, v166 row_ror:15 row_mask:0xf bank_mask:0xf
	v_mov_b32_e32 v166, 0
	v_pk_add_f32 v[160:161], v[112:113], v[160:161]
	s_nop 0
	v_mov_b32_dpp v166, v167 row_ror:15 row_mask:0xf bank_mask:0xf
	v_mov_b32_e32 v167, 0
	s_nop 1
	v_mov_b32_dpp v167, v199 row_ror:15 row_mask:0xf bank_mask:0xf
	v_cndmask_b32_e64 v199, v200, 0, vcc
	v_cndmask_b32_e64 v200, v195, 0, vcc
	v_pk_mul_f32 v[200:201], v[80:81], v[200:201]
	v_pk_mul_f32 v[198:199], v[82:83], v[198:199]
	v_pk_fma_f32 v[200:201], v[144:145], v[84:85], v[200:201]
	v_pk_fma_f32 v[198:199], v[146:147], v[86:87], v[198:199]
	v_pk_fma_f32 v[164:165], v[88:89], v[164:165], v[200:201]
	v_pk_fma_f32 v[166:167], v[90:91], v[166:167], v[198:199]
	v_pk_add_f32 v[164:165], v[92:93], v[164:165]
	v_pk_add_f32 v[166:167], v[94:95], v[166:167]
	s_and_saveexec_b64 s[28:29], s[46:47]
	s_xor_b64 s[28:29], exec, s[28:29]
	s_cbranch_execz .LBB1_2486
	v_mul_f32_e32 v195, 0xbfb8aa3b, v160
	v_exp_f32_e32 v195, v195
	v_mul_f32_e32 v196, 0xbfb8aa3b, v161
	v_exp_f32_e32 v196, v196
	v_pk_mul_f32 v[160:161], v[156:157], v[160:161]
	v_add_f32_e32 v195, 1.0, v195
	v_rcp_f32_e32 v198, v195
	v_add_f32_e32 v196, 1.0, v196
	v_mul_f32_e32 v195, 0xbfb8aa3b, v162
	v_rcp_f32_e32 v199, v196
	v_exp_f32_e32 v195, v195
	v_mul_f32_e32 v196, 0xbfb8aa3b, v163
	v_exp_f32_e32 v196, v196
	v_pk_mul_f32 v[160:161], v[160:161], v[198:199]
	v_add_f32_e32 v195, 1.0, v195
	v_rcp_f32_e32 v200, v195
	v_add_f32_e32 v195, 1.0, v196
	v_rcp_f32_e32 v201, v195
	v_cvt_pk_bf16_f32 v160, v160, v161
	v_mul_f32_e32 v161, 0xbfb8aa3b, v164
	v_exp_f32_e32 v195, v161
	v_mul_f32_e32 v161, 0xbfb8aa3b, v165
	v_exp_f32_e32 v196, v161
	v_pk_mul_f32 v[162:163], v[158:159], v[162:163]
	v_pk_mul_f32 v[164:165], v[152:153], v[164:165]
	v_pk_mul_f32 v[162:163], v[162:163], v[200:201]
	s_nop 0
	v_cvt_pk_bf16_f32 v161, v162, v163
	v_add_f32_e32 v162, 1.0, v195
	v_mul_f32_e32 v195, 0xbfb8aa3b, v166
	v_add_f32_e32 v163, 1.0, v196
	v_exp_f32_e32 v195, v195
	v_mul_f32_e32 v196, 0xbfb8aa3b, v167
	v_exp_f32_e32 v196, v196
	v_rcp_f32_e32 v162, v162
	v_add_f32_e32 v195, 1.0, v195
	v_rcp_f32_e32 v198, v195
	v_add_f32_e32 v195, 1.0, v196
	v_rcp_f32_e32 v163, v163
	v_rcp_f32_e32 v199, v195
	v_pk_mul_f32 v[166:167], v[154:155], v[166:167]
	v_pk_mul_f32 v[162:163], v[164:165], v[162:163]
	v_pk_mul_f32 v[164:165], v[166:167], v[198:199]
	v_cvt_pk_bf16_f32 v162, v162, v163
	v_cvt_pk_bf16_f32 v163, v164, v165
	v_mov_b64_e32 v[164:165], s[52:53]
	v_mad_i64_i32 v[164:165], s[42:43], v193, s60, v[164:165]
	v_lshl_add_u64 v[164:165], v[184:185], 1, v[164:165]
	global_store_dwordx4 v[164:165], v[160:163], off

; #define PG8_STAGE(bufoff, gbase, voff) do { _Pragma("unroll") for (int _i = 0; _i < 2; ++_i) \
;         __builtin_amdgcn_global_load_lds((const unsigned*)((const char*)(gbase) + (voff)[_i]), (LAS unsigned*)(lds + (bufoff) + ldsw + _i * 8192), 16, 0, 0); } while (0)
; #define PG8_LDA(dst, b, h) do { _Pragma("unroll") for (int m = 0; m < 4; ++m) _Pragma("unroll") for (int k = 0; k < 2; ++k) dst[m][k] = *(const LAS bf16x8*)(lds + PG8_SA(b, h) + aoff + m * 2048 + k * 1024); } while (0)
; #define PG8_LDB(dst, b, h) do { _Pragma("unroll") for (int n = 0; n < 2; ++n) _Pragma("unroll") for (int k = 0; k < 2; ++k) dst[n][k] = *(const LAS bf16x8*)(lds + PG8_SB(b, h) + boff + n * 2048 + k * 1024); } while (0)
; #define PG8_MMA(ai, bj, At, Bt) do { __builtin_amdgcn_s_setprio(1); _Pragma("unroll") for (int m = 0; m < 4; ++m) _Pragma("unroll") for (int n = 0; n < 2; ++n) _Pragma("unroll") for (int k = 0; k < 2; ++k) \
;         acc[ai][bj][m][n] = __builtin_amdgcn_mfma_f32_16x16x32_bf16(Bt[n][k], At[m][k], acc[ai][bj][m][n], 0, 0, 0); __builtin_amdgcn_s_setprio(0); } while (0)
; #define PG8_WAIT_V(n) asm volatile("s_waitcnt vmcnt(" #n ")" ::: "memory")
; #define PG8_WAIT_L(n) asm volatile("s_waitcnt lgkmcnt(" #n ")" ::: "memory")
; template <class Map, class Epi>
; DI void gemm_phase(LAS unsigned char* lds, const Map& MP, const Epi& E, const int nM, const int nN, const int K, const int lda, const int ldb) {
;     ...
;         for (int t = 0; t < nt; t += 2) {
;             const bool last = (t == nt - 2);
;             const char* a1 = cA + (size_t)(t + 1) * kstep;
;             const char* a2 = last ? nA : cA + (size_t)(t + 2) * kstep; const char* b2 = last ? nB : cB + (size_t)(t + 2) * kstep;
;             const char* a3 = a2 + kstep; const char* b3 = b2 + kstep;
;             PG8_LDB(B0, 0, 0); PG8_SCHED; PG8_LDA(At, 0, 0); PG8_STAGE(PG8_SA(1, 1), a1 + hstepA, voffA);
;             PG8_WAIT_L(8); PG8_BAR; PG8_WAIT_L(0); PG8_MMA(0, 0, At, B0); PG8_BAR; PG8_SCHED;
;             PG8_LDB(B1, 0, 1); PG8_STAGE(PG8_SB(0, 0), b2, voffB);
;             PG8_BAR; PG8_WAIT_L(0); PG8_MMA(0, 1, At, B1); PG8_BAR;
;             PG8_LDA(At, 0, 1); PG8_STAGE(PG8_SA(0, 0), a2, voffA);
;             PG8_BAR; PG8_WAIT_L(0); PG8_MMA(1, 0, At, B0); PG8_BAR; PG8_SCHED;
;             PG8_STAGE(PG8_SB(0, 1), b2 + hstepB, voffB);
;             PG8_WAIT_V(6); PG8_BAR; PG8_MMA(1, 1, At, B1); PG8_BAR;
.LBB1_2653:
	s_add_u32 s10, s8, 0x100
	s_addc_u32 s11, s9, 0
	s_cmpk_eq_i32 s48, 0x54
	s_cselect_b32 s15, s43, s11
	s_cselect_b32 s14, s42, s10
	s_cselect_b32 s13, s45, s39
	s_cselect_b32 s12, s44, s38
	s_add_i32 m0, s22, 0xc000
	ds_read_b128 v[168:171], v150
	ds_read_b128 v[172:175], v150 offset:1024
	ds_read_b128 v[176:179], v150 offset:2048
	ds_read_b128 v[180:183], v150 offset:3072
	ds_read_b128 v[184:187], v150 offset:4096
	ds_read_b128 v[188:191], v150 offset:5120
	ds_read_b128 v[192:195], v150 offset:6144
	ds_read_b128 v[196:199], v150 offset:7168
	global_load_lds_dwordx4 v138, s[8:9]
	s_add_i32 m0, s22, 0xe000
	s_nop 0
	global_load_lds_dwordx4 v136, s[8:9]
	s_waitcnt lgkmcnt(8)
	s_barrier
	s_setprio 1
	s_waitcnt lgkmcnt(7)
	v_mfma_f32_16x16x32_bf16 v[124:127], v[152:155], v[168:171], v[124:127]
	v_mfma_f32_16x16x32_bf16 v[120:123], v[160:163], v[168:171], v[120:123]
	s_waitcnt lgkmcnt(5)
	v_mfma_f32_16x16x32_bf16 v[108:111], v[152:155], v[176:179], v[108:111]
	v_mfma_f32_16x16x32_bf16 v[104:107], v[160:163], v[176:179], v[104:107]
	s_waitcnt lgkmcnt(3)
	v_mfma_f32_16x16x32_bf16 v[92:95], v[152:155], v[184:187], v[92:95]
	v_mfma_f32_16x16x32_bf16 v[88:91], v[160:163], v[184:187], v[88:91]
	s_waitcnt lgkmcnt(1)
	v_mfma_f32_16x16x32_bf16 v[76:79], v[152:155], v[192:195], v[76:79]
	v_mfma_f32_16x16x32_bf16 v[72:75], v[160:163], v[192:195], v[72:75]
	v_mfma_f32_16x16x32_bf16 v[124:127], v[156:159], v[172:175], v[124:127]
	v_mfma_f32_16x16x32_bf16 v[120:123], v[164:167], v[172:175], v[120:123]
	v_mfma_f32_16x16x32_bf16 v[108:111], v[156:159], v[180:183], v[108:111]
	v_mfma_f32_16x16x32_bf16 v[104:107], v[164:167], v[180:183], v[104:107]
	v_mfma_f32_16x16x32_bf16 v[92:95], v[156:159], v[188:191], v[92:95]
	v_mfma_f32_16x16x32_bf16 v[88:91], v[164:167], v[188:191], v[88:91]
	s_waitcnt lgkmcnt(0)
	v_mfma_f32_16x16x32_bf16 v[76:79], v[156:159], v[196:199], v[76:79]
	v_mfma_f32_16x16x32_bf16 v[72:75], v[164:167], v[196:199], v[72:75]
	s_setprio 0
	s_barrier
	s_add_i32 s8, s33, s20
	v_lshl_add_u64 v[144:145], s[12:13], 0, v[132:133]
	s_mov_b32 m0, s8
	ds_read_b128 v[200:203], v151
	ds_read_b128 v[204:207], v151 offset:1024
	ds_read_b128 v[208:211], v151 offset:2048
	ds_read_b128 v[212:215], v151 offset:3072
	global_load_lds_dwordx4 v[144:145], off
	v_lshl_add_u64 v[216:217], s[12:13], 0, v[128:129]
	s_add_i32 m0, s8, 0x2000
	s_nop 0
	global_load_lds_dwordx4 v[216:217], off
	s_barrier
	s_setprio 1
	s_waitcnt lgkmcnt(3)
	v_mfma_f32_16x16x32_bf16 v[116:119], v[200:203], v[168:171], v[116:119]
	s_waitcnt lgkmcnt(1)
	v_mfma_f32_16x16x32_bf16 v[112:115], v[208:211], v[168:171], v[112:115]
	v_mfma_f32_16x16x32_bf16 v[100:103], v[200:203], v[176:179], v[100:103]
	v_mfma_f32_16x16x32_bf16 v[96:99], v[208:211], v[176:179], v[96:99]
	v_mfma_f32_16x16x32_bf16 v[84:87], v[200:203], v[184:187], v[84:87]
	v_mfma_f32_16x16x32_bf16 v[80:83], v[208:211], v[184:187], v[80:83]
	v_mfma_f32_16x16x32_bf16 v[68:71], v[200:203], v[192:195], v[68:71]
	v_mfma_f32_16x16x32_bf16 v[64:67], v[208:211], v[192:195], v[64:67]
	v_mfma_f32_16x16x32_bf16 v[116:119], v[204:207], v[172:175], v[116:119]
	s_mov_b32 m0, s22
	s_waitcnt lgkmcnt(0)
	v_mfma_f32_16x16x32_bf16 v[112:115], v[212:215], v[172:175], v[112:115]
	v_lshl_add_u64 v[218:219], s[14:15], 0, v[134:135]
	v_mfma_f32_16x16x32_bf16 v[100:103], v[204:207], v[180:183], v[100:103]
	v_mfma_f32_16x16x32_bf16 v[96:99], v[212:215], v[180:183], v[96:99]
	v_mfma_f32_16x16x32_bf16 v[84:87], v[204:207], v[188:191], v[84:87]
	v_mfma_f32_16x16x32_bf16 v[80:83], v[212:215], v[188:191], v[80:83]
	v_mfma_f32_16x16x32_bf16 v[68:71], v[204:207], v[196:199], v[68:71]
	v_mfma_f32_16x16x32_bf16 v[64:67], v[212:215], v[196:199], v[64:67]
	s_setprio 0
	s_barrier
	ds_read_b128 v[168:171], v150 offset:16384
	ds_read_b128 v[172:175], v150 offset:17408
	ds_read_b128 v[176:179], v150 offset:18432
	ds_read_b128 v[180:183], v150 offset:19456
	ds_read_b128 v[184:187], v150 offset:20480
	ds_read_b128 v[188:191], v150 offset:21504
	ds_read_b128 v[192:195], v150 offset:22528
	ds_read_b128 v[196:199], v150 offset:23552
	global_load_lds_dwordx4 v[218:219], off
	v_lshl_add_u64 v[220:221], s[14:15], 0, v[130:131]
	s_mov_b32 m0, s23
	s_nop 0
	global_load_lds_dwordx4 v[220:221], off
	s_waitcnt vmcnt(10)
	s_barrier
	s_setprio 1
	s_waitcnt lgkmcnt(7)
	v_mfma_f32_16x16x32_bf16 v[60:63], v[152:155], v[168:171], v[60:63]
	v_mfma_f32_16x16x32_bf16 v[56:59], v[160:163], v[168:171], v[56:59]
	s_waitcnt lgkmcnt(5)
	v_mfma_f32_16x16x32_bf16 v[44:47], v[152:155], v[176:179], v[44:47]
	v_mfma_f32_16x16x32_bf16 v[40:43], v[160:163], v[176:179], v[40:43]
	s_waitcnt lgkmcnt(3)
	v_mfma_f32_16x16x32_bf16 v[28:31], v[152:155], v[184:187], v[28:31]
	v_mfma_f32_16x16x32_bf16 v[24:27], v[160:163], v[184:187], v[24:27]
	s_waitcnt lgkmcnt(1)
	v_mfma_f32_16x16x32_bf16 v[12:15], v[152:155], v[192:195], v[12:15]
	v_mfma_f32_16x16x32_bf16 v[8:11], v[160:163], v[192:195], v[8:11]
	v_mfma_f32_16x16x32_bf16 v[60:63], v[156:159], v[172:175], v[60:63]
	v_mfma_f32_16x16x32_bf16 v[56:59], v[164:167], v[172:175], v[56:59]
	v_mfma_f32_16x16x32_bf16 v[44:47], v[156:159], v[180:183], v[44:47]
	v_mfma_f32_16x16x32_bf16 v[40:43], v[164:167], v[180:183], v[40:43]
	v_mfma_f32_16x16x32_bf16 v[28:31], v[156:159], v[188:191], v[28:31]
	v_mfma_f32_16x16x32_bf16 v[24:27], v[164:167], v[188:191], v[24:27]
	s_waitcnt lgkmcnt(0)
	v_mfma_f32_16x16x32_bf16 v[12:15], v[156:159], v[196:199], v[12:15]
	v_mfma_f32_16x16x32_bf16 v[8:11], v[164:167], v[196:199], v[8:11]
	s_setprio 0
	s_barrier
; #define PG8_STAGE(bufoff, gbase, voff) do { _Pragma("unroll") for (int _i = 0; _i < 2; ++_i) \
;         __builtin_amdgcn_global_load_lds((const unsigned*)((const char*)(gbase) + (voff)[_i]), (LAS unsigned*)(lds + (bufoff) + ldsw + _i * 8192), 16, 0, 0); } while (0)
; #define PG8_LDA(dst, b, h) do { _Pragma("unroll") for (int m = 0; m < 4; ++m) _Pragma("unroll") for (int k = 0; k < 2; ++k) dst[m][k] = *(const LAS bf16x8*)(lds + PG8_SA(b, h) + aoff + m * 2048 + k * 1024); } while (0)
; #define PG8_LDB(dst, b, h) do { _Pragma("unroll") for (int n = 0; n < 2; ++n) _Pragma("unroll") for (int k = 0; k < 2; ++k) dst[n][k] = *(const LAS bf16x8*)(lds + PG8_SB(b, h) + boff + n * 2048 + k * 1024); } while (0)
; #define PG8_MMA(ai, bj, At, Bt) do { __builtin_amdgcn_s_setprio(1); _Pragma("unroll") for (int m = 0; m < 4; ++m) _Pragma("unroll") for (int n = 0; n < 2; ++n) _Pragma("unroll") for (int k = 0; k < 2; ++k) \
;         acc[ai][bj][m][n] = __builtin_amdgcn_mfma_f32_16x16x32_bf16(Bt[n][k], At[m][k], acc[ai][bj][m][n], 0, 0, 0); __builtin_amdgcn_s_setprio(0); } while (0)
; #define PG8_WAIT_V(n) asm volatile("s_waitcnt vmcnt(" #n ")" ::: "memory")
; #define PG8_WAIT_L(n) asm volatile("s_waitcnt lgkmcnt(" #n ")" ::: "memory")
; #define PG8_BAR __builtin_amdgcn_s_barrier()
; #define PG8_SCHED __builtin_amdgcn_sched_barrier(0)
; template <class Map, class Epi>
; DI void gemm_phase(LAS unsigned char* lds, const Map& MP, const Epi& E, const int nM, const int nN, const int K, const int lda, const int ldb) {
;     ...
;             PG8_BAR; PG8_WAIT_L(0); PG8_MMA(1, 0, At, B0); PG8_BAR; PG8_SCHED;
;             PG8_STAGE(PG8_SB(0, 1), b2 + hstepB, voffB);
;             PG8_WAIT_V(6); PG8_BAR; PG8_MMA(1, 1, At, B1); PG8_BAR;
;             PG8_LDB(B0, 1, 0); PG8_SCHED; PG8_LDA(At, 1, 0); PG8_STAGE(PG8_SA(0, 1), a2 + hstepA, voffA);
;             PG8_WAIT_L(8); PG8_BAR; PG8_WAIT_L(0); PG8_MMA(0, 0, At, B0); PG8_BAR; PG8_SCHED;
;             PG8_LDB(B1, 1, 1); PG8_STAGE(PG8_SB(1, 0), b3, voffB);
;             PG8_BAR; PG8_WAIT_L(0); PG8_MMA(0, 1, At, B1); PG8_BAR;
;             PG8_LDA(At, 1, 1); PG8_STAGE(PG8_SA(1, 0), a3, voffA);
;             PG8_BAR; PG8_WAIT_L(0); PG8_MMA(1, 0, At, B0); PG8_BAR; PG8_SCHED;
;             PG8_STAGE(PG8_SB(1, 1), b3 + hstepB, voffB);
	s_add_u32 s8, s12, 0x160000
	s_addc_u32 s9, s13, 0
	s_add_i32 s49, s34, s20
	s_mov_b32 m0, s49
	s_nop 0
	global_load_lds_dwordx4 v132, s[8:9]
	s_add_i32 m0, s49, 0x2000
	s_nop 0
	global_load_lds_dwordx4 v128, s[8:9]
	s_waitcnt vmcnt(6)
	s_barrier
	s_setprio 1
	v_mfma_f32_16x16x32_bf16 v[52:55], v[200:203], v[168:171], v[52:55]
	v_mfma_f32_16x16x32_bf16 v[48:51], v[208:211], v[168:171], v[48:51]
	s_add_i32 s49, 0, 0x18000
	v_add_u32_e32 v164, s49, v148
	ds_read_b128 v[152:155], v164
	v_mfma_f32_16x16x32_bf16 v[36:39], v[200:203], v[176:179], v[36:39]
	v_mfma_f32_16x16x32_bf16 v[32:35], v[208:211], v[176:179], v[32:35]
	ds_read_b128 v[156:159], v164 offset:1024
	v_mfma_f32_16x16x32_bf16 v[20:23], v[200:203], v[184:187], v[20:23]
	v_mfma_f32_16x16x32_bf16 v[16:19], v[208:211], v[184:187], v[16:19]
	ds_read_b128 v[160:163], v164 offset:2048
	v_mfma_f32_16x16x32_bf16 v[4:7], v[200:203], v[192:195], v[4:7]
	v_mfma_f32_16x16x32_bf16 v[0:3], v[208:211], v[192:195], v[0:3]
	ds_read_b128 v[164:167], v164 offset:3072
	v_mfma_f32_16x16x32_bf16 v[52:55], v[204:207], v[172:175], v[52:55]
	v_mfma_f32_16x16x32_bf16 v[48:51], v[212:215], v[172:175], v[48:51]
	v_mfma_f32_16x16x32_bf16 v[36:39], v[204:207], v[180:183], v[36:39]
	v_mfma_f32_16x16x32_bf16 v[32:35], v[212:215], v[180:183], v[32:35]
	v_mfma_f32_16x16x32_bf16 v[20:23], v[204:207], v[188:191], v[20:23]
	v_mfma_f32_16x16x32_bf16 v[16:19], v[212:215], v[188:191], v[16:19]
	v_mfma_f32_16x16x32_bf16 v[4:7], v[204:207], v[196:199], v[4:7]
	v_mfma_f32_16x16x32_bf16 v[0:3], v[212:215], v[196:199], v[0:3]
	s_setprio 0
	s_barrier
	s_add_u32 s8, s14, 0x160000
	s_addc_u32 s9, s15, 0
	s_mov_b32 m0, s24
	ds_read_b128 v[168:171], v150 offset:32768
	ds_read_b128 v[172:175], v150 offset:33792
	ds_read_b128 v[176:179], v150 offset:34816
	ds_read_b128 v[180:183], v150 offset:35840
	ds_read_b128 v[184:187], v150 offset:36864
	ds_read_b128 v[188:191], v150 offset:37888
	ds_read_b128 v[192:195], v150 offset:38912
	ds_read_b128 v[196:199], v150 offset:39936
	global_load_lds_dwordx4 v134, s[8:9]
	s_mov_b32 m0, s25
	s_nop 0
	global_load_lds_dwordx4 v130, s[8:9]
	s_waitcnt lgkmcnt(8)
	s_barrier
	s_setprio 1
	s_waitcnt lgkmcnt(7)
	v_mfma_f32_16x16x32_bf16 v[124:127], v[152:155], v[168:171], v[124:127]
	v_mfma_f32_16x16x32_bf16 v[120:123], v[160:163], v[168:171], v[120:123]
	s_waitcnt lgkmcnt(5)
	v_mfma_f32_16x16x32_bf16 v[108:111], v[152:155], v[176:179], v[108:111]
	v_mfma_f32_16x16x32_bf16 v[104:107], v[160:163], v[176:179], v[104:107]
	s_waitcnt lgkmcnt(3)
	v_mfma_f32_16x16x32_bf16 v[92:95], v[152:155], v[184:187], v[92:95]
	v_mfma_f32_16x16x32_bf16 v[88:91], v[160:163], v[184:187], v[88:91]
	s_waitcnt lgkmcnt(1)
	v_mfma_f32_16x16x32_bf16 v[76:79], v[152:155], v[192:195], v[76:79]
	v_mfma_f32_16x16x32_bf16 v[72:75], v[160:163], v[192:195], v[72:75]
	v_mfma_f32_16x16x32_bf16 v[124:127], v[156:159], v[172:175], v[124:127]
	v_mfma_f32_16x16x32_bf16 v[120:123], v[164:167], v[172:175], v[120:123]
	v_mfma_f32_16x16x32_bf16 v[108:111], v[156:159], v[180:183], v[108:111]
	v_mfma_f32_16x16x32_bf16 v[104:107], v[164:167], v[180:183], v[104:107]
	v_mfma_f32_16x16x32_bf16 v[92:95], v[156:159], v[188:191], v[92:95]
	v_mfma_f32_16x16x32_bf16 v[88:91], v[164:167], v[188:191], v[88:91]
	s_waitcnt lgkmcnt(0)
	v_mfma_f32_16x16x32_bf16 v[76:79], v[156:159], v[196:199], v[76:79]
	v_mfma_f32_16x16x32_bf16 v[72:75], v[164:167], v[196:199], v[72:75]
	s_setprio 0
	s_barrier
	s_add_i32 s14, 0, 0x1c000
	s_add_i32 s8, s49, s20
	v_add_u32_e32 v212, s14, v148
	v_lshl_add_u64 v[144:145], v[144:145], 0, s[46:47]
	s_mov_b32 m0, s8
	ds_read_b128 v[200:203], v212
	ds_read_b128 v[204:207], v212 offset:1024
	ds_read_b128 v[208:211], v212 offset:2048
	ds_read_b128 v[212:215], v212 offset:3072
	global_load_lds_dwordx4 v[144:145], off
	v_lshl_add_u64 v[144:145], v[216:217], 0, s[46:47]
	s_add_i32 m0, s8, 0x2000
	s_nop 0
	global_load_lds_dwordx4 v[144:145], off
	s_barrier
	s_setprio 1
	s_waitcnt lgkmcnt(3)
	v_mfma_f32_16x16x32_bf16 v[116:119], v[200:203], v[168:171], v[116:119]
	s_waitcnt lgkmcnt(1)
	v_mfma_f32_16x16x32_bf16 v[112:115], v[208:211], v[168:171], v[112:115]
	v_mfma_f32_16x16x32_bf16 v[100:103], v[200:203], v[176:179], v[100:103]
	v_mfma_f32_16x16x32_bf16 v[96:99], v[208:211], v[176:179], v[96:99]
	v_mfma_f32_16x16x32_bf16 v[84:87], v[200:203], v[184:187], v[84:87]
	v_mfma_f32_16x16x32_bf16 v[80:83], v[208:211], v[184:187], v[80:83]
	v_mfma_f32_16x16x32_bf16 v[68:71], v[200:203], v[192:195], v[68:71]
	v_mfma_f32_16x16x32_bf16 v[64:67], v[208:211], v[192:195], v[64:67]
	v_mfma_f32_16x16x32_bf16 v[116:119], v[204:207], v[172:175], v[116:119]
	s_mov_b32 m0, s29
	s_waitcnt lgkmcnt(0)
	v_mfma_f32_16x16x32_bf16 v[112:115], v[212:215], v[172:175], v[112:115]
	v_lshl_add_u64 v[144:145], v[218:219], 0, s[46:47]
	v_mfma_f32_16x16x32_bf16 v[100:103], v[204:207], v[180:183], v[100:103]
	v_mfma_f32_16x16x32_bf16 v[96:99], v[212:215], v[180:183], v[96:99]
	v_mfma_f32_16x16x32_bf16 v[84:87], v[204:207], v[188:191], v[84:87]
	v_mfma_f32_16x16x32_bf16 v[80:83], v[212:215], v[188:191], v[80:83]
	v_mfma_f32_16x16x32_bf16 v[68:71], v[204:207], v[196:199], v[68:71]
	v_mfma_f32_16x16x32_bf16 v[64:67], v[212:215], v[196:199], v[64:67]
	s_setprio 0
	s_barrier
	ds_read_b128 v[168:171], v150 offset:49152
	ds_read_b128 v[172:175], v150 offset:50176
	ds_read_b128 v[176:179], v150 offset:51200
	ds_read_b128 v[180:183], v150 offset:52224
	ds_read_b128 v[184:187], v150 offset:53248
	ds_read_b128 v[188:191], v150 offset:54272
	ds_read_b128 v[192:195], v150 offset:55296
	ds_read_b128 v[196:199], v150 offset:56320
	global_load_lds_dwordx4 v[144:145], off
	v_lshl_add_u64 v[144:145], v[220:221], 0, s[46:47]
	s_mov_b32 m0, s30
	s_nop 0
	global_load_lds_dwordx4 v[144:145], off
	s_waitcnt vmcnt(10)
	s_barrier
; DI unsigned pack2(float a, float b) { f32x2 v = {a, b}; hwbf16x2 r = __builtin_convertvector(v, hwbf16x2); return __builtin_bit_cast(unsigned, r); }
; DI float bflo(unsigned w) { return __uint_as_float(w << 16); }
; DI float bfhi(unsigned w) { return __uint_as_float(w & 0xffff0000u); }
; #define PG8_STAGE(bufoff, gbase, voff) do { _Pragma("unroll") for (int _i = 0; _i < 2; ++_i) \
;         __builtin_amdgcn_global_load_lds((const unsigned*)((const char*)(gbase) + (voff)[_i]), (LAS unsigned*)(lds + (bufoff) + ldsw + _i * 8192), 16, 0, 0); } while (0)
;     DI void operator()(const f32x4 (&acc)[2][2][4][2], const Unit& u, int wr, int wc, int fr, int fq) const {
;     ...
;         for (int ai = 0; ai < 2; ++ai)
; #pragma unroll
;             for (int m = 0; m < 4; ++m) { const size_t ro = (size_t)(row0 + ai * HALF + m * 16) * D + col0;
; #pragma unroll
;                 for (int bj = 0; bj < 2; ++bj) {
;                     f32x4 x0, x1;
;                     if constexpr (IB) { const u32x4 w = *(const u32x4*)((const bf16_t*)Xin + ro + bj * HALF);
;                         x0 = (f32x4){bflo(w[0]), bfhi(w[0]), bflo(w[1]), bfhi(w[1])}; x1 = (f32x4){bflo(w[2]), bfhi(w[2]), bflo(w[3]), bfhi(w[3])}; }
;                     else { x0 = *(const f32x4*)((const float*)Xin + ro + bj * HALF); x1 = *(const f32x4*)((const float*)Xin + ro + bj * HALF + 4); }
;                     x0 += acc[ai][bj][m][0] * sc[bj][0]; x1 += acc[ai][bj][m][1] * sc[bj][1];
;                     if constexpr (OB) { u32x4 o; o[0] = pack2(x0[0], x0[1]); o[1] = pack2(x0[2], x0[3]); o[2] = pack2(x1[0], x1[1]); o[3] = pack2(x1[2], x1[3]);
;                         *(u32x4*)((bf16_t*)Xout + ro + bj * HALF) = o; }
;                     else { *(f32x4*)((float*)Xout + ro + bj * HALF) = x0; *(f32x4*)((float*)Xout + ro + bj * HALF + 4) = x1; } } }
; template <class Map, class Epi>
; DI void gemm_phase(LAS unsigned char* lds, const Map& MP, const Epi& E, const int nM, const int nN, const int K, const int lda, const int ldb) {
;     ...
;             PG8_BAR; PG8_WAIT_L(0); PG8_MMA(0, 1, At, B1); PG8_BAR;
;             PG8_LDA(At, 1, 1); PG8_STAGE(PG8_SA(1, 0), a3, voffA);
;             PG8_BAR; PG8_WAIT_L(0); PG8_MMA(1, 0, At, B0); PG8_BAR; PG8_SCHED;
;             PG8_STAGE(PG8_SB(1, 1), b3 + hstepB, voffB);
;             PG8_WAIT_V(6); PG8_BAR; PG8_MMA(1, 1, At, B1); PG8_BAR;
;         }
	s_setprio 1
	s_waitcnt lgkmcnt(7)
	v_mfma_f32_16x16x32_bf16 v[60:63], v[152:155], v[168:171], v[60:63]
	v_mfma_f32_16x16x32_bf16 v[56:59], v[160:163], v[168:171], v[56:59]
	s_waitcnt lgkmcnt(5)
	v_mfma_f32_16x16x32_bf16 v[44:47], v[152:155], v[176:179], v[44:47]
	v_mfma_f32_16x16x32_bf16 v[40:43], v[160:163], v[176:179], v[40:43]
	s_waitcnt lgkmcnt(3)
	v_mfma_f32_16x16x32_bf16 v[28:31], v[152:155], v[184:187], v[28:31]
	v_mfma_f32_16x16x32_bf16 v[24:27], v[160:163], v[184:187], v[24:27]
	s_waitcnt lgkmcnt(1)
	v_mfma_f32_16x16x32_bf16 v[12:15], v[152:155], v[192:195], v[12:15]
	v_mfma_f32_16x16x32_bf16 v[8:11], v[160:163], v[192:195], v[8:11]
	v_mfma_f32_16x16x32_bf16 v[60:63], v[156:159], v[172:175], v[60:63]
	v_mfma_f32_16x16x32_bf16 v[56:59], v[164:167], v[172:175], v[56:59]
	v_mfma_f32_16x16x32_bf16 v[44:47], v[156:159], v[180:183], v[44:47]
	v_mfma_f32_16x16x32_bf16 v[40:43], v[164:167], v[180:183], v[40:43]
	v_mfma_f32_16x16x32_bf16 v[28:31], v[156:159], v[188:191], v[28:31]
	v_mfma_f32_16x16x32_bf16 v[24:27], v[164:167], v[188:191], v[24:27]
	s_waitcnt lgkmcnt(0)
	v_mfma_f32_16x16x32_bf16 v[12:15], v[156:159], v[196:199], v[12:15]
	v_mfma_f32_16x16x32_bf16 v[8:11], v[164:167], v[196:199], v[8:11]
	s_setprio 0
	s_barrier
	s_add_u32 s8, s12, 0x160080
	s_addc_u32 s9, s13, 0
	s_add_i32 s12, s14, s20
	s_mov_b32 m0, s12
	s_nop 0
	global_load_lds_dwordx4 v132, s[8:9]
	s_add_i32 m0, s12, 0x2000
	s_nop 0
	global_load_lds_dwordx4 v128, s[8:9]
	s_waitcnt vmcnt(6)
	s_barrier
	s_setprio 1
	v_mfma_f32_16x16x32_bf16 v[52:55], v[200:203], v[168:171], v[52:55]
	v_mfma_f32_16x16x32_bf16 v[48:51], v[208:211], v[168:171], v[48:51]
	ds_read_b128 v[152:155], v149
	v_mfma_f32_16x16x32_bf16 v[36:39], v[200:203], v[176:179], v[36:39]
	v_mfma_f32_16x16x32_bf16 v[32:35], v[208:211], v[176:179], v[32:35]
	ds_read_b128 v[156:159], v149 offset:1024
	v_mfma_f32_16x16x32_bf16 v[20:23], v[200:203], v[184:187], v[20:23]
	v_mfma_f32_16x16x32_bf16 v[16:19], v[208:211], v[184:187], v[16:19]
	ds_read_b128 v[160:163], v149 offset:2048
	v_mfma_f32_16x16x32_bf16 v[4:7], v[200:203], v[192:195], v[4:7]
	v_mfma_f32_16x16x32_bf16 v[0:3], v[208:211], v[192:195], v[0:3]
	ds_read_b128 v[164:167], v149 offset:3072
	v_mfma_f32_16x16x32_bf16 v[52:55], v[204:207], v[172:175], v[52:55]
	s_add_i32 s48, s48, 2
	v_mfma_f32_16x16x32_bf16 v[48:51], v[212:215], v[172:175], v[48:51]
	s_add_u32 s38, s38, 0x100
	s_addc_u32 s39, s39, 0
	v_mfma_f32_16x16x32_bf16 v[36:39], v[204:207], v[180:183], v[36:39]
	s_cmpk_gt_u32 s48, 0x55
	v_mfma_f32_16x16x32_bf16 v[32:35], v[212:215], v[180:183], v[32:35]
	s_mov_b64 s[8:9], s[10:11]
	v_mfma_f32_16x16x32_bf16 v[20:23], v[204:207], v[188:191], v[20:23]
	v_mfma_f32_16x16x32_bf16 v[16:19], v[212:215], v[188:191], v[16:19]
	v_mfma_f32_16x16x32_bf16 v[4:7], v[204:207], v[196:199], v[4:7]
	v_mfma_f32_16x16x32_bf16 v[0:3], v[212:215], v[196:199], v[0:3]
	s_setprio 0
	s_barrier
	s_cbranch_scc0 .LBB1_2653
	s_waitcnt lgkmcnt(0)
	v_mov_b32_e32 v144, v147
	v_mov_b32_e32 v152, v146
	s_lshl_b32 s2, s2, 8
	s_lshl_b32 s8, s37, 8
	s_add_i32 s2, s2, s27
	s_or_b32 s8, s8, s28
	v_add_u32_e32 v152, s2, v152
	v_lshl_add_u32 v144, v144, 3, s8
	v_ashrrev_i32_e32 v153, 31, v152
	v_ashrrev_i32_e32 v145, 31, v144
	v_lshlrev_b64 v[152:153], 11, v[152:153]
	v_lshl_add_u64 v[144:145], v[152:153], 0, v[144:145]
	v_lshl_add_u64 v[156:157], v[144:145], 1, s[6:7]
	global_load_dwordx4 v[162:165], v[156:157], off
	global_load_dwordx4 v[166:169], v[156:157], off offset:256
	s_mov_b64 s[98:99], 0x10000
	v_lshl_add_u64 v[154:155], v[156:157], 0, s[98:99]
	global_load_dwordx4 v[170:173], v[154:155], off
	global_load_dwordx4 v[174:177], v[154:155], off offset:256
	s_mov_b64 s[98:99], 0x20000
	v_lshl_add_u64 v[154:155], v[156:157], 0, s[98:99]
	global_load_dwordx4 v[178:181], v[154:155], off
	global_load_dwordx4 v[182:185], v[154:155], off offset:256
	s_mov_b64 s[98:99], 0x30000
	v_lshl_add_u64 v[154:155], v[156:157], 0, s[98:99]
	global_load_dwordx4 v[186:189], v[154:155], off
	global_load_dwordx4 v[190:193], v[154:155], off offset:256
	s_mov_b64 s[98:99], 0x80000
	v_lshl_add_u64 v[154:155], v[156:157], 0, s[98:99]
	global_load_dwordx4 v[194:197], v[154:155], off
	global_load_dwordx4 v[198:201], v[154:155], off offset:256
	s_mov_b64 s[98:99], 0x90000
	v_lshl_add_u64 v[154:155], v[156:157], 0, s[98:99]
	global_load_dwordx4 v[202:205], v[154:155], off
	global_load_dwordx4 v[206:209], v[154:155], off offset:256
	s_mov_b64 s[98:99], 0xa0000
	v_lshl_add_u64 v[154:155], v[156:157], 0, s[98:99]
	global_load_dwordx4 v[210:213], v[154:155], off
	global_load_dwordx4 v[248:251], v[154:155], off offset:256
	s_mov_b64 s[98:99], 0xb0000
	v_lshl_add_u64 v[154:155], v[156:157], 0, s[98:99]
	global_load_dwordx4 v[252:255], v[154:155], off
	s_waitcnt vmcnt(14)
	s_nop 1
	v_mov_b32_e32 v152, v162
	v_mov_b32_e32 v153, v163
	v_mov_b32_e32 v154, v164
	v_mov_b32_e32 v155, v165
	s_mov_b64 s[8:9], 0x8000
	s_and_b64 vcc, exec, s[40:41]
	s_mov_b32 s37, s35
	s_mov_b32 s2, s36
	s_mov_b64 s[10:11], s[44:45]
	s_waitcnt lgkmcnt(0)
	v_lshlrev_b32_e32 v158, 16, v152
	v_and_b32_e32 v159, 0xffff0000, v152
	v_lshlrev_b32_e32 v152, 16, v153
	v_and_b32_e32 v153, 0xffff0000, v153
	v_lshlrev_b32_e32 v160, 16, v154
	v_and_b32_e32 v161, 0xffff0000, v154
	v_lshlrev_b32_e32 v154, 16, v155
	v_and_b32_e32 v155, 0xffff0000, v155
	v_pk_add_f32 v[126:127], v[126:127], v[152:153]
	v_pk_add_f32 v[124:125], v[124:125], v[158:159]
	v_lshl_add_u64 v[152:153], v[144:145], 2, s[4:5]
	v_pk_add_f32 v[122:123], v[122:123], v[154:155]
	v_pk_add_f32 v[120:121], v[120:121], v[160:161]
	global_store_dwordx4 v[152:153], v[124:127], off
	global_store_dwordx4 v[152:153], v[120:123], off offset:16
	s_waitcnt vmcnt(15)
; DI unsigned pack2(float a, float b) { f32x2 v = {a, b}; hwbf16x2 r = __builtin_convertvector(v, hwbf16x2); return __builtin_bit_cast(unsigned, r); }
; DI float bflo(unsigned w) { return __uint_as_float(w << 16); }
; DI float bfhi(unsigned w) { return __uint_as_float(w & 0xffff0000u); }
;     DI void operator()(const f32x4 (&acc)[2][2][4][2], const Unit& u, int wr, int wc, int fr, int fq) const {
;     ...
;         for (int ai = 0; ai < 2; ++ai)
; #pragma unroll
;             for (int m = 0; m < 4; ++m) { const size_t ro = (size_t)(row0 + ai * HALF + m * 16) * D + col0;
; #pragma unroll
;                 for (int bj = 0; bj < 2; ++bj) {
;                     f32x4 x0, x1;
;                     if constexpr (IB) { const u32x4 w = *(const u32x4*)((const bf16_t*)Xin + ro + bj * HALF);
;                         x0 = (f32x4){bflo(w[0]), bfhi(w[0]), bflo(w[1]), bfhi(w[1])}; x1 = (f32x4){bflo(w[2]), bfhi(w[2]), bflo(w[3]), bfhi(w[3])}; }
;                     else { x0 = *(const f32x4*)((const float*)Xin + ro + bj * HALF); x1 = *(const f32x4*)((const float*)Xin + ro + bj * HALF + 4); }
;                     x0 += acc[ai][bj][m][0] * sc[bj][0]; x1 += acc[ai][bj][m][1] * sc[bj][1];
;                     if constexpr (OB) { u32x4 o; o[0] = pack2(x0[0], x0[1]); o[1] = pack2(x0[2], x0[3]); o[2] = pack2(x1[0], x1[1]); o[3] = pack2(x1[2], x1[3]);
;                         *(u32x4*)((bf16_t*)Xout + ro + bj * HALF) = o; }
;                     else { *(f32x4*)((float*)Xout + ro + bj * HALF) = x0; *(f32x4*)((float*)Xout + ro + bj * HALF + 4) = x1; } } }
	s_nop 1
	v_mov_b32_e32 v120, v166
	v_mov_b32_e32 v121, v167
	v_mov_b32_e32 v122, v168
	v_mov_b32_e32 v123, v169
	s_waitcnt lgkmcnt(0)
	v_lshlrev_b32_e32 v124, 16, v120
	v_and_b32_e32 v125, 0xffff0000, v120
	v_lshlrev_b32_e32 v120, 16, v121
	v_and_b32_e32 v121, 0xffff0000, v121
	v_lshlrev_b32_e32 v126, 16, v122
	v_and_b32_e32 v127, 0xffff0000, v122
	v_lshlrev_b32_e32 v122, 16, v123
	v_and_b32_e32 v123, 0xffff0000, v123
	v_pk_add_f32 v[118:119], v[118:119], v[120:121]
	v_pk_add_f32 v[116:117], v[116:117], v[124:125]
	v_pk_add_f32 v[114:115], v[114:115], v[122:123]
	v_pk_add_f32 v[112:113], v[112:113], v[126:127]
	global_store_dwordx4 v[152:153], v[116:119], off offset:512
	global_store_dwordx4 v[152:153], v[112:115], off offset:528
	s_nop 0
	v_lshl_add_u64 v[116:117], v[144:145], 0, s[8:9]
	v_lshl_add_u64 v[118:119], v[116:117], 1, s[6:7]
	s_waitcnt vmcnt(16)
	s_nop 1
	v_mov_b32_e32 v112, v170
	v_mov_b32_e32 v113, v171
	v_mov_b32_e32 v114, v172
	v_mov_b32_e32 v115, v173
	s_mov_b64 s[8:9], 0x10000
	s_waitcnt lgkmcnt(0)
	v_lshlrev_b32_e32 v120, 16, v112
	v_and_b32_e32 v121, 0xffff0000, v112
	v_lshlrev_b32_e32 v112, 16, v113
	v_and_b32_e32 v113, 0xffff0000, v113
	v_lshlrev_b32_e32 v122, 16, v114
	v_and_b32_e32 v123, 0xffff0000, v114
	v_lshlrev_b32_e32 v114, 16, v115
	v_and_b32_e32 v115, 0xffff0000, v115
	v_pk_add_f32 v[110:111], v[110:111], v[112:113]
	v_pk_add_f32 v[108:109], v[108:109], v[120:121]
	v_lshl_add_u64 v[112:113], v[116:117], 2, s[4:5]
	v_pk_add_f32 v[106:107], v[106:107], v[114:115]
	v_pk_add_f32 v[104:105], v[104:105], v[122:123]
	global_store_dwordx4 v[112:113], v[108:111], off
	global_store_dwordx4 v[112:113], v[104:107], off offset:16
	s_waitcnt vmcnt(17)
	s_nop 1
	v_mov_b32_e32 v104, v174
	v_mov_b32_e32 v105, v175
	v_mov_b32_e32 v106, v176
	v_mov_b32_e32 v107, v177
	s_waitcnt lgkmcnt(0)
	v_lshlrev_b32_e32 v108, 16, v104
	v_and_b32_e32 v109, 0xffff0000, v104
	v_lshlrev_b32_e32 v104, 16, v105
	v_and_b32_e32 v105, 0xffff0000, v105
	v_lshlrev_b32_e32 v110, 16, v106
	v_and_b32_e32 v111, 0xffff0000, v106
	v_lshlrev_b32_e32 v106, 16, v107
	v_and_b32_e32 v107, 0xffff0000, v107
	v_pk_add_f32 v[102:103], v[102:103], v[104:105]
	v_pk_add_f32 v[100:101], v[100:101], v[108:109]
	v_pk_add_f32 v[98:99], v[98:99], v[106:107]
	v_pk_add_f32 v[96:97], v[96:97], v[110:111]
	global_store_dwordx4 v[112:113], v[100:103], off offset:512
	global_store_dwordx4 v[112:113], v[96:99], off offset:528
	s_nop 0
	v_lshl_add_u64 v[100:101], v[144:145], 0, s[8:9]
	v_lshl_add_u64 v[102:103], v[100:101], 1, s[6:7]
	s_waitcnt vmcnt(18)
	s_nop 1
	v_mov_b32_e32 v96, v178
	v_mov_b32_e32 v97, v179
	v_mov_b32_e32 v98, v180
	v_mov_b32_e32 v99, v181
	s_mov_b64 s[8:9], 0x18000
	s_waitcnt lgkmcnt(0)
	v_lshlrev_b32_e32 v104, 16, v96
	v_and_b32_e32 v105, 0xffff0000, v96
	v_lshlrev_b32_e32 v96, 16, v97
	v_and_b32_e32 v97, 0xffff0000, v97
	v_lshlrev_b32_e32 v106, 16, v98
	v_and_b32_e32 v107, 0xffff0000, v98
	v_lshlrev_b32_e32 v98, 16, v99
	v_and_b32_e32 v99, 0xffff0000, v99
	v_pk_add_f32 v[94:95], v[94:95], v[96:97]
	v_pk_add_f32 v[92:93], v[92:93], v[104:105]
	v_lshl_add_u64 v[96:97], v[100:101], 2, s[4:5]
	v_pk_add_f32 v[90:91], v[90:91], v[98:99]
	v_pk_add_f32 v[88:89], v[88:89], v[106:107]
	global_store_dwordx4 v[96:97], v[92:95], off
	global_store_dwordx4 v[96:97], v[88:91], off offset:16
	s_waitcnt vmcnt(19)
	s_nop 1
	v_mov_b32_e32 v88, v182
	v_mov_b32_e32 v89, v183
	v_mov_b32_e32 v90, v184
	v_mov_b32_e32 v91, v185
	s_waitcnt lgkmcnt(0)
	v_lshlrev_b32_e32 v92, 16, v88
	v_and_b32_e32 v93, 0xffff0000, v88
	v_lshlrev_b32_e32 v88, 16, v89
	v_and_b32_e32 v89, 0xffff0000, v89
	v_lshlrev_b32_e32 v94, 16, v90
	v_and_b32_e32 v95, 0xffff0000, v90
	v_lshlrev_b32_e32 v90, 16, v91
	v_and_b32_e32 v91, 0xffff0000, v91
	v_pk_add_f32 v[86:87], v[86:87], v[88:89]
	v_pk_add_f32 v[84:85], v[84:85], v[92:93]
	v_pk_add_f32 v[82:83], v[82:83], v[90:91]
	v_pk_add_f32 v[80:81], v[80:81], v[94:95]
	global_store_dwordx4 v[96:97], v[84:87], off offset:512
	global_store_dwordx4 v[96:97], v[80:83], off offset:528
	s_nop 0
	v_lshl_add_u64 v[84:85], v[144:145], 0, s[8:9]
	v_lshl_add_u64 v[86:87], v[84:85], 1, s[6:7]
	s_waitcnt vmcnt(20)
	s_nop 1
	v_mov_b32_e32 v80, v186
	v_mov_b32_e32 v81, v187
	v_mov_b32_e32 v82, v188
	v_mov_b32_e32 v83, v189
	s_mov_b64 s[8:9], 0x40000
	s_waitcnt lgkmcnt(0)
	v_lshlrev_b32_e32 v88, 16, v80
	v_and_b32_e32 v89, 0xffff0000, v80
	v_lshlrev_b32_e32 v80, 16, v81
	v_and_b32_e32 v81, 0xffff0000, v81
	v_lshlrev_b32_e32 v90, 16, v82
	v_and_b32_e32 v91, 0xffff0000, v82
	v_lshlrev_b32_e32 v82, 16, v83
	v_and_b32_e32 v83, 0xffff0000, v83
	v_pk_add_f32 v[78:79], v[78:79], v[80:81]
	v_pk_add_f32 v[76:77], v[76:77], v[88:89]
	v_lshl_add_u64 v[80:81], v[84:85], 2, s[4:5]
	v_pk_add_f32 v[74:75], v[74:75], v[82:83]
	v_pk_add_f32 v[72:73], v[72:73], v[90:91]
	global_store_dwordx4 v[80:81], v[76:79], off
	global_store_dwordx4 v[80:81], v[72:75], off offset:16
	s_waitcnt vmcnt(21)
	s_nop 1
	v_mov_b32_e32 v72, v190
	v_mov_b32_e32 v73, v191
	v_mov_b32_e32 v74, v192
	v_mov_b32_e32 v75, v193
	s_waitcnt lgkmcnt(0)
	v_lshlrev_b32_e32 v76, 16, v72
	v_and_b32_e32 v77, 0xffff0000, v72
	v_lshlrev_b32_e32 v72, 16, v73
	v_and_b32_e32 v73, 0xffff0000, v73
	v_lshlrev_b32_e32 v78, 16, v74
	v_and_b32_e32 v79, 0xffff0000, v74
	v_lshlrev_b32_e32 v74, 16, v75
	v_and_b32_e32 v75, 0xffff0000, v75
	v_pk_add_f32 v[70:71], v[70:71], v[72:73]
	v_pk_add_f32 v[68:69], v[68:69], v[76:77]
	v_pk_add_f32 v[66:67], v[66:67], v[74:75]
	v_pk_add_f32 v[64:65], v[64:65], v[78:79]
	global_store_dwordx4 v[80:81], v[68:71], off offset:512
	global_store_dwordx4 v[80:81], v[64:67], off offset:528
	s_nop 0
	v_lshl_add_u64 v[68:69], v[144:145], 0, s[8:9]
	v_lshl_add_u64 v[70:71], v[68:69], 1, s[6:7]
	s_waitcnt vmcnt(22)
; DI unsigned pack2(float a, float b) { f32x2 v = {a, b}; hwbf16x2 r = __builtin_convertvector(v, hwbf16x2); return __builtin_bit_cast(unsigned, r); }
; DI float bflo(unsigned w) { return __uint_as_float(w << 16); }
; DI float bfhi(unsigned w) { return __uint_as_float(w & 0xffff0000u); }
; #define PG8_WAIT_V(n) asm volatile("s_waitcnt vmcnt(" #n ")" ::: "memory")
; #define PG8_BAR __builtin_amdgcn_s_barrier()
;     DI void operator()(const f32x4 (&acc)[2][2][4][2], const Unit& u, int wr, int wc, int fr, int fq) const {
;     ...
;         for (int ai = 0; ai < 2; ++ai)
; #pragma unroll
;             for (int m = 0; m < 4; ++m) { const size_t ro = (size_t)(row0 + ai * HALF + m * 16) * D + col0;
; #pragma unroll
;                 for (int bj = 0; bj < 2; ++bj) {
;                     f32x4 x0, x1;
;                     if constexpr (IB) { const u32x4 w = *(const u32x4*)((const bf16_t*)Xin + ro + bj * HALF);
;                         x0 = (f32x4){bflo(w[0]), bfhi(w[0]), bflo(w[1]), bfhi(w[1])}; x1 = (f32x4){bflo(w[2]), bfhi(w[2]), bflo(w[3]), bfhi(w[3])}; }
;                     else { x0 = *(const f32x4*)((const float*)Xin + ro + bj * HALF); x1 = *(const f32x4*)((const float*)Xin + ro + bj * HALF + 4); }
;                     x0 += acc[ai][bj][m][0] * sc[bj][0]; x1 += acc[ai][bj][m][1] * sc[bj][1];
;                     if constexpr (OB) { u32x4 o; o[0] = pack2(x0[0], x0[1]); o[1] = pack2(x0[2], x0[3]); o[2] = pack2(x1[0], x1[1]); o[3] = pack2(x1[2], x1[3]);
;                         *(u32x4*)((bf16_t*)Xout + ro + bj * HALF) = o; }
;                     else { *(f32x4*)((float*)Xout + ro + bj * HALF) = x0; *(f32x4*)((float*)Xout + ro + bj * HALF + 4) = x1; } } }
; template <class Map, class Epi>
; DI void gemm_phase(LAS unsigned char* lds, const Map& MP, const Epi& E, const int nM, const int nN, const int K, const int lda, const int ldb) {
;     ...
;     PG8_WAIT_V(0);
;     if (wr == 0) PG8_BAR;
;     PG8_BAR;
	s_nop 1
	v_mov_b32_e32 v64, v194
	v_mov_b32_e32 v65, v195
	v_mov_b32_e32 v66, v196
	v_mov_b32_e32 v67, v197
	s_mov_b64 s[8:9], 0x48000
	s_waitcnt lgkmcnt(0)
	v_lshlrev_b32_e32 v72, 16, v64
	v_and_b32_e32 v73, 0xffff0000, v64
	v_lshlrev_b32_e32 v64, 16, v65
	v_and_b32_e32 v65, 0xffff0000, v65
	v_lshlrev_b32_e32 v74, 16, v66
	v_and_b32_e32 v75, 0xffff0000, v66
	v_lshlrev_b32_e32 v66, 16, v67
	v_and_b32_e32 v67, 0xffff0000, v67
	v_pk_add_f32 v[62:63], v[62:63], v[64:65]
	v_pk_add_f32 v[60:61], v[60:61], v[72:73]
	v_lshl_add_u64 v[64:65], v[68:69], 2, s[4:5]
	v_pk_add_f32 v[58:59], v[58:59], v[66:67]
	v_pk_add_f32 v[56:57], v[56:57], v[74:75]
	global_store_dwordx4 v[64:65], v[60:63], off
	global_store_dwordx4 v[64:65], v[56:59], off offset:16
	s_waitcnt vmcnt(23)
	s_nop 1
	v_mov_b32_e32 v56, v198
	v_mov_b32_e32 v57, v199
	v_mov_b32_e32 v58, v200
	v_mov_b32_e32 v59, v201
	s_waitcnt lgkmcnt(0)
	v_lshlrev_b32_e32 v60, 16, v56
	v_and_b32_e32 v61, 0xffff0000, v56
	v_lshlrev_b32_e32 v56, 16, v57
	v_and_b32_e32 v57, 0xffff0000, v57
	v_lshlrev_b32_e32 v62, 16, v58
	v_and_b32_e32 v63, 0xffff0000, v58
	v_lshlrev_b32_e32 v58, 16, v59
	v_and_b32_e32 v59, 0xffff0000, v59
	v_pk_add_f32 v[54:55], v[54:55], v[56:57]
	v_pk_add_f32 v[52:53], v[52:53], v[60:61]
	v_pk_add_f32 v[50:51], v[50:51], v[58:59]
	v_pk_add_f32 v[48:49], v[48:49], v[62:63]
	global_store_dwordx4 v[64:65], v[52:55], off offset:512
	global_store_dwordx4 v[64:65], v[48:51], off offset:528
	s_nop 0
	v_lshl_add_u64 v[52:53], v[144:145], 0, s[8:9]
	v_lshl_add_u64 v[54:55], v[52:53], 1, s[6:7]
	s_waitcnt vmcnt(24)
	s_nop 1
	v_mov_b32_e32 v48, v202
	v_mov_b32_e32 v49, v203
	v_mov_b32_e32 v50, v204
	v_mov_b32_e32 v51, v205
	s_mov_b64 s[8:9], 0x50000
	s_waitcnt lgkmcnt(0)
	v_lshlrev_b32_e32 v56, 16, v48
	v_and_b32_e32 v57, 0xffff0000, v48
	v_lshlrev_b32_e32 v48, 16, v49
	v_and_b32_e32 v49, 0xffff0000, v49
	v_lshlrev_b32_e32 v58, 16, v50
	v_and_b32_e32 v59, 0xffff0000, v50
	v_lshlrev_b32_e32 v50, 16, v51
	v_and_b32_e32 v51, 0xffff0000, v51
	v_pk_add_f32 v[46:47], v[46:47], v[48:49]
	v_pk_add_f32 v[44:45], v[44:45], v[56:57]
	v_lshl_add_u64 v[48:49], v[52:53], 2, s[4:5]
	v_pk_add_f32 v[42:43], v[42:43], v[50:51]
	v_pk_add_f32 v[40:41], v[40:41], v[58:59]
	global_store_dwordx4 v[48:49], v[44:47], off
	global_store_dwordx4 v[48:49], v[40:43], off offset:16
	s_waitcnt vmcnt(25)
	s_nop 1
	v_mov_b32_e32 v40, v206
	v_mov_b32_e32 v41, v207
	v_mov_b32_e32 v42, v208
	v_mov_b32_e32 v43, v209
	s_waitcnt lgkmcnt(0)
	v_lshlrev_b32_e32 v44, 16, v40
	v_and_b32_e32 v45, 0xffff0000, v40
	v_lshlrev_b32_e32 v40, 16, v41
	v_and_b32_e32 v41, 0xffff0000, v41
	v_lshlrev_b32_e32 v46, 16, v42
	v_and_b32_e32 v47, 0xffff0000, v42
	v_lshlrev_b32_e32 v42, 16, v43
	v_and_b32_e32 v43, 0xffff0000, v43
	v_pk_add_f32 v[38:39], v[38:39], v[40:41]
	v_pk_add_f32 v[36:37], v[36:37], v[44:45]
	v_pk_add_f32 v[34:35], v[34:35], v[42:43]
	v_pk_add_f32 v[32:33], v[32:33], v[46:47]
	global_store_dwordx4 v[48:49], v[36:39], off offset:512
	global_store_dwordx4 v[48:49], v[32:35], off offset:528
	s_nop 0
	v_lshl_add_u64 v[36:37], v[144:145], 0, s[8:9]
	v_lshl_add_u64 v[38:39], v[36:37], 1, s[6:7]
	s_waitcnt vmcnt(26)
	s_nop 1
	v_mov_b32_e32 v32, v210
	v_mov_b32_e32 v33, v211
	v_mov_b32_e32 v34, v212
	v_mov_b32_e32 v35, v213
	s_mov_b64 s[8:9], 0x58000
	s_waitcnt lgkmcnt(0)
	v_lshlrev_b32_e32 v40, 16, v32
	v_and_b32_e32 v41, 0xffff0000, v32
	v_lshlrev_b32_e32 v32, 16, v33
	v_and_b32_e32 v33, 0xffff0000, v33
	v_lshlrev_b32_e32 v42, 16, v34
	v_and_b32_e32 v43, 0xffff0000, v34
	v_lshlrev_b32_e32 v34, 16, v35
	v_and_b32_e32 v35, 0xffff0000, v35
	v_pk_add_f32 v[30:31], v[30:31], v[32:33]
	v_pk_add_f32 v[28:29], v[28:29], v[40:41]
	v_lshl_add_u64 v[32:33], v[36:37], 2, s[4:5]
	v_pk_add_f32 v[26:27], v[26:27], v[34:35]
	v_pk_add_f32 v[24:25], v[24:25], v[42:43]
	global_store_dwordx4 v[32:33], v[28:31], off
	global_store_dwordx4 v[32:33], v[24:27], off offset:16
	s_waitcnt vmcnt(27)
	s_nop 1
	v_mov_b32_e32 v24, v248
	v_mov_b32_e32 v25, v249
	v_mov_b32_e32 v26, v250
	v_mov_b32_e32 v27, v251
	s_waitcnt lgkmcnt(0)
	v_lshlrev_b32_e32 v28, 16, v24
	v_and_b32_e32 v29, 0xffff0000, v24
	v_lshlrev_b32_e32 v24, 16, v25
	v_and_b32_e32 v25, 0xffff0000, v25
	v_lshlrev_b32_e32 v30, 16, v26
	v_and_b32_e32 v31, 0xffff0000, v26
	v_lshlrev_b32_e32 v26, 16, v27
	v_and_b32_e32 v27, 0xffff0000, v27
	v_pk_add_f32 v[22:23], v[22:23], v[24:25]
	v_pk_add_f32 v[20:21], v[20:21], v[28:29]
	v_pk_add_f32 v[18:19], v[18:19], v[26:27]
	v_pk_add_f32 v[16:17], v[16:17], v[30:31]
	global_store_dwordx4 v[32:33], v[20:23], off offset:512
	global_store_dwordx4 v[32:33], v[16:19], off offset:528
	s_nop 0
	v_lshl_add_u64 v[20:21], v[144:145], 0, s[8:9]
	v_lshl_add_u64 v[22:23], v[20:21], 1, s[6:7]
	s_waitcnt vmcnt(28)
	s_nop 1
	v_mov_b32_e32 v16, v252
	v_mov_b32_e32 v17, v253
	v_mov_b32_e32 v18, v254
	v_mov_b32_e32 v19, v255
	s_mov_b64 s[8:9], s[42:43]
	s_waitcnt lgkmcnt(0)
	v_lshlrev_b32_e32 v24, 16, v16
	v_and_b32_e32 v25, 0xffff0000, v16
	v_lshlrev_b32_e32 v16, 16, v17
	v_and_b32_e32 v17, 0xffff0000, v17
	v_lshlrev_b32_e32 v26, 16, v18
	v_and_b32_e32 v27, 0xffff0000, v18
	v_lshlrev_b32_e32 v18, 16, v19
	v_and_b32_e32 v19, 0xffff0000, v19
	v_pk_add_f32 v[14:15], v[14:15], v[16:17]
	v_pk_add_f32 v[12:13], v[12:13], v[24:25]
	v_lshl_add_u64 v[16:17], v[20:21], 2, s[4:5]
	v_pk_add_f32 v[10:11], v[10:11], v[18:19]
	v_pk_add_f32 v[8:9], v[8:9], v[26:27]
	global_store_dwordx4 v[16:17], v[12:15], off
	global_store_dwordx4 v[16:17], v[8:11], off offset:16
	global_load_dwordx4 v[8:11], v[22:23], off offset:256
	s_waitcnt vmcnt(0) lgkmcnt(0)
	v_lshlrev_b32_e32 v12, 16, v8
	v_and_b32_e32 v13, 0xffff0000, v8
	v_lshlrev_b32_e32 v8, 16, v9
	v_and_b32_e32 v9, 0xffff0000, v9
	v_lshlrev_b32_e32 v14, 16, v10
	v_and_b32_e32 v15, 0xffff0000, v10
	v_lshlrev_b32_e32 v10, 16, v11
	v_and_b32_e32 v11, 0xffff0000, v11
	v_pk_add_f32 v[6:7], v[6:7], v[8:9]
	v_pk_add_f32 v[4:5], v[4:5], v[12:13]
	v_pk_add_f32 v[2:3], v[2:3], v[10:11]
	v_pk_add_f32 v[0:1], v[0:1], v[14:15]
	global_store_dwordx4 v[16:17], v[4:7], off offset:512
	global_store_dwordx4 v[16:17], v[0:3], off offset:528
	s_cbranch_vccz .LBB1_2646
	s_waitcnt vmcnt(0)
	s_cmpk_gt_u32 s3, 0xff
	s_cbranch_scc1 .LBB1_2657
	s_barrier
